# phase12 PEER v-gather rewritten by hand: rolling 16-row prefetch, 2 tokens of equal walk direction interleaved per wave
# speedup vs baseline: 1.0720x; 1.0246x over previous
; DEVI int launder(int x) { asm volatile("" : "+v"(x)); return x; }
; template <int PART>
; DEVI void phase_peer_gather(const Params& p, unsigned char* smem) {
;   const int w0_ = threadIdx.x >> 6;
; #pragma unroll 1
;   for (int tok = blockIdx.x * 4 + w0_; tok < NTOK; tok += gridDim.x * 4) {
;     if (NTOK % (gridDim.x * 4) == 0) __syncthreads();
;     const int tid = launder(threadIdx.x), lane = tid & 63;
;     const uint4* hp4 = (const uint4*)(p.hn + (size_t)tok * LDA + lane * 16);
;     float hv[16], xn[16], y[16];
;     {
;       const uint4 a0 = hp4[0], a1 = hp4[1];
;       const unsigned hu[8] = {a0.x, a0.y, a0.z, a0.w, a1.x, a1.y, a1.z, a1.w};
; #pragma unroll
;       for (int i = 0; i < 8; ++i) { hv[2 * i] = __uint_as_float(hu[i] << 16); hv[2 * i + 1] = __uint_as_float(hu[i] & 0xffff0000u); }
;     }
;     float ss = 0.f;
; #pragma unroll
;     for (int i = 0; i < 16; ++i) ss += hv[i] * hv[i];
;     ss = wave_sum(ss);
;     const float rstd = rsqrtf(ss * (1.f / D) + 1e-6f);
;     {
;       const float4* g4 = (const float4*)p.peer_g + lane * 4;
;       const float4 a0 = g4[0], a1 = g4[1], a2 = g4[2], a3 = g4[3];
;       const float gg[16] = {a0.x, a0.y, a0.z, a0.w, a1.x, a1.y, a1.z, a1.w, a2.x, a2.y, a2.z, a2.w, a3.x, a3.y, a3.z, a3.w};
; #pragma unroll
;       for (int i = 0; i < 16; ++i) { xn[i] = hv[i] * rstd * gg[i]; y[i] = 0.f; }
;     }
;     int e0 = p.experts[(size_t)tok * 128 + lane], e1 = p.experts[(size_t)tok * 128 + 64 + lane];
;     float g0 = p.gates[(size_t)tok * 128 + lane], g1 = p.gates[(size_t)tok * 128 + 64 + lane];
;     ...
;     f32x2 xn2[8], y2[8];
; #pragma unroll
;     for (int i = 0; i < 8; ++i) { xn2[i] = f32x2{xn[2 * i], xn[2 * i + 1]}; y2[i] = f32x2{0.f, 0.f}; }
;     if (PART == 0) {
;       LOADB_(ca, 0)
; #pragma unroll 1
;       for (int bi = 0; bi < 16; bi += 2) {
;         LOADB_(cb, bi + 1)
;         COMPU_(ca, bi)
;         if (bi + 2 < 16) { LOADB_(ca, bi + 2) }
;         COMPU_(cb, bi + 1)
;       }
;       p.gates[(size_t)tok * 128 + lane] = cf0;
;       p.gates[(size_t)tok * 128 + 64 + lane] = cf1;
;       continue;
;     }
;     cf0 = g0; cf1 = g1;
;     LOADB_(ca, 16)
; #pragma unroll 1
;     for (int bi = 16; bi < 32; bi += 2) {
;       LOADB_(cb, bi + 1)
;       COMPV_(ca, bi)
;       if (bi + 2 < 32) { LOADB_(ca, bi + 2) }
;       COMPV_(cb, bi + 1)
.LBB0_1447:
	s_cmp_gt_i32 s88, 12
	s_cselect_b64 s[0:1], -1, 0
	s_cmp_lt_i32 s89, 12
	s_cselect_b64 s[2:3], -1, 0
	s_or_b64 s[0:1], s[0:1], s[2:3]
	s_and_b64 vcc, exec, s[0:1]
	s_cbranch_vccnz .LBB0_1511
	v_and_b32_e32 v238, 63, v210
	v_lshlrev_b32_e32 v208, 4, v238
	v_lshlrev_b32_e32 v209, 2, v238
	v_lshlrev_b32_e32 v211, 5, v238
	v_lshlrev_b32_e32 v212, 6, v238
	s_load_dwordx2 s[16:17], s[68:69], 0xd0
	s_load_dwordx2 s[14:15], s[68:69], 0xd8
	s_load_dwordx2 s[6:7], s[68:69], 0xe0
	s_load_dwordx2 s[8:9], s[68:69], 0x1b0
	s_load_dwordx2 s[10:11], s[68:69], 0x1b8
	s_load_dwordx2 s[12:13], s[68:69], 0x1c8
	s_load_dword s2, s[68:69], 0x200
	v_lshrrev_b32_e32 v239, 6, v210
	s_nop 0
	v_readfirstlane_b32 s3, v239
	s_waitcnt lgkmcnt(0)
	s_lshl_b32 s2, s2, 2
	s_lshl_b32 s18, s90, 2
	s_add_u32 s3, s3, s18
	s_add_i32 s18, s2, -1
	s_and_b32 s19, s18, s2
	s_and_b32 s18, s18, 0x8000
	s_or_b32 s32, s18, s19
	s_mov_b32 s34, 0
	s_cmp_ge_u32 s3, 0x8000
	s_cbranch_scc1 .Lp12_done
	global_load_dwordx4 v[128:131], v212, s[16:17]
	global_load_dwordx4 v[132:135], v212, s[16:17] offset:16
	global_load_dwordx4 v[136:139], v212, s[16:17] offset:32
	global_load_dwordx4 v[140:143], v212, s[16:17] offset:48
	s_mov_b32 s33, s3
	s_cmp_lt_u32 s33, 0x8000
	s_cselect_b32 s33, s33, s3
	s_lshl_b32 s18, s33, 9
	v_add_u32_e32 v236, s18, v209
	global_load_dword v176, v236, s[8:9]
	global_load_dword v177, v236, s[8:9] offset:256
	global_load_dword v178, v236, s[10:11]
	global_load_dword v179, v236, s[10:11] offset:256
	s_mov_b32 s33, s3
	s_add_u32 s33, s33, s2
	s_add_u32 s33, s33, s2
	s_cmp_lt_u32 s33, 0x8000
	s_cselect_b32 s33, s33, s3
	s_lshl_b32 s18, s33, 9
	v_add_u32_e32 v236, s18, v209
	global_load_dword v180, v236, s[8:9]
	global_load_dword v181, v236, s[8:9] offset:256
	global_load_dword v182, v236, s[10:11]
	global_load_dword v183, v236, s[10:11] offset:256
	v_mov_b32_e32 v64, 0
	v_mov_b32_e32 v65, 0
	v_mov_b32_e32 v66, 0
	v_mov_b32_e32 v67, 0
	v_mov_b32_e32 v68, 0
	v_mov_b32_e32 v69, 0
	v_mov_b32_e32 v70, 0
	v_mov_b32_e32 v71, 0
	v_mov_b32_e32 v72, 0
	v_mov_b32_e32 v73, 0
	v_mov_b32_e32 v74, 0
	v_mov_b32_e32 v75, 0
	v_mov_b32_e32 v76, 0
	v_mov_b32_e32 v77, 0
	v_mov_b32_e32 v78, 0
	v_mov_b32_e32 v79, 0
	v_mov_b32_e32 v80, 0
	v_mov_b32_e32 v81, 0
	v_mov_b32_e32 v82, 0
	v_mov_b32_e32 v83, 0
	v_mov_b32_e32 v84, 0
	v_mov_b32_e32 v85, 0
	v_mov_b32_e32 v86, 0
	v_mov_b32_e32 v87, 0
	v_mov_b32_e32 v88, 0
	v_mov_b32_e32 v89, 0
	v_mov_b32_e32 v90, 0
	v_mov_b32_e32 v91, 0
	v_mov_b32_e32 v92, 0
	v_mov_b32_e32 v93, 0
	v_mov_b32_e32 v94, 0
	v_mov_b32_e32 v95, 0
	s_waitcnt vmcnt(0)
	v_readlane_b32 s28, v176, 0
	s_lshl_b32 s28, s28, 10
	v_add_u32_e32 v232, s28, v208
	global_load_dwordx4 v[0:3], v232, s[12:13]
	v_readlane_b32 s29, v180, 0
	s_lshl_b32 s29, s29, 10
	v_add_u32_e32 v233, s29, v208
	global_load_dwordx4 v[4:7], v233, s[12:13]
	v_readlane_b32 s30, v176, 1
	s_lshl_b32 s30, s30, 10
	v_add_u32_e32 v234, s30, v208
	global_load_dwordx4 v[8:11], v234, s[12:13]
	v_readlane_b32 s31, v180, 1
	s_lshl_b32 s31, s31, 10
	v_add_u32_e32 v235, s31, v208
	global_load_dwordx4 v[12:15], v235, s[12:13]
	v_readlane_b32 s28, v176, 2
	s_lshl_b32 s28, s28, 10
	v_add_u32_e32 v232, s28, v208
	global_load_dwordx4 v[16:19], v232, s[12:13]
	v_readlane_b32 s29, v180, 2
	s_lshl_b32 s29, s29, 10
	v_add_u32_e32 v233, s29, v208
	global_load_dwordx4 v[20:23], v233, s[12:13]
	v_readlane_b32 s30, v176, 3
	s_lshl_b32 s30, s30, 10
	v_add_u32_e32 v234, s30, v208
	global_load_dwordx4 v[24:27], v234, s[12:13]
	v_readlane_b32 s31, v180, 3
	s_lshl_b32 s31, s31, 10
	v_add_u32_e32 v235, s31, v208
	global_load_dwordx4 v[28:31], v235, s[12:13]
	v_readlane_b32 s28, v176, 4
	s_lshl_b32 s28, s28, 10
	v_add_u32_e32 v232, s28, v208
	global_load_dwordx4 v[32:35], v232, s[12:13]
	v_readlane_b32 s29, v180, 4
	s_lshl_b32 s29, s29, 10
	v_add_u32_e32 v233, s29, v208
	global_load_dwordx4 v[36:39], v233, s[12:13]
	v_readlane_b32 s30, v176, 5
	s_lshl_b32 s30, s30, 10
	v_add_u32_e32 v234, s30, v208
	global_load_dwordx4 v[40:43], v234, s[12:13]
	v_readlane_b32 s31, v180, 5
	s_lshl_b32 s31, s31, 10
	v_add_u32_e32 v235, s31, v208
	global_load_dwordx4 v[44:47], v235, s[12:13]
	v_readlane_b32 s28, v176, 6
	s_lshl_b32 s28, s28, 10
	v_add_u32_e32 v232, s28, v208
	global_load_dwordx4 v[48:51], v232, s[12:13]
	v_readlane_b32 s29, v180, 6
	s_lshl_b32 s29, s29, 10
	v_add_u32_e32 v233, s29, v208
	global_load_dwordx4 v[52:55], v233, s[12:13]
	v_readlane_b32 s30, v176, 7
	s_lshl_b32 s30, s30, 10
	v_add_u32_e32 v234, s30, v208
	global_load_dwordx4 v[56:59], v234, s[12:13]
	v_readlane_b32 s31, v180, 7
	s_lshl_b32 s31, s31, 10
	v_add_u32_e32 v235, s31, v208
	global_load_dwordx4 v[60:63], v235, s[12:13]
	global_load_dwordx4 v[128:131], v212, s[16:17]
	global_load_dwordx4 v[132:135], v212, s[16:17] offset:16
	global_load_dwordx4 v[136:139], v212, s[16:17] offset:32
	global_load_dwordx4 v[140:143], v212, s[16:17] offset:48
	global_load_dwordx4 v[128:131], v212, s[16:17]
	global_load_dwordx4 v[132:135], v212, s[16:17] offset:16
	global_load_dwordx4 v[136:139], v212, s[16:17] offset:32
	global_load_dwordx4 v[140:143], v212, s[16:17] offset:48
.Lp12_group:
	s_cmp_lg_u32 s32, 0
	s_cbranch_scc1 .Lp12_nobar
	s_barrier
; DEVI int launder(int x) { asm volatile("" : "+v"(x)); return x; }
; template <int PART>
; DEVI void phase_peer_gather(const Params& p, unsigned char* smem) {
;     ...
;   for (int tok = blockIdx.x * 4 + w0_; tok < NTOK; tok += gridDim.x * 4) {
;     if (NTOK % (gridDim.x * 4) == 0) __syncthreads();
;     const int tid = launder(threadIdx.x), lane = tid & 63;
;     const uint4* hp4 = (const uint4*)(p.hn + (size_t)tok * LDA + lane * 16);
;     float hv[16], xn[16], y[16];
;     {
;       const uint4 a0 = hp4[0], a1 = hp4[1];
;       const unsigned hu[8] = {a0.x, a0.y, a0.z, a0.w, a1.x, a1.y, a1.z, a1.w};
; #pragma unroll
;       for (int i = 0; i < 8; ++i) { hv[2 * i] = __uint_as_float(hu[i] << 16); hv[2 * i + 1] = __uint_as_float(hu[i] & 0xffff0000u); }
;     }
;     float ss = 0.f;
; #pragma unroll
;     for (int i = 0; i < 16; ++i) ss += hv[i] * hv[i];
;     ss = wave_sum(ss);
;     const float rstd = rsqrtf(ss * (1.f / D) + 1e-6f);
;     {
;       const float4* g4 = (const float4*)p.peer_g + lane * 4;
;       const float4 a0 = g4[0], a1 = g4[1], a2 = g4[2], a3 = g4[3];
;       const float gg[16] = {a0.x, a0.y, a0.z, a0.w, a1.x, a1.y, a1.z, a1.w, a2.x, a2.y, a2.z, a2.w, a3.x, a3.y, a3.z, a3.w};
; #pragma unroll
;       for (int i = 0; i < 16; ++i) { xn[i] = hv[i] * rstd * gg[i]; y[i] = 0.f; }
;     }
;     int e0 = p.experts[(size_t)tok * 128 + lane], e1 = p.experts[(size_t)tok * 128 + 64 + lane];
;     float g0 = p.gates[(size_t)tok * 128 + lane], g1 = p.gates[(size_t)tok * 128 + 64 + lane];
.Lp12_nobar:
	s_mul_i32 s35, s2, 3
	s_bitcmp1_b32 s34, 0
	s_cselect_b32 s35, s35, s2
	s_add_u32 s33, s3, s35
	s_cmp_lt_u32 s33, 0x8000
	s_cselect_b32 s33, s33, s3
	s_lshl_b32 s18, s33, 9
	v_add_u32_e32 v236, s18, v209
	global_load_dword v192, v236, s[8:9]
	global_load_dword v193, v236, s[8:9] offset:256
	global_load_dword v194, v236, s[10:11]
	global_load_dword v195, v236, s[10:11] offset:256
	s_add_u32 s33, s3, s35
	s_add_u32 s33, s33, s2
	s_add_u32 s33, s33, s2
	s_cmp_lt_u32 s33, 0x8000
	s_cselect_b32 s33, s33, s3
	s_lshl_b32 s18, s33, 9
	v_add_u32_e32 v236, s18, v209
	global_load_dword v196, v236, s[8:9]
	global_load_dword v197, v236, s[8:9] offset:256
	global_load_dword v198, v236, s[10:11]
	global_load_dword v199, v236, s[10:11] offset:256
	s_mov_b32 s33, s3
	s_cmp_lt_u32 s33, 0x8000
	s_cselect_b32 s33, s33, s3
	s_mul_i32 s19, s33, 0x880
	v_add_u32_e32 v237, s19, v211
	global_load_dwordx4 v[144:147], v237, s[6:7]
	global_load_dwordx4 v[148:151], v237, s[6:7] offset:16
	s_mov_b32 s33, s3
	s_add_u32 s33, s33, s2
	s_add_u32 s33, s33, s2
	s_cmp_lt_u32 s33, 0x8000
	s_cselect_b32 s33, s33, s3
	s_mul_i32 s19, s33, 0x880
	v_add_u32_e32 v237, s19, v211
	global_load_dwordx4 v[152:155], v237, s[6:7]
	global_load_dwordx4 v[156:159], v237, s[6:7] offset:16
	v_readlane_b32 s20, v178, 0
	s_waitcnt vmcnt(35)
	v_readlane_b32 s22, v182, 0
	v_cvt_pk_f32_fp8_e32 v[216:217], v0
	v_cvt_pk_f32_fp8_sdwa v[218:219], v0 src0_sel:WORD_1
	v_cvt_pk_f32_fp8_e32 v[220:221], v1
	v_cvt_pk_f32_fp8_sdwa v[222:223], v1 src0_sel:WORD_1
	v_cvt_pk_f32_fp8_e32 v[224:225], v2
	v_cvt_pk_f32_fp8_sdwa v[226:227], v2 src0_sel:WORD_1
	v_cvt_pk_f32_fp8_e32 v[228:229], v3
	v_cvt_pk_f32_fp8_sdwa v[230:231], v3 src0_sel:WORD_1
	v_pk_fma_f32 v[64:65], s[20:21], v[216:217], v[64:65] op_sel_hi:[0,1,1]
	v_pk_fma_f32 v[66:67], s[20:21], v[218:219], v[66:67] op_sel_hi:[0,1,1]
	v_pk_fma_f32 v[68:69], s[20:21], v[220:221], v[68:69] op_sel_hi:[0,1,1]
	v_pk_fma_f32 v[70:71], s[20:21], v[222:223], v[70:71] op_sel_hi:[0,1,1]
	v_pk_fma_f32 v[72:73], s[20:21], v[224:225], v[72:73] op_sel_hi:[0,1,1]
	v_pk_fma_f32 v[74:75], s[20:21], v[226:227], v[74:75] op_sel_hi:[0,1,1]
	v_pk_fma_f32 v[76:77], s[20:21], v[228:229], v[76:77] op_sel_hi:[0,1,1]
	v_pk_fma_f32 v[78:79], s[20:21], v[230:231], v[78:79] op_sel_hi:[0,1,1]
	v_readlane_b32 s28, v176, 8
	s_lshl_b32 s28, s28, 10
	v_add_u32_e32 v232, s28, v208
	global_load_dwordx4 v[0:3], v232, s[12:13]
	s_waitcnt vmcnt(35)
	v_readlane_b32 s24, v178, 1
	v_cvt_pk_f32_fp8_e32 v[216:217], v4
	v_cvt_pk_f32_fp8_sdwa v[218:219], v4 src0_sel:WORD_1
	v_cvt_pk_f32_fp8_e32 v[220:221], v5
	v_cvt_pk_f32_fp8_sdwa v[222:223], v5 src0_sel:WORD_1
	v_cvt_pk_f32_fp8_e32 v[224:225], v6
	v_cvt_pk_f32_fp8_sdwa v[226:227], v6 src0_sel:WORD_1
	v_cvt_pk_f32_fp8_e32 v[228:229], v7
	v_cvt_pk_f32_fp8_sdwa v[230:231], v7 src0_sel:WORD_1
	v_pk_fma_f32 v[80:81], s[22:23], v[216:217], v[80:81] op_sel_hi:[0,1,1]
	v_pk_fma_f32 v[82:83], s[22:23], v[218:219], v[82:83] op_sel_hi:[0,1,1]
	v_pk_fma_f32 v[84:85], s[22:23], v[220:221], v[84:85] op_sel_hi:[0,1,1]
	v_pk_fma_f32 v[86:87], s[22:23], v[222:223], v[86:87] op_sel_hi:[0,1,1]
	v_pk_fma_f32 v[88:89], s[22:23], v[224:225], v[88:89] op_sel_hi:[0,1,1]
	v_pk_fma_f32 v[90:91], s[22:23], v[226:227], v[90:91] op_sel_hi:[0,1,1]
	v_pk_fma_f32 v[92:93], s[22:23], v[228:229], v[92:93] op_sel_hi:[0,1,1]
	v_pk_fma_f32 v[94:95], s[22:23], v[230:231], v[94:95] op_sel_hi:[0,1,1]
	v_readlane_b32 s29, v180, 8
	s_lshl_b32 s29, s29, 10
	v_add_u32_e32 v233, s29, v208
	global_load_dwordx4 v[4:7], v233, s[12:13]
	s_waitcnt vmcnt(35)
	v_readlane_b32 s26, v182, 1
	v_cvt_pk_f32_fp8_e32 v[216:217], v8
	v_cvt_pk_f32_fp8_sdwa v[218:219], v8 src0_sel:WORD_1
	v_cvt_pk_f32_fp8_e32 v[220:221], v9
	v_cvt_pk_f32_fp8_sdwa v[222:223], v9 src0_sel:WORD_1
	v_cvt_pk_f32_fp8_e32 v[224:225], v10
	v_cvt_pk_f32_fp8_sdwa v[226:227], v10 src0_sel:WORD_1
	v_cvt_pk_f32_fp8_e32 v[228:229], v11
	v_cvt_pk_f32_fp8_sdwa v[230:231], v11 src0_sel:WORD_1
	v_pk_fma_f32 v[64:65], s[24:25], v[216:217], v[64:65] op_sel_hi:[0,1,1]
	v_pk_fma_f32 v[66:67], s[24:25], v[218:219], v[66:67] op_sel_hi:[0,1,1]
	v_pk_fma_f32 v[68:69], s[24:25], v[220:221], v[68:69] op_sel_hi:[0,1,1]
	v_pk_fma_f32 v[70:71], s[24:25], v[222:223], v[70:71] op_sel_hi:[0,1,1]
	v_pk_fma_f32 v[72:73], s[24:25], v[224:225], v[72:73] op_sel_hi:[0,1,1]
	v_pk_fma_f32 v[74:75], s[24:25], v[226:227], v[74:75] op_sel_hi:[0,1,1]
	v_pk_fma_f32 v[76:77], s[24:25], v[228:229], v[76:77] op_sel_hi:[0,1,1]
	v_pk_fma_f32 v[78:79], s[24:25], v[230:231], v[78:79] op_sel_hi:[0,1,1]
	v_readlane_b32 s30, v176, 9
	s_lshl_b32 s30, s30, 10
	v_add_u32_e32 v234, s30, v208
	global_load_dwordx4 v[8:11], v234, s[12:13]
	s_waitcnt vmcnt(35)
	v_readlane_b32 s20, v178, 2
	v_cvt_pk_f32_fp8_e32 v[216:217], v12
	v_cvt_pk_f32_fp8_sdwa v[218:219], v12 src0_sel:WORD_1
	v_cvt_pk_f32_fp8_e32 v[220:221], v13
	v_cvt_pk_f32_fp8_sdwa v[222:223], v13 src0_sel:WORD_1
	v_cvt_pk_f32_fp8_e32 v[224:225], v14
	v_cvt_pk_f32_fp8_sdwa v[226:227], v14 src0_sel:WORD_1
	v_cvt_pk_f32_fp8_e32 v[228:229], v15
	v_cvt_pk_f32_fp8_sdwa v[230:231], v15 src0_sel:WORD_1
	v_pk_fma_f32 v[80:81], s[26:27], v[216:217], v[80:81] op_sel_hi:[0,1,1]
	v_pk_fma_f32 v[82:83], s[26:27], v[218:219], v[82:83] op_sel_hi:[0,1,1]
	v_pk_fma_f32 v[84:85], s[26:27], v[220:221], v[84:85] op_sel_hi:[0,1,1]
	v_pk_fma_f32 v[86:87], s[26:27], v[222:223], v[86:87] op_sel_hi:[0,1,1]
	v_pk_fma_f32 v[88:89], s[26:27], v[224:225], v[88:89] op_sel_hi:[0,1,1]
	v_pk_fma_f32 v[90:91], s[26:27], v[226:227], v[90:91] op_sel_hi:[0,1,1]
	v_pk_fma_f32 v[92:93], s[26:27], v[228:229], v[92:93] op_sel_hi:[0,1,1]
	v_pk_fma_f32 v[94:95], s[26:27], v[230:231], v[94:95] op_sel_hi:[0,1,1]
	v_readlane_b32 s31, v180, 9
	s_lshl_b32 s31, s31, 10
	v_add_u32_e32 v235, s31, v208
	global_load_dwordx4 v[12:15], v235, s[12:13]
	s_waitcnt vmcnt(35)
; template <int PART>
; DEVI void phase_peer_gather(const Params& p, unsigned char* smem) {
;     ...
;     const bool b5 = (lane & 32) != 0, b4 = (lane & 16) != 0, b3 = (lane & 8) != 0;
;     const int fsrc = ((lane & 4) << 3) | ((lane & 2) << 3) | ((lane & 1) << 3);
;     f32x2 xn2[8], y2[8];
; #pragma unroll
;     for (int i = 0; i < 8; ++i) { xn2[i] = f32x2{xn[2 * i], xn[2 * i + 1]}; y2[i] = f32x2{0.f, 0.f}; }
;     if (PART == 0) {
;       LOADB_(ca, 0)
; #pragma unroll 1
;       for (int bi = 0; bi < 16; bi += 2) {
;         LOADB_(cb, bi + 1)
;         COMPU_(ca, bi)
;         if (bi + 2 < 16) { LOADB_(ca, bi + 2) }
;         COMPU_(cb, bi + 1)
;       }
;       p.gates[(size_t)tok * 128 + lane] = cf0;
;       p.gates[(size_t)tok * 128 + 64 + lane] = cf1;
;       continue;
;     }
;     cf0 = g0; cf1 = g1;
;     LOADB_(ca, 16)
; #pragma unroll 1
;     for (int bi = 16; bi < 32; bi += 2) {
;       LOADB_(cb, bi + 1)
;       COMPV_(ca, bi)
;       if (bi + 2 < 32) { LOADB_(ca, bi + 2) }
;       COMPV_(cb, bi + 1)
;     }
	v_readlane_b32 s22, v182, 2
	v_cvt_pk_f32_fp8_e32 v[216:217], v16
	v_cvt_pk_f32_fp8_sdwa v[218:219], v16 src0_sel:WORD_1
	v_cvt_pk_f32_fp8_e32 v[220:221], v17
	v_cvt_pk_f32_fp8_sdwa v[222:223], v17 src0_sel:WORD_1
	v_cvt_pk_f32_fp8_e32 v[224:225], v18
	v_cvt_pk_f32_fp8_sdwa v[226:227], v18 src0_sel:WORD_1
	v_cvt_pk_f32_fp8_e32 v[228:229], v19
	v_cvt_pk_f32_fp8_sdwa v[230:231], v19 src0_sel:WORD_1
	v_pk_fma_f32 v[64:65], s[20:21], v[216:217], v[64:65] op_sel_hi:[0,1,1]
	v_pk_fma_f32 v[66:67], s[20:21], v[218:219], v[66:67] op_sel_hi:[0,1,1]
	v_pk_fma_f32 v[68:69], s[20:21], v[220:221], v[68:69] op_sel_hi:[0,1,1]
	v_pk_fma_f32 v[70:71], s[20:21], v[222:223], v[70:71] op_sel_hi:[0,1,1]
	v_pk_fma_f32 v[72:73], s[20:21], v[224:225], v[72:73] op_sel_hi:[0,1,1]
	v_pk_fma_f32 v[74:75], s[20:21], v[226:227], v[74:75] op_sel_hi:[0,1,1]
	v_pk_fma_f32 v[76:77], s[20:21], v[228:229], v[76:77] op_sel_hi:[0,1,1]
	v_pk_fma_f32 v[78:79], s[20:21], v[230:231], v[78:79] op_sel_hi:[0,1,1]
	v_readlane_b32 s28, v176, 10
	s_lshl_b32 s28, s28, 10
	v_add_u32_e32 v232, s28, v208
	global_load_dwordx4 v[16:19], v232, s[12:13]
	s_waitcnt vmcnt(35)
	v_readlane_b32 s24, v178, 3
	v_cvt_pk_f32_fp8_e32 v[216:217], v20
	v_cvt_pk_f32_fp8_sdwa v[218:219], v20 src0_sel:WORD_1
	v_cvt_pk_f32_fp8_e32 v[220:221], v21
	v_cvt_pk_f32_fp8_sdwa v[222:223], v21 src0_sel:WORD_1
	v_cvt_pk_f32_fp8_e32 v[224:225], v22
	v_cvt_pk_f32_fp8_sdwa v[226:227], v22 src0_sel:WORD_1
	v_cvt_pk_f32_fp8_e32 v[228:229], v23
	v_cvt_pk_f32_fp8_sdwa v[230:231], v23 src0_sel:WORD_1
	v_pk_fma_f32 v[80:81], s[22:23], v[216:217], v[80:81] op_sel_hi:[0,1,1]
	v_pk_fma_f32 v[82:83], s[22:23], v[218:219], v[82:83] op_sel_hi:[0,1,1]
	v_pk_fma_f32 v[84:85], s[22:23], v[220:221], v[84:85] op_sel_hi:[0,1,1]
	v_pk_fma_f32 v[86:87], s[22:23], v[222:223], v[86:87] op_sel_hi:[0,1,1]
	v_pk_fma_f32 v[88:89], s[22:23], v[224:225], v[88:89] op_sel_hi:[0,1,1]
	v_pk_fma_f32 v[90:91], s[22:23], v[226:227], v[90:91] op_sel_hi:[0,1,1]
	v_pk_fma_f32 v[92:93], s[22:23], v[228:229], v[92:93] op_sel_hi:[0,1,1]
	v_pk_fma_f32 v[94:95], s[22:23], v[230:231], v[94:95] op_sel_hi:[0,1,1]
	v_readlane_b32 s29, v180, 10
	s_lshl_b32 s29, s29, 10
	v_add_u32_e32 v233, s29, v208
	global_load_dwordx4 v[20:23], v233, s[12:13]
	s_waitcnt vmcnt(35)
	v_readlane_b32 s26, v182, 3
	v_cvt_pk_f32_fp8_e32 v[216:217], v24
	v_cvt_pk_f32_fp8_sdwa v[218:219], v24 src0_sel:WORD_1
	v_cvt_pk_f32_fp8_e32 v[220:221], v25
	v_cvt_pk_f32_fp8_sdwa v[222:223], v25 src0_sel:WORD_1
	v_cvt_pk_f32_fp8_e32 v[224:225], v26
	v_cvt_pk_f32_fp8_sdwa v[226:227], v26 src0_sel:WORD_1
	v_cvt_pk_f32_fp8_e32 v[228:229], v27
	v_cvt_pk_f32_fp8_sdwa v[230:231], v27 src0_sel:WORD_1
	v_pk_fma_f32 v[64:65], s[24:25], v[216:217], v[64:65] op_sel_hi:[0,1,1]
	v_pk_fma_f32 v[66:67], s[24:25], v[218:219], v[66:67] op_sel_hi:[0,1,1]
	v_pk_fma_f32 v[68:69], s[24:25], v[220:221], v[68:69] op_sel_hi:[0,1,1]
	v_pk_fma_f32 v[70:71], s[24:25], v[222:223], v[70:71] op_sel_hi:[0,1,1]
	v_pk_fma_f32 v[72:73], s[24:25], v[224:225], v[72:73] op_sel_hi:[0,1,1]
	v_pk_fma_f32 v[74:75], s[24:25], v[226:227], v[74:75] op_sel_hi:[0,1,1]
	v_pk_fma_f32 v[76:77], s[24:25], v[228:229], v[76:77] op_sel_hi:[0,1,1]
	v_pk_fma_f32 v[78:79], s[24:25], v[230:231], v[78:79] op_sel_hi:[0,1,1]
	v_readlane_b32 s30, v176, 11
	s_lshl_b32 s30, s30, 10
	v_add_u32_e32 v234, s30, v208
	global_load_dwordx4 v[24:27], v234, s[12:13]
	s_waitcnt vmcnt(35)
	v_readlane_b32 s20, v178, 4
	v_cvt_pk_f32_fp8_e32 v[216:217], v28
	v_cvt_pk_f32_fp8_sdwa v[218:219], v28 src0_sel:WORD_1
	v_cvt_pk_f32_fp8_e32 v[220:221], v29
	v_cvt_pk_f32_fp8_sdwa v[222:223], v29 src0_sel:WORD_1
	v_cvt_pk_f32_fp8_e32 v[224:225], v30
	v_cvt_pk_f32_fp8_sdwa v[226:227], v30 src0_sel:WORD_1
	v_cvt_pk_f32_fp8_e32 v[228:229], v31
	v_cvt_pk_f32_fp8_sdwa v[230:231], v31 src0_sel:WORD_1
	v_pk_fma_f32 v[80:81], s[26:27], v[216:217], v[80:81] op_sel_hi:[0,1,1]
	v_pk_fma_f32 v[82:83], s[26:27], v[218:219], v[82:83] op_sel_hi:[0,1,1]
	v_pk_fma_f32 v[84:85], s[26:27], v[220:221], v[84:85] op_sel_hi:[0,1,1]
	v_pk_fma_f32 v[86:87], s[26:27], v[222:223], v[86:87] op_sel_hi:[0,1,1]
	v_pk_fma_f32 v[88:89], s[26:27], v[224:225], v[88:89] op_sel_hi:[0,1,1]
	v_pk_fma_f32 v[90:91], s[26:27], v[226:227], v[90:91] op_sel_hi:[0,1,1]
	v_pk_fma_f32 v[92:93], s[26:27], v[228:229], v[92:93] op_sel_hi:[0,1,1]
	v_pk_fma_f32 v[94:95], s[26:27], v[230:231], v[94:95] op_sel_hi:[0,1,1]
	v_readlane_b32 s31, v180, 11
	s_lshl_b32 s31, s31, 10
	v_add_u32_e32 v235, s31, v208
	global_load_dwordx4 v[28:31], v235, s[12:13]
	s_waitcnt vmcnt(35)
	v_readlane_b32 s22, v182, 4
	v_cvt_pk_f32_fp8_e32 v[216:217], v32
	v_cvt_pk_f32_fp8_sdwa v[218:219], v32 src0_sel:WORD_1
	v_cvt_pk_f32_fp8_e32 v[220:221], v33
	v_cvt_pk_f32_fp8_sdwa v[222:223], v33 src0_sel:WORD_1
	v_cvt_pk_f32_fp8_e32 v[224:225], v34
	v_cvt_pk_f32_fp8_sdwa v[226:227], v34 src0_sel:WORD_1
	v_cvt_pk_f32_fp8_e32 v[228:229], v35
	v_cvt_pk_f32_fp8_sdwa v[230:231], v35 src0_sel:WORD_1
	v_pk_fma_f32 v[64:65], s[20:21], v[216:217], v[64:65] op_sel_hi:[0,1,1]
	v_pk_fma_f32 v[66:67], s[20:21], v[218:219], v[66:67] op_sel_hi:[0,1,1]
	v_pk_fma_f32 v[68:69], s[20:21], v[220:221], v[68:69] op_sel_hi:[0,1,1]
	v_pk_fma_f32 v[70:71], s[20:21], v[222:223], v[70:71] op_sel_hi:[0,1,1]
	v_pk_fma_f32 v[72:73], s[20:21], v[224:225], v[72:73] op_sel_hi:[0,1,1]
	v_pk_fma_f32 v[74:75], s[20:21], v[226:227], v[74:75] op_sel_hi:[0,1,1]
	v_pk_fma_f32 v[76:77], s[20:21], v[228:229], v[76:77] op_sel_hi:[0,1,1]
	v_pk_fma_f32 v[78:79], s[20:21], v[230:231], v[78:79] op_sel_hi:[0,1,1]
	v_readlane_b32 s28, v176, 12
	s_lshl_b32 s28, s28, 10
	v_add_u32_e32 v232, s28, v208
	global_load_dwordx4 v[32:35], v232, s[12:13]
	s_waitcnt vmcnt(35)
; template <int PART>
; DEVI void phase_peer_gather(const Params& p, unsigned char* smem) {
;     ...
;     const bool b5 = (lane & 32) != 0, b4 = (lane & 16) != 0, b3 = (lane & 8) != 0;
;     const int fsrc = ((lane & 4) << 3) | ((lane & 2) << 3) | ((lane & 1) << 3);
;     f32x2 xn2[8], y2[8];
; #pragma unroll
;     for (int i = 0; i < 8; ++i) { xn2[i] = f32x2{xn[2 * i], xn[2 * i + 1]}; y2[i] = f32x2{0.f, 0.f}; }
;     if (PART == 0) {
;       LOADB_(ca, 0)
; #pragma unroll 1
;       for (int bi = 0; bi < 16; bi += 2) {
;         LOADB_(cb, bi + 1)
;         COMPU_(ca, bi)
;         if (bi + 2 < 16) { LOADB_(ca, bi + 2) }
;         COMPU_(cb, bi + 1)
;       }
;       p.gates[(size_t)tok * 128 + lane] = cf0;
;       p.gates[(size_t)tok * 128 + 64 + lane] = cf1;
;       continue;
;     }
;     cf0 = g0; cf1 = g1;
;     LOADB_(ca, 16)
; #pragma unroll 1
;     for (int bi = 16; bi < 32; bi += 2) {
;       LOADB_(cb, bi + 1)
;       COMPV_(ca, bi)
;       if (bi + 2 < 32) { LOADB_(ca, bi + 2) }
;       COMPV_(cb, bi + 1)
;     }
	v_readlane_b32 s24, v178, 5
	v_cvt_pk_f32_fp8_e32 v[216:217], v36
	v_cvt_pk_f32_fp8_sdwa v[218:219], v36 src0_sel:WORD_1
	v_cvt_pk_f32_fp8_e32 v[220:221], v37
	v_cvt_pk_f32_fp8_sdwa v[222:223], v37 src0_sel:WORD_1
	v_cvt_pk_f32_fp8_e32 v[224:225], v38
	v_cvt_pk_f32_fp8_sdwa v[226:227], v38 src0_sel:WORD_1
	v_cvt_pk_f32_fp8_e32 v[228:229], v39
	v_cvt_pk_f32_fp8_sdwa v[230:231], v39 src0_sel:WORD_1
	v_pk_fma_f32 v[80:81], s[22:23], v[216:217], v[80:81] op_sel_hi:[0,1,1]
	v_pk_fma_f32 v[82:83], s[22:23], v[218:219], v[82:83] op_sel_hi:[0,1,1]
	v_pk_fma_f32 v[84:85], s[22:23], v[220:221], v[84:85] op_sel_hi:[0,1,1]
	v_pk_fma_f32 v[86:87], s[22:23], v[222:223], v[86:87] op_sel_hi:[0,1,1]
	v_pk_fma_f32 v[88:89], s[22:23], v[224:225], v[88:89] op_sel_hi:[0,1,1]
	v_pk_fma_f32 v[90:91], s[22:23], v[226:227], v[90:91] op_sel_hi:[0,1,1]
	v_pk_fma_f32 v[92:93], s[22:23], v[228:229], v[92:93] op_sel_hi:[0,1,1]
	v_pk_fma_f32 v[94:95], s[22:23], v[230:231], v[94:95] op_sel_hi:[0,1,1]
	v_readlane_b32 s29, v180, 12
	s_lshl_b32 s29, s29, 10
	v_add_u32_e32 v233, s29, v208
	global_load_dwordx4 v[36:39], v233, s[12:13]
	s_waitcnt vmcnt(35)
	v_readlane_b32 s26, v182, 5
	v_cvt_pk_f32_fp8_e32 v[216:217], v40
	v_cvt_pk_f32_fp8_sdwa v[218:219], v40 src0_sel:WORD_1
	v_cvt_pk_f32_fp8_e32 v[220:221], v41
	v_cvt_pk_f32_fp8_sdwa v[222:223], v41 src0_sel:WORD_1
	v_cvt_pk_f32_fp8_e32 v[224:225], v42
	v_cvt_pk_f32_fp8_sdwa v[226:227], v42 src0_sel:WORD_1
	v_cvt_pk_f32_fp8_e32 v[228:229], v43
	v_cvt_pk_f32_fp8_sdwa v[230:231], v43 src0_sel:WORD_1
	v_pk_fma_f32 v[64:65], s[24:25], v[216:217], v[64:65] op_sel_hi:[0,1,1]
	v_pk_fma_f32 v[66:67], s[24:25], v[218:219], v[66:67] op_sel_hi:[0,1,1]
	v_pk_fma_f32 v[68:69], s[24:25], v[220:221], v[68:69] op_sel_hi:[0,1,1]
	v_pk_fma_f32 v[70:71], s[24:25], v[222:223], v[70:71] op_sel_hi:[0,1,1]
	v_pk_fma_f32 v[72:73], s[24:25], v[224:225], v[72:73] op_sel_hi:[0,1,1]
	v_pk_fma_f32 v[74:75], s[24:25], v[226:227], v[74:75] op_sel_hi:[0,1,1]
	v_pk_fma_f32 v[76:77], s[24:25], v[228:229], v[76:77] op_sel_hi:[0,1,1]
	v_pk_fma_f32 v[78:79], s[24:25], v[230:231], v[78:79] op_sel_hi:[0,1,1]
	v_readlane_b32 s30, v176, 13
	s_lshl_b32 s30, s30, 10
	v_add_u32_e32 v234, s30, v208
	global_load_dwordx4 v[40:43], v234, s[12:13]
	s_waitcnt vmcnt(35)
	v_readlane_b32 s20, v178, 6
	v_cvt_pk_f32_fp8_e32 v[216:217], v44
	v_cvt_pk_f32_fp8_sdwa v[218:219], v44 src0_sel:WORD_1
	v_cvt_pk_f32_fp8_e32 v[220:221], v45
	v_cvt_pk_f32_fp8_sdwa v[222:223], v45 src0_sel:WORD_1
	v_cvt_pk_f32_fp8_e32 v[224:225], v46
	v_cvt_pk_f32_fp8_sdwa v[226:227], v46 src0_sel:WORD_1
	v_cvt_pk_f32_fp8_e32 v[228:229], v47
	v_cvt_pk_f32_fp8_sdwa v[230:231], v47 src0_sel:WORD_1
	v_pk_fma_f32 v[80:81], s[26:27], v[216:217], v[80:81] op_sel_hi:[0,1,1]
	v_pk_fma_f32 v[82:83], s[26:27], v[218:219], v[82:83] op_sel_hi:[0,1,1]
	v_pk_fma_f32 v[84:85], s[26:27], v[220:221], v[84:85] op_sel_hi:[0,1,1]
	v_pk_fma_f32 v[86:87], s[26:27], v[222:223], v[86:87] op_sel_hi:[0,1,1]
	v_pk_fma_f32 v[88:89], s[26:27], v[224:225], v[88:89] op_sel_hi:[0,1,1]
	v_pk_fma_f32 v[90:91], s[26:27], v[226:227], v[90:91] op_sel_hi:[0,1,1]
	v_pk_fma_f32 v[92:93], s[26:27], v[228:229], v[92:93] op_sel_hi:[0,1,1]
	v_pk_fma_f32 v[94:95], s[26:27], v[230:231], v[94:95] op_sel_hi:[0,1,1]
	v_readlane_b32 s31, v180, 13
	s_lshl_b32 s31, s31, 10
	v_add_u32_e32 v235, s31, v208
	global_load_dwordx4 v[44:47], v235, s[12:13]
	s_waitcnt vmcnt(35)
	v_readlane_b32 s22, v182, 6
	v_cvt_pk_f32_fp8_e32 v[216:217], v48
	v_cvt_pk_f32_fp8_sdwa v[218:219], v48 src0_sel:WORD_1
	v_cvt_pk_f32_fp8_e32 v[220:221], v49
	v_cvt_pk_f32_fp8_sdwa v[222:223], v49 src0_sel:WORD_1
	v_cvt_pk_f32_fp8_e32 v[224:225], v50
	v_cvt_pk_f32_fp8_sdwa v[226:227], v50 src0_sel:WORD_1
	v_cvt_pk_f32_fp8_e32 v[228:229], v51
	v_cvt_pk_f32_fp8_sdwa v[230:231], v51 src0_sel:WORD_1
	v_pk_fma_f32 v[64:65], s[20:21], v[216:217], v[64:65] op_sel_hi:[0,1,1]
	v_pk_fma_f32 v[66:67], s[20:21], v[218:219], v[66:67] op_sel_hi:[0,1,1]
	v_pk_fma_f32 v[68:69], s[20:21], v[220:221], v[68:69] op_sel_hi:[0,1,1]
	v_pk_fma_f32 v[70:71], s[20:21], v[222:223], v[70:71] op_sel_hi:[0,1,1]
	v_pk_fma_f32 v[72:73], s[20:21], v[224:225], v[72:73] op_sel_hi:[0,1,1]
	v_pk_fma_f32 v[74:75], s[20:21], v[226:227], v[74:75] op_sel_hi:[0,1,1]
	v_pk_fma_f32 v[76:77], s[20:21], v[228:229], v[76:77] op_sel_hi:[0,1,1]
	v_pk_fma_f32 v[78:79], s[20:21], v[230:231], v[78:79] op_sel_hi:[0,1,1]
	v_readlane_b32 s28, v176, 14
	s_lshl_b32 s28, s28, 10
	v_add_u32_e32 v232, s28, v208
	global_load_dwordx4 v[48:51], v232, s[12:13]
	s_waitcnt vmcnt(35)
	v_readlane_b32 s24, v178, 7
	v_cvt_pk_f32_fp8_e32 v[216:217], v52
	v_cvt_pk_f32_fp8_sdwa v[218:219], v52 src0_sel:WORD_1
	v_cvt_pk_f32_fp8_e32 v[220:221], v53
	v_cvt_pk_f32_fp8_sdwa v[222:223], v53 src0_sel:WORD_1
	v_cvt_pk_f32_fp8_e32 v[224:225], v54
	v_cvt_pk_f32_fp8_sdwa v[226:227], v54 src0_sel:WORD_1
	v_cvt_pk_f32_fp8_e32 v[228:229], v55
	v_cvt_pk_f32_fp8_sdwa v[230:231], v55 src0_sel:WORD_1
	v_pk_fma_f32 v[80:81], s[22:23], v[216:217], v[80:81] op_sel_hi:[0,1,1]
	v_pk_fma_f32 v[82:83], s[22:23], v[218:219], v[82:83] op_sel_hi:[0,1,1]
	v_pk_fma_f32 v[84:85], s[22:23], v[220:221], v[84:85] op_sel_hi:[0,1,1]
	v_pk_fma_f32 v[86:87], s[22:23], v[222:223], v[86:87] op_sel_hi:[0,1,1]
	v_pk_fma_f32 v[88:89], s[22:23], v[224:225], v[88:89] op_sel_hi:[0,1,1]
	v_pk_fma_f32 v[90:91], s[22:23], v[226:227], v[90:91] op_sel_hi:[0,1,1]
	v_pk_fma_f32 v[92:93], s[22:23], v[228:229], v[92:93] op_sel_hi:[0,1,1]
	v_pk_fma_f32 v[94:95], s[22:23], v[230:231], v[94:95] op_sel_hi:[0,1,1]
	v_readlane_b32 s29, v180, 14
	s_lshl_b32 s29, s29, 10
	v_add_u32_e32 v233, s29, v208
	global_load_dwordx4 v[52:55], v233, s[12:13]
	s_waitcnt vmcnt(35)
; template <int PART>
; DEVI void phase_peer_gather(const Params& p, unsigned char* smem) {
;     ...
;     const bool b5 = (lane & 32) != 0, b4 = (lane & 16) != 0, b3 = (lane & 8) != 0;
;     const int fsrc = ((lane & 4) << 3) | ((lane & 2) << 3) | ((lane & 1) << 3);
;     f32x2 xn2[8], y2[8];
; #pragma unroll
;     for (int i = 0; i < 8; ++i) { xn2[i] = f32x2{xn[2 * i], xn[2 * i + 1]}; y2[i] = f32x2{0.f, 0.f}; }
;     if (PART == 0) {
;       LOADB_(ca, 0)
; #pragma unroll 1
;       for (int bi = 0; bi < 16; bi += 2) {
;         LOADB_(cb, bi + 1)
;         COMPU_(ca, bi)
;         if (bi + 2 < 16) { LOADB_(ca, bi + 2) }
;         COMPU_(cb, bi + 1)
;       }
;       p.gates[(size_t)tok * 128 + lane] = cf0;
;       p.gates[(size_t)tok * 128 + 64 + lane] = cf1;
;       continue;
;     }
;     cf0 = g0; cf1 = g1;
;     LOADB_(ca, 16)
; #pragma unroll 1
;     for (int bi = 16; bi < 32; bi += 2) {
;       LOADB_(cb, bi + 1)
;       COMPV_(ca, bi)
;       if (bi + 2 < 32) { LOADB_(ca, bi + 2) }
;       COMPV_(cb, bi + 1)
;     }
	v_readlane_b32 s26, v182, 7
	v_cvt_pk_f32_fp8_e32 v[216:217], v56
	v_cvt_pk_f32_fp8_sdwa v[218:219], v56 src0_sel:WORD_1
	v_cvt_pk_f32_fp8_e32 v[220:221], v57
	v_cvt_pk_f32_fp8_sdwa v[222:223], v57 src0_sel:WORD_1
	v_cvt_pk_f32_fp8_e32 v[224:225], v58
	v_cvt_pk_f32_fp8_sdwa v[226:227], v58 src0_sel:WORD_1
	v_cvt_pk_f32_fp8_e32 v[228:229], v59
	v_cvt_pk_f32_fp8_sdwa v[230:231], v59 src0_sel:WORD_1
	v_pk_fma_f32 v[64:65], s[24:25], v[216:217], v[64:65] op_sel_hi:[0,1,1]
	v_pk_fma_f32 v[66:67], s[24:25], v[218:219], v[66:67] op_sel_hi:[0,1,1]
	v_pk_fma_f32 v[68:69], s[24:25], v[220:221], v[68:69] op_sel_hi:[0,1,1]
	v_pk_fma_f32 v[70:71], s[24:25], v[222:223], v[70:71] op_sel_hi:[0,1,1]
	v_pk_fma_f32 v[72:73], s[24:25], v[224:225], v[72:73] op_sel_hi:[0,1,1]
	v_pk_fma_f32 v[74:75], s[24:25], v[226:227], v[74:75] op_sel_hi:[0,1,1]
	v_pk_fma_f32 v[76:77], s[24:25], v[228:229], v[76:77] op_sel_hi:[0,1,1]
	v_pk_fma_f32 v[78:79], s[24:25], v[230:231], v[78:79] op_sel_hi:[0,1,1]
	v_readlane_b32 s30, v176, 15
	s_lshl_b32 s30, s30, 10
	v_add_u32_e32 v234, s30, v208
	global_load_dwordx4 v[56:59], v234, s[12:13]
	s_waitcnt vmcnt(35)
	v_readlane_b32 s20, v178, 8
	v_cvt_pk_f32_fp8_e32 v[216:217], v60
	v_cvt_pk_f32_fp8_sdwa v[218:219], v60 src0_sel:WORD_1
	v_cvt_pk_f32_fp8_e32 v[220:221], v61
	v_cvt_pk_f32_fp8_sdwa v[222:223], v61 src0_sel:WORD_1
	v_cvt_pk_f32_fp8_e32 v[224:225], v62
	v_cvt_pk_f32_fp8_sdwa v[226:227], v62 src0_sel:WORD_1
	v_cvt_pk_f32_fp8_e32 v[228:229], v63
	v_cvt_pk_f32_fp8_sdwa v[230:231], v63 src0_sel:WORD_1
	v_pk_fma_f32 v[80:81], s[26:27], v[216:217], v[80:81] op_sel_hi:[0,1,1]
	v_pk_fma_f32 v[82:83], s[26:27], v[218:219], v[82:83] op_sel_hi:[0,1,1]
	v_pk_fma_f32 v[84:85], s[26:27], v[220:221], v[84:85] op_sel_hi:[0,1,1]
	v_pk_fma_f32 v[86:87], s[26:27], v[222:223], v[86:87] op_sel_hi:[0,1,1]
	v_pk_fma_f32 v[88:89], s[26:27], v[224:225], v[88:89] op_sel_hi:[0,1,1]
	v_pk_fma_f32 v[90:91], s[26:27], v[226:227], v[90:91] op_sel_hi:[0,1,1]
	v_pk_fma_f32 v[92:93], s[26:27], v[228:229], v[92:93] op_sel_hi:[0,1,1]
	v_pk_fma_f32 v[94:95], s[26:27], v[230:231], v[94:95] op_sel_hi:[0,1,1]
	v_readlane_b32 s31, v180, 15
	s_lshl_b32 s31, s31, 10
	v_add_u32_e32 v235, s31, v208
	global_load_dwordx4 v[60:63], v235, s[12:13]
	s_waitcnt vmcnt(15)
	v_readlane_b32 s22, v182, 8
	v_cvt_pk_f32_fp8_e32 v[216:217], v0
	v_cvt_pk_f32_fp8_sdwa v[218:219], v0 src0_sel:WORD_1
	v_cvt_pk_f32_fp8_e32 v[220:221], v1
	v_cvt_pk_f32_fp8_sdwa v[222:223], v1 src0_sel:WORD_1
	v_cvt_pk_f32_fp8_e32 v[224:225], v2
	v_cvt_pk_f32_fp8_sdwa v[226:227], v2 src0_sel:WORD_1
	v_cvt_pk_f32_fp8_e32 v[228:229], v3
	v_cvt_pk_f32_fp8_sdwa v[230:231], v3 src0_sel:WORD_1
	v_pk_fma_f32 v[64:65], s[20:21], v[216:217], v[64:65] op_sel_hi:[0,1,1]
	v_pk_fma_f32 v[66:67], s[20:21], v[218:219], v[66:67] op_sel_hi:[0,1,1]
	v_pk_fma_f32 v[68:69], s[20:21], v[220:221], v[68:69] op_sel_hi:[0,1,1]
	v_pk_fma_f32 v[70:71], s[20:21], v[222:223], v[70:71] op_sel_hi:[0,1,1]
	v_pk_fma_f32 v[72:73], s[20:21], v[224:225], v[72:73] op_sel_hi:[0,1,1]
	v_pk_fma_f32 v[74:75], s[20:21], v[226:227], v[74:75] op_sel_hi:[0,1,1]
	v_pk_fma_f32 v[76:77], s[20:21], v[228:229], v[76:77] op_sel_hi:[0,1,1]
	v_pk_fma_f32 v[78:79], s[20:21], v[230:231], v[78:79] op_sel_hi:[0,1,1]
	v_readlane_b32 s28, v176, 16
	s_lshl_b32 s28, s28, 10
	v_add_u32_e32 v232, s28, v208
	global_load_dwordx4 v[0:3], v232, s[12:13]
	s_waitcnt vmcnt(15)
	v_readlane_b32 s24, v178, 9
	v_cvt_pk_f32_fp8_e32 v[216:217], v4
	v_cvt_pk_f32_fp8_sdwa v[218:219], v4 src0_sel:WORD_1
	v_cvt_pk_f32_fp8_e32 v[220:221], v5
	v_cvt_pk_f32_fp8_sdwa v[222:223], v5 src0_sel:WORD_1
	v_cvt_pk_f32_fp8_e32 v[224:225], v6
	v_cvt_pk_f32_fp8_sdwa v[226:227], v6 src0_sel:WORD_1
	v_cvt_pk_f32_fp8_e32 v[228:229], v7
	v_cvt_pk_f32_fp8_sdwa v[230:231], v7 src0_sel:WORD_1
	v_pk_fma_f32 v[80:81], s[22:23], v[216:217], v[80:81] op_sel_hi:[0,1,1]
	v_pk_fma_f32 v[82:83], s[22:23], v[218:219], v[82:83] op_sel_hi:[0,1,1]
	v_pk_fma_f32 v[84:85], s[22:23], v[220:221], v[84:85] op_sel_hi:[0,1,1]
	v_pk_fma_f32 v[86:87], s[22:23], v[222:223], v[86:87] op_sel_hi:[0,1,1]
	v_pk_fma_f32 v[88:89], s[22:23], v[224:225], v[88:89] op_sel_hi:[0,1,1]
	v_pk_fma_f32 v[90:91], s[22:23], v[226:227], v[90:91] op_sel_hi:[0,1,1]
	v_pk_fma_f32 v[92:93], s[22:23], v[228:229], v[92:93] op_sel_hi:[0,1,1]
	v_pk_fma_f32 v[94:95], s[22:23], v[230:231], v[94:95] op_sel_hi:[0,1,1]
	v_readlane_b32 s29, v180, 16
	s_lshl_b32 s29, s29, 10
	v_add_u32_e32 v233, s29, v208
	global_load_dwordx4 v[4:7], v233, s[12:13]
	s_waitcnt vmcnt(15)
	v_readlane_b32 s26, v182, 9
	v_cvt_pk_f32_fp8_e32 v[216:217], v8
	v_cvt_pk_f32_fp8_sdwa v[218:219], v8 src0_sel:WORD_1
	v_cvt_pk_f32_fp8_e32 v[220:221], v9
	v_cvt_pk_f32_fp8_sdwa v[222:223], v9 src0_sel:WORD_1
	v_cvt_pk_f32_fp8_e32 v[224:225], v10
	v_cvt_pk_f32_fp8_sdwa v[226:227], v10 src0_sel:WORD_1
	v_cvt_pk_f32_fp8_e32 v[228:229], v11
	v_cvt_pk_f32_fp8_sdwa v[230:231], v11 src0_sel:WORD_1
	v_pk_fma_f32 v[64:65], s[24:25], v[216:217], v[64:65] op_sel_hi:[0,1,1]
	v_pk_fma_f32 v[66:67], s[24:25], v[218:219], v[66:67] op_sel_hi:[0,1,1]
	v_pk_fma_f32 v[68:69], s[24:25], v[220:221], v[68:69] op_sel_hi:[0,1,1]
	v_pk_fma_f32 v[70:71], s[24:25], v[222:223], v[70:71] op_sel_hi:[0,1,1]
	v_pk_fma_f32 v[72:73], s[24:25], v[224:225], v[72:73] op_sel_hi:[0,1,1]
	v_pk_fma_f32 v[74:75], s[24:25], v[226:227], v[74:75] op_sel_hi:[0,1,1]
	v_pk_fma_f32 v[76:77], s[24:25], v[228:229], v[76:77] op_sel_hi:[0,1,1]
	v_pk_fma_f32 v[78:79], s[24:25], v[230:231], v[78:79] op_sel_hi:[0,1,1]
	v_readlane_b32 s30, v176, 17
	s_lshl_b32 s30, s30, 10
	v_add_u32_e32 v234, s30, v208
	global_load_dwordx4 v[8:11], v234, s[12:13]
	s_waitcnt vmcnt(15)
; template <int PART>
; DEVI void phase_peer_gather(const Params& p, unsigned char* smem) {
;     ...
;     const bool b5 = (lane & 32) != 0, b4 = (lane & 16) != 0, b3 = (lane & 8) != 0;
;     const int fsrc = ((lane & 4) << 3) | ((lane & 2) << 3) | ((lane & 1) << 3);
;     f32x2 xn2[8], y2[8];
; #pragma unroll
;     for (int i = 0; i < 8; ++i) { xn2[i] = f32x2{xn[2 * i], xn[2 * i + 1]}; y2[i] = f32x2{0.f, 0.f}; }
;     if (PART == 0) {
;       LOADB_(ca, 0)
; #pragma unroll 1
;       for (int bi = 0; bi < 16; bi += 2) {
;         LOADB_(cb, bi + 1)
;         COMPU_(ca, bi)
;         if (bi + 2 < 16) { LOADB_(ca, bi + 2) }
;         COMPU_(cb, bi + 1)
;       }
;       p.gates[(size_t)tok * 128 + lane] = cf0;
;       p.gates[(size_t)tok * 128 + 64 + lane] = cf1;
;       continue;
;     }
;     cf0 = g0; cf1 = g1;
;     LOADB_(ca, 16)
; #pragma unroll 1
;     for (int bi = 16; bi < 32; bi += 2) {
;       LOADB_(cb, bi + 1)
;       COMPV_(ca, bi)
;       if (bi + 2 < 32) { LOADB_(ca, bi + 2) }
;       COMPV_(cb, bi + 1)
;     }
	v_readlane_b32 s20, v178, 10
	v_cvt_pk_f32_fp8_e32 v[216:217], v12
	v_cvt_pk_f32_fp8_sdwa v[218:219], v12 src0_sel:WORD_1
	v_cvt_pk_f32_fp8_e32 v[220:221], v13
	v_cvt_pk_f32_fp8_sdwa v[222:223], v13 src0_sel:WORD_1
	v_cvt_pk_f32_fp8_e32 v[224:225], v14
	v_cvt_pk_f32_fp8_sdwa v[226:227], v14 src0_sel:WORD_1
	v_cvt_pk_f32_fp8_e32 v[228:229], v15
	v_cvt_pk_f32_fp8_sdwa v[230:231], v15 src0_sel:WORD_1
	v_pk_fma_f32 v[80:81], s[26:27], v[216:217], v[80:81] op_sel_hi:[0,1,1]
	v_pk_fma_f32 v[82:83], s[26:27], v[218:219], v[82:83] op_sel_hi:[0,1,1]
	v_pk_fma_f32 v[84:85], s[26:27], v[220:221], v[84:85] op_sel_hi:[0,1,1]
	v_pk_fma_f32 v[86:87], s[26:27], v[222:223], v[86:87] op_sel_hi:[0,1,1]
	v_pk_fma_f32 v[88:89], s[26:27], v[224:225], v[88:89] op_sel_hi:[0,1,1]
	v_pk_fma_f32 v[90:91], s[26:27], v[226:227], v[90:91] op_sel_hi:[0,1,1]
	v_pk_fma_f32 v[92:93], s[26:27], v[228:229], v[92:93] op_sel_hi:[0,1,1]
	v_pk_fma_f32 v[94:95], s[26:27], v[230:231], v[94:95] op_sel_hi:[0,1,1]
	v_readlane_b32 s31, v180, 17
	s_lshl_b32 s31, s31, 10
	v_add_u32_e32 v235, s31, v208
	global_load_dwordx4 v[12:15], v235, s[12:13]
	s_waitcnt vmcnt(15)
	v_readlane_b32 s22, v182, 10
	v_cvt_pk_f32_fp8_e32 v[216:217], v16
	v_cvt_pk_f32_fp8_sdwa v[218:219], v16 src0_sel:WORD_1
	v_cvt_pk_f32_fp8_e32 v[220:221], v17
	v_cvt_pk_f32_fp8_sdwa v[222:223], v17 src0_sel:WORD_1
	v_cvt_pk_f32_fp8_e32 v[224:225], v18
	v_cvt_pk_f32_fp8_sdwa v[226:227], v18 src0_sel:WORD_1
	v_cvt_pk_f32_fp8_e32 v[228:229], v19
	v_cvt_pk_f32_fp8_sdwa v[230:231], v19 src0_sel:WORD_1
	v_pk_fma_f32 v[64:65], s[20:21], v[216:217], v[64:65] op_sel_hi:[0,1,1]
	v_pk_fma_f32 v[66:67], s[20:21], v[218:219], v[66:67] op_sel_hi:[0,1,1]
	v_pk_fma_f32 v[68:69], s[20:21], v[220:221], v[68:69] op_sel_hi:[0,1,1]
	v_pk_fma_f32 v[70:71], s[20:21], v[222:223], v[70:71] op_sel_hi:[0,1,1]
	v_pk_fma_f32 v[72:73], s[20:21], v[224:225], v[72:73] op_sel_hi:[0,1,1]
	v_pk_fma_f32 v[74:75], s[20:21], v[226:227], v[74:75] op_sel_hi:[0,1,1]
	v_pk_fma_f32 v[76:77], s[20:21], v[228:229], v[76:77] op_sel_hi:[0,1,1]
	v_pk_fma_f32 v[78:79], s[20:21], v[230:231], v[78:79] op_sel_hi:[0,1,1]
	v_readlane_b32 s28, v176, 18
	s_lshl_b32 s28, s28, 10
	v_add_u32_e32 v232, s28, v208
	global_load_dwordx4 v[16:19], v232, s[12:13]
	s_waitcnt vmcnt(15)
	v_readlane_b32 s24, v178, 11
	v_cvt_pk_f32_fp8_e32 v[216:217], v20
	v_cvt_pk_f32_fp8_sdwa v[218:219], v20 src0_sel:WORD_1
	v_cvt_pk_f32_fp8_e32 v[220:221], v21
	v_cvt_pk_f32_fp8_sdwa v[222:223], v21 src0_sel:WORD_1
	v_cvt_pk_f32_fp8_e32 v[224:225], v22
	v_cvt_pk_f32_fp8_sdwa v[226:227], v22 src0_sel:WORD_1
	v_cvt_pk_f32_fp8_e32 v[228:229], v23
	v_cvt_pk_f32_fp8_sdwa v[230:231], v23 src0_sel:WORD_1
	v_pk_fma_f32 v[80:81], s[22:23], v[216:217], v[80:81] op_sel_hi:[0,1,1]
	v_pk_fma_f32 v[82:83], s[22:23], v[218:219], v[82:83] op_sel_hi:[0,1,1]
	v_pk_fma_f32 v[84:85], s[22:23], v[220:221], v[84:85] op_sel_hi:[0,1,1]
	v_pk_fma_f32 v[86:87], s[22:23], v[222:223], v[86:87] op_sel_hi:[0,1,1]
	v_pk_fma_f32 v[88:89], s[22:23], v[224:225], v[88:89] op_sel_hi:[0,1,1]
	v_pk_fma_f32 v[90:91], s[22:23], v[226:227], v[90:91] op_sel_hi:[0,1,1]
	v_pk_fma_f32 v[92:93], s[22:23], v[228:229], v[92:93] op_sel_hi:[0,1,1]
	v_pk_fma_f32 v[94:95], s[22:23], v[230:231], v[94:95] op_sel_hi:[0,1,1]
	v_readlane_b32 s29, v180, 18
	s_lshl_b32 s29, s29, 10
	v_add_u32_e32 v233, s29, v208
	global_load_dwordx4 v[20:23], v233, s[12:13]
	s_waitcnt vmcnt(15)
	v_readlane_b32 s26, v182, 11
	v_cvt_pk_f32_fp8_e32 v[216:217], v24
	v_cvt_pk_f32_fp8_sdwa v[218:219], v24 src0_sel:WORD_1
	v_cvt_pk_f32_fp8_e32 v[220:221], v25
	v_cvt_pk_f32_fp8_sdwa v[222:223], v25 src0_sel:WORD_1
	v_cvt_pk_f32_fp8_e32 v[224:225], v26
	v_cvt_pk_f32_fp8_sdwa v[226:227], v26 src0_sel:WORD_1
	v_cvt_pk_f32_fp8_e32 v[228:229], v27
	v_cvt_pk_f32_fp8_sdwa v[230:231], v27 src0_sel:WORD_1
	v_pk_fma_f32 v[64:65], s[24:25], v[216:217], v[64:65] op_sel_hi:[0,1,1]
	v_pk_fma_f32 v[66:67], s[24:25], v[218:219], v[66:67] op_sel_hi:[0,1,1]
	v_pk_fma_f32 v[68:69], s[24:25], v[220:221], v[68:69] op_sel_hi:[0,1,1]
	v_pk_fma_f32 v[70:71], s[24:25], v[222:223], v[70:71] op_sel_hi:[0,1,1]
	v_pk_fma_f32 v[72:73], s[24:25], v[224:225], v[72:73] op_sel_hi:[0,1,1]
	v_pk_fma_f32 v[74:75], s[24:25], v[226:227], v[74:75] op_sel_hi:[0,1,1]
	v_pk_fma_f32 v[76:77], s[24:25], v[228:229], v[76:77] op_sel_hi:[0,1,1]
	v_pk_fma_f32 v[78:79], s[24:25], v[230:231], v[78:79] op_sel_hi:[0,1,1]
	v_readlane_b32 s30, v176, 19
	s_lshl_b32 s30, s30, 10
	v_add_u32_e32 v234, s30, v208
	global_load_dwordx4 v[24:27], v234, s[12:13]
	s_waitcnt vmcnt(15)
	v_readlane_b32 s20, v178, 12
	v_cvt_pk_f32_fp8_e32 v[216:217], v28
	v_cvt_pk_f32_fp8_sdwa v[218:219], v28 src0_sel:WORD_1
	v_cvt_pk_f32_fp8_e32 v[220:221], v29
	v_cvt_pk_f32_fp8_sdwa v[222:223], v29 src0_sel:WORD_1
	v_cvt_pk_f32_fp8_e32 v[224:225], v30
	v_cvt_pk_f32_fp8_sdwa v[226:227], v30 src0_sel:WORD_1
	v_cvt_pk_f32_fp8_e32 v[228:229], v31
	v_cvt_pk_f32_fp8_sdwa v[230:231], v31 src0_sel:WORD_1
	v_pk_fma_f32 v[80:81], s[26:27], v[216:217], v[80:81] op_sel_hi:[0,1,1]
	v_pk_fma_f32 v[82:83], s[26:27], v[218:219], v[82:83] op_sel_hi:[0,1,1]
	v_pk_fma_f32 v[84:85], s[26:27], v[220:221], v[84:85] op_sel_hi:[0,1,1]
	v_pk_fma_f32 v[86:87], s[26:27], v[222:223], v[86:87] op_sel_hi:[0,1,1]
	v_pk_fma_f32 v[88:89], s[26:27], v[224:225], v[88:89] op_sel_hi:[0,1,1]
	v_pk_fma_f32 v[90:91], s[26:27], v[226:227], v[90:91] op_sel_hi:[0,1,1]
	v_pk_fma_f32 v[92:93], s[26:27], v[228:229], v[92:93] op_sel_hi:[0,1,1]
	v_pk_fma_f32 v[94:95], s[26:27], v[230:231], v[94:95] op_sel_hi:[0,1,1]
	v_readlane_b32 s31, v180, 19
	s_lshl_b32 s31, s31, 10
	v_add_u32_e32 v235, s31, v208
	global_load_dwordx4 v[28:31], v235, s[12:13]
	s_waitcnt vmcnt(15)
; template <int PART>
; DEVI void phase_peer_gather(const Params& p, unsigned char* smem) {
;     ...
;     const bool b5 = (lane & 32) != 0, b4 = (lane & 16) != 0, b3 = (lane & 8) != 0;
;     const int fsrc = ((lane & 4) << 3) | ((lane & 2) << 3) | ((lane & 1) << 3);
;     f32x2 xn2[8], y2[8];
; #pragma unroll
;     for (int i = 0; i < 8; ++i) { xn2[i] = f32x2{xn[2 * i], xn[2 * i + 1]}; y2[i] = f32x2{0.f, 0.f}; }
;     if (PART == 0) {
;       LOADB_(ca, 0)
; #pragma unroll 1
;       for (int bi = 0; bi < 16; bi += 2) {
;         LOADB_(cb, bi + 1)
;         COMPU_(ca, bi)
;         if (bi + 2 < 16) { LOADB_(ca, bi + 2) }
;         COMPU_(cb, bi + 1)
;       }
;       p.gates[(size_t)tok * 128 + lane] = cf0;
;       p.gates[(size_t)tok * 128 + 64 + lane] = cf1;
;       continue;
;     }
;     cf0 = g0; cf1 = g1;
;     LOADB_(ca, 16)
; #pragma unroll 1
;     for (int bi = 16; bi < 32; bi += 2) {
;       LOADB_(cb, bi + 1)
;       COMPV_(ca, bi)
;       if (bi + 2 < 32) { LOADB_(ca, bi + 2) }
;       COMPV_(cb, bi + 1)
;     }
	v_readlane_b32 s22, v182, 12
	v_cvt_pk_f32_fp8_e32 v[216:217], v32
	v_cvt_pk_f32_fp8_sdwa v[218:219], v32 src0_sel:WORD_1
	v_cvt_pk_f32_fp8_e32 v[220:221], v33
	v_cvt_pk_f32_fp8_sdwa v[222:223], v33 src0_sel:WORD_1
	v_cvt_pk_f32_fp8_e32 v[224:225], v34
	v_cvt_pk_f32_fp8_sdwa v[226:227], v34 src0_sel:WORD_1
	v_cvt_pk_f32_fp8_e32 v[228:229], v35
	v_cvt_pk_f32_fp8_sdwa v[230:231], v35 src0_sel:WORD_1
	v_pk_fma_f32 v[64:65], s[20:21], v[216:217], v[64:65] op_sel_hi:[0,1,1]
	v_pk_fma_f32 v[66:67], s[20:21], v[218:219], v[66:67] op_sel_hi:[0,1,1]
	v_pk_fma_f32 v[68:69], s[20:21], v[220:221], v[68:69] op_sel_hi:[0,1,1]
	v_pk_fma_f32 v[70:71], s[20:21], v[222:223], v[70:71] op_sel_hi:[0,1,1]
	v_pk_fma_f32 v[72:73], s[20:21], v[224:225], v[72:73] op_sel_hi:[0,1,1]
	v_pk_fma_f32 v[74:75], s[20:21], v[226:227], v[74:75] op_sel_hi:[0,1,1]
	v_pk_fma_f32 v[76:77], s[20:21], v[228:229], v[76:77] op_sel_hi:[0,1,1]
	v_pk_fma_f32 v[78:79], s[20:21], v[230:231], v[78:79] op_sel_hi:[0,1,1]
	v_readlane_b32 s28, v176, 20
	s_lshl_b32 s28, s28, 10
	v_add_u32_e32 v232, s28, v208
	global_load_dwordx4 v[32:35], v232, s[12:13]
	s_waitcnt vmcnt(15)
	v_readlane_b32 s24, v178, 13
	v_cvt_pk_f32_fp8_e32 v[216:217], v36
	v_cvt_pk_f32_fp8_sdwa v[218:219], v36 src0_sel:WORD_1
	v_cvt_pk_f32_fp8_e32 v[220:221], v37
	v_cvt_pk_f32_fp8_sdwa v[222:223], v37 src0_sel:WORD_1
	v_cvt_pk_f32_fp8_e32 v[224:225], v38
	v_cvt_pk_f32_fp8_sdwa v[226:227], v38 src0_sel:WORD_1
	v_cvt_pk_f32_fp8_e32 v[228:229], v39
	v_cvt_pk_f32_fp8_sdwa v[230:231], v39 src0_sel:WORD_1
	v_pk_fma_f32 v[80:81], s[22:23], v[216:217], v[80:81] op_sel_hi:[0,1,1]
	v_pk_fma_f32 v[82:83], s[22:23], v[218:219], v[82:83] op_sel_hi:[0,1,1]
	v_pk_fma_f32 v[84:85], s[22:23], v[220:221], v[84:85] op_sel_hi:[0,1,1]
	v_pk_fma_f32 v[86:87], s[22:23], v[222:223], v[86:87] op_sel_hi:[0,1,1]
	v_pk_fma_f32 v[88:89], s[22:23], v[224:225], v[88:89] op_sel_hi:[0,1,1]
	v_pk_fma_f32 v[90:91], s[22:23], v[226:227], v[90:91] op_sel_hi:[0,1,1]
	v_pk_fma_f32 v[92:93], s[22:23], v[228:229], v[92:93] op_sel_hi:[0,1,1]
	v_pk_fma_f32 v[94:95], s[22:23], v[230:231], v[94:95] op_sel_hi:[0,1,1]
	v_readlane_b32 s29, v180, 20
	s_lshl_b32 s29, s29, 10
	v_add_u32_e32 v233, s29, v208
	global_load_dwordx4 v[36:39], v233, s[12:13]
	s_waitcnt vmcnt(15)
	v_readlane_b32 s26, v182, 13
	v_cvt_pk_f32_fp8_e32 v[216:217], v40
	v_cvt_pk_f32_fp8_sdwa v[218:219], v40 src0_sel:WORD_1
	v_cvt_pk_f32_fp8_e32 v[220:221], v41
	v_cvt_pk_f32_fp8_sdwa v[222:223], v41 src0_sel:WORD_1
	v_cvt_pk_f32_fp8_e32 v[224:225], v42
	v_cvt_pk_f32_fp8_sdwa v[226:227], v42 src0_sel:WORD_1
	v_cvt_pk_f32_fp8_e32 v[228:229], v43
	v_cvt_pk_f32_fp8_sdwa v[230:231], v43 src0_sel:WORD_1
	v_pk_fma_f32 v[64:65], s[24:25], v[216:217], v[64:65] op_sel_hi:[0,1,1]
	v_pk_fma_f32 v[66:67], s[24:25], v[218:219], v[66:67] op_sel_hi:[0,1,1]
	v_pk_fma_f32 v[68:69], s[24:25], v[220:221], v[68:69] op_sel_hi:[0,1,1]
	v_pk_fma_f32 v[70:71], s[24:25], v[222:223], v[70:71] op_sel_hi:[0,1,1]
	v_pk_fma_f32 v[72:73], s[24:25], v[224:225], v[72:73] op_sel_hi:[0,1,1]
	v_pk_fma_f32 v[74:75], s[24:25], v[226:227], v[74:75] op_sel_hi:[0,1,1]
	v_pk_fma_f32 v[76:77], s[24:25], v[228:229], v[76:77] op_sel_hi:[0,1,1]
	v_pk_fma_f32 v[78:79], s[24:25], v[230:231], v[78:79] op_sel_hi:[0,1,1]
	v_readlane_b32 s30, v176, 21
	s_lshl_b32 s30, s30, 10
	v_add_u32_e32 v234, s30, v208
	global_load_dwordx4 v[40:43], v234, s[12:13]
	s_waitcnt vmcnt(15)
	v_readlane_b32 s20, v178, 14
	v_cvt_pk_f32_fp8_e32 v[216:217], v44
	v_cvt_pk_f32_fp8_sdwa v[218:219], v44 src0_sel:WORD_1
	v_cvt_pk_f32_fp8_e32 v[220:221], v45
	v_cvt_pk_f32_fp8_sdwa v[222:223], v45 src0_sel:WORD_1
	v_cvt_pk_f32_fp8_e32 v[224:225], v46
	v_cvt_pk_f32_fp8_sdwa v[226:227], v46 src0_sel:WORD_1
	v_cvt_pk_f32_fp8_e32 v[228:229], v47
	v_cvt_pk_f32_fp8_sdwa v[230:231], v47 src0_sel:WORD_1
	v_pk_fma_f32 v[80:81], s[26:27], v[216:217], v[80:81] op_sel_hi:[0,1,1]
	v_pk_fma_f32 v[82:83], s[26:27], v[218:219], v[82:83] op_sel_hi:[0,1,1]
	v_pk_fma_f32 v[84:85], s[26:27], v[220:221], v[84:85] op_sel_hi:[0,1,1]
	v_pk_fma_f32 v[86:87], s[26:27], v[222:223], v[86:87] op_sel_hi:[0,1,1]
	v_pk_fma_f32 v[88:89], s[26:27], v[224:225], v[88:89] op_sel_hi:[0,1,1]
	v_pk_fma_f32 v[90:91], s[26:27], v[226:227], v[90:91] op_sel_hi:[0,1,1]
	v_pk_fma_f32 v[92:93], s[26:27], v[228:229], v[92:93] op_sel_hi:[0,1,1]
	v_pk_fma_f32 v[94:95], s[26:27], v[230:231], v[94:95] op_sel_hi:[0,1,1]
	v_readlane_b32 s31, v180, 21
	s_lshl_b32 s31, s31, 10
	v_add_u32_e32 v235, s31, v208
	global_load_dwordx4 v[44:47], v235, s[12:13]
	s_waitcnt vmcnt(15)
	v_readlane_b32 s22, v182, 14
	v_cvt_pk_f32_fp8_e32 v[216:217], v48
	v_cvt_pk_f32_fp8_sdwa v[218:219], v48 src0_sel:WORD_1
	v_cvt_pk_f32_fp8_e32 v[220:221], v49
	v_cvt_pk_f32_fp8_sdwa v[222:223], v49 src0_sel:WORD_1
	v_cvt_pk_f32_fp8_e32 v[224:225], v50
	v_cvt_pk_f32_fp8_sdwa v[226:227], v50 src0_sel:WORD_1
	v_cvt_pk_f32_fp8_e32 v[228:229], v51
	v_cvt_pk_f32_fp8_sdwa v[230:231], v51 src0_sel:WORD_1
	v_pk_fma_f32 v[64:65], s[20:21], v[216:217], v[64:65] op_sel_hi:[0,1,1]
	v_pk_fma_f32 v[66:67], s[20:21], v[218:219], v[66:67] op_sel_hi:[0,1,1]
	v_pk_fma_f32 v[68:69], s[20:21], v[220:221], v[68:69] op_sel_hi:[0,1,1]
	v_pk_fma_f32 v[70:71], s[20:21], v[222:223], v[70:71] op_sel_hi:[0,1,1]
	v_pk_fma_f32 v[72:73], s[20:21], v[224:225], v[72:73] op_sel_hi:[0,1,1]
	v_pk_fma_f32 v[74:75], s[20:21], v[226:227], v[74:75] op_sel_hi:[0,1,1]
	v_pk_fma_f32 v[76:77], s[20:21], v[228:229], v[76:77] op_sel_hi:[0,1,1]
	v_pk_fma_f32 v[78:79], s[20:21], v[230:231], v[78:79] op_sel_hi:[0,1,1]
	v_readlane_b32 s28, v176, 22
	s_lshl_b32 s28, s28, 10
	v_add_u32_e32 v232, s28, v208
	global_load_dwordx4 v[48:51], v232, s[12:13]
	s_waitcnt vmcnt(15)
; template <int PART>
; DEVI void phase_peer_gather(const Params& p, unsigned char* smem) {
;     ...
;     const bool b5 = (lane & 32) != 0, b4 = (lane & 16) != 0, b3 = (lane & 8) != 0;
;     const int fsrc = ((lane & 4) << 3) | ((lane & 2) << 3) | ((lane & 1) << 3);
;     f32x2 xn2[8], y2[8];
; #pragma unroll
;     for (int i = 0; i < 8; ++i) { xn2[i] = f32x2{xn[2 * i], xn[2 * i + 1]}; y2[i] = f32x2{0.f, 0.f}; }
;     if (PART == 0) {
;       LOADB_(ca, 0)
; #pragma unroll 1
;       for (int bi = 0; bi < 16; bi += 2) {
;         LOADB_(cb, bi + 1)
;         COMPU_(ca, bi)
;         if (bi + 2 < 16) { LOADB_(ca, bi + 2) }
;         COMPU_(cb, bi + 1)
;       }
;       p.gates[(size_t)tok * 128 + lane] = cf0;
;       p.gates[(size_t)tok * 128 + 64 + lane] = cf1;
;       continue;
;     }
;     cf0 = g0; cf1 = g1;
;     LOADB_(ca, 16)
; #pragma unroll 1
;     for (int bi = 16; bi < 32; bi += 2) {
;       LOADB_(cb, bi + 1)
;       COMPV_(ca, bi)
;       if (bi + 2 < 32) { LOADB_(ca, bi + 2) }
;       COMPV_(cb, bi + 1)
;     }
	v_readlane_b32 s24, v178, 15
	v_cvt_pk_f32_fp8_e32 v[216:217], v52
	v_cvt_pk_f32_fp8_sdwa v[218:219], v52 src0_sel:WORD_1
	v_cvt_pk_f32_fp8_e32 v[220:221], v53
	v_cvt_pk_f32_fp8_sdwa v[222:223], v53 src0_sel:WORD_1
	v_cvt_pk_f32_fp8_e32 v[224:225], v54
	v_cvt_pk_f32_fp8_sdwa v[226:227], v54 src0_sel:WORD_1
	v_cvt_pk_f32_fp8_e32 v[228:229], v55
	v_cvt_pk_f32_fp8_sdwa v[230:231], v55 src0_sel:WORD_1
	v_pk_fma_f32 v[80:81], s[22:23], v[216:217], v[80:81] op_sel_hi:[0,1,1]
	v_pk_fma_f32 v[82:83], s[22:23], v[218:219], v[82:83] op_sel_hi:[0,1,1]
	v_pk_fma_f32 v[84:85], s[22:23], v[220:221], v[84:85] op_sel_hi:[0,1,1]
	v_pk_fma_f32 v[86:87], s[22:23], v[222:223], v[86:87] op_sel_hi:[0,1,1]
	v_pk_fma_f32 v[88:89], s[22:23], v[224:225], v[88:89] op_sel_hi:[0,1,1]
	v_pk_fma_f32 v[90:91], s[22:23], v[226:227], v[90:91] op_sel_hi:[0,1,1]
	v_pk_fma_f32 v[92:93], s[22:23], v[228:229], v[92:93] op_sel_hi:[0,1,1]
	v_pk_fma_f32 v[94:95], s[22:23], v[230:231], v[94:95] op_sel_hi:[0,1,1]
	v_readlane_b32 s29, v180, 22
	s_lshl_b32 s29, s29, 10
	v_add_u32_e32 v233, s29, v208
	global_load_dwordx4 v[52:55], v233, s[12:13]
	s_waitcnt vmcnt(15)
	v_readlane_b32 s26, v182, 15
	v_cvt_pk_f32_fp8_e32 v[216:217], v56
	v_cvt_pk_f32_fp8_sdwa v[218:219], v56 src0_sel:WORD_1
	v_cvt_pk_f32_fp8_e32 v[220:221], v57
	v_cvt_pk_f32_fp8_sdwa v[222:223], v57 src0_sel:WORD_1
	v_cvt_pk_f32_fp8_e32 v[224:225], v58
	v_cvt_pk_f32_fp8_sdwa v[226:227], v58 src0_sel:WORD_1
	v_cvt_pk_f32_fp8_e32 v[228:229], v59
	v_cvt_pk_f32_fp8_sdwa v[230:231], v59 src0_sel:WORD_1
	v_pk_fma_f32 v[64:65], s[24:25], v[216:217], v[64:65] op_sel_hi:[0,1,1]
	v_pk_fma_f32 v[66:67], s[24:25], v[218:219], v[66:67] op_sel_hi:[0,1,1]
	v_pk_fma_f32 v[68:69], s[24:25], v[220:221], v[68:69] op_sel_hi:[0,1,1]
	v_pk_fma_f32 v[70:71], s[24:25], v[222:223], v[70:71] op_sel_hi:[0,1,1]
	v_pk_fma_f32 v[72:73], s[24:25], v[224:225], v[72:73] op_sel_hi:[0,1,1]
	v_pk_fma_f32 v[74:75], s[24:25], v[226:227], v[74:75] op_sel_hi:[0,1,1]
	v_pk_fma_f32 v[76:77], s[24:25], v[228:229], v[76:77] op_sel_hi:[0,1,1]
	v_pk_fma_f32 v[78:79], s[24:25], v[230:231], v[78:79] op_sel_hi:[0,1,1]
	v_readlane_b32 s30, v176, 23
	s_lshl_b32 s30, s30, 10
	v_add_u32_e32 v234, s30, v208
	global_load_dwordx4 v[56:59], v234, s[12:13]
	s_waitcnt vmcnt(15)
	v_readlane_b32 s20, v178, 16
	v_cvt_pk_f32_fp8_e32 v[216:217], v60
	v_cvt_pk_f32_fp8_sdwa v[218:219], v60 src0_sel:WORD_1
	v_cvt_pk_f32_fp8_e32 v[220:221], v61
	v_cvt_pk_f32_fp8_sdwa v[222:223], v61 src0_sel:WORD_1
	v_cvt_pk_f32_fp8_e32 v[224:225], v62
	v_cvt_pk_f32_fp8_sdwa v[226:227], v62 src0_sel:WORD_1
	v_cvt_pk_f32_fp8_e32 v[228:229], v63
	v_cvt_pk_f32_fp8_sdwa v[230:231], v63 src0_sel:WORD_1
	v_pk_fma_f32 v[80:81], s[26:27], v[216:217], v[80:81] op_sel_hi:[0,1,1]
	v_pk_fma_f32 v[82:83], s[26:27], v[218:219], v[82:83] op_sel_hi:[0,1,1]
	v_pk_fma_f32 v[84:85], s[26:27], v[220:221], v[84:85] op_sel_hi:[0,1,1]
	v_pk_fma_f32 v[86:87], s[26:27], v[222:223], v[86:87] op_sel_hi:[0,1,1]
	v_pk_fma_f32 v[88:89], s[26:27], v[224:225], v[88:89] op_sel_hi:[0,1,1]
	v_pk_fma_f32 v[90:91], s[26:27], v[226:227], v[90:91] op_sel_hi:[0,1,1]
	v_pk_fma_f32 v[92:93], s[26:27], v[228:229], v[92:93] op_sel_hi:[0,1,1]
	v_pk_fma_f32 v[94:95], s[26:27], v[230:231], v[94:95] op_sel_hi:[0,1,1]
	v_readlane_b32 s31, v180, 23
	s_lshl_b32 s31, s31, 10
	v_add_u32_e32 v235, s31, v208
	global_load_dwordx4 v[60:63], v235, s[12:13]
	s_waitcnt vmcnt(15)
	v_readlane_b32 s22, v182, 16
	v_cvt_pk_f32_fp8_e32 v[216:217], v0
	v_cvt_pk_f32_fp8_sdwa v[218:219], v0 src0_sel:WORD_1
	v_cvt_pk_f32_fp8_e32 v[220:221], v1
	v_cvt_pk_f32_fp8_sdwa v[222:223], v1 src0_sel:WORD_1
	v_cvt_pk_f32_fp8_e32 v[224:225], v2
	v_cvt_pk_f32_fp8_sdwa v[226:227], v2 src0_sel:WORD_1
	v_cvt_pk_f32_fp8_e32 v[228:229], v3
	v_cvt_pk_f32_fp8_sdwa v[230:231], v3 src0_sel:WORD_1
	v_pk_fma_f32 v[64:65], s[20:21], v[216:217], v[64:65] op_sel_hi:[0,1,1]
	v_pk_fma_f32 v[66:67], s[20:21], v[218:219], v[66:67] op_sel_hi:[0,1,1]
	v_pk_fma_f32 v[68:69], s[20:21], v[220:221], v[68:69] op_sel_hi:[0,1,1]
	v_pk_fma_f32 v[70:71], s[20:21], v[222:223], v[70:71] op_sel_hi:[0,1,1]
	v_pk_fma_f32 v[72:73], s[20:21], v[224:225], v[72:73] op_sel_hi:[0,1,1]
	v_pk_fma_f32 v[74:75], s[20:21], v[226:227], v[74:75] op_sel_hi:[0,1,1]
	v_pk_fma_f32 v[76:77], s[20:21], v[228:229], v[76:77] op_sel_hi:[0,1,1]
	v_pk_fma_f32 v[78:79], s[20:21], v[230:231], v[78:79] op_sel_hi:[0,1,1]
	v_readlane_b32 s28, v176, 24
	s_lshl_b32 s28, s28, 10
	v_add_u32_e32 v232, s28, v208
	global_load_dwordx4 v[0:3], v232, s[12:13]
	s_waitcnt vmcnt(15)
	v_readlane_b32 s24, v178, 17
	v_cvt_pk_f32_fp8_e32 v[216:217], v4
	v_cvt_pk_f32_fp8_sdwa v[218:219], v4 src0_sel:WORD_1
	v_cvt_pk_f32_fp8_e32 v[220:221], v5
	v_cvt_pk_f32_fp8_sdwa v[222:223], v5 src0_sel:WORD_1
	v_cvt_pk_f32_fp8_e32 v[224:225], v6
	v_cvt_pk_f32_fp8_sdwa v[226:227], v6 src0_sel:WORD_1
	v_cvt_pk_f32_fp8_e32 v[228:229], v7
	v_cvt_pk_f32_fp8_sdwa v[230:231], v7 src0_sel:WORD_1
	v_pk_fma_f32 v[80:81], s[22:23], v[216:217], v[80:81] op_sel_hi:[0,1,1]
	v_pk_fma_f32 v[82:83], s[22:23], v[218:219], v[82:83] op_sel_hi:[0,1,1]
	v_pk_fma_f32 v[84:85], s[22:23], v[220:221], v[84:85] op_sel_hi:[0,1,1]
	v_pk_fma_f32 v[86:87], s[22:23], v[222:223], v[86:87] op_sel_hi:[0,1,1]
	v_pk_fma_f32 v[88:89], s[22:23], v[224:225], v[88:89] op_sel_hi:[0,1,1]
	v_pk_fma_f32 v[90:91], s[22:23], v[226:227], v[90:91] op_sel_hi:[0,1,1]
	v_pk_fma_f32 v[92:93], s[22:23], v[228:229], v[92:93] op_sel_hi:[0,1,1]
	v_pk_fma_f32 v[94:95], s[22:23], v[230:231], v[94:95] op_sel_hi:[0,1,1]
	v_readlane_b32 s29, v180, 24
	s_lshl_b32 s29, s29, 10
	v_add_u32_e32 v233, s29, v208
	global_load_dwordx4 v[4:7], v233, s[12:13]
	s_waitcnt vmcnt(15)
; template <int PART>
; DEVI void phase_peer_gather(const Params& p, unsigned char* smem) {
;     ...
;     const bool b5 = (lane & 32) != 0, b4 = (lane & 16) != 0, b3 = (lane & 8) != 0;
;     const int fsrc = ((lane & 4) << 3) | ((lane & 2) << 3) | ((lane & 1) << 3);
;     f32x2 xn2[8], y2[8];
; #pragma unroll
;     for (int i = 0; i < 8; ++i) { xn2[i] = f32x2{xn[2 * i], xn[2 * i + 1]}; y2[i] = f32x2{0.f, 0.f}; }
;     if (PART == 0) {
;       LOADB_(ca, 0)
; #pragma unroll 1
;       for (int bi = 0; bi < 16; bi += 2) {
;         LOADB_(cb, bi + 1)
;         COMPU_(ca, bi)
;         if (bi + 2 < 16) { LOADB_(ca, bi + 2) }
;         COMPU_(cb, bi + 1)
;       }
;       p.gates[(size_t)tok * 128 + lane] = cf0;
;       p.gates[(size_t)tok * 128 + 64 + lane] = cf1;
;       continue;
;     }
;     cf0 = g0; cf1 = g1;
;     LOADB_(ca, 16)
; #pragma unroll 1
;     for (int bi = 16; bi < 32; bi += 2) {
;       LOADB_(cb, bi + 1)
;       COMPV_(ca, bi)
;       if (bi + 2 < 32) { LOADB_(ca, bi + 2) }
;       COMPV_(cb, bi + 1)
;     }
	v_readlane_b32 s26, v182, 17
	v_cvt_pk_f32_fp8_e32 v[216:217], v8
	v_cvt_pk_f32_fp8_sdwa v[218:219], v8 src0_sel:WORD_1
	v_cvt_pk_f32_fp8_e32 v[220:221], v9
	v_cvt_pk_f32_fp8_sdwa v[222:223], v9 src0_sel:WORD_1
	v_cvt_pk_f32_fp8_e32 v[224:225], v10
	v_cvt_pk_f32_fp8_sdwa v[226:227], v10 src0_sel:WORD_1
	v_cvt_pk_f32_fp8_e32 v[228:229], v11
	v_cvt_pk_f32_fp8_sdwa v[230:231], v11 src0_sel:WORD_1
	v_pk_fma_f32 v[64:65], s[24:25], v[216:217], v[64:65] op_sel_hi:[0,1,1]
	v_pk_fma_f32 v[66:67], s[24:25], v[218:219], v[66:67] op_sel_hi:[0,1,1]
	v_pk_fma_f32 v[68:69], s[24:25], v[220:221], v[68:69] op_sel_hi:[0,1,1]
	v_pk_fma_f32 v[70:71], s[24:25], v[222:223], v[70:71] op_sel_hi:[0,1,1]
	v_pk_fma_f32 v[72:73], s[24:25], v[224:225], v[72:73] op_sel_hi:[0,1,1]
	v_pk_fma_f32 v[74:75], s[24:25], v[226:227], v[74:75] op_sel_hi:[0,1,1]
	v_pk_fma_f32 v[76:77], s[24:25], v[228:229], v[76:77] op_sel_hi:[0,1,1]
	v_pk_fma_f32 v[78:79], s[24:25], v[230:231], v[78:79] op_sel_hi:[0,1,1]
	v_readlane_b32 s30, v176, 25
	s_lshl_b32 s30, s30, 10
	v_add_u32_e32 v234, s30, v208
	global_load_dwordx4 v[8:11], v234, s[12:13]
	s_waitcnt vmcnt(15)
	v_readlane_b32 s20, v178, 18
	v_cvt_pk_f32_fp8_e32 v[216:217], v12
	v_cvt_pk_f32_fp8_sdwa v[218:219], v12 src0_sel:WORD_1
	v_cvt_pk_f32_fp8_e32 v[220:221], v13
	v_cvt_pk_f32_fp8_sdwa v[222:223], v13 src0_sel:WORD_1
	v_cvt_pk_f32_fp8_e32 v[224:225], v14
	v_cvt_pk_f32_fp8_sdwa v[226:227], v14 src0_sel:WORD_1
	v_cvt_pk_f32_fp8_e32 v[228:229], v15
	v_cvt_pk_f32_fp8_sdwa v[230:231], v15 src0_sel:WORD_1
	v_pk_fma_f32 v[80:81], s[26:27], v[216:217], v[80:81] op_sel_hi:[0,1,1]
	v_pk_fma_f32 v[82:83], s[26:27], v[218:219], v[82:83] op_sel_hi:[0,1,1]
	v_pk_fma_f32 v[84:85], s[26:27], v[220:221], v[84:85] op_sel_hi:[0,1,1]
	v_pk_fma_f32 v[86:87], s[26:27], v[222:223], v[86:87] op_sel_hi:[0,1,1]
	v_pk_fma_f32 v[88:89], s[26:27], v[224:225], v[88:89] op_sel_hi:[0,1,1]
	v_pk_fma_f32 v[90:91], s[26:27], v[226:227], v[90:91] op_sel_hi:[0,1,1]
	v_pk_fma_f32 v[92:93], s[26:27], v[228:229], v[92:93] op_sel_hi:[0,1,1]
	v_pk_fma_f32 v[94:95], s[26:27], v[230:231], v[94:95] op_sel_hi:[0,1,1]
	v_readlane_b32 s31, v180, 25
	s_lshl_b32 s31, s31, 10
	v_add_u32_e32 v235, s31, v208
	global_load_dwordx4 v[12:15], v235, s[12:13]
	s_waitcnt vmcnt(15)
	v_readlane_b32 s22, v182, 18
	v_cvt_pk_f32_fp8_e32 v[216:217], v16
	v_cvt_pk_f32_fp8_sdwa v[218:219], v16 src0_sel:WORD_1
	v_cvt_pk_f32_fp8_e32 v[220:221], v17
	v_cvt_pk_f32_fp8_sdwa v[222:223], v17 src0_sel:WORD_1
	v_cvt_pk_f32_fp8_e32 v[224:225], v18
	v_cvt_pk_f32_fp8_sdwa v[226:227], v18 src0_sel:WORD_1
	v_cvt_pk_f32_fp8_e32 v[228:229], v19
	v_cvt_pk_f32_fp8_sdwa v[230:231], v19 src0_sel:WORD_1
	v_pk_fma_f32 v[64:65], s[20:21], v[216:217], v[64:65] op_sel_hi:[0,1,1]
	v_pk_fma_f32 v[66:67], s[20:21], v[218:219], v[66:67] op_sel_hi:[0,1,1]
	v_pk_fma_f32 v[68:69], s[20:21], v[220:221], v[68:69] op_sel_hi:[0,1,1]
	v_pk_fma_f32 v[70:71], s[20:21], v[222:223], v[70:71] op_sel_hi:[0,1,1]
	v_pk_fma_f32 v[72:73], s[20:21], v[224:225], v[72:73] op_sel_hi:[0,1,1]
	v_pk_fma_f32 v[74:75], s[20:21], v[226:227], v[74:75] op_sel_hi:[0,1,1]
	v_pk_fma_f32 v[76:77], s[20:21], v[228:229], v[76:77] op_sel_hi:[0,1,1]
	v_pk_fma_f32 v[78:79], s[20:21], v[230:231], v[78:79] op_sel_hi:[0,1,1]
	v_readlane_b32 s28, v176, 26
	s_lshl_b32 s28, s28, 10
	v_add_u32_e32 v232, s28, v208
	global_load_dwordx4 v[16:19], v232, s[12:13]
	s_waitcnt vmcnt(15)
	v_readlane_b32 s24, v178, 19
	v_cvt_pk_f32_fp8_e32 v[216:217], v20
	v_cvt_pk_f32_fp8_sdwa v[218:219], v20 src0_sel:WORD_1
	v_cvt_pk_f32_fp8_e32 v[220:221], v21
	v_cvt_pk_f32_fp8_sdwa v[222:223], v21 src0_sel:WORD_1
	v_cvt_pk_f32_fp8_e32 v[224:225], v22
	v_cvt_pk_f32_fp8_sdwa v[226:227], v22 src0_sel:WORD_1
	v_cvt_pk_f32_fp8_e32 v[228:229], v23
	v_cvt_pk_f32_fp8_sdwa v[230:231], v23 src0_sel:WORD_1
	v_pk_fma_f32 v[80:81], s[22:23], v[216:217], v[80:81] op_sel_hi:[0,1,1]
	v_pk_fma_f32 v[82:83], s[22:23], v[218:219], v[82:83] op_sel_hi:[0,1,1]
	v_pk_fma_f32 v[84:85], s[22:23], v[220:221], v[84:85] op_sel_hi:[0,1,1]
	v_pk_fma_f32 v[86:87], s[22:23], v[222:223], v[86:87] op_sel_hi:[0,1,1]
	v_pk_fma_f32 v[88:89], s[22:23], v[224:225], v[88:89] op_sel_hi:[0,1,1]
	v_pk_fma_f32 v[90:91], s[22:23], v[226:227], v[90:91] op_sel_hi:[0,1,1]
	v_pk_fma_f32 v[92:93], s[22:23], v[228:229], v[92:93] op_sel_hi:[0,1,1]
	v_pk_fma_f32 v[94:95], s[22:23], v[230:231], v[94:95] op_sel_hi:[0,1,1]
	v_readlane_b32 s29, v180, 26
	s_lshl_b32 s29, s29, 10
	v_add_u32_e32 v233, s29, v208
	global_load_dwordx4 v[20:23], v233, s[12:13]
	s_waitcnt vmcnt(15)
	v_readlane_b32 s26, v182, 19
	v_cvt_pk_f32_fp8_e32 v[216:217], v24
	v_cvt_pk_f32_fp8_sdwa v[218:219], v24 src0_sel:WORD_1
	v_cvt_pk_f32_fp8_e32 v[220:221], v25
	v_cvt_pk_f32_fp8_sdwa v[222:223], v25 src0_sel:WORD_1
	v_cvt_pk_f32_fp8_e32 v[224:225], v26
	v_cvt_pk_f32_fp8_sdwa v[226:227], v26 src0_sel:WORD_1
	v_cvt_pk_f32_fp8_e32 v[228:229], v27
	v_cvt_pk_f32_fp8_sdwa v[230:231], v27 src0_sel:WORD_1
	v_pk_fma_f32 v[64:65], s[24:25], v[216:217], v[64:65] op_sel_hi:[0,1,1]
	v_pk_fma_f32 v[66:67], s[24:25], v[218:219], v[66:67] op_sel_hi:[0,1,1]
	v_pk_fma_f32 v[68:69], s[24:25], v[220:221], v[68:69] op_sel_hi:[0,1,1]
	v_pk_fma_f32 v[70:71], s[24:25], v[222:223], v[70:71] op_sel_hi:[0,1,1]
	v_pk_fma_f32 v[72:73], s[24:25], v[224:225], v[72:73] op_sel_hi:[0,1,1]
	v_pk_fma_f32 v[74:75], s[24:25], v[226:227], v[74:75] op_sel_hi:[0,1,1]
	v_pk_fma_f32 v[76:77], s[24:25], v[228:229], v[76:77] op_sel_hi:[0,1,1]
	v_pk_fma_f32 v[78:79], s[24:25], v[230:231], v[78:79] op_sel_hi:[0,1,1]
	v_readlane_b32 s30, v176, 27
	s_lshl_b32 s30, s30, 10
	v_add_u32_e32 v234, s30, v208
	global_load_dwordx4 v[24:27], v234, s[12:13]
	s_waitcnt vmcnt(15)
; template <int PART>
; DEVI void phase_peer_gather(const Params& p, unsigned char* smem) {
;     ...
;     const bool b5 = (lane & 32) != 0, b4 = (lane & 16) != 0, b3 = (lane & 8) != 0;
;     const int fsrc = ((lane & 4) << 3) | ((lane & 2) << 3) | ((lane & 1) << 3);
;     f32x2 xn2[8], y2[8];
; #pragma unroll
;     for (int i = 0; i < 8; ++i) { xn2[i] = f32x2{xn[2 * i], xn[2 * i + 1]}; y2[i] = f32x2{0.f, 0.f}; }
;     if (PART == 0) {
;       LOADB_(ca, 0)
; #pragma unroll 1
;       for (int bi = 0; bi < 16; bi += 2) {
;         LOADB_(cb, bi + 1)
;         COMPU_(ca, bi)
;         if (bi + 2 < 16) { LOADB_(ca, bi + 2) }
;         COMPU_(cb, bi + 1)
;       }
;       p.gates[(size_t)tok * 128 + lane] = cf0;
;       p.gates[(size_t)tok * 128 + 64 + lane] = cf1;
;       continue;
;     }
;     cf0 = g0; cf1 = g1;
;     LOADB_(ca, 16)
; #pragma unroll 1
;     for (int bi = 16; bi < 32; bi += 2) {
;       LOADB_(cb, bi + 1)
;       COMPV_(ca, bi)
;       if (bi + 2 < 32) { LOADB_(ca, bi + 2) }
;       COMPV_(cb, bi + 1)
;     }
	v_readlane_b32 s20, v178, 20
	v_cvt_pk_f32_fp8_e32 v[216:217], v28
	v_cvt_pk_f32_fp8_sdwa v[218:219], v28 src0_sel:WORD_1
	v_cvt_pk_f32_fp8_e32 v[220:221], v29
	v_cvt_pk_f32_fp8_sdwa v[222:223], v29 src0_sel:WORD_1
	v_cvt_pk_f32_fp8_e32 v[224:225], v30
	v_cvt_pk_f32_fp8_sdwa v[226:227], v30 src0_sel:WORD_1
	v_cvt_pk_f32_fp8_e32 v[228:229], v31
	v_cvt_pk_f32_fp8_sdwa v[230:231], v31 src0_sel:WORD_1
	v_pk_fma_f32 v[80:81], s[26:27], v[216:217], v[80:81] op_sel_hi:[0,1,1]
	v_pk_fma_f32 v[82:83], s[26:27], v[218:219], v[82:83] op_sel_hi:[0,1,1]
	v_pk_fma_f32 v[84:85], s[26:27], v[220:221], v[84:85] op_sel_hi:[0,1,1]
	v_pk_fma_f32 v[86:87], s[26:27], v[222:223], v[86:87] op_sel_hi:[0,1,1]
	v_pk_fma_f32 v[88:89], s[26:27], v[224:225], v[88:89] op_sel_hi:[0,1,1]
	v_pk_fma_f32 v[90:91], s[26:27], v[226:227], v[90:91] op_sel_hi:[0,1,1]
	v_pk_fma_f32 v[92:93], s[26:27], v[228:229], v[92:93] op_sel_hi:[0,1,1]
	v_pk_fma_f32 v[94:95], s[26:27], v[230:231], v[94:95] op_sel_hi:[0,1,1]
	v_readlane_b32 s31, v180, 27
	s_lshl_b32 s31, s31, 10
	v_add_u32_e32 v235, s31, v208
	global_load_dwordx4 v[28:31], v235, s[12:13]
	s_waitcnt vmcnt(15)
	v_readlane_b32 s22, v182, 20
	v_cvt_pk_f32_fp8_e32 v[216:217], v32
	v_cvt_pk_f32_fp8_sdwa v[218:219], v32 src0_sel:WORD_1
	v_cvt_pk_f32_fp8_e32 v[220:221], v33
	v_cvt_pk_f32_fp8_sdwa v[222:223], v33 src0_sel:WORD_1
	v_cvt_pk_f32_fp8_e32 v[224:225], v34
	v_cvt_pk_f32_fp8_sdwa v[226:227], v34 src0_sel:WORD_1
	v_cvt_pk_f32_fp8_e32 v[228:229], v35
	v_cvt_pk_f32_fp8_sdwa v[230:231], v35 src0_sel:WORD_1
	v_pk_fma_f32 v[64:65], s[20:21], v[216:217], v[64:65] op_sel_hi:[0,1,1]
	v_pk_fma_f32 v[66:67], s[20:21], v[218:219], v[66:67] op_sel_hi:[0,1,1]
	v_pk_fma_f32 v[68:69], s[20:21], v[220:221], v[68:69] op_sel_hi:[0,1,1]
	v_pk_fma_f32 v[70:71], s[20:21], v[222:223], v[70:71] op_sel_hi:[0,1,1]
	v_pk_fma_f32 v[72:73], s[20:21], v[224:225], v[72:73] op_sel_hi:[0,1,1]
	v_pk_fma_f32 v[74:75], s[20:21], v[226:227], v[74:75] op_sel_hi:[0,1,1]
	v_pk_fma_f32 v[76:77], s[20:21], v[228:229], v[76:77] op_sel_hi:[0,1,1]
	v_pk_fma_f32 v[78:79], s[20:21], v[230:231], v[78:79] op_sel_hi:[0,1,1]
	v_readlane_b32 s28, v176, 28
	s_lshl_b32 s28, s28, 10
	v_add_u32_e32 v232, s28, v208
	global_load_dwordx4 v[32:35], v232, s[12:13]
	s_waitcnt vmcnt(15)
	v_readlane_b32 s24, v178, 21
	v_cvt_pk_f32_fp8_e32 v[216:217], v36
	v_cvt_pk_f32_fp8_sdwa v[218:219], v36 src0_sel:WORD_1
	v_cvt_pk_f32_fp8_e32 v[220:221], v37
	v_cvt_pk_f32_fp8_sdwa v[222:223], v37 src0_sel:WORD_1
	v_cvt_pk_f32_fp8_e32 v[224:225], v38
	v_cvt_pk_f32_fp8_sdwa v[226:227], v38 src0_sel:WORD_1
	v_cvt_pk_f32_fp8_e32 v[228:229], v39
	v_cvt_pk_f32_fp8_sdwa v[230:231], v39 src0_sel:WORD_1
	v_pk_fma_f32 v[80:81], s[22:23], v[216:217], v[80:81] op_sel_hi:[0,1,1]
	v_pk_fma_f32 v[82:83], s[22:23], v[218:219], v[82:83] op_sel_hi:[0,1,1]
	v_pk_fma_f32 v[84:85], s[22:23], v[220:221], v[84:85] op_sel_hi:[0,1,1]
	v_pk_fma_f32 v[86:87], s[22:23], v[222:223], v[86:87] op_sel_hi:[0,1,1]
	v_pk_fma_f32 v[88:89], s[22:23], v[224:225], v[88:89] op_sel_hi:[0,1,1]
	v_pk_fma_f32 v[90:91], s[22:23], v[226:227], v[90:91] op_sel_hi:[0,1,1]
	v_pk_fma_f32 v[92:93], s[22:23], v[228:229], v[92:93] op_sel_hi:[0,1,1]
	v_pk_fma_f32 v[94:95], s[22:23], v[230:231], v[94:95] op_sel_hi:[0,1,1]
	v_readlane_b32 s29, v180, 28
	s_lshl_b32 s29, s29, 10
	v_add_u32_e32 v233, s29, v208
	global_load_dwordx4 v[36:39], v233, s[12:13]
	s_waitcnt vmcnt(15)
	v_readlane_b32 s26, v182, 21
	v_cvt_pk_f32_fp8_e32 v[216:217], v40
	v_cvt_pk_f32_fp8_sdwa v[218:219], v40 src0_sel:WORD_1
	v_cvt_pk_f32_fp8_e32 v[220:221], v41
	v_cvt_pk_f32_fp8_sdwa v[222:223], v41 src0_sel:WORD_1
	v_cvt_pk_f32_fp8_e32 v[224:225], v42
	v_cvt_pk_f32_fp8_sdwa v[226:227], v42 src0_sel:WORD_1
	v_cvt_pk_f32_fp8_e32 v[228:229], v43
	v_cvt_pk_f32_fp8_sdwa v[230:231], v43 src0_sel:WORD_1
	v_pk_fma_f32 v[64:65], s[24:25], v[216:217], v[64:65] op_sel_hi:[0,1,1]
	v_pk_fma_f32 v[66:67], s[24:25], v[218:219], v[66:67] op_sel_hi:[0,1,1]
	v_pk_fma_f32 v[68:69], s[24:25], v[220:221], v[68:69] op_sel_hi:[0,1,1]
	v_pk_fma_f32 v[70:71], s[24:25], v[222:223], v[70:71] op_sel_hi:[0,1,1]
	v_pk_fma_f32 v[72:73], s[24:25], v[224:225], v[72:73] op_sel_hi:[0,1,1]
	v_pk_fma_f32 v[74:75], s[24:25], v[226:227], v[74:75] op_sel_hi:[0,1,1]
	v_pk_fma_f32 v[76:77], s[24:25], v[228:229], v[76:77] op_sel_hi:[0,1,1]
	v_pk_fma_f32 v[78:79], s[24:25], v[230:231], v[78:79] op_sel_hi:[0,1,1]
	v_readlane_b32 s30, v176, 29
	s_lshl_b32 s30, s30, 10
	v_add_u32_e32 v234, s30, v208
	global_load_dwordx4 v[40:43], v234, s[12:13]
	s_waitcnt vmcnt(15)
	v_readlane_b32 s20, v178, 22
	v_cvt_pk_f32_fp8_e32 v[216:217], v44
	v_cvt_pk_f32_fp8_sdwa v[218:219], v44 src0_sel:WORD_1
	v_cvt_pk_f32_fp8_e32 v[220:221], v45
	v_cvt_pk_f32_fp8_sdwa v[222:223], v45 src0_sel:WORD_1
	v_cvt_pk_f32_fp8_e32 v[224:225], v46
	v_cvt_pk_f32_fp8_sdwa v[226:227], v46 src0_sel:WORD_1
	v_cvt_pk_f32_fp8_e32 v[228:229], v47
	v_cvt_pk_f32_fp8_sdwa v[230:231], v47 src0_sel:WORD_1
	v_pk_fma_f32 v[80:81], s[26:27], v[216:217], v[80:81] op_sel_hi:[0,1,1]
	v_pk_fma_f32 v[82:83], s[26:27], v[218:219], v[82:83] op_sel_hi:[0,1,1]
	v_pk_fma_f32 v[84:85], s[26:27], v[220:221], v[84:85] op_sel_hi:[0,1,1]
	v_pk_fma_f32 v[86:87], s[26:27], v[222:223], v[86:87] op_sel_hi:[0,1,1]
	v_pk_fma_f32 v[88:89], s[26:27], v[224:225], v[88:89] op_sel_hi:[0,1,1]
	v_pk_fma_f32 v[90:91], s[26:27], v[226:227], v[90:91] op_sel_hi:[0,1,1]
	v_pk_fma_f32 v[92:93], s[26:27], v[228:229], v[92:93] op_sel_hi:[0,1,1]
	v_pk_fma_f32 v[94:95], s[26:27], v[230:231], v[94:95] op_sel_hi:[0,1,1]
	v_readlane_b32 s31, v180, 29
	s_lshl_b32 s31, s31, 10
	v_add_u32_e32 v235, s31, v208
	global_load_dwordx4 v[44:47], v235, s[12:13]
	s_waitcnt vmcnt(15)
; template <int PART>
; DEVI void phase_peer_gather(const Params& p, unsigned char* smem) {
;     ...
;     const bool b5 = (lane & 32) != 0, b4 = (lane & 16) != 0, b3 = (lane & 8) != 0;
;     const int fsrc = ((lane & 4) << 3) | ((lane & 2) << 3) | ((lane & 1) << 3);
;     f32x2 xn2[8], y2[8];
; #pragma unroll
;     for (int i = 0; i < 8; ++i) { xn2[i] = f32x2{xn[2 * i], xn[2 * i + 1]}; y2[i] = f32x2{0.f, 0.f}; }
;     if (PART == 0) {
;       LOADB_(ca, 0)
; #pragma unroll 1
;       for (int bi = 0; bi < 16; bi += 2) {
;         LOADB_(cb, bi + 1)
;         COMPU_(ca, bi)
;         if (bi + 2 < 16) { LOADB_(ca, bi + 2) }
;         COMPU_(cb, bi + 1)
;       }
;       p.gates[(size_t)tok * 128 + lane] = cf0;
;       p.gates[(size_t)tok * 128 + 64 + lane] = cf1;
;       continue;
;     }
;     cf0 = g0; cf1 = g1;
;     LOADB_(ca, 16)
; #pragma unroll 1
;     for (int bi = 16; bi < 32; bi += 2) {
;       LOADB_(cb, bi + 1)
;       COMPV_(ca, bi)
;       if (bi + 2 < 32) { LOADB_(ca, bi + 2) }
;       COMPV_(cb, bi + 1)
;     }
	v_readlane_b32 s22, v182, 22
	v_cvt_pk_f32_fp8_e32 v[216:217], v48
	v_cvt_pk_f32_fp8_sdwa v[218:219], v48 src0_sel:WORD_1
	v_cvt_pk_f32_fp8_e32 v[220:221], v49
	v_cvt_pk_f32_fp8_sdwa v[222:223], v49 src0_sel:WORD_1
	v_cvt_pk_f32_fp8_e32 v[224:225], v50
	v_cvt_pk_f32_fp8_sdwa v[226:227], v50 src0_sel:WORD_1
	v_cvt_pk_f32_fp8_e32 v[228:229], v51
	v_cvt_pk_f32_fp8_sdwa v[230:231], v51 src0_sel:WORD_1
	v_pk_fma_f32 v[64:65], s[20:21], v[216:217], v[64:65] op_sel_hi:[0,1,1]
	v_pk_fma_f32 v[66:67], s[20:21], v[218:219], v[66:67] op_sel_hi:[0,1,1]
	v_pk_fma_f32 v[68:69], s[20:21], v[220:221], v[68:69] op_sel_hi:[0,1,1]
	v_pk_fma_f32 v[70:71], s[20:21], v[222:223], v[70:71] op_sel_hi:[0,1,1]
	v_pk_fma_f32 v[72:73], s[20:21], v[224:225], v[72:73] op_sel_hi:[0,1,1]
	v_pk_fma_f32 v[74:75], s[20:21], v[226:227], v[74:75] op_sel_hi:[0,1,1]
	v_pk_fma_f32 v[76:77], s[20:21], v[228:229], v[76:77] op_sel_hi:[0,1,1]
	v_pk_fma_f32 v[78:79], s[20:21], v[230:231], v[78:79] op_sel_hi:[0,1,1]
	v_readlane_b32 s28, v176, 30
	s_lshl_b32 s28, s28, 10
	v_add_u32_e32 v232, s28, v208
	global_load_dwordx4 v[48:51], v232, s[12:13]
	s_waitcnt vmcnt(15)
	v_readlane_b32 s24, v178, 23
	v_cvt_pk_f32_fp8_e32 v[216:217], v52
	v_cvt_pk_f32_fp8_sdwa v[218:219], v52 src0_sel:WORD_1
	v_cvt_pk_f32_fp8_e32 v[220:221], v53
	v_cvt_pk_f32_fp8_sdwa v[222:223], v53 src0_sel:WORD_1
	v_cvt_pk_f32_fp8_e32 v[224:225], v54
	v_cvt_pk_f32_fp8_sdwa v[226:227], v54 src0_sel:WORD_1
	v_cvt_pk_f32_fp8_e32 v[228:229], v55
	v_cvt_pk_f32_fp8_sdwa v[230:231], v55 src0_sel:WORD_1
	v_pk_fma_f32 v[80:81], s[22:23], v[216:217], v[80:81] op_sel_hi:[0,1,1]
	v_pk_fma_f32 v[82:83], s[22:23], v[218:219], v[82:83] op_sel_hi:[0,1,1]
	v_pk_fma_f32 v[84:85], s[22:23], v[220:221], v[84:85] op_sel_hi:[0,1,1]
	v_pk_fma_f32 v[86:87], s[22:23], v[222:223], v[86:87] op_sel_hi:[0,1,1]
	v_pk_fma_f32 v[88:89], s[22:23], v[224:225], v[88:89] op_sel_hi:[0,1,1]
	v_pk_fma_f32 v[90:91], s[22:23], v[226:227], v[90:91] op_sel_hi:[0,1,1]
	v_pk_fma_f32 v[92:93], s[22:23], v[228:229], v[92:93] op_sel_hi:[0,1,1]
	v_pk_fma_f32 v[94:95], s[22:23], v[230:231], v[94:95] op_sel_hi:[0,1,1]
	v_readlane_b32 s29, v180, 30
	s_lshl_b32 s29, s29, 10
	v_add_u32_e32 v233, s29, v208
	global_load_dwordx4 v[52:55], v233, s[12:13]
	s_waitcnt vmcnt(15)
	v_readlane_b32 s26, v182, 23
	v_cvt_pk_f32_fp8_e32 v[216:217], v56
	v_cvt_pk_f32_fp8_sdwa v[218:219], v56 src0_sel:WORD_1
	v_cvt_pk_f32_fp8_e32 v[220:221], v57
	v_cvt_pk_f32_fp8_sdwa v[222:223], v57 src0_sel:WORD_1
	v_cvt_pk_f32_fp8_e32 v[224:225], v58
	v_cvt_pk_f32_fp8_sdwa v[226:227], v58 src0_sel:WORD_1
	v_cvt_pk_f32_fp8_e32 v[228:229], v59
	v_cvt_pk_f32_fp8_sdwa v[230:231], v59 src0_sel:WORD_1
	v_pk_fma_f32 v[64:65], s[24:25], v[216:217], v[64:65] op_sel_hi:[0,1,1]
	v_pk_fma_f32 v[66:67], s[24:25], v[218:219], v[66:67] op_sel_hi:[0,1,1]
	v_pk_fma_f32 v[68:69], s[24:25], v[220:221], v[68:69] op_sel_hi:[0,1,1]
	v_pk_fma_f32 v[70:71], s[24:25], v[222:223], v[70:71] op_sel_hi:[0,1,1]
	v_pk_fma_f32 v[72:73], s[24:25], v[224:225], v[72:73] op_sel_hi:[0,1,1]
	v_pk_fma_f32 v[74:75], s[24:25], v[226:227], v[74:75] op_sel_hi:[0,1,1]
	v_pk_fma_f32 v[76:77], s[24:25], v[228:229], v[76:77] op_sel_hi:[0,1,1]
	v_pk_fma_f32 v[78:79], s[24:25], v[230:231], v[78:79] op_sel_hi:[0,1,1]
	v_readlane_b32 s30, v176, 31
	s_lshl_b32 s30, s30, 10
	v_add_u32_e32 v234, s30, v208
	global_load_dwordx4 v[56:59], v234, s[12:13]
	s_waitcnt vmcnt(15)
	v_readlane_b32 s20, v178, 24
	v_cvt_pk_f32_fp8_e32 v[216:217], v60
	v_cvt_pk_f32_fp8_sdwa v[218:219], v60 src0_sel:WORD_1
	v_cvt_pk_f32_fp8_e32 v[220:221], v61
	v_cvt_pk_f32_fp8_sdwa v[222:223], v61 src0_sel:WORD_1
	v_cvt_pk_f32_fp8_e32 v[224:225], v62
	v_cvt_pk_f32_fp8_sdwa v[226:227], v62 src0_sel:WORD_1
	v_cvt_pk_f32_fp8_e32 v[228:229], v63
	v_cvt_pk_f32_fp8_sdwa v[230:231], v63 src0_sel:WORD_1
	v_pk_fma_f32 v[80:81], s[26:27], v[216:217], v[80:81] op_sel_hi:[0,1,1]
	v_pk_fma_f32 v[82:83], s[26:27], v[218:219], v[82:83] op_sel_hi:[0,1,1]
	v_pk_fma_f32 v[84:85], s[26:27], v[220:221], v[84:85] op_sel_hi:[0,1,1]
	v_pk_fma_f32 v[86:87], s[26:27], v[222:223], v[86:87] op_sel_hi:[0,1,1]
	v_pk_fma_f32 v[88:89], s[26:27], v[224:225], v[88:89] op_sel_hi:[0,1,1]
	v_pk_fma_f32 v[90:91], s[26:27], v[226:227], v[90:91] op_sel_hi:[0,1,1]
	v_pk_fma_f32 v[92:93], s[26:27], v[228:229], v[92:93] op_sel_hi:[0,1,1]
	v_pk_fma_f32 v[94:95], s[26:27], v[230:231], v[94:95] op_sel_hi:[0,1,1]
	v_readlane_b32 s31, v180, 31
	s_lshl_b32 s31, s31, 10
	v_add_u32_e32 v235, s31, v208
	global_load_dwordx4 v[60:63], v235, s[12:13]
	s_waitcnt vmcnt(15)
	v_readlane_b32 s22, v182, 24
	v_cvt_pk_f32_fp8_e32 v[216:217], v0
	v_cvt_pk_f32_fp8_sdwa v[218:219], v0 src0_sel:WORD_1
	v_cvt_pk_f32_fp8_e32 v[220:221], v1
	v_cvt_pk_f32_fp8_sdwa v[222:223], v1 src0_sel:WORD_1
	v_cvt_pk_f32_fp8_e32 v[224:225], v2
	v_cvt_pk_f32_fp8_sdwa v[226:227], v2 src0_sel:WORD_1
	v_cvt_pk_f32_fp8_e32 v[228:229], v3
	v_cvt_pk_f32_fp8_sdwa v[230:231], v3 src0_sel:WORD_1
	v_pk_fma_f32 v[64:65], s[20:21], v[216:217], v[64:65] op_sel_hi:[0,1,1]
	v_pk_fma_f32 v[66:67], s[20:21], v[218:219], v[66:67] op_sel_hi:[0,1,1]
	v_pk_fma_f32 v[68:69], s[20:21], v[220:221], v[68:69] op_sel_hi:[0,1,1]
	v_pk_fma_f32 v[70:71], s[20:21], v[222:223], v[70:71] op_sel_hi:[0,1,1]
	v_pk_fma_f32 v[72:73], s[20:21], v[224:225], v[72:73] op_sel_hi:[0,1,1]
	v_pk_fma_f32 v[74:75], s[20:21], v[226:227], v[74:75] op_sel_hi:[0,1,1]
	v_pk_fma_f32 v[76:77], s[20:21], v[228:229], v[76:77] op_sel_hi:[0,1,1]
	v_pk_fma_f32 v[78:79], s[20:21], v[230:231], v[78:79] op_sel_hi:[0,1,1]
	v_readlane_b32 s28, v176, 32
	s_lshl_b32 s28, s28, 10
	v_add_u32_e32 v232, s28, v208
	global_load_dwordx4 v[0:3], v232, s[12:13]
	s_waitcnt vmcnt(15)
	v_readlane_b32 s24, v178, 25
	v_cvt_pk_f32_fp8_e32 v[216:217], v4
	v_cvt_pk_f32_fp8_sdwa v[218:219], v4 src0_sel:WORD_1
	v_cvt_pk_f32_fp8_e32 v[220:221], v5
	v_cvt_pk_f32_fp8_sdwa v[222:223], v5 src0_sel:WORD_1
	v_cvt_pk_f32_fp8_e32 v[224:225], v6
	v_cvt_pk_f32_fp8_sdwa v[226:227], v6 src0_sel:WORD_1
	v_cvt_pk_f32_fp8_e32 v[228:229], v7
	v_cvt_pk_f32_fp8_sdwa v[230:231], v7 src0_sel:WORD_1
	v_pk_fma_f32 v[80:81], s[22:23], v[216:217], v[80:81] op_sel_hi:[0,1,1]
	v_pk_fma_f32 v[82:83], s[22:23], v[218:219], v[82:83] op_sel_hi:[0,1,1]
	v_pk_fma_f32 v[84:85], s[22:23], v[220:221], v[84:85] op_sel_hi:[0,1,1]
	v_pk_fma_f32 v[86:87], s[22:23], v[222:223], v[86:87] op_sel_hi:[0,1,1]
	v_pk_fma_f32 v[88:89], s[22:23], v[224:225], v[88:89] op_sel_hi:[0,1,1]
	v_pk_fma_f32 v[90:91], s[22:23], v[226:227], v[90:91] op_sel_hi:[0,1,1]
	v_pk_fma_f32 v[92:93], s[22:23], v[228:229], v[92:93] op_sel_hi:[0,1,1]
	v_pk_fma_f32 v[94:95], s[22:23], v[230:231], v[94:95] op_sel_hi:[0,1,1]
	v_readlane_b32 s29, v180, 32
	s_lshl_b32 s29, s29, 10
	v_add_u32_e32 v233, s29, v208
	global_load_dwordx4 v[4:7], v233, s[12:13]
	s_waitcnt vmcnt(15)
	v_readlane_b32 s26, v182, 25
	v_cvt_pk_f32_fp8_e32 v[216:217], v8
	v_cvt_pk_f32_fp8_sdwa v[218:219], v8 src0_sel:WORD_1
	v_cvt_pk_f32_fp8_e32 v[220:221], v9
	v_cvt_pk_f32_fp8_sdwa v[222:223], v9 src0_sel:WORD_1
	v_cvt_pk_f32_fp8_e32 v[224:225], v10
	v_cvt_pk_f32_fp8_sdwa v[226:227], v10 src0_sel:WORD_1
	v_cvt_pk_f32_fp8_e32 v[228:229], v11
	v_cvt_pk_f32_fp8_sdwa v[230:231], v11 src0_sel:WORD_1
	v_pk_fma_f32 v[64:65], s[24:25], v[216:217], v[64:65] op_sel_hi:[0,1,1]
	v_pk_fma_f32 v[66:67], s[24:25], v[218:219], v[66:67] op_sel_hi:[0,1,1]
	v_pk_fma_f32 v[68:69], s[24:25], v[220:221], v[68:69] op_sel_hi:[0,1,1]
	v_pk_fma_f32 v[70:71], s[24:25], v[222:223], v[70:71] op_sel_hi:[0,1,1]
	v_pk_fma_f32 v[72:73], s[24:25], v[224:225], v[72:73] op_sel_hi:[0,1,1]
	v_pk_fma_f32 v[74:75], s[24:25], v[226:227], v[74:75] op_sel_hi:[0,1,1]
	v_pk_fma_f32 v[76:77], s[24:25], v[228:229], v[76:77] op_sel_hi:[0,1,1]
	v_pk_fma_f32 v[78:79], s[24:25], v[230:231], v[78:79] op_sel_hi:[0,1,1]
	v_readlane_b32 s30, v176, 33
	s_lshl_b32 s30, s30, 10
	v_add_u32_e32 v234, s30, v208
	global_load_dwordx4 v[8:11], v234, s[12:13]
	s_waitcnt vmcnt(15)
	v_readlane_b32 s20, v178, 26
	v_cvt_pk_f32_fp8_e32 v[216:217], v12
	v_cvt_pk_f32_fp8_sdwa v[218:219], v12 src0_sel:WORD_1
	v_cvt_pk_f32_fp8_e32 v[220:221], v13
	v_cvt_pk_f32_fp8_sdwa v[222:223], v13 src0_sel:WORD_1
	v_cvt_pk_f32_fp8_e32 v[224:225], v14
	v_cvt_pk_f32_fp8_sdwa v[226:227], v14 src0_sel:WORD_1
	v_cvt_pk_f32_fp8_e32 v[228:229], v15
	v_cvt_pk_f32_fp8_sdwa v[230:231], v15 src0_sel:WORD_1
	v_pk_fma_f32 v[80:81], s[26:27], v[216:217], v[80:81] op_sel_hi:[0,1,1]
	v_pk_fma_f32 v[82:83], s[26:27], v[218:219], v[82:83] op_sel_hi:[0,1,1]
	v_pk_fma_f32 v[84:85], s[26:27], v[220:221], v[84:85] op_sel_hi:[0,1,1]
	v_pk_fma_f32 v[86:87], s[26:27], v[222:223], v[86:87] op_sel_hi:[0,1,1]
	v_pk_fma_f32 v[88:89], s[26:27], v[224:225], v[88:89] op_sel_hi:[0,1,1]
	v_pk_fma_f32 v[90:91], s[26:27], v[226:227], v[90:91] op_sel_hi:[0,1,1]
	v_pk_fma_f32 v[92:93], s[26:27], v[228:229], v[92:93] op_sel_hi:[0,1,1]
	v_pk_fma_f32 v[94:95], s[26:27], v[230:231], v[94:95] op_sel_hi:[0,1,1]
	v_readlane_b32 s31, v180, 33
	s_lshl_b32 s31, s31, 10
	v_add_u32_e32 v235, s31, v208
	global_load_dwordx4 v[12:15], v235, s[12:13]
	s_waitcnt vmcnt(15)
	v_readlane_b32 s22, v182, 26
	v_cvt_pk_f32_fp8_e32 v[216:217], v16
	v_cvt_pk_f32_fp8_sdwa v[218:219], v16 src0_sel:WORD_1
	v_cvt_pk_f32_fp8_e32 v[220:221], v17
	v_cvt_pk_f32_fp8_sdwa v[222:223], v17 src0_sel:WORD_1
	v_cvt_pk_f32_fp8_e32 v[224:225], v18
	v_cvt_pk_f32_fp8_sdwa v[226:227], v18 src0_sel:WORD_1
	v_cvt_pk_f32_fp8_e32 v[228:229], v19
	v_cvt_pk_f32_fp8_sdwa v[230:231], v19 src0_sel:WORD_1
	v_pk_fma_f32 v[64:65], s[20:21], v[216:217], v[64:65] op_sel_hi:[0,1,1]
	v_pk_fma_f32 v[66:67], s[20:21], v[218:219], v[66:67] op_sel_hi:[0,1,1]
	v_pk_fma_f32 v[68:69], s[20:21], v[220:221], v[68:69] op_sel_hi:[0,1,1]
	v_pk_fma_f32 v[70:71], s[20:21], v[222:223], v[70:71] op_sel_hi:[0,1,1]
	v_pk_fma_f32 v[72:73], s[20:21], v[224:225], v[72:73] op_sel_hi:[0,1,1]
	v_pk_fma_f32 v[74:75], s[20:21], v[226:227], v[74:75] op_sel_hi:[0,1,1]
	v_pk_fma_f32 v[76:77], s[20:21], v[228:229], v[76:77] op_sel_hi:[0,1,1]
	v_pk_fma_f32 v[78:79], s[20:21], v[230:231], v[78:79] op_sel_hi:[0,1,1]
	v_readlane_b32 s28, v176, 34
	s_lshl_b32 s28, s28, 10
	v_add_u32_e32 v232, s28, v208
	global_load_dwordx4 v[16:19], v232, s[12:13]
	s_waitcnt vmcnt(15)
	v_readlane_b32 s24, v178, 27
	v_cvt_pk_f32_fp8_e32 v[216:217], v20
	v_cvt_pk_f32_fp8_sdwa v[218:219], v20 src0_sel:WORD_1
	v_cvt_pk_f32_fp8_e32 v[220:221], v21
	v_cvt_pk_f32_fp8_sdwa v[222:223], v21 src0_sel:WORD_1
	v_cvt_pk_f32_fp8_e32 v[224:225], v22
	v_cvt_pk_f32_fp8_sdwa v[226:227], v22 src0_sel:WORD_1
	v_cvt_pk_f32_fp8_e32 v[228:229], v23
	v_cvt_pk_f32_fp8_sdwa v[230:231], v23 src0_sel:WORD_1
	v_pk_fma_f32 v[80:81], s[22:23], v[216:217], v[80:81] op_sel_hi:[0,1,1]
	v_pk_fma_f32 v[82:83], s[22:23], v[218:219], v[82:83] op_sel_hi:[0,1,1]
	v_pk_fma_f32 v[84:85], s[22:23], v[220:221], v[84:85] op_sel_hi:[0,1,1]
	v_pk_fma_f32 v[86:87], s[22:23], v[222:223], v[86:87] op_sel_hi:[0,1,1]
	v_pk_fma_f32 v[88:89], s[22:23], v[224:225], v[88:89] op_sel_hi:[0,1,1]
	v_pk_fma_f32 v[90:91], s[22:23], v[226:227], v[90:91] op_sel_hi:[0,1,1]
	v_pk_fma_f32 v[92:93], s[22:23], v[228:229], v[92:93] op_sel_hi:[0,1,1]
	v_pk_fma_f32 v[94:95], s[22:23], v[230:231], v[94:95] op_sel_hi:[0,1,1]
	v_readlane_b32 s29, v180, 34
	s_lshl_b32 s29, s29, 10
	v_add_u32_e32 v233, s29, v208
	global_load_dwordx4 v[20:23], v233, s[12:13]
	s_waitcnt vmcnt(15)
	v_readlane_b32 s26, v182, 27
	v_cvt_pk_f32_fp8_e32 v[216:217], v24
	v_cvt_pk_f32_fp8_sdwa v[218:219], v24 src0_sel:WORD_1
	v_cvt_pk_f32_fp8_e32 v[220:221], v25
	v_cvt_pk_f32_fp8_sdwa v[222:223], v25 src0_sel:WORD_1
	v_cvt_pk_f32_fp8_e32 v[224:225], v26
	v_cvt_pk_f32_fp8_sdwa v[226:227], v26 src0_sel:WORD_1
	v_cvt_pk_f32_fp8_e32 v[228:229], v27
	v_cvt_pk_f32_fp8_sdwa v[230:231], v27 src0_sel:WORD_1
	v_pk_fma_f32 v[64:65], s[24:25], v[216:217], v[64:65] op_sel_hi:[0,1,1]
	v_pk_fma_f32 v[66:67], s[24:25], v[218:219], v[66:67] op_sel_hi:[0,1,1]
	v_pk_fma_f32 v[68:69], s[24:25], v[220:221], v[68:69] op_sel_hi:[0,1,1]
	v_pk_fma_f32 v[70:71], s[24:25], v[222:223], v[70:71] op_sel_hi:[0,1,1]
	v_pk_fma_f32 v[72:73], s[24:25], v[224:225], v[72:73] op_sel_hi:[0,1,1]
	v_pk_fma_f32 v[74:75], s[24:25], v[226:227], v[74:75] op_sel_hi:[0,1,1]
	v_pk_fma_f32 v[76:77], s[24:25], v[228:229], v[76:77] op_sel_hi:[0,1,1]
	v_pk_fma_f32 v[78:79], s[24:25], v[230:231], v[78:79] op_sel_hi:[0,1,1]
	v_readlane_b32 s30, v176, 35
	s_lshl_b32 s30, s30, 10
	v_add_u32_e32 v234, s30, v208
	global_load_dwordx4 v[24:27], v234, s[12:13]
	s_waitcnt vmcnt(15)
	v_readlane_b32 s20, v178, 28
	v_cvt_pk_f32_fp8_e32 v[216:217], v28
	v_cvt_pk_f32_fp8_sdwa v[218:219], v28 src0_sel:WORD_1
	v_cvt_pk_f32_fp8_e32 v[220:221], v29
	v_cvt_pk_f32_fp8_sdwa v[222:223], v29 src0_sel:WORD_1
	v_cvt_pk_f32_fp8_e32 v[224:225], v30
	v_cvt_pk_f32_fp8_sdwa v[226:227], v30 src0_sel:WORD_1
	v_cvt_pk_f32_fp8_e32 v[228:229], v31
	v_cvt_pk_f32_fp8_sdwa v[230:231], v31 src0_sel:WORD_1
	v_pk_fma_f32 v[80:81], s[26:27], v[216:217], v[80:81] op_sel_hi:[0,1,1]
	v_pk_fma_f32 v[82:83], s[26:27], v[218:219], v[82:83] op_sel_hi:[0,1,1]
	v_pk_fma_f32 v[84:85], s[26:27], v[220:221], v[84:85] op_sel_hi:[0,1,1]
	v_pk_fma_f32 v[86:87], s[26:27], v[222:223], v[86:87] op_sel_hi:[0,1,1]
	v_pk_fma_f32 v[88:89], s[26:27], v[224:225], v[88:89] op_sel_hi:[0,1,1]
	v_pk_fma_f32 v[90:91], s[26:27], v[226:227], v[90:91] op_sel_hi:[0,1,1]
	v_pk_fma_f32 v[92:93], s[26:27], v[228:229], v[92:93] op_sel_hi:[0,1,1]
	v_pk_fma_f32 v[94:95], s[26:27], v[230:231], v[94:95] op_sel_hi:[0,1,1]
	v_readlane_b32 s31, v180, 35
	s_lshl_b32 s31, s31, 10
	v_add_u32_e32 v235, s31, v208
	global_load_dwordx4 v[28:31], v235, s[12:13]
	s_waitcnt vmcnt(15)
	v_readlane_b32 s22, v182, 28
	v_cvt_pk_f32_fp8_e32 v[216:217], v32
	v_cvt_pk_f32_fp8_sdwa v[218:219], v32 src0_sel:WORD_1
	v_cvt_pk_f32_fp8_e32 v[220:221], v33
	v_cvt_pk_f32_fp8_sdwa v[222:223], v33 src0_sel:WORD_1
	v_cvt_pk_f32_fp8_e32 v[224:225], v34
	v_cvt_pk_f32_fp8_sdwa v[226:227], v34 src0_sel:WORD_1
	v_cvt_pk_f32_fp8_e32 v[228:229], v35
	v_cvt_pk_f32_fp8_sdwa v[230:231], v35 src0_sel:WORD_1
	v_pk_fma_f32 v[64:65], s[20:21], v[216:217], v[64:65] op_sel_hi:[0,1,1]
	v_pk_fma_f32 v[66:67], s[20:21], v[218:219], v[66:67] op_sel_hi:[0,1,1]
	v_pk_fma_f32 v[68:69], s[20:21], v[220:221], v[68:69] op_sel_hi:[0,1,1]
	v_pk_fma_f32 v[70:71], s[20:21], v[222:223], v[70:71] op_sel_hi:[0,1,1]
	v_pk_fma_f32 v[72:73], s[20:21], v[224:225], v[72:73] op_sel_hi:[0,1,1]
	v_pk_fma_f32 v[74:75], s[20:21], v[226:227], v[74:75] op_sel_hi:[0,1,1]
	v_pk_fma_f32 v[76:77], s[20:21], v[228:229], v[76:77] op_sel_hi:[0,1,1]
	v_pk_fma_f32 v[78:79], s[20:21], v[230:231], v[78:79] op_sel_hi:[0,1,1]
	v_readlane_b32 s28, v176, 36
	s_lshl_b32 s28, s28, 10
	v_add_u32_e32 v232, s28, v208
	global_load_dwordx4 v[32:35], v232, s[12:13]
	s_waitcnt vmcnt(15)
	v_readlane_b32 s24, v178, 29
	v_cvt_pk_f32_fp8_e32 v[216:217], v36
	v_cvt_pk_f32_fp8_sdwa v[218:219], v36 src0_sel:WORD_1
	v_cvt_pk_f32_fp8_e32 v[220:221], v37
	v_cvt_pk_f32_fp8_sdwa v[222:223], v37 src0_sel:WORD_1
	v_cvt_pk_f32_fp8_e32 v[224:225], v38
	v_cvt_pk_f32_fp8_sdwa v[226:227], v38 src0_sel:WORD_1
	v_cvt_pk_f32_fp8_e32 v[228:229], v39
	v_cvt_pk_f32_fp8_sdwa v[230:231], v39 src0_sel:WORD_1
	v_pk_fma_f32 v[80:81], s[22:23], v[216:217], v[80:81] op_sel_hi:[0,1,1]
	v_pk_fma_f32 v[82:83], s[22:23], v[218:219], v[82:83] op_sel_hi:[0,1,1]
	v_pk_fma_f32 v[84:85], s[22:23], v[220:221], v[84:85] op_sel_hi:[0,1,1]
	v_pk_fma_f32 v[86:87], s[22:23], v[222:223], v[86:87] op_sel_hi:[0,1,1]
	v_pk_fma_f32 v[88:89], s[22:23], v[224:225], v[88:89] op_sel_hi:[0,1,1]
	v_pk_fma_f32 v[90:91], s[22:23], v[226:227], v[90:91] op_sel_hi:[0,1,1]
	v_pk_fma_f32 v[92:93], s[22:23], v[228:229], v[92:93] op_sel_hi:[0,1,1]
	v_pk_fma_f32 v[94:95], s[22:23], v[230:231], v[94:95] op_sel_hi:[0,1,1]
	v_readlane_b32 s29, v180, 36
	s_lshl_b32 s29, s29, 10
	v_add_u32_e32 v233, s29, v208
	global_load_dwordx4 v[36:39], v233, s[12:13]
	s_waitcnt vmcnt(15)
	v_readlane_b32 s26, v182, 29
	v_cvt_pk_f32_fp8_e32 v[216:217], v40
	v_cvt_pk_f32_fp8_sdwa v[218:219], v40 src0_sel:WORD_1
	v_cvt_pk_f32_fp8_e32 v[220:221], v41
	v_cvt_pk_f32_fp8_sdwa v[222:223], v41 src0_sel:WORD_1
	v_cvt_pk_f32_fp8_e32 v[224:225], v42
	v_cvt_pk_f32_fp8_sdwa v[226:227], v42 src0_sel:WORD_1
	v_cvt_pk_f32_fp8_e32 v[228:229], v43
	v_cvt_pk_f32_fp8_sdwa v[230:231], v43 src0_sel:WORD_1
	v_pk_fma_f32 v[64:65], s[24:25], v[216:217], v[64:65] op_sel_hi:[0,1,1]
	v_pk_fma_f32 v[66:67], s[24:25], v[218:219], v[66:67] op_sel_hi:[0,1,1]
	v_pk_fma_f32 v[68:69], s[24:25], v[220:221], v[68:69] op_sel_hi:[0,1,1]
	v_pk_fma_f32 v[70:71], s[24:25], v[222:223], v[70:71] op_sel_hi:[0,1,1]
	v_pk_fma_f32 v[72:73], s[24:25], v[224:225], v[72:73] op_sel_hi:[0,1,1]
	v_pk_fma_f32 v[74:75], s[24:25], v[226:227], v[74:75] op_sel_hi:[0,1,1]
	v_pk_fma_f32 v[76:77], s[24:25], v[228:229], v[76:77] op_sel_hi:[0,1,1]
	v_pk_fma_f32 v[78:79], s[24:25], v[230:231], v[78:79] op_sel_hi:[0,1,1]
	v_readlane_b32 s30, v176, 37
	s_lshl_b32 s30, s30, 10
	v_add_u32_e32 v234, s30, v208
	global_load_dwordx4 v[40:43], v234, s[12:13]
	s_waitcnt vmcnt(15)
	v_readlane_b32 s20, v178, 30
	v_cvt_pk_f32_fp8_e32 v[216:217], v44
	v_cvt_pk_f32_fp8_sdwa v[218:219], v44 src0_sel:WORD_1
	v_cvt_pk_f32_fp8_e32 v[220:221], v45
	v_cvt_pk_f32_fp8_sdwa v[222:223], v45 src0_sel:WORD_1
	v_cvt_pk_f32_fp8_e32 v[224:225], v46
	v_cvt_pk_f32_fp8_sdwa v[226:227], v46 src0_sel:WORD_1
	v_cvt_pk_f32_fp8_e32 v[228:229], v47
	v_cvt_pk_f32_fp8_sdwa v[230:231], v47 src0_sel:WORD_1
	v_pk_fma_f32 v[80:81], s[26:27], v[216:217], v[80:81] op_sel_hi:[0,1,1]
	v_pk_fma_f32 v[82:83], s[26:27], v[218:219], v[82:83] op_sel_hi:[0,1,1]
	v_pk_fma_f32 v[84:85], s[26:27], v[220:221], v[84:85] op_sel_hi:[0,1,1]
	v_pk_fma_f32 v[86:87], s[26:27], v[222:223], v[86:87] op_sel_hi:[0,1,1]
	v_pk_fma_f32 v[88:89], s[26:27], v[224:225], v[88:89] op_sel_hi:[0,1,1]
	v_pk_fma_f32 v[90:91], s[26:27], v[226:227], v[90:91] op_sel_hi:[0,1,1]
	v_pk_fma_f32 v[92:93], s[26:27], v[228:229], v[92:93] op_sel_hi:[0,1,1]
	v_pk_fma_f32 v[94:95], s[26:27], v[230:231], v[94:95] op_sel_hi:[0,1,1]
	v_readlane_b32 s31, v180, 37
	s_lshl_b32 s31, s31, 10
	v_add_u32_e32 v235, s31, v208
	global_load_dwordx4 v[44:47], v235, s[12:13]
	s_waitcnt vmcnt(15)
	v_readlane_b32 s22, v182, 30
	v_cvt_pk_f32_fp8_e32 v[216:217], v48
	v_cvt_pk_f32_fp8_sdwa v[218:219], v48 src0_sel:WORD_1
	v_cvt_pk_f32_fp8_e32 v[220:221], v49
	v_cvt_pk_f32_fp8_sdwa v[222:223], v49 src0_sel:WORD_1
	v_cvt_pk_f32_fp8_e32 v[224:225], v50
	v_cvt_pk_f32_fp8_sdwa v[226:227], v50 src0_sel:WORD_1
	v_cvt_pk_f32_fp8_e32 v[228:229], v51
	v_cvt_pk_f32_fp8_sdwa v[230:231], v51 src0_sel:WORD_1
	v_pk_fma_f32 v[64:65], s[20:21], v[216:217], v[64:65] op_sel_hi:[0,1,1]
	v_pk_fma_f32 v[66:67], s[20:21], v[218:219], v[66:67] op_sel_hi:[0,1,1]
	v_pk_fma_f32 v[68:69], s[20:21], v[220:221], v[68:69] op_sel_hi:[0,1,1]
	v_pk_fma_f32 v[70:71], s[20:21], v[222:223], v[70:71] op_sel_hi:[0,1,1]
	v_pk_fma_f32 v[72:73], s[20:21], v[224:225], v[72:73] op_sel_hi:[0,1,1]
	v_pk_fma_f32 v[74:75], s[20:21], v[226:227], v[74:75] op_sel_hi:[0,1,1]
	v_pk_fma_f32 v[76:77], s[20:21], v[228:229], v[76:77] op_sel_hi:[0,1,1]
	v_pk_fma_f32 v[78:79], s[20:21], v[230:231], v[78:79] op_sel_hi:[0,1,1]
	v_readlane_b32 s28, v176, 38
	s_lshl_b32 s28, s28, 10
	v_add_u32_e32 v232, s28, v208
	global_load_dwordx4 v[48:51], v232, s[12:13]
	s_waitcnt vmcnt(15)
	v_readlane_b32 s24, v178, 31
	v_cvt_pk_f32_fp8_e32 v[216:217], v52
	v_cvt_pk_f32_fp8_sdwa v[218:219], v52 src0_sel:WORD_1
	v_cvt_pk_f32_fp8_e32 v[220:221], v53
	v_cvt_pk_f32_fp8_sdwa v[222:223], v53 src0_sel:WORD_1
	v_cvt_pk_f32_fp8_e32 v[224:225], v54
	v_cvt_pk_f32_fp8_sdwa v[226:227], v54 src0_sel:WORD_1
	v_cvt_pk_f32_fp8_e32 v[228:229], v55
	v_cvt_pk_f32_fp8_sdwa v[230:231], v55 src0_sel:WORD_1
	v_pk_fma_f32 v[80:81], s[22:23], v[216:217], v[80:81] op_sel_hi:[0,1,1]
	v_pk_fma_f32 v[82:83], s[22:23], v[218:219], v[82:83] op_sel_hi:[0,1,1]
	v_pk_fma_f32 v[84:85], s[22:23], v[220:221], v[84:85] op_sel_hi:[0,1,1]
	v_pk_fma_f32 v[86:87], s[22:23], v[222:223], v[86:87] op_sel_hi:[0,1,1]
	v_pk_fma_f32 v[88:89], s[22:23], v[224:225], v[88:89] op_sel_hi:[0,1,1]
	v_pk_fma_f32 v[90:91], s[22:23], v[226:227], v[90:91] op_sel_hi:[0,1,1]
	v_pk_fma_f32 v[92:93], s[22:23], v[228:229], v[92:93] op_sel_hi:[0,1,1]
	v_pk_fma_f32 v[94:95], s[22:23], v[230:231], v[94:95] op_sel_hi:[0,1,1]
	v_readlane_b32 s29, v180, 38
	s_lshl_b32 s29, s29, 10
	v_add_u32_e32 v233, s29, v208
	global_load_dwordx4 v[52:55], v233, s[12:13]
	s_waitcnt vmcnt(15)
	v_readlane_b32 s26, v182, 31
	v_cvt_pk_f32_fp8_e32 v[216:217], v56
	v_cvt_pk_f32_fp8_sdwa v[218:219], v56 src0_sel:WORD_1
	v_cvt_pk_f32_fp8_e32 v[220:221], v57
	v_cvt_pk_f32_fp8_sdwa v[222:223], v57 src0_sel:WORD_1
	v_cvt_pk_f32_fp8_e32 v[224:225], v58
	v_cvt_pk_f32_fp8_sdwa v[226:227], v58 src0_sel:WORD_1
	v_cvt_pk_f32_fp8_e32 v[228:229], v59
	v_cvt_pk_f32_fp8_sdwa v[230:231], v59 src0_sel:WORD_1
	v_pk_fma_f32 v[64:65], s[24:25], v[216:217], v[64:65] op_sel_hi:[0,1,1]
	v_pk_fma_f32 v[66:67], s[24:25], v[218:219], v[66:67] op_sel_hi:[0,1,1]
	v_pk_fma_f32 v[68:69], s[24:25], v[220:221], v[68:69] op_sel_hi:[0,1,1]
	v_pk_fma_f32 v[70:71], s[24:25], v[222:223], v[70:71] op_sel_hi:[0,1,1]
	v_pk_fma_f32 v[72:73], s[24:25], v[224:225], v[72:73] op_sel_hi:[0,1,1]
	v_pk_fma_f32 v[74:75], s[24:25], v[226:227], v[74:75] op_sel_hi:[0,1,1]
	v_pk_fma_f32 v[76:77], s[24:25], v[228:229], v[76:77] op_sel_hi:[0,1,1]
	v_pk_fma_f32 v[78:79], s[24:25], v[230:231], v[78:79] op_sel_hi:[0,1,1]
	v_readlane_b32 s30, v176, 39
	s_lshl_b32 s30, s30, 10
	v_add_u32_e32 v234, s30, v208
	global_load_dwordx4 v[56:59], v234, s[12:13]
	s_waitcnt vmcnt(15)
	v_readlane_b32 s20, v178, 32
	v_cvt_pk_f32_fp8_e32 v[216:217], v60
	v_cvt_pk_f32_fp8_sdwa v[218:219], v60 src0_sel:WORD_1
	v_cvt_pk_f32_fp8_e32 v[220:221], v61
	v_cvt_pk_f32_fp8_sdwa v[222:223], v61 src0_sel:WORD_1
	v_cvt_pk_f32_fp8_e32 v[224:225], v62
	v_cvt_pk_f32_fp8_sdwa v[226:227], v62 src0_sel:WORD_1
	v_cvt_pk_f32_fp8_e32 v[228:229], v63
	v_cvt_pk_f32_fp8_sdwa v[230:231], v63 src0_sel:WORD_1
	v_pk_fma_f32 v[80:81], s[26:27], v[216:217], v[80:81] op_sel_hi:[0,1,1]
	v_pk_fma_f32 v[82:83], s[26:27], v[218:219], v[82:83] op_sel_hi:[0,1,1]
	v_pk_fma_f32 v[84:85], s[26:27], v[220:221], v[84:85] op_sel_hi:[0,1,1]
	v_pk_fma_f32 v[86:87], s[26:27], v[222:223], v[86:87] op_sel_hi:[0,1,1]
	v_pk_fma_f32 v[88:89], s[26:27], v[224:225], v[88:89] op_sel_hi:[0,1,1]
	v_pk_fma_f32 v[90:91], s[26:27], v[226:227], v[90:91] op_sel_hi:[0,1,1]
	v_pk_fma_f32 v[92:93], s[26:27], v[228:229], v[92:93] op_sel_hi:[0,1,1]
	v_pk_fma_f32 v[94:95], s[26:27], v[230:231], v[94:95] op_sel_hi:[0,1,1]
	v_readlane_b32 s31, v180, 39
	s_lshl_b32 s31, s31, 10
	v_add_u32_e32 v235, s31, v208
	global_load_dwordx4 v[60:63], v235, s[12:13]
	s_waitcnt vmcnt(15)
	v_readlane_b32 s22, v182, 32
	v_cvt_pk_f32_fp8_e32 v[216:217], v0
	v_cvt_pk_f32_fp8_sdwa v[218:219], v0 src0_sel:WORD_1
	v_cvt_pk_f32_fp8_e32 v[220:221], v1
	v_cvt_pk_f32_fp8_sdwa v[222:223], v1 src0_sel:WORD_1
	v_cvt_pk_f32_fp8_e32 v[224:225], v2
	v_cvt_pk_f32_fp8_sdwa v[226:227], v2 src0_sel:WORD_1
	v_cvt_pk_f32_fp8_e32 v[228:229], v3
	v_cvt_pk_f32_fp8_sdwa v[230:231], v3 src0_sel:WORD_1
	v_pk_fma_f32 v[64:65], s[20:21], v[216:217], v[64:65] op_sel_hi:[0,1,1]
	v_pk_fma_f32 v[66:67], s[20:21], v[218:219], v[66:67] op_sel_hi:[0,1,1]
	v_pk_fma_f32 v[68:69], s[20:21], v[220:221], v[68:69] op_sel_hi:[0,1,1]
	v_pk_fma_f32 v[70:71], s[20:21], v[222:223], v[70:71] op_sel_hi:[0,1,1]
	v_pk_fma_f32 v[72:73], s[20:21], v[224:225], v[72:73] op_sel_hi:[0,1,1]
	v_pk_fma_f32 v[74:75], s[20:21], v[226:227], v[74:75] op_sel_hi:[0,1,1]
	v_pk_fma_f32 v[76:77], s[20:21], v[228:229], v[76:77] op_sel_hi:[0,1,1]
	v_pk_fma_f32 v[78:79], s[20:21], v[230:231], v[78:79] op_sel_hi:[0,1,1]
	v_readlane_b32 s28, v176, 40
	s_lshl_b32 s28, s28, 10
	v_add_u32_e32 v232, s28, v208
	global_load_dwordx4 v[0:3], v232, s[12:13]
	s_waitcnt vmcnt(15)
	v_readlane_b32 s24, v178, 33
	v_cvt_pk_f32_fp8_e32 v[216:217], v4
	v_cvt_pk_f32_fp8_sdwa v[218:219], v4 src0_sel:WORD_1
	v_cvt_pk_f32_fp8_e32 v[220:221], v5
	v_cvt_pk_f32_fp8_sdwa v[222:223], v5 src0_sel:WORD_1
	v_cvt_pk_f32_fp8_e32 v[224:225], v6
	v_cvt_pk_f32_fp8_sdwa v[226:227], v6 src0_sel:WORD_1
	v_cvt_pk_f32_fp8_e32 v[228:229], v7
	v_cvt_pk_f32_fp8_sdwa v[230:231], v7 src0_sel:WORD_1
	v_pk_fma_f32 v[80:81], s[22:23], v[216:217], v[80:81] op_sel_hi:[0,1,1]
	v_pk_fma_f32 v[82:83], s[22:23], v[218:219], v[82:83] op_sel_hi:[0,1,1]
	v_pk_fma_f32 v[84:85], s[22:23], v[220:221], v[84:85] op_sel_hi:[0,1,1]
	v_pk_fma_f32 v[86:87], s[22:23], v[222:223], v[86:87] op_sel_hi:[0,1,1]
	v_pk_fma_f32 v[88:89], s[22:23], v[224:225], v[88:89] op_sel_hi:[0,1,1]
	v_pk_fma_f32 v[90:91], s[22:23], v[226:227], v[90:91] op_sel_hi:[0,1,1]
	v_pk_fma_f32 v[92:93], s[22:23], v[228:229], v[92:93] op_sel_hi:[0,1,1]
	v_pk_fma_f32 v[94:95], s[22:23], v[230:231], v[94:95] op_sel_hi:[0,1,1]
	v_readlane_b32 s29, v180, 40
	s_lshl_b32 s29, s29, 10
	v_add_u32_e32 v233, s29, v208
	global_load_dwordx4 v[4:7], v233, s[12:13]
	s_waitcnt vmcnt(15)
	v_readlane_b32 s26, v182, 33
	v_cvt_pk_f32_fp8_e32 v[216:217], v8
	v_cvt_pk_f32_fp8_sdwa v[218:219], v8 src0_sel:WORD_1
	v_cvt_pk_f32_fp8_e32 v[220:221], v9
	v_cvt_pk_f32_fp8_sdwa v[222:223], v9 src0_sel:WORD_1
	v_cvt_pk_f32_fp8_e32 v[224:225], v10
	v_cvt_pk_f32_fp8_sdwa v[226:227], v10 src0_sel:WORD_1
	v_cvt_pk_f32_fp8_e32 v[228:229], v11
	v_cvt_pk_f32_fp8_sdwa v[230:231], v11 src0_sel:WORD_1
	v_pk_fma_f32 v[64:65], s[24:25], v[216:217], v[64:65] op_sel_hi:[0,1,1]
	v_pk_fma_f32 v[66:67], s[24:25], v[218:219], v[66:67] op_sel_hi:[0,1,1]
	v_pk_fma_f32 v[68:69], s[24:25], v[220:221], v[68:69] op_sel_hi:[0,1,1]
	v_pk_fma_f32 v[70:71], s[24:25], v[222:223], v[70:71] op_sel_hi:[0,1,1]
	v_pk_fma_f32 v[72:73], s[24:25], v[224:225], v[72:73] op_sel_hi:[0,1,1]
	v_pk_fma_f32 v[74:75], s[24:25], v[226:227], v[74:75] op_sel_hi:[0,1,1]
	v_pk_fma_f32 v[76:77], s[24:25], v[228:229], v[76:77] op_sel_hi:[0,1,1]
	v_pk_fma_f32 v[78:79], s[24:25], v[230:231], v[78:79] op_sel_hi:[0,1,1]
	v_readlane_b32 s30, v176, 41
	s_lshl_b32 s30, s30, 10
	v_add_u32_e32 v234, s30, v208
	global_load_dwordx4 v[8:11], v234, s[12:13]
	s_waitcnt vmcnt(15)
	v_readlane_b32 s20, v178, 34
	v_cvt_pk_f32_fp8_e32 v[216:217], v12
	v_cvt_pk_f32_fp8_sdwa v[218:219], v12 src0_sel:WORD_1
	v_cvt_pk_f32_fp8_e32 v[220:221], v13
	v_cvt_pk_f32_fp8_sdwa v[222:223], v13 src0_sel:WORD_1
	v_cvt_pk_f32_fp8_e32 v[224:225], v14
	v_cvt_pk_f32_fp8_sdwa v[226:227], v14 src0_sel:WORD_1
	v_cvt_pk_f32_fp8_e32 v[228:229], v15
	v_cvt_pk_f32_fp8_sdwa v[230:231], v15 src0_sel:WORD_1
	v_pk_fma_f32 v[80:81], s[26:27], v[216:217], v[80:81] op_sel_hi:[0,1,1]
	v_pk_fma_f32 v[82:83], s[26:27], v[218:219], v[82:83] op_sel_hi:[0,1,1]
	v_pk_fma_f32 v[84:85], s[26:27], v[220:221], v[84:85] op_sel_hi:[0,1,1]
	v_pk_fma_f32 v[86:87], s[26:27], v[222:223], v[86:87] op_sel_hi:[0,1,1]
	v_pk_fma_f32 v[88:89], s[26:27], v[224:225], v[88:89] op_sel_hi:[0,1,1]
	v_pk_fma_f32 v[90:91], s[26:27], v[226:227], v[90:91] op_sel_hi:[0,1,1]
	v_pk_fma_f32 v[92:93], s[26:27], v[228:229], v[92:93] op_sel_hi:[0,1,1]
	v_pk_fma_f32 v[94:95], s[26:27], v[230:231], v[94:95] op_sel_hi:[0,1,1]
	v_readlane_b32 s31, v180, 41
	s_lshl_b32 s31, s31, 10
	v_add_u32_e32 v235, s31, v208
	global_load_dwordx4 v[12:15], v235, s[12:13]
	s_waitcnt vmcnt(15)
	v_readlane_b32 s22, v182, 34
	v_cvt_pk_f32_fp8_e32 v[216:217], v16
	v_cvt_pk_f32_fp8_sdwa v[218:219], v16 src0_sel:WORD_1
	v_cvt_pk_f32_fp8_e32 v[220:221], v17
	v_cvt_pk_f32_fp8_sdwa v[222:223], v17 src0_sel:WORD_1
	v_cvt_pk_f32_fp8_e32 v[224:225], v18
	v_cvt_pk_f32_fp8_sdwa v[226:227], v18 src0_sel:WORD_1
	v_cvt_pk_f32_fp8_e32 v[228:229], v19
	v_cvt_pk_f32_fp8_sdwa v[230:231], v19 src0_sel:WORD_1
	v_pk_fma_f32 v[64:65], s[20:21], v[216:217], v[64:65] op_sel_hi:[0,1,1]
	v_pk_fma_f32 v[66:67], s[20:21], v[218:219], v[66:67] op_sel_hi:[0,1,1]
	v_pk_fma_f32 v[68:69], s[20:21], v[220:221], v[68:69] op_sel_hi:[0,1,1]
	v_pk_fma_f32 v[70:71], s[20:21], v[222:223], v[70:71] op_sel_hi:[0,1,1]
	v_pk_fma_f32 v[72:73], s[20:21], v[224:225], v[72:73] op_sel_hi:[0,1,1]
	v_pk_fma_f32 v[74:75], s[20:21], v[226:227], v[74:75] op_sel_hi:[0,1,1]
	v_pk_fma_f32 v[76:77], s[20:21], v[228:229], v[76:77] op_sel_hi:[0,1,1]
	v_pk_fma_f32 v[78:79], s[20:21], v[230:231], v[78:79] op_sel_hi:[0,1,1]
	v_readlane_b32 s28, v176, 42
	s_lshl_b32 s28, s28, 10
	v_add_u32_e32 v232, s28, v208
	global_load_dwordx4 v[16:19], v232, s[12:13]
	s_waitcnt vmcnt(15)
	v_readlane_b32 s24, v178, 35
	v_cvt_pk_f32_fp8_e32 v[216:217], v20
	v_cvt_pk_f32_fp8_sdwa v[218:219], v20 src0_sel:WORD_1
	v_cvt_pk_f32_fp8_e32 v[220:221], v21
	v_cvt_pk_f32_fp8_sdwa v[222:223], v21 src0_sel:WORD_1
	v_cvt_pk_f32_fp8_e32 v[224:225], v22
	v_cvt_pk_f32_fp8_sdwa v[226:227], v22 src0_sel:WORD_1
	v_cvt_pk_f32_fp8_e32 v[228:229], v23
	v_cvt_pk_f32_fp8_sdwa v[230:231], v23 src0_sel:WORD_1
	v_pk_fma_f32 v[80:81], s[22:23], v[216:217], v[80:81] op_sel_hi:[0,1,1]
	v_pk_fma_f32 v[82:83], s[22:23], v[218:219], v[82:83] op_sel_hi:[0,1,1]
	v_pk_fma_f32 v[84:85], s[22:23], v[220:221], v[84:85] op_sel_hi:[0,1,1]
	v_pk_fma_f32 v[86:87], s[22:23], v[222:223], v[86:87] op_sel_hi:[0,1,1]
	v_pk_fma_f32 v[88:89], s[22:23], v[224:225], v[88:89] op_sel_hi:[0,1,1]
	v_pk_fma_f32 v[90:91], s[22:23], v[226:227], v[90:91] op_sel_hi:[0,1,1]
	v_pk_fma_f32 v[92:93], s[22:23], v[228:229], v[92:93] op_sel_hi:[0,1,1]
	v_pk_fma_f32 v[94:95], s[22:23], v[230:231], v[94:95] op_sel_hi:[0,1,1]
	v_readlane_b32 s29, v180, 42
	s_lshl_b32 s29, s29, 10
	v_add_u32_e32 v233, s29, v208
	global_load_dwordx4 v[20:23], v233, s[12:13]
	s_waitcnt vmcnt(15)
	v_readlane_b32 s26, v182, 35
	v_cvt_pk_f32_fp8_e32 v[216:217], v24
	v_cvt_pk_f32_fp8_sdwa v[218:219], v24 src0_sel:WORD_1
	v_cvt_pk_f32_fp8_e32 v[220:221], v25
	v_cvt_pk_f32_fp8_sdwa v[222:223], v25 src0_sel:WORD_1
	v_cvt_pk_f32_fp8_e32 v[224:225], v26
	v_cvt_pk_f32_fp8_sdwa v[226:227], v26 src0_sel:WORD_1
	v_cvt_pk_f32_fp8_e32 v[228:229], v27
	v_cvt_pk_f32_fp8_sdwa v[230:231], v27 src0_sel:WORD_1
	v_pk_fma_f32 v[64:65], s[24:25], v[216:217], v[64:65] op_sel_hi:[0,1,1]
	v_pk_fma_f32 v[66:67], s[24:25], v[218:219], v[66:67] op_sel_hi:[0,1,1]
	v_pk_fma_f32 v[68:69], s[24:25], v[220:221], v[68:69] op_sel_hi:[0,1,1]
	v_pk_fma_f32 v[70:71], s[24:25], v[222:223], v[70:71] op_sel_hi:[0,1,1]
	v_pk_fma_f32 v[72:73], s[24:25], v[224:225], v[72:73] op_sel_hi:[0,1,1]
	v_pk_fma_f32 v[74:75], s[24:25], v[226:227], v[74:75] op_sel_hi:[0,1,1]
	v_pk_fma_f32 v[76:77], s[24:25], v[228:229], v[76:77] op_sel_hi:[0,1,1]
	v_pk_fma_f32 v[78:79], s[24:25], v[230:231], v[78:79] op_sel_hi:[0,1,1]
	v_readlane_b32 s30, v176, 43
	s_lshl_b32 s30, s30, 10
	v_add_u32_e32 v234, s30, v208
	global_load_dwordx4 v[24:27], v234, s[12:13]
	s_waitcnt vmcnt(15)
	v_readlane_b32 s20, v178, 36
	v_cvt_pk_f32_fp8_e32 v[216:217], v28
	v_cvt_pk_f32_fp8_sdwa v[218:219], v28 src0_sel:WORD_1
	v_cvt_pk_f32_fp8_e32 v[220:221], v29
	v_cvt_pk_f32_fp8_sdwa v[222:223], v29 src0_sel:WORD_1
	v_cvt_pk_f32_fp8_e32 v[224:225], v30
	v_cvt_pk_f32_fp8_sdwa v[226:227], v30 src0_sel:WORD_1
	v_cvt_pk_f32_fp8_e32 v[228:229], v31
	v_cvt_pk_f32_fp8_sdwa v[230:231], v31 src0_sel:WORD_1
	v_pk_fma_f32 v[80:81], s[26:27], v[216:217], v[80:81] op_sel_hi:[0,1,1]
	v_pk_fma_f32 v[82:83], s[26:27], v[218:219], v[82:83] op_sel_hi:[0,1,1]
	v_pk_fma_f32 v[84:85], s[26:27], v[220:221], v[84:85] op_sel_hi:[0,1,1]
	v_pk_fma_f32 v[86:87], s[26:27], v[222:223], v[86:87] op_sel_hi:[0,1,1]
	v_pk_fma_f32 v[88:89], s[26:27], v[224:225], v[88:89] op_sel_hi:[0,1,1]
	v_pk_fma_f32 v[90:91], s[26:27], v[226:227], v[90:91] op_sel_hi:[0,1,1]
	v_pk_fma_f32 v[92:93], s[26:27], v[228:229], v[92:93] op_sel_hi:[0,1,1]
	v_pk_fma_f32 v[94:95], s[26:27], v[230:231], v[94:95] op_sel_hi:[0,1,1]
	v_readlane_b32 s31, v180, 43
	s_lshl_b32 s31, s31, 10
	v_add_u32_e32 v235, s31, v208
	global_load_dwordx4 v[28:31], v235, s[12:13]
	s_waitcnt vmcnt(15)
	v_readlane_b32 s22, v182, 36
	v_cvt_pk_f32_fp8_e32 v[216:217], v32
	v_cvt_pk_f32_fp8_sdwa v[218:219], v32 src0_sel:WORD_1
	v_cvt_pk_f32_fp8_e32 v[220:221], v33
	v_cvt_pk_f32_fp8_sdwa v[222:223], v33 src0_sel:WORD_1
	v_cvt_pk_f32_fp8_e32 v[224:225], v34
	v_cvt_pk_f32_fp8_sdwa v[226:227], v34 src0_sel:WORD_1
	v_cvt_pk_f32_fp8_e32 v[228:229], v35
	v_cvt_pk_f32_fp8_sdwa v[230:231], v35 src0_sel:WORD_1
	v_pk_fma_f32 v[64:65], s[20:21], v[216:217], v[64:65] op_sel_hi:[0,1,1]
	v_pk_fma_f32 v[66:67], s[20:21], v[218:219], v[66:67] op_sel_hi:[0,1,1]
	v_pk_fma_f32 v[68:69], s[20:21], v[220:221], v[68:69] op_sel_hi:[0,1,1]
	v_pk_fma_f32 v[70:71], s[20:21], v[222:223], v[70:71] op_sel_hi:[0,1,1]
	v_pk_fma_f32 v[72:73], s[20:21], v[224:225], v[72:73] op_sel_hi:[0,1,1]
	v_pk_fma_f32 v[74:75], s[20:21], v[226:227], v[74:75] op_sel_hi:[0,1,1]
	v_pk_fma_f32 v[76:77], s[20:21], v[228:229], v[76:77] op_sel_hi:[0,1,1]
	v_pk_fma_f32 v[78:79], s[20:21], v[230:231], v[78:79] op_sel_hi:[0,1,1]
	v_readlane_b32 s28, v176, 44
	s_lshl_b32 s28, s28, 10
	v_add_u32_e32 v232, s28, v208
	global_load_dwordx4 v[32:35], v232, s[12:13]
	s_waitcnt vmcnt(15)
	v_readlane_b32 s24, v178, 37
	v_cvt_pk_f32_fp8_e32 v[216:217], v36
	v_cvt_pk_f32_fp8_sdwa v[218:219], v36 src0_sel:WORD_1
	v_cvt_pk_f32_fp8_e32 v[220:221], v37
	v_cvt_pk_f32_fp8_sdwa v[222:223], v37 src0_sel:WORD_1
	v_cvt_pk_f32_fp8_e32 v[224:225], v38
	v_cvt_pk_f32_fp8_sdwa v[226:227], v38 src0_sel:WORD_1
	v_cvt_pk_f32_fp8_e32 v[228:229], v39
	v_cvt_pk_f32_fp8_sdwa v[230:231], v39 src0_sel:WORD_1
	v_pk_fma_f32 v[80:81], s[22:23], v[216:217], v[80:81] op_sel_hi:[0,1,1]
	v_pk_fma_f32 v[82:83], s[22:23], v[218:219], v[82:83] op_sel_hi:[0,1,1]
	v_pk_fma_f32 v[84:85], s[22:23], v[220:221], v[84:85] op_sel_hi:[0,1,1]
	v_pk_fma_f32 v[86:87], s[22:23], v[222:223], v[86:87] op_sel_hi:[0,1,1]
	v_pk_fma_f32 v[88:89], s[22:23], v[224:225], v[88:89] op_sel_hi:[0,1,1]
	v_pk_fma_f32 v[90:91], s[22:23], v[226:227], v[90:91] op_sel_hi:[0,1,1]
	v_pk_fma_f32 v[92:93], s[22:23], v[228:229], v[92:93] op_sel_hi:[0,1,1]
	v_pk_fma_f32 v[94:95], s[22:23], v[230:231], v[94:95] op_sel_hi:[0,1,1]
	v_readlane_b32 s29, v180, 44
	s_lshl_b32 s29, s29, 10
	v_add_u32_e32 v233, s29, v208
	global_load_dwordx4 v[36:39], v233, s[12:13]
	s_waitcnt vmcnt(15)
	v_readlane_b32 s26, v182, 37
	v_cvt_pk_f32_fp8_e32 v[216:217], v40
	v_cvt_pk_f32_fp8_sdwa v[218:219], v40 src0_sel:WORD_1
	v_cvt_pk_f32_fp8_e32 v[220:221], v41
	v_cvt_pk_f32_fp8_sdwa v[222:223], v41 src0_sel:WORD_1
	v_cvt_pk_f32_fp8_e32 v[224:225], v42
	v_cvt_pk_f32_fp8_sdwa v[226:227], v42 src0_sel:WORD_1
	v_cvt_pk_f32_fp8_e32 v[228:229], v43
	v_cvt_pk_f32_fp8_sdwa v[230:231], v43 src0_sel:WORD_1
	v_pk_fma_f32 v[64:65], s[24:25], v[216:217], v[64:65] op_sel_hi:[0,1,1]
	v_pk_fma_f32 v[66:67], s[24:25], v[218:219], v[66:67] op_sel_hi:[0,1,1]
	v_pk_fma_f32 v[68:69], s[24:25], v[220:221], v[68:69] op_sel_hi:[0,1,1]
	v_pk_fma_f32 v[70:71], s[24:25], v[222:223], v[70:71] op_sel_hi:[0,1,1]
	v_pk_fma_f32 v[72:73], s[24:25], v[224:225], v[72:73] op_sel_hi:[0,1,1]
	v_pk_fma_f32 v[74:75], s[24:25], v[226:227], v[74:75] op_sel_hi:[0,1,1]
	v_pk_fma_f32 v[76:77], s[24:25], v[228:229], v[76:77] op_sel_hi:[0,1,1]
	v_pk_fma_f32 v[78:79], s[24:25], v[230:231], v[78:79] op_sel_hi:[0,1,1]
	v_readlane_b32 s30, v176, 45
	s_lshl_b32 s30, s30, 10
	v_add_u32_e32 v234, s30, v208
	global_load_dwordx4 v[40:43], v234, s[12:13]
	s_waitcnt vmcnt(15)
	v_readlane_b32 s20, v178, 38
	v_cvt_pk_f32_fp8_e32 v[216:217], v44
	v_cvt_pk_f32_fp8_sdwa v[218:219], v44 src0_sel:WORD_1
	v_cvt_pk_f32_fp8_e32 v[220:221], v45
	v_cvt_pk_f32_fp8_sdwa v[222:223], v45 src0_sel:WORD_1
	v_cvt_pk_f32_fp8_e32 v[224:225], v46
	v_cvt_pk_f32_fp8_sdwa v[226:227], v46 src0_sel:WORD_1
	v_cvt_pk_f32_fp8_e32 v[228:229], v47
	v_cvt_pk_f32_fp8_sdwa v[230:231], v47 src0_sel:WORD_1
	v_pk_fma_f32 v[80:81], s[26:27], v[216:217], v[80:81] op_sel_hi:[0,1,1]
	v_pk_fma_f32 v[82:83], s[26:27], v[218:219], v[82:83] op_sel_hi:[0,1,1]
	v_pk_fma_f32 v[84:85], s[26:27], v[220:221], v[84:85] op_sel_hi:[0,1,1]
	v_pk_fma_f32 v[86:87], s[26:27], v[222:223], v[86:87] op_sel_hi:[0,1,1]
	v_pk_fma_f32 v[88:89], s[26:27], v[224:225], v[88:89] op_sel_hi:[0,1,1]
	v_pk_fma_f32 v[90:91], s[26:27], v[226:227], v[90:91] op_sel_hi:[0,1,1]
	v_pk_fma_f32 v[92:93], s[26:27], v[228:229], v[92:93] op_sel_hi:[0,1,1]
	v_pk_fma_f32 v[94:95], s[26:27], v[230:231], v[94:95] op_sel_hi:[0,1,1]
	v_readlane_b32 s31, v180, 45
	s_lshl_b32 s31, s31, 10
	v_add_u32_e32 v235, s31, v208
	global_load_dwordx4 v[44:47], v235, s[12:13]
	s_waitcnt vmcnt(15)
	v_readlane_b32 s22, v182, 38
	v_cvt_pk_f32_fp8_e32 v[216:217], v48
	v_cvt_pk_f32_fp8_sdwa v[218:219], v48 src0_sel:WORD_1
	v_cvt_pk_f32_fp8_e32 v[220:221], v49
	v_cvt_pk_f32_fp8_sdwa v[222:223], v49 src0_sel:WORD_1
	v_cvt_pk_f32_fp8_e32 v[224:225], v50
	v_cvt_pk_f32_fp8_sdwa v[226:227], v50 src0_sel:WORD_1
	v_cvt_pk_f32_fp8_e32 v[228:229], v51
	v_cvt_pk_f32_fp8_sdwa v[230:231], v51 src0_sel:WORD_1
	v_pk_fma_f32 v[64:65], s[20:21], v[216:217], v[64:65] op_sel_hi:[0,1,1]
	v_pk_fma_f32 v[66:67], s[20:21], v[218:219], v[66:67] op_sel_hi:[0,1,1]
	v_pk_fma_f32 v[68:69], s[20:21], v[220:221], v[68:69] op_sel_hi:[0,1,1]
	v_pk_fma_f32 v[70:71], s[20:21], v[222:223], v[70:71] op_sel_hi:[0,1,1]
	v_pk_fma_f32 v[72:73], s[20:21], v[224:225], v[72:73] op_sel_hi:[0,1,1]
	v_pk_fma_f32 v[74:75], s[20:21], v[226:227], v[74:75] op_sel_hi:[0,1,1]
	v_pk_fma_f32 v[76:77], s[20:21], v[228:229], v[76:77] op_sel_hi:[0,1,1]
	v_pk_fma_f32 v[78:79], s[20:21], v[230:231], v[78:79] op_sel_hi:[0,1,1]
	v_readlane_b32 s28, v176, 46
	s_lshl_b32 s28, s28, 10
	v_add_u32_e32 v232, s28, v208
	global_load_dwordx4 v[48:51], v232, s[12:13]
	s_waitcnt vmcnt(15)
	v_readlane_b32 s24, v178, 39
	v_cvt_pk_f32_fp8_e32 v[216:217], v52
	v_cvt_pk_f32_fp8_sdwa v[218:219], v52 src0_sel:WORD_1
	v_cvt_pk_f32_fp8_e32 v[220:221], v53
	v_cvt_pk_f32_fp8_sdwa v[222:223], v53 src0_sel:WORD_1
	v_cvt_pk_f32_fp8_e32 v[224:225], v54
	v_cvt_pk_f32_fp8_sdwa v[226:227], v54 src0_sel:WORD_1
	v_cvt_pk_f32_fp8_e32 v[228:229], v55
	v_cvt_pk_f32_fp8_sdwa v[230:231], v55 src0_sel:WORD_1
	v_pk_fma_f32 v[80:81], s[22:23], v[216:217], v[80:81] op_sel_hi:[0,1,1]
	v_pk_fma_f32 v[82:83], s[22:23], v[218:219], v[82:83] op_sel_hi:[0,1,1]
	v_pk_fma_f32 v[84:85], s[22:23], v[220:221], v[84:85] op_sel_hi:[0,1,1]
	v_pk_fma_f32 v[86:87], s[22:23], v[222:223], v[86:87] op_sel_hi:[0,1,1]
	v_pk_fma_f32 v[88:89], s[22:23], v[224:225], v[88:89] op_sel_hi:[0,1,1]
	v_pk_fma_f32 v[90:91], s[22:23], v[226:227], v[90:91] op_sel_hi:[0,1,1]
	v_pk_fma_f32 v[92:93], s[22:23], v[228:229], v[92:93] op_sel_hi:[0,1,1]
	v_pk_fma_f32 v[94:95], s[22:23], v[230:231], v[94:95] op_sel_hi:[0,1,1]
	v_readlane_b32 s29, v180, 46
	s_lshl_b32 s29, s29, 10
	v_add_u32_e32 v233, s29, v208
	global_load_dwordx4 v[52:55], v233, s[12:13]
	s_waitcnt vmcnt(15)
	v_readlane_b32 s26, v182, 39
	v_cvt_pk_f32_fp8_e32 v[216:217], v56
	v_cvt_pk_f32_fp8_sdwa v[218:219], v56 src0_sel:WORD_1
	v_cvt_pk_f32_fp8_e32 v[220:221], v57
	v_cvt_pk_f32_fp8_sdwa v[222:223], v57 src0_sel:WORD_1
	v_cvt_pk_f32_fp8_e32 v[224:225], v58
	v_cvt_pk_f32_fp8_sdwa v[226:227], v58 src0_sel:WORD_1
	v_cvt_pk_f32_fp8_e32 v[228:229], v59
	v_cvt_pk_f32_fp8_sdwa v[230:231], v59 src0_sel:WORD_1
	v_pk_fma_f32 v[64:65], s[24:25], v[216:217], v[64:65] op_sel_hi:[0,1,1]
	v_pk_fma_f32 v[66:67], s[24:25], v[218:219], v[66:67] op_sel_hi:[0,1,1]
	v_pk_fma_f32 v[68:69], s[24:25], v[220:221], v[68:69] op_sel_hi:[0,1,1]
	v_pk_fma_f32 v[70:71], s[24:25], v[222:223], v[70:71] op_sel_hi:[0,1,1]
	v_pk_fma_f32 v[72:73], s[24:25], v[224:225], v[72:73] op_sel_hi:[0,1,1]
	v_pk_fma_f32 v[74:75], s[24:25], v[226:227], v[74:75] op_sel_hi:[0,1,1]
	v_pk_fma_f32 v[76:77], s[24:25], v[228:229], v[76:77] op_sel_hi:[0,1,1]
	v_pk_fma_f32 v[78:79], s[24:25], v[230:231], v[78:79] op_sel_hi:[0,1,1]
	v_readlane_b32 s30, v176, 47
	s_lshl_b32 s30, s30, 10
	v_add_u32_e32 v234, s30, v208
	global_load_dwordx4 v[56:59], v234, s[12:13]
	s_waitcnt vmcnt(15)
	v_readlane_b32 s20, v178, 40
	v_cvt_pk_f32_fp8_e32 v[216:217], v60
	v_cvt_pk_f32_fp8_sdwa v[218:219], v60 src0_sel:WORD_1
	v_cvt_pk_f32_fp8_e32 v[220:221], v61
	v_cvt_pk_f32_fp8_sdwa v[222:223], v61 src0_sel:WORD_1
	v_cvt_pk_f32_fp8_e32 v[224:225], v62
	v_cvt_pk_f32_fp8_sdwa v[226:227], v62 src0_sel:WORD_1
	v_cvt_pk_f32_fp8_e32 v[228:229], v63
	v_cvt_pk_f32_fp8_sdwa v[230:231], v63 src0_sel:WORD_1
	v_pk_fma_f32 v[80:81], s[26:27], v[216:217], v[80:81] op_sel_hi:[0,1,1]
	v_pk_fma_f32 v[82:83], s[26:27], v[218:219], v[82:83] op_sel_hi:[0,1,1]
	v_pk_fma_f32 v[84:85], s[26:27], v[220:221], v[84:85] op_sel_hi:[0,1,1]
	v_pk_fma_f32 v[86:87], s[26:27], v[222:223], v[86:87] op_sel_hi:[0,1,1]
	v_pk_fma_f32 v[88:89], s[26:27], v[224:225], v[88:89] op_sel_hi:[0,1,1]
	v_pk_fma_f32 v[90:91], s[26:27], v[226:227], v[90:91] op_sel_hi:[0,1,1]
	v_pk_fma_f32 v[92:93], s[26:27], v[228:229], v[92:93] op_sel_hi:[0,1,1]
	v_pk_fma_f32 v[94:95], s[26:27], v[230:231], v[94:95] op_sel_hi:[0,1,1]
	v_readlane_b32 s31, v180, 47
	s_lshl_b32 s31, s31, 10
	v_add_u32_e32 v235, s31, v208
	global_load_dwordx4 v[60:63], v235, s[12:13]
	s_waitcnt vmcnt(15)
	v_readlane_b32 s22, v182, 40
	v_cvt_pk_f32_fp8_e32 v[216:217], v0
	v_cvt_pk_f32_fp8_sdwa v[218:219], v0 src0_sel:WORD_1
	v_cvt_pk_f32_fp8_e32 v[220:221], v1
	v_cvt_pk_f32_fp8_sdwa v[222:223], v1 src0_sel:WORD_1
	v_cvt_pk_f32_fp8_e32 v[224:225], v2
	v_cvt_pk_f32_fp8_sdwa v[226:227], v2 src0_sel:WORD_1
	v_cvt_pk_f32_fp8_e32 v[228:229], v3
	v_cvt_pk_f32_fp8_sdwa v[230:231], v3 src0_sel:WORD_1
	v_pk_fma_f32 v[64:65], s[20:21], v[216:217], v[64:65] op_sel_hi:[0,1,1]
	v_pk_fma_f32 v[66:67], s[20:21], v[218:219], v[66:67] op_sel_hi:[0,1,1]
	v_pk_fma_f32 v[68:69], s[20:21], v[220:221], v[68:69] op_sel_hi:[0,1,1]
	v_pk_fma_f32 v[70:71], s[20:21], v[222:223], v[70:71] op_sel_hi:[0,1,1]
	v_pk_fma_f32 v[72:73], s[20:21], v[224:225], v[72:73] op_sel_hi:[0,1,1]
	v_pk_fma_f32 v[74:75], s[20:21], v[226:227], v[74:75] op_sel_hi:[0,1,1]
	v_pk_fma_f32 v[76:77], s[20:21], v[228:229], v[76:77] op_sel_hi:[0,1,1]
	v_pk_fma_f32 v[78:79], s[20:21], v[230:231], v[78:79] op_sel_hi:[0,1,1]
	v_readlane_b32 s28, v176, 48
	s_lshl_b32 s28, s28, 10
	v_add_u32_e32 v232, s28, v208
	global_load_dwordx4 v[0:3], v232, s[12:13]
	s_waitcnt vmcnt(15)
	v_readlane_b32 s24, v178, 41
	v_cvt_pk_f32_fp8_e32 v[216:217], v4
	v_cvt_pk_f32_fp8_sdwa v[218:219], v4 src0_sel:WORD_1
	v_cvt_pk_f32_fp8_e32 v[220:221], v5
	v_cvt_pk_f32_fp8_sdwa v[222:223], v5 src0_sel:WORD_1
	v_cvt_pk_f32_fp8_e32 v[224:225], v6
	v_cvt_pk_f32_fp8_sdwa v[226:227], v6 src0_sel:WORD_1
	v_cvt_pk_f32_fp8_e32 v[228:229], v7
	v_cvt_pk_f32_fp8_sdwa v[230:231], v7 src0_sel:WORD_1
	v_pk_fma_f32 v[80:81], s[22:23], v[216:217], v[80:81] op_sel_hi:[0,1,1]
	v_pk_fma_f32 v[82:83], s[22:23], v[218:219], v[82:83] op_sel_hi:[0,1,1]
	v_pk_fma_f32 v[84:85], s[22:23], v[220:221], v[84:85] op_sel_hi:[0,1,1]
	v_pk_fma_f32 v[86:87], s[22:23], v[222:223], v[86:87] op_sel_hi:[0,1,1]
	v_pk_fma_f32 v[88:89], s[22:23], v[224:225], v[88:89] op_sel_hi:[0,1,1]
	v_pk_fma_f32 v[90:91], s[22:23], v[226:227], v[90:91] op_sel_hi:[0,1,1]
	v_pk_fma_f32 v[92:93], s[22:23], v[228:229], v[92:93] op_sel_hi:[0,1,1]
	v_pk_fma_f32 v[94:95], s[22:23], v[230:231], v[94:95] op_sel_hi:[0,1,1]
	v_readlane_b32 s29, v180, 48
	s_lshl_b32 s29, s29, 10
	v_add_u32_e32 v233, s29, v208
	global_load_dwordx4 v[4:7], v233, s[12:13]
	s_waitcnt vmcnt(15)
	v_readlane_b32 s26, v182, 41
	v_cvt_pk_f32_fp8_e32 v[216:217], v8
	v_cvt_pk_f32_fp8_sdwa v[218:219], v8 src0_sel:WORD_1
	v_cvt_pk_f32_fp8_e32 v[220:221], v9
	v_cvt_pk_f32_fp8_sdwa v[222:223], v9 src0_sel:WORD_1
	v_cvt_pk_f32_fp8_e32 v[224:225], v10
	v_cvt_pk_f32_fp8_sdwa v[226:227], v10 src0_sel:WORD_1
	v_cvt_pk_f32_fp8_e32 v[228:229], v11
	v_cvt_pk_f32_fp8_sdwa v[230:231], v11 src0_sel:WORD_1
	v_pk_fma_f32 v[64:65], s[24:25], v[216:217], v[64:65] op_sel_hi:[0,1,1]
	v_pk_fma_f32 v[66:67], s[24:25], v[218:219], v[66:67] op_sel_hi:[0,1,1]
	v_pk_fma_f32 v[68:69], s[24:25], v[220:221], v[68:69] op_sel_hi:[0,1,1]
	v_pk_fma_f32 v[70:71], s[24:25], v[222:223], v[70:71] op_sel_hi:[0,1,1]
	v_pk_fma_f32 v[72:73], s[24:25], v[224:225], v[72:73] op_sel_hi:[0,1,1]
	v_pk_fma_f32 v[74:75], s[24:25], v[226:227], v[74:75] op_sel_hi:[0,1,1]
	v_pk_fma_f32 v[76:77], s[24:25], v[228:229], v[76:77] op_sel_hi:[0,1,1]
	v_pk_fma_f32 v[78:79], s[24:25], v[230:231], v[78:79] op_sel_hi:[0,1,1]
	v_readlane_b32 s30, v176, 49
	s_lshl_b32 s30, s30, 10
	v_add_u32_e32 v234, s30, v208
	global_load_dwordx4 v[8:11], v234, s[12:13]
	s_waitcnt vmcnt(15)
	v_readlane_b32 s20, v178, 42
	v_cvt_pk_f32_fp8_e32 v[216:217], v12
	v_cvt_pk_f32_fp8_sdwa v[218:219], v12 src0_sel:WORD_1
	v_cvt_pk_f32_fp8_e32 v[220:221], v13
	v_cvt_pk_f32_fp8_sdwa v[222:223], v13 src0_sel:WORD_1
	v_cvt_pk_f32_fp8_e32 v[224:225], v14
	v_cvt_pk_f32_fp8_sdwa v[226:227], v14 src0_sel:WORD_1
	v_cvt_pk_f32_fp8_e32 v[228:229], v15
	v_cvt_pk_f32_fp8_sdwa v[230:231], v15 src0_sel:WORD_1
	v_pk_fma_f32 v[80:81], s[26:27], v[216:217], v[80:81] op_sel_hi:[0,1,1]
	v_pk_fma_f32 v[82:83], s[26:27], v[218:219], v[82:83] op_sel_hi:[0,1,1]
	v_pk_fma_f32 v[84:85], s[26:27], v[220:221], v[84:85] op_sel_hi:[0,1,1]
	v_pk_fma_f32 v[86:87], s[26:27], v[222:223], v[86:87] op_sel_hi:[0,1,1]
	v_pk_fma_f32 v[88:89], s[26:27], v[224:225], v[88:89] op_sel_hi:[0,1,1]
	v_pk_fma_f32 v[90:91], s[26:27], v[226:227], v[90:91] op_sel_hi:[0,1,1]
	v_pk_fma_f32 v[92:93], s[26:27], v[228:229], v[92:93] op_sel_hi:[0,1,1]
	v_pk_fma_f32 v[94:95], s[26:27], v[230:231], v[94:95] op_sel_hi:[0,1,1]
	v_readlane_b32 s31, v180, 49
	s_lshl_b32 s31, s31, 10
	v_add_u32_e32 v235, s31, v208
	global_load_dwordx4 v[12:15], v235, s[12:13]
	s_waitcnt vmcnt(15)
	v_readlane_b32 s22, v182, 42
	v_cvt_pk_f32_fp8_e32 v[216:217], v16
	v_cvt_pk_f32_fp8_sdwa v[218:219], v16 src0_sel:WORD_1
	v_cvt_pk_f32_fp8_e32 v[220:221], v17
	v_cvt_pk_f32_fp8_sdwa v[222:223], v17 src0_sel:WORD_1
	v_cvt_pk_f32_fp8_e32 v[224:225], v18
	v_cvt_pk_f32_fp8_sdwa v[226:227], v18 src0_sel:WORD_1
	v_cvt_pk_f32_fp8_e32 v[228:229], v19
	v_cvt_pk_f32_fp8_sdwa v[230:231], v19 src0_sel:WORD_1
	v_pk_fma_f32 v[64:65], s[20:21], v[216:217], v[64:65] op_sel_hi:[0,1,1]
	v_pk_fma_f32 v[66:67], s[20:21], v[218:219], v[66:67] op_sel_hi:[0,1,1]
	v_pk_fma_f32 v[68:69], s[20:21], v[220:221], v[68:69] op_sel_hi:[0,1,1]
	v_pk_fma_f32 v[70:71], s[20:21], v[222:223], v[70:71] op_sel_hi:[0,1,1]
	v_pk_fma_f32 v[72:73], s[20:21], v[224:225], v[72:73] op_sel_hi:[0,1,1]
	v_pk_fma_f32 v[74:75], s[20:21], v[226:227], v[74:75] op_sel_hi:[0,1,1]
	v_pk_fma_f32 v[76:77], s[20:21], v[228:229], v[76:77] op_sel_hi:[0,1,1]
	v_pk_fma_f32 v[78:79], s[20:21], v[230:231], v[78:79] op_sel_hi:[0,1,1]
	v_readlane_b32 s28, v176, 50
	s_lshl_b32 s28, s28, 10
	v_add_u32_e32 v232, s28, v208
	global_load_dwordx4 v[16:19], v232, s[12:13]
	s_waitcnt vmcnt(15)
	v_readlane_b32 s24, v178, 43
	v_cvt_pk_f32_fp8_e32 v[216:217], v20
	v_cvt_pk_f32_fp8_sdwa v[218:219], v20 src0_sel:WORD_1
	v_cvt_pk_f32_fp8_e32 v[220:221], v21
	v_cvt_pk_f32_fp8_sdwa v[222:223], v21 src0_sel:WORD_1
	v_cvt_pk_f32_fp8_e32 v[224:225], v22
	v_cvt_pk_f32_fp8_sdwa v[226:227], v22 src0_sel:WORD_1
	v_cvt_pk_f32_fp8_e32 v[228:229], v23
	v_cvt_pk_f32_fp8_sdwa v[230:231], v23 src0_sel:WORD_1
	v_pk_fma_f32 v[80:81], s[22:23], v[216:217], v[80:81] op_sel_hi:[0,1,1]
	v_pk_fma_f32 v[82:83], s[22:23], v[218:219], v[82:83] op_sel_hi:[0,1,1]
	v_pk_fma_f32 v[84:85], s[22:23], v[220:221], v[84:85] op_sel_hi:[0,1,1]
	v_pk_fma_f32 v[86:87], s[22:23], v[222:223], v[86:87] op_sel_hi:[0,1,1]
	v_pk_fma_f32 v[88:89], s[22:23], v[224:225], v[88:89] op_sel_hi:[0,1,1]
	v_pk_fma_f32 v[90:91], s[22:23], v[226:227], v[90:91] op_sel_hi:[0,1,1]
	v_pk_fma_f32 v[92:93], s[22:23], v[228:229], v[92:93] op_sel_hi:[0,1,1]
	v_pk_fma_f32 v[94:95], s[22:23], v[230:231], v[94:95] op_sel_hi:[0,1,1]
	v_readlane_b32 s29, v180, 50
	s_lshl_b32 s29, s29, 10
	v_add_u32_e32 v233, s29, v208
	global_load_dwordx4 v[20:23], v233, s[12:13]
	s_waitcnt vmcnt(15)
	v_readlane_b32 s26, v182, 43
	v_cvt_pk_f32_fp8_e32 v[216:217], v24
	v_cvt_pk_f32_fp8_sdwa v[218:219], v24 src0_sel:WORD_1
	v_cvt_pk_f32_fp8_e32 v[220:221], v25
	v_cvt_pk_f32_fp8_sdwa v[222:223], v25 src0_sel:WORD_1
	v_cvt_pk_f32_fp8_e32 v[224:225], v26
	v_cvt_pk_f32_fp8_sdwa v[226:227], v26 src0_sel:WORD_1
	v_cvt_pk_f32_fp8_e32 v[228:229], v27
	v_cvt_pk_f32_fp8_sdwa v[230:231], v27 src0_sel:WORD_1
	v_pk_fma_f32 v[64:65], s[24:25], v[216:217], v[64:65] op_sel_hi:[0,1,1]
	v_pk_fma_f32 v[66:67], s[24:25], v[218:219], v[66:67] op_sel_hi:[0,1,1]
	v_pk_fma_f32 v[68:69], s[24:25], v[220:221], v[68:69] op_sel_hi:[0,1,1]
	v_pk_fma_f32 v[70:71], s[24:25], v[222:223], v[70:71] op_sel_hi:[0,1,1]
	v_pk_fma_f32 v[72:73], s[24:25], v[224:225], v[72:73] op_sel_hi:[0,1,1]
	v_pk_fma_f32 v[74:75], s[24:25], v[226:227], v[74:75] op_sel_hi:[0,1,1]
	v_pk_fma_f32 v[76:77], s[24:25], v[228:229], v[76:77] op_sel_hi:[0,1,1]
	v_pk_fma_f32 v[78:79], s[24:25], v[230:231], v[78:79] op_sel_hi:[0,1,1]
	v_readlane_b32 s30, v176, 51
	s_lshl_b32 s30, s30, 10
	v_add_u32_e32 v234, s30, v208
	global_load_dwordx4 v[24:27], v234, s[12:13]
	s_waitcnt vmcnt(15)
	v_readlane_b32 s20, v178, 44
	v_cvt_pk_f32_fp8_e32 v[216:217], v28
	v_cvt_pk_f32_fp8_sdwa v[218:219], v28 src0_sel:WORD_1
	v_cvt_pk_f32_fp8_e32 v[220:221], v29
	v_cvt_pk_f32_fp8_sdwa v[222:223], v29 src0_sel:WORD_1
	v_cvt_pk_f32_fp8_e32 v[224:225], v30
	v_cvt_pk_f32_fp8_sdwa v[226:227], v30 src0_sel:WORD_1
	v_cvt_pk_f32_fp8_e32 v[228:229], v31
	v_cvt_pk_f32_fp8_sdwa v[230:231], v31 src0_sel:WORD_1
	v_pk_fma_f32 v[80:81], s[26:27], v[216:217], v[80:81] op_sel_hi:[0,1,1]
	v_pk_fma_f32 v[82:83], s[26:27], v[218:219], v[82:83] op_sel_hi:[0,1,1]
	v_pk_fma_f32 v[84:85], s[26:27], v[220:221], v[84:85] op_sel_hi:[0,1,1]
	v_pk_fma_f32 v[86:87], s[26:27], v[222:223], v[86:87] op_sel_hi:[0,1,1]
	v_pk_fma_f32 v[88:89], s[26:27], v[224:225], v[88:89] op_sel_hi:[0,1,1]
	v_pk_fma_f32 v[90:91], s[26:27], v[226:227], v[90:91] op_sel_hi:[0,1,1]
	v_pk_fma_f32 v[92:93], s[26:27], v[228:229], v[92:93] op_sel_hi:[0,1,1]
	v_pk_fma_f32 v[94:95], s[26:27], v[230:231], v[94:95] op_sel_hi:[0,1,1]
	v_readlane_b32 s31, v180, 51
	s_lshl_b32 s31, s31, 10
	v_add_u32_e32 v235, s31, v208
	global_load_dwordx4 v[28:31], v235, s[12:13]
	s_waitcnt vmcnt(15)
	v_readlane_b32 s22, v182, 44
	v_cvt_pk_f32_fp8_e32 v[216:217], v32
	v_cvt_pk_f32_fp8_sdwa v[218:219], v32 src0_sel:WORD_1
	v_cvt_pk_f32_fp8_e32 v[220:221], v33
	v_cvt_pk_f32_fp8_sdwa v[222:223], v33 src0_sel:WORD_1
	v_cvt_pk_f32_fp8_e32 v[224:225], v34
	v_cvt_pk_f32_fp8_sdwa v[226:227], v34 src0_sel:WORD_1
	v_cvt_pk_f32_fp8_e32 v[228:229], v35
	v_cvt_pk_f32_fp8_sdwa v[230:231], v35 src0_sel:WORD_1
	v_pk_fma_f32 v[64:65], s[20:21], v[216:217], v[64:65] op_sel_hi:[0,1,1]
	v_pk_fma_f32 v[66:67], s[20:21], v[218:219], v[66:67] op_sel_hi:[0,1,1]
	v_pk_fma_f32 v[68:69], s[20:21], v[220:221], v[68:69] op_sel_hi:[0,1,1]
	v_pk_fma_f32 v[70:71], s[20:21], v[222:223], v[70:71] op_sel_hi:[0,1,1]
	v_pk_fma_f32 v[72:73], s[20:21], v[224:225], v[72:73] op_sel_hi:[0,1,1]
	v_pk_fma_f32 v[74:75], s[20:21], v[226:227], v[74:75] op_sel_hi:[0,1,1]
	v_pk_fma_f32 v[76:77], s[20:21], v[228:229], v[76:77] op_sel_hi:[0,1,1]
	v_pk_fma_f32 v[78:79], s[20:21], v[230:231], v[78:79] op_sel_hi:[0,1,1]
	v_readlane_b32 s28, v176, 52
	s_lshl_b32 s28, s28, 10
	v_add_u32_e32 v232, s28, v208
	global_load_dwordx4 v[32:35], v232, s[12:13]
	s_waitcnt vmcnt(15)
	v_readlane_b32 s24, v178, 45
	v_cvt_pk_f32_fp8_e32 v[216:217], v36
	v_cvt_pk_f32_fp8_sdwa v[218:219], v36 src0_sel:WORD_1
	v_cvt_pk_f32_fp8_e32 v[220:221], v37
	v_cvt_pk_f32_fp8_sdwa v[222:223], v37 src0_sel:WORD_1
	v_cvt_pk_f32_fp8_e32 v[224:225], v38
	v_cvt_pk_f32_fp8_sdwa v[226:227], v38 src0_sel:WORD_1
	v_cvt_pk_f32_fp8_e32 v[228:229], v39
	v_cvt_pk_f32_fp8_sdwa v[230:231], v39 src0_sel:WORD_1
	v_pk_fma_f32 v[80:81], s[22:23], v[216:217], v[80:81] op_sel_hi:[0,1,1]
	v_pk_fma_f32 v[82:83], s[22:23], v[218:219], v[82:83] op_sel_hi:[0,1,1]
	v_pk_fma_f32 v[84:85], s[22:23], v[220:221], v[84:85] op_sel_hi:[0,1,1]
	v_pk_fma_f32 v[86:87], s[22:23], v[222:223], v[86:87] op_sel_hi:[0,1,1]
	v_pk_fma_f32 v[88:89], s[22:23], v[224:225], v[88:89] op_sel_hi:[0,1,1]
	v_pk_fma_f32 v[90:91], s[22:23], v[226:227], v[90:91] op_sel_hi:[0,1,1]
	v_pk_fma_f32 v[92:93], s[22:23], v[228:229], v[92:93] op_sel_hi:[0,1,1]
	v_pk_fma_f32 v[94:95], s[22:23], v[230:231], v[94:95] op_sel_hi:[0,1,1]
	v_readlane_b32 s29, v180, 52
	s_lshl_b32 s29, s29, 10
	v_add_u32_e32 v233, s29, v208
	global_load_dwordx4 v[36:39], v233, s[12:13]
	s_waitcnt vmcnt(15)
	v_readlane_b32 s26, v182, 45
	v_cvt_pk_f32_fp8_e32 v[216:217], v40
	v_cvt_pk_f32_fp8_sdwa v[218:219], v40 src0_sel:WORD_1
	v_cvt_pk_f32_fp8_e32 v[220:221], v41
	v_cvt_pk_f32_fp8_sdwa v[222:223], v41 src0_sel:WORD_1
	v_cvt_pk_f32_fp8_e32 v[224:225], v42
	v_cvt_pk_f32_fp8_sdwa v[226:227], v42 src0_sel:WORD_1
	v_cvt_pk_f32_fp8_e32 v[228:229], v43
	v_cvt_pk_f32_fp8_sdwa v[230:231], v43 src0_sel:WORD_1
	v_pk_fma_f32 v[64:65], s[24:25], v[216:217], v[64:65] op_sel_hi:[0,1,1]
	v_pk_fma_f32 v[66:67], s[24:25], v[218:219], v[66:67] op_sel_hi:[0,1,1]
	v_pk_fma_f32 v[68:69], s[24:25], v[220:221], v[68:69] op_sel_hi:[0,1,1]
	v_pk_fma_f32 v[70:71], s[24:25], v[222:223], v[70:71] op_sel_hi:[0,1,1]
	v_pk_fma_f32 v[72:73], s[24:25], v[224:225], v[72:73] op_sel_hi:[0,1,1]
	v_pk_fma_f32 v[74:75], s[24:25], v[226:227], v[74:75] op_sel_hi:[0,1,1]
	v_pk_fma_f32 v[76:77], s[24:25], v[228:229], v[76:77] op_sel_hi:[0,1,1]
	v_pk_fma_f32 v[78:79], s[24:25], v[230:231], v[78:79] op_sel_hi:[0,1,1]
	v_readlane_b32 s30, v176, 53
	s_lshl_b32 s30, s30, 10
	v_add_u32_e32 v234, s30, v208
	global_load_dwordx4 v[40:43], v234, s[12:13]
	s_waitcnt vmcnt(15)
	v_readlane_b32 s20, v178, 46
	v_cvt_pk_f32_fp8_e32 v[216:217], v44
	v_cvt_pk_f32_fp8_sdwa v[218:219], v44 src0_sel:WORD_1
	v_cvt_pk_f32_fp8_e32 v[220:221], v45
	v_cvt_pk_f32_fp8_sdwa v[222:223], v45 src0_sel:WORD_1
	v_cvt_pk_f32_fp8_e32 v[224:225], v46
	v_cvt_pk_f32_fp8_sdwa v[226:227], v46 src0_sel:WORD_1
	v_cvt_pk_f32_fp8_e32 v[228:229], v47
	v_cvt_pk_f32_fp8_sdwa v[230:231], v47 src0_sel:WORD_1
	v_pk_fma_f32 v[80:81], s[26:27], v[216:217], v[80:81] op_sel_hi:[0,1,1]
	v_pk_fma_f32 v[82:83], s[26:27], v[218:219], v[82:83] op_sel_hi:[0,1,1]
	v_pk_fma_f32 v[84:85], s[26:27], v[220:221], v[84:85] op_sel_hi:[0,1,1]
	v_pk_fma_f32 v[86:87], s[26:27], v[222:223], v[86:87] op_sel_hi:[0,1,1]
	v_pk_fma_f32 v[88:89], s[26:27], v[224:225], v[88:89] op_sel_hi:[0,1,1]
	v_pk_fma_f32 v[90:91], s[26:27], v[226:227], v[90:91] op_sel_hi:[0,1,1]
	v_pk_fma_f32 v[92:93], s[26:27], v[228:229], v[92:93] op_sel_hi:[0,1,1]
	v_pk_fma_f32 v[94:95], s[26:27], v[230:231], v[94:95] op_sel_hi:[0,1,1]
	v_readlane_b32 s31, v180, 53
	s_lshl_b32 s31, s31, 10
	v_add_u32_e32 v235, s31, v208
	global_load_dwordx4 v[44:47], v235, s[12:13]
	s_waitcnt vmcnt(15)
	v_readlane_b32 s22, v182, 46
	v_cvt_pk_f32_fp8_e32 v[216:217], v48
	v_cvt_pk_f32_fp8_sdwa v[218:219], v48 src0_sel:WORD_1
	v_cvt_pk_f32_fp8_e32 v[220:221], v49
	v_cvt_pk_f32_fp8_sdwa v[222:223], v49 src0_sel:WORD_1
	v_cvt_pk_f32_fp8_e32 v[224:225], v50
	v_cvt_pk_f32_fp8_sdwa v[226:227], v50 src0_sel:WORD_1
	v_cvt_pk_f32_fp8_e32 v[228:229], v51
	v_cvt_pk_f32_fp8_sdwa v[230:231], v51 src0_sel:WORD_1
	v_pk_fma_f32 v[64:65], s[20:21], v[216:217], v[64:65] op_sel_hi:[0,1,1]
	v_pk_fma_f32 v[66:67], s[20:21], v[218:219], v[66:67] op_sel_hi:[0,1,1]
	v_pk_fma_f32 v[68:69], s[20:21], v[220:221], v[68:69] op_sel_hi:[0,1,1]
	v_pk_fma_f32 v[70:71], s[20:21], v[222:223], v[70:71] op_sel_hi:[0,1,1]
	v_pk_fma_f32 v[72:73], s[20:21], v[224:225], v[72:73] op_sel_hi:[0,1,1]
	v_pk_fma_f32 v[74:75], s[20:21], v[226:227], v[74:75] op_sel_hi:[0,1,1]
	v_pk_fma_f32 v[76:77], s[20:21], v[228:229], v[76:77] op_sel_hi:[0,1,1]
	v_pk_fma_f32 v[78:79], s[20:21], v[230:231], v[78:79] op_sel_hi:[0,1,1]
	v_readlane_b32 s28, v176, 54
	s_lshl_b32 s28, s28, 10
	v_add_u32_e32 v232, s28, v208
	global_load_dwordx4 v[48:51], v232, s[12:13]
	s_waitcnt vmcnt(15)
	v_readlane_b32 s24, v178, 47
	v_cvt_pk_f32_fp8_e32 v[216:217], v52
	v_cvt_pk_f32_fp8_sdwa v[218:219], v52 src0_sel:WORD_1
	v_cvt_pk_f32_fp8_e32 v[220:221], v53
	v_cvt_pk_f32_fp8_sdwa v[222:223], v53 src0_sel:WORD_1
	v_cvt_pk_f32_fp8_e32 v[224:225], v54
	v_cvt_pk_f32_fp8_sdwa v[226:227], v54 src0_sel:WORD_1
	v_cvt_pk_f32_fp8_e32 v[228:229], v55
	v_cvt_pk_f32_fp8_sdwa v[230:231], v55 src0_sel:WORD_1
	v_pk_fma_f32 v[80:81], s[22:23], v[216:217], v[80:81] op_sel_hi:[0,1,1]
	v_pk_fma_f32 v[82:83], s[22:23], v[218:219], v[82:83] op_sel_hi:[0,1,1]
	v_pk_fma_f32 v[84:85], s[22:23], v[220:221], v[84:85] op_sel_hi:[0,1,1]
	v_pk_fma_f32 v[86:87], s[22:23], v[222:223], v[86:87] op_sel_hi:[0,1,1]
	v_pk_fma_f32 v[88:89], s[22:23], v[224:225], v[88:89] op_sel_hi:[0,1,1]
	v_pk_fma_f32 v[90:91], s[22:23], v[226:227], v[90:91] op_sel_hi:[0,1,1]
	v_pk_fma_f32 v[92:93], s[22:23], v[228:229], v[92:93] op_sel_hi:[0,1,1]
	v_pk_fma_f32 v[94:95], s[22:23], v[230:231], v[94:95] op_sel_hi:[0,1,1]
	v_readlane_b32 s29, v180, 54
	s_lshl_b32 s29, s29, 10
	v_add_u32_e32 v233, s29, v208
	global_load_dwordx4 v[52:55], v233, s[12:13]
	s_waitcnt vmcnt(15)
	v_readlane_b32 s26, v182, 47
	v_cvt_pk_f32_fp8_e32 v[216:217], v56
	v_cvt_pk_f32_fp8_sdwa v[218:219], v56 src0_sel:WORD_1
	v_cvt_pk_f32_fp8_e32 v[220:221], v57
	v_cvt_pk_f32_fp8_sdwa v[222:223], v57 src0_sel:WORD_1
	v_cvt_pk_f32_fp8_e32 v[224:225], v58
	v_cvt_pk_f32_fp8_sdwa v[226:227], v58 src0_sel:WORD_1
	v_cvt_pk_f32_fp8_e32 v[228:229], v59
	v_cvt_pk_f32_fp8_sdwa v[230:231], v59 src0_sel:WORD_1
	v_pk_fma_f32 v[64:65], s[24:25], v[216:217], v[64:65] op_sel_hi:[0,1,1]
	v_pk_fma_f32 v[66:67], s[24:25], v[218:219], v[66:67] op_sel_hi:[0,1,1]
	v_pk_fma_f32 v[68:69], s[24:25], v[220:221], v[68:69] op_sel_hi:[0,1,1]
	v_pk_fma_f32 v[70:71], s[24:25], v[222:223], v[70:71] op_sel_hi:[0,1,1]
	v_pk_fma_f32 v[72:73], s[24:25], v[224:225], v[72:73] op_sel_hi:[0,1,1]
	v_pk_fma_f32 v[74:75], s[24:25], v[226:227], v[74:75] op_sel_hi:[0,1,1]
	v_pk_fma_f32 v[76:77], s[24:25], v[228:229], v[76:77] op_sel_hi:[0,1,1]
	v_pk_fma_f32 v[78:79], s[24:25], v[230:231], v[78:79] op_sel_hi:[0,1,1]
	v_readlane_b32 s30, v176, 55
	s_lshl_b32 s30, s30, 10
	v_add_u32_e32 v234, s30, v208
	global_load_dwordx4 v[56:59], v234, s[12:13]
	s_waitcnt vmcnt(15)
	v_readlane_b32 s20, v178, 48
	v_cvt_pk_f32_fp8_e32 v[216:217], v60
	v_cvt_pk_f32_fp8_sdwa v[218:219], v60 src0_sel:WORD_1
	v_cvt_pk_f32_fp8_e32 v[220:221], v61
	v_cvt_pk_f32_fp8_sdwa v[222:223], v61 src0_sel:WORD_1
	v_cvt_pk_f32_fp8_e32 v[224:225], v62
	v_cvt_pk_f32_fp8_sdwa v[226:227], v62 src0_sel:WORD_1
	v_cvt_pk_f32_fp8_e32 v[228:229], v63
	v_cvt_pk_f32_fp8_sdwa v[230:231], v63 src0_sel:WORD_1
	v_pk_fma_f32 v[80:81], s[26:27], v[216:217], v[80:81] op_sel_hi:[0,1,1]
	v_pk_fma_f32 v[82:83], s[26:27], v[218:219], v[82:83] op_sel_hi:[0,1,1]
	v_pk_fma_f32 v[84:85], s[26:27], v[220:221], v[84:85] op_sel_hi:[0,1,1]
	v_pk_fma_f32 v[86:87], s[26:27], v[222:223], v[86:87] op_sel_hi:[0,1,1]
	v_pk_fma_f32 v[88:89], s[26:27], v[224:225], v[88:89] op_sel_hi:[0,1,1]
	v_pk_fma_f32 v[90:91], s[26:27], v[226:227], v[90:91] op_sel_hi:[0,1,1]
	v_pk_fma_f32 v[92:93], s[26:27], v[228:229], v[92:93] op_sel_hi:[0,1,1]
	v_pk_fma_f32 v[94:95], s[26:27], v[230:231], v[94:95] op_sel_hi:[0,1,1]
	v_readlane_b32 s31, v180, 55
	s_lshl_b32 s31, s31, 10
	v_add_u32_e32 v235, s31, v208
	global_load_dwordx4 v[60:63], v235, s[12:13]
	s_waitcnt vmcnt(15)
	v_readlane_b32 s22, v182, 48
	v_cvt_pk_f32_fp8_e32 v[216:217], v0
	v_cvt_pk_f32_fp8_sdwa v[218:219], v0 src0_sel:WORD_1
	v_cvt_pk_f32_fp8_e32 v[220:221], v1
	v_cvt_pk_f32_fp8_sdwa v[222:223], v1 src0_sel:WORD_1
	v_cvt_pk_f32_fp8_e32 v[224:225], v2
	v_cvt_pk_f32_fp8_sdwa v[226:227], v2 src0_sel:WORD_1
	v_cvt_pk_f32_fp8_e32 v[228:229], v3
	v_cvt_pk_f32_fp8_sdwa v[230:231], v3 src0_sel:WORD_1
	v_pk_fma_f32 v[64:65], s[20:21], v[216:217], v[64:65] op_sel_hi:[0,1,1]
	v_pk_fma_f32 v[66:67], s[20:21], v[218:219], v[66:67] op_sel_hi:[0,1,1]
	v_pk_fma_f32 v[68:69], s[20:21], v[220:221], v[68:69] op_sel_hi:[0,1,1]
	v_pk_fma_f32 v[70:71], s[20:21], v[222:223], v[70:71] op_sel_hi:[0,1,1]
	v_pk_fma_f32 v[72:73], s[20:21], v[224:225], v[72:73] op_sel_hi:[0,1,1]
	v_pk_fma_f32 v[74:75], s[20:21], v[226:227], v[74:75] op_sel_hi:[0,1,1]
	v_pk_fma_f32 v[76:77], s[20:21], v[228:229], v[76:77] op_sel_hi:[0,1,1]
	v_pk_fma_f32 v[78:79], s[20:21], v[230:231], v[78:79] op_sel_hi:[0,1,1]
	v_readlane_b32 s28, v176, 56
	s_lshl_b32 s28, s28, 10
	v_add_u32_e32 v232, s28, v208
	global_load_dwordx4 v[0:3], v232, s[12:13]
	s_waitcnt vmcnt(15)
	v_readlane_b32 s24, v178, 49
	v_cvt_pk_f32_fp8_e32 v[216:217], v4
	v_cvt_pk_f32_fp8_sdwa v[218:219], v4 src0_sel:WORD_1
	v_cvt_pk_f32_fp8_e32 v[220:221], v5
	v_cvt_pk_f32_fp8_sdwa v[222:223], v5 src0_sel:WORD_1
	v_cvt_pk_f32_fp8_e32 v[224:225], v6
	v_cvt_pk_f32_fp8_sdwa v[226:227], v6 src0_sel:WORD_1
	v_cvt_pk_f32_fp8_e32 v[228:229], v7
	v_cvt_pk_f32_fp8_sdwa v[230:231], v7 src0_sel:WORD_1
	v_pk_fma_f32 v[80:81], s[22:23], v[216:217], v[80:81] op_sel_hi:[0,1,1]
	v_pk_fma_f32 v[82:83], s[22:23], v[218:219], v[82:83] op_sel_hi:[0,1,1]
	v_pk_fma_f32 v[84:85], s[22:23], v[220:221], v[84:85] op_sel_hi:[0,1,1]
	v_pk_fma_f32 v[86:87], s[22:23], v[222:223], v[86:87] op_sel_hi:[0,1,1]
	v_pk_fma_f32 v[88:89], s[22:23], v[224:225], v[88:89] op_sel_hi:[0,1,1]
	v_pk_fma_f32 v[90:91], s[22:23], v[226:227], v[90:91] op_sel_hi:[0,1,1]
	v_pk_fma_f32 v[92:93], s[22:23], v[228:229], v[92:93] op_sel_hi:[0,1,1]
	v_pk_fma_f32 v[94:95], s[22:23], v[230:231], v[94:95] op_sel_hi:[0,1,1]
	v_readlane_b32 s29, v180, 56
	s_lshl_b32 s29, s29, 10
	v_add_u32_e32 v233, s29, v208
	global_load_dwordx4 v[4:7], v233, s[12:13]
	s_waitcnt vmcnt(15)
	v_readlane_b32 s26, v182, 49
	v_cvt_pk_f32_fp8_e32 v[216:217], v8
	v_cvt_pk_f32_fp8_sdwa v[218:219], v8 src0_sel:WORD_1
	v_cvt_pk_f32_fp8_e32 v[220:221], v9
	v_cvt_pk_f32_fp8_sdwa v[222:223], v9 src0_sel:WORD_1
	v_cvt_pk_f32_fp8_e32 v[224:225], v10
	v_cvt_pk_f32_fp8_sdwa v[226:227], v10 src0_sel:WORD_1
	v_cvt_pk_f32_fp8_e32 v[228:229], v11
	v_cvt_pk_f32_fp8_sdwa v[230:231], v11 src0_sel:WORD_1
	v_pk_fma_f32 v[64:65], s[24:25], v[216:217], v[64:65] op_sel_hi:[0,1,1]
	v_pk_fma_f32 v[66:67], s[24:25], v[218:219], v[66:67] op_sel_hi:[0,1,1]
	v_pk_fma_f32 v[68:69], s[24:25], v[220:221], v[68:69] op_sel_hi:[0,1,1]
	v_pk_fma_f32 v[70:71], s[24:25], v[222:223], v[70:71] op_sel_hi:[0,1,1]
	v_pk_fma_f32 v[72:73], s[24:25], v[224:225], v[72:73] op_sel_hi:[0,1,1]
	v_pk_fma_f32 v[74:75], s[24:25], v[226:227], v[74:75] op_sel_hi:[0,1,1]
	v_pk_fma_f32 v[76:77], s[24:25], v[228:229], v[76:77] op_sel_hi:[0,1,1]
	v_pk_fma_f32 v[78:79], s[24:25], v[230:231], v[78:79] op_sel_hi:[0,1,1]
	v_readlane_b32 s30, v176, 57
	s_lshl_b32 s30, s30, 10
	v_add_u32_e32 v234, s30, v208
	global_load_dwordx4 v[8:11], v234, s[12:13]
	s_waitcnt vmcnt(15)
	v_readlane_b32 s20, v178, 50
	v_cvt_pk_f32_fp8_e32 v[216:217], v12
	v_cvt_pk_f32_fp8_sdwa v[218:219], v12 src0_sel:WORD_1
	v_cvt_pk_f32_fp8_e32 v[220:221], v13
	v_cvt_pk_f32_fp8_sdwa v[222:223], v13 src0_sel:WORD_1
	v_cvt_pk_f32_fp8_e32 v[224:225], v14
	v_cvt_pk_f32_fp8_sdwa v[226:227], v14 src0_sel:WORD_1
	v_cvt_pk_f32_fp8_e32 v[228:229], v15
	v_cvt_pk_f32_fp8_sdwa v[230:231], v15 src0_sel:WORD_1
	v_pk_fma_f32 v[80:81], s[26:27], v[216:217], v[80:81] op_sel_hi:[0,1,1]
	v_pk_fma_f32 v[82:83], s[26:27], v[218:219], v[82:83] op_sel_hi:[0,1,1]
	v_pk_fma_f32 v[84:85], s[26:27], v[220:221], v[84:85] op_sel_hi:[0,1,1]
	v_pk_fma_f32 v[86:87], s[26:27], v[222:223], v[86:87] op_sel_hi:[0,1,1]
	v_pk_fma_f32 v[88:89], s[26:27], v[224:225], v[88:89] op_sel_hi:[0,1,1]
	v_pk_fma_f32 v[90:91], s[26:27], v[226:227], v[90:91] op_sel_hi:[0,1,1]
	v_pk_fma_f32 v[92:93], s[26:27], v[228:229], v[92:93] op_sel_hi:[0,1,1]
	v_pk_fma_f32 v[94:95], s[26:27], v[230:231], v[94:95] op_sel_hi:[0,1,1]
	v_readlane_b32 s31, v180, 57
	s_lshl_b32 s31, s31, 10
	v_add_u32_e32 v235, s31, v208
	global_load_dwordx4 v[12:15], v235, s[12:13]
	s_waitcnt vmcnt(15)
	v_readlane_b32 s22, v182, 50
	v_cvt_pk_f32_fp8_e32 v[216:217], v16
	v_cvt_pk_f32_fp8_sdwa v[218:219], v16 src0_sel:WORD_1
	v_cvt_pk_f32_fp8_e32 v[220:221], v17
	v_cvt_pk_f32_fp8_sdwa v[222:223], v17 src0_sel:WORD_1
	v_cvt_pk_f32_fp8_e32 v[224:225], v18
	v_cvt_pk_f32_fp8_sdwa v[226:227], v18 src0_sel:WORD_1
	v_cvt_pk_f32_fp8_e32 v[228:229], v19
	v_cvt_pk_f32_fp8_sdwa v[230:231], v19 src0_sel:WORD_1
	v_pk_fma_f32 v[64:65], s[20:21], v[216:217], v[64:65] op_sel_hi:[0,1,1]
	v_pk_fma_f32 v[66:67], s[20:21], v[218:219], v[66:67] op_sel_hi:[0,1,1]
	v_pk_fma_f32 v[68:69], s[20:21], v[220:221], v[68:69] op_sel_hi:[0,1,1]
	v_pk_fma_f32 v[70:71], s[20:21], v[222:223], v[70:71] op_sel_hi:[0,1,1]
	v_pk_fma_f32 v[72:73], s[20:21], v[224:225], v[72:73] op_sel_hi:[0,1,1]
	v_pk_fma_f32 v[74:75], s[20:21], v[226:227], v[74:75] op_sel_hi:[0,1,1]
	v_pk_fma_f32 v[76:77], s[20:21], v[228:229], v[76:77] op_sel_hi:[0,1,1]
	v_pk_fma_f32 v[78:79], s[20:21], v[230:231], v[78:79] op_sel_hi:[0,1,1]
	v_readlane_b32 s28, v176, 58
	s_lshl_b32 s28, s28, 10
	v_add_u32_e32 v232, s28, v208
	global_load_dwordx4 v[16:19], v232, s[12:13]
	s_waitcnt vmcnt(15)
	v_readlane_b32 s24, v178, 51
	v_cvt_pk_f32_fp8_e32 v[216:217], v20
	v_cvt_pk_f32_fp8_sdwa v[218:219], v20 src0_sel:WORD_1
	v_cvt_pk_f32_fp8_e32 v[220:221], v21
	v_cvt_pk_f32_fp8_sdwa v[222:223], v21 src0_sel:WORD_1
	v_cvt_pk_f32_fp8_e32 v[224:225], v22
	v_cvt_pk_f32_fp8_sdwa v[226:227], v22 src0_sel:WORD_1
	v_cvt_pk_f32_fp8_e32 v[228:229], v23
	v_cvt_pk_f32_fp8_sdwa v[230:231], v23 src0_sel:WORD_1
	v_pk_fma_f32 v[80:81], s[22:23], v[216:217], v[80:81] op_sel_hi:[0,1,1]
	v_pk_fma_f32 v[82:83], s[22:23], v[218:219], v[82:83] op_sel_hi:[0,1,1]
	v_pk_fma_f32 v[84:85], s[22:23], v[220:221], v[84:85] op_sel_hi:[0,1,1]
	v_pk_fma_f32 v[86:87], s[22:23], v[222:223], v[86:87] op_sel_hi:[0,1,1]
	v_pk_fma_f32 v[88:89], s[22:23], v[224:225], v[88:89] op_sel_hi:[0,1,1]
	v_pk_fma_f32 v[90:91], s[22:23], v[226:227], v[90:91] op_sel_hi:[0,1,1]
	v_pk_fma_f32 v[92:93], s[22:23], v[228:229], v[92:93] op_sel_hi:[0,1,1]
	v_pk_fma_f32 v[94:95], s[22:23], v[230:231], v[94:95] op_sel_hi:[0,1,1]
	v_readlane_b32 s29, v180, 58
	s_lshl_b32 s29, s29, 10
	v_add_u32_e32 v233, s29, v208
	global_load_dwordx4 v[20:23], v233, s[12:13]
	s_waitcnt vmcnt(15)
	v_readlane_b32 s26, v182, 51
	v_cvt_pk_f32_fp8_e32 v[216:217], v24
	v_cvt_pk_f32_fp8_sdwa v[218:219], v24 src0_sel:WORD_1
	v_cvt_pk_f32_fp8_e32 v[220:221], v25
	v_cvt_pk_f32_fp8_sdwa v[222:223], v25 src0_sel:WORD_1
	v_cvt_pk_f32_fp8_e32 v[224:225], v26
	v_cvt_pk_f32_fp8_sdwa v[226:227], v26 src0_sel:WORD_1
	v_cvt_pk_f32_fp8_e32 v[228:229], v27
	v_cvt_pk_f32_fp8_sdwa v[230:231], v27 src0_sel:WORD_1
	v_pk_fma_f32 v[64:65], s[24:25], v[216:217], v[64:65] op_sel_hi:[0,1,1]
	v_pk_fma_f32 v[66:67], s[24:25], v[218:219], v[66:67] op_sel_hi:[0,1,1]
	v_pk_fma_f32 v[68:69], s[24:25], v[220:221], v[68:69] op_sel_hi:[0,1,1]
	v_pk_fma_f32 v[70:71], s[24:25], v[222:223], v[70:71] op_sel_hi:[0,1,1]
	v_pk_fma_f32 v[72:73], s[24:25], v[224:225], v[72:73] op_sel_hi:[0,1,1]
	v_pk_fma_f32 v[74:75], s[24:25], v[226:227], v[74:75] op_sel_hi:[0,1,1]
	v_pk_fma_f32 v[76:77], s[24:25], v[228:229], v[76:77] op_sel_hi:[0,1,1]
	v_pk_fma_f32 v[78:79], s[24:25], v[230:231], v[78:79] op_sel_hi:[0,1,1]
	v_readlane_b32 s30, v176, 59
	s_lshl_b32 s30, s30, 10
	v_add_u32_e32 v234, s30, v208
	global_load_dwordx4 v[24:27], v234, s[12:13]
	s_waitcnt vmcnt(15)
	v_readlane_b32 s20, v178, 52
	v_cvt_pk_f32_fp8_e32 v[216:217], v28
	v_cvt_pk_f32_fp8_sdwa v[218:219], v28 src0_sel:WORD_1
	v_cvt_pk_f32_fp8_e32 v[220:221], v29
	v_cvt_pk_f32_fp8_sdwa v[222:223], v29 src0_sel:WORD_1
	v_cvt_pk_f32_fp8_e32 v[224:225], v30
	v_cvt_pk_f32_fp8_sdwa v[226:227], v30 src0_sel:WORD_1
	v_cvt_pk_f32_fp8_e32 v[228:229], v31
	v_cvt_pk_f32_fp8_sdwa v[230:231], v31 src0_sel:WORD_1
	v_pk_fma_f32 v[80:81], s[26:27], v[216:217], v[80:81] op_sel_hi:[0,1,1]
	v_pk_fma_f32 v[82:83], s[26:27], v[218:219], v[82:83] op_sel_hi:[0,1,1]
	v_pk_fma_f32 v[84:85], s[26:27], v[220:221], v[84:85] op_sel_hi:[0,1,1]
	v_pk_fma_f32 v[86:87], s[26:27], v[222:223], v[86:87] op_sel_hi:[0,1,1]
	v_pk_fma_f32 v[88:89], s[26:27], v[224:225], v[88:89] op_sel_hi:[0,1,1]
	v_pk_fma_f32 v[90:91], s[26:27], v[226:227], v[90:91] op_sel_hi:[0,1,1]
	v_pk_fma_f32 v[92:93], s[26:27], v[228:229], v[92:93] op_sel_hi:[0,1,1]
	v_pk_fma_f32 v[94:95], s[26:27], v[230:231], v[94:95] op_sel_hi:[0,1,1]
	v_readlane_b32 s31, v180, 59
	s_lshl_b32 s31, s31, 10
	v_add_u32_e32 v235, s31, v208
	global_load_dwordx4 v[28:31], v235, s[12:13]
	s_waitcnt vmcnt(15)
	v_readlane_b32 s22, v182, 52
	v_cvt_pk_f32_fp8_e32 v[216:217], v32
	v_cvt_pk_f32_fp8_sdwa v[218:219], v32 src0_sel:WORD_1
	v_cvt_pk_f32_fp8_e32 v[220:221], v33
	v_cvt_pk_f32_fp8_sdwa v[222:223], v33 src0_sel:WORD_1
	v_cvt_pk_f32_fp8_e32 v[224:225], v34
	v_cvt_pk_f32_fp8_sdwa v[226:227], v34 src0_sel:WORD_1
	v_cvt_pk_f32_fp8_e32 v[228:229], v35
	v_cvt_pk_f32_fp8_sdwa v[230:231], v35 src0_sel:WORD_1
	v_pk_fma_f32 v[64:65], s[20:21], v[216:217], v[64:65] op_sel_hi:[0,1,1]
	v_pk_fma_f32 v[66:67], s[20:21], v[218:219], v[66:67] op_sel_hi:[0,1,1]
	v_pk_fma_f32 v[68:69], s[20:21], v[220:221], v[68:69] op_sel_hi:[0,1,1]
	v_pk_fma_f32 v[70:71], s[20:21], v[222:223], v[70:71] op_sel_hi:[0,1,1]
	v_pk_fma_f32 v[72:73], s[20:21], v[224:225], v[72:73] op_sel_hi:[0,1,1]
	v_pk_fma_f32 v[74:75], s[20:21], v[226:227], v[74:75] op_sel_hi:[0,1,1]
	v_pk_fma_f32 v[76:77], s[20:21], v[228:229], v[76:77] op_sel_hi:[0,1,1]
	v_pk_fma_f32 v[78:79], s[20:21], v[230:231], v[78:79] op_sel_hi:[0,1,1]
	v_readlane_b32 s28, v176, 60
	s_lshl_b32 s28, s28, 10
	v_add_u32_e32 v232, s28, v208
	global_load_dwordx4 v[32:35], v232, s[12:13]
	s_waitcnt vmcnt(15)
	v_readlane_b32 s24, v178, 53
	v_cvt_pk_f32_fp8_e32 v[216:217], v36
	v_cvt_pk_f32_fp8_sdwa v[218:219], v36 src0_sel:WORD_1
	v_cvt_pk_f32_fp8_e32 v[220:221], v37
	v_cvt_pk_f32_fp8_sdwa v[222:223], v37 src0_sel:WORD_1
	v_cvt_pk_f32_fp8_e32 v[224:225], v38
	v_cvt_pk_f32_fp8_sdwa v[226:227], v38 src0_sel:WORD_1
	v_cvt_pk_f32_fp8_e32 v[228:229], v39
	v_cvt_pk_f32_fp8_sdwa v[230:231], v39 src0_sel:WORD_1
	v_pk_fma_f32 v[80:81], s[22:23], v[216:217], v[80:81] op_sel_hi:[0,1,1]
	v_pk_fma_f32 v[82:83], s[22:23], v[218:219], v[82:83] op_sel_hi:[0,1,1]
	v_pk_fma_f32 v[84:85], s[22:23], v[220:221], v[84:85] op_sel_hi:[0,1,1]
	v_pk_fma_f32 v[86:87], s[22:23], v[222:223], v[86:87] op_sel_hi:[0,1,1]
	v_pk_fma_f32 v[88:89], s[22:23], v[224:225], v[88:89] op_sel_hi:[0,1,1]
	v_pk_fma_f32 v[90:91], s[22:23], v[226:227], v[90:91] op_sel_hi:[0,1,1]
	v_pk_fma_f32 v[92:93], s[22:23], v[228:229], v[92:93] op_sel_hi:[0,1,1]
	v_pk_fma_f32 v[94:95], s[22:23], v[230:231], v[94:95] op_sel_hi:[0,1,1]
	v_readlane_b32 s29, v180, 60
	s_lshl_b32 s29, s29, 10
	v_add_u32_e32 v233, s29, v208
	global_load_dwordx4 v[36:39], v233, s[12:13]
	s_waitcnt vmcnt(15)
	v_readlane_b32 s26, v182, 53
	v_cvt_pk_f32_fp8_e32 v[216:217], v40
	v_cvt_pk_f32_fp8_sdwa v[218:219], v40 src0_sel:WORD_1
	v_cvt_pk_f32_fp8_e32 v[220:221], v41
	v_cvt_pk_f32_fp8_sdwa v[222:223], v41 src0_sel:WORD_1
	v_cvt_pk_f32_fp8_e32 v[224:225], v42
	v_cvt_pk_f32_fp8_sdwa v[226:227], v42 src0_sel:WORD_1
	v_cvt_pk_f32_fp8_e32 v[228:229], v43
	v_cvt_pk_f32_fp8_sdwa v[230:231], v43 src0_sel:WORD_1
	v_pk_fma_f32 v[64:65], s[24:25], v[216:217], v[64:65] op_sel_hi:[0,1,1]
	v_pk_fma_f32 v[66:67], s[24:25], v[218:219], v[66:67] op_sel_hi:[0,1,1]
	v_pk_fma_f32 v[68:69], s[24:25], v[220:221], v[68:69] op_sel_hi:[0,1,1]
	v_pk_fma_f32 v[70:71], s[24:25], v[222:223], v[70:71] op_sel_hi:[0,1,1]
	v_pk_fma_f32 v[72:73], s[24:25], v[224:225], v[72:73] op_sel_hi:[0,1,1]
	v_pk_fma_f32 v[74:75], s[24:25], v[226:227], v[74:75] op_sel_hi:[0,1,1]
	v_pk_fma_f32 v[76:77], s[24:25], v[228:229], v[76:77] op_sel_hi:[0,1,1]
	v_pk_fma_f32 v[78:79], s[24:25], v[230:231], v[78:79] op_sel_hi:[0,1,1]
	v_readlane_b32 s30, v176, 61
	s_lshl_b32 s30, s30, 10
	v_add_u32_e32 v234, s30, v208
	global_load_dwordx4 v[40:43], v234, s[12:13]
	s_waitcnt vmcnt(15)
	v_readlane_b32 s20, v178, 54
	v_cvt_pk_f32_fp8_e32 v[216:217], v44
	v_cvt_pk_f32_fp8_sdwa v[218:219], v44 src0_sel:WORD_1
	v_cvt_pk_f32_fp8_e32 v[220:221], v45
	v_cvt_pk_f32_fp8_sdwa v[222:223], v45 src0_sel:WORD_1
	v_cvt_pk_f32_fp8_e32 v[224:225], v46
	v_cvt_pk_f32_fp8_sdwa v[226:227], v46 src0_sel:WORD_1
	v_cvt_pk_f32_fp8_e32 v[228:229], v47
	v_cvt_pk_f32_fp8_sdwa v[230:231], v47 src0_sel:WORD_1
	v_pk_fma_f32 v[80:81], s[26:27], v[216:217], v[80:81] op_sel_hi:[0,1,1]
	v_pk_fma_f32 v[82:83], s[26:27], v[218:219], v[82:83] op_sel_hi:[0,1,1]
	v_pk_fma_f32 v[84:85], s[26:27], v[220:221], v[84:85] op_sel_hi:[0,1,1]
	v_pk_fma_f32 v[86:87], s[26:27], v[222:223], v[86:87] op_sel_hi:[0,1,1]
	v_pk_fma_f32 v[88:89], s[26:27], v[224:225], v[88:89] op_sel_hi:[0,1,1]
	v_pk_fma_f32 v[90:91], s[26:27], v[226:227], v[90:91] op_sel_hi:[0,1,1]
	v_pk_fma_f32 v[92:93], s[26:27], v[228:229], v[92:93] op_sel_hi:[0,1,1]
	v_pk_fma_f32 v[94:95], s[26:27], v[230:231], v[94:95] op_sel_hi:[0,1,1]
	v_readlane_b32 s31, v180, 61
	s_lshl_b32 s31, s31, 10
	v_add_u32_e32 v235, s31, v208
	global_load_dwordx4 v[44:47], v235, s[12:13]
	s_waitcnt vmcnt(15)
	v_readlane_b32 s22, v182, 54
	v_cvt_pk_f32_fp8_e32 v[216:217], v48
	v_cvt_pk_f32_fp8_sdwa v[218:219], v48 src0_sel:WORD_1
	v_cvt_pk_f32_fp8_e32 v[220:221], v49
	v_cvt_pk_f32_fp8_sdwa v[222:223], v49 src0_sel:WORD_1
	v_cvt_pk_f32_fp8_e32 v[224:225], v50
	v_cvt_pk_f32_fp8_sdwa v[226:227], v50 src0_sel:WORD_1
	v_cvt_pk_f32_fp8_e32 v[228:229], v51
	v_cvt_pk_f32_fp8_sdwa v[230:231], v51 src0_sel:WORD_1
	v_pk_fma_f32 v[64:65], s[20:21], v[216:217], v[64:65] op_sel_hi:[0,1,1]
	v_pk_fma_f32 v[66:67], s[20:21], v[218:219], v[66:67] op_sel_hi:[0,1,1]
	v_pk_fma_f32 v[68:69], s[20:21], v[220:221], v[68:69] op_sel_hi:[0,1,1]
	v_pk_fma_f32 v[70:71], s[20:21], v[222:223], v[70:71] op_sel_hi:[0,1,1]
	v_pk_fma_f32 v[72:73], s[20:21], v[224:225], v[72:73] op_sel_hi:[0,1,1]
	v_pk_fma_f32 v[74:75], s[20:21], v[226:227], v[74:75] op_sel_hi:[0,1,1]
	v_pk_fma_f32 v[76:77], s[20:21], v[228:229], v[76:77] op_sel_hi:[0,1,1]
	v_pk_fma_f32 v[78:79], s[20:21], v[230:231], v[78:79] op_sel_hi:[0,1,1]
	v_readlane_b32 s28, v176, 62
	s_lshl_b32 s28, s28, 10
	v_add_u32_e32 v232, s28, v208
	global_load_dwordx4 v[48:51], v232, s[12:13]
	s_waitcnt vmcnt(15)
	v_readlane_b32 s24, v178, 55
	v_cvt_pk_f32_fp8_e32 v[216:217], v52
	v_cvt_pk_f32_fp8_sdwa v[218:219], v52 src0_sel:WORD_1
	v_cvt_pk_f32_fp8_e32 v[220:221], v53
	v_cvt_pk_f32_fp8_sdwa v[222:223], v53 src0_sel:WORD_1
	v_cvt_pk_f32_fp8_e32 v[224:225], v54
	v_cvt_pk_f32_fp8_sdwa v[226:227], v54 src0_sel:WORD_1
	v_cvt_pk_f32_fp8_e32 v[228:229], v55
	v_cvt_pk_f32_fp8_sdwa v[230:231], v55 src0_sel:WORD_1
	v_pk_fma_f32 v[80:81], s[22:23], v[216:217], v[80:81] op_sel_hi:[0,1,1]
	v_pk_fma_f32 v[82:83], s[22:23], v[218:219], v[82:83] op_sel_hi:[0,1,1]
	v_pk_fma_f32 v[84:85], s[22:23], v[220:221], v[84:85] op_sel_hi:[0,1,1]
	v_pk_fma_f32 v[86:87], s[22:23], v[222:223], v[86:87] op_sel_hi:[0,1,1]
	v_pk_fma_f32 v[88:89], s[22:23], v[224:225], v[88:89] op_sel_hi:[0,1,1]
	v_pk_fma_f32 v[90:91], s[22:23], v[226:227], v[90:91] op_sel_hi:[0,1,1]
	v_pk_fma_f32 v[92:93], s[22:23], v[228:229], v[92:93] op_sel_hi:[0,1,1]
	v_pk_fma_f32 v[94:95], s[22:23], v[230:231], v[94:95] op_sel_hi:[0,1,1]
	v_readlane_b32 s29, v180, 62
	s_lshl_b32 s29, s29, 10
	v_add_u32_e32 v233, s29, v208
	global_load_dwordx4 v[52:55], v233, s[12:13]
	s_waitcnt vmcnt(15)
	v_readlane_b32 s26, v182, 55
	v_cvt_pk_f32_fp8_e32 v[216:217], v56
	v_cvt_pk_f32_fp8_sdwa v[218:219], v56 src0_sel:WORD_1
	v_cvt_pk_f32_fp8_e32 v[220:221], v57
	v_cvt_pk_f32_fp8_sdwa v[222:223], v57 src0_sel:WORD_1
	v_cvt_pk_f32_fp8_e32 v[224:225], v58
	v_cvt_pk_f32_fp8_sdwa v[226:227], v58 src0_sel:WORD_1
	v_cvt_pk_f32_fp8_e32 v[228:229], v59
	v_cvt_pk_f32_fp8_sdwa v[230:231], v59 src0_sel:WORD_1
	v_pk_fma_f32 v[64:65], s[24:25], v[216:217], v[64:65] op_sel_hi:[0,1,1]
	v_pk_fma_f32 v[66:67], s[24:25], v[218:219], v[66:67] op_sel_hi:[0,1,1]
	v_pk_fma_f32 v[68:69], s[24:25], v[220:221], v[68:69] op_sel_hi:[0,1,1]
	v_pk_fma_f32 v[70:71], s[24:25], v[222:223], v[70:71] op_sel_hi:[0,1,1]
	v_pk_fma_f32 v[72:73], s[24:25], v[224:225], v[72:73] op_sel_hi:[0,1,1]
	v_pk_fma_f32 v[74:75], s[24:25], v[226:227], v[74:75] op_sel_hi:[0,1,1]
	v_pk_fma_f32 v[76:77], s[24:25], v[228:229], v[76:77] op_sel_hi:[0,1,1]
	v_pk_fma_f32 v[78:79], s[24:25], v[230:231], v[78:79] op_sel_hi:[0,1,1]
	v_readlane_b32 s30, v176, 63
	s_lshl_b32 s30, s30, 10
	v_add_u32_e32 v234, s30, v208
	global_load_dwordx4 v[56:59], v234, s[12:13]
	s_waitcnt vmcnt(15)
	v_readlane_b32 s20, v178, 56
	v_cvt_pk_f32_fp8_e32 v[216:217], v60
	v_cvt_pk_f32_fp8_sdwa v[218:219], v60 src0_sel:WORD_1
	v_cvt_pk_f32_fp8_e32 v[220:221], v61
	v_cvt_pk_f32_fp8_sdwa v[222:223], v61 src0_sel:WORD_1
	v_cvt_pk_f32_fp8_e32 v[224:225], v62
	v_cvt_pk_f32_fp8_sdwa v[226:227], v62 src0_sel:WORD_1
	v_cvt_pk_f32_fp8_e32 v[228:229], v63
	v_cvt_pk_f32_fp8_sdwa v[230:231], v63 src0_sel:WORD_1
	v_pk_fma_f32 v[80:81], s[26:27], v[216:217], v[80:81] op_sel_hi:[0,1,1]
	v_pk_fma_f32 v[82:83], s[26:27], v[218:219], v[82:83] op_sel_hi:[0,1,1]
	v_pk_fma_f32 v[84:85], s[26:27], v[220:221], v[84:85] op_sel_hi:[0,1,1]
	v_pk_fma_f32 v[86:87], s[26:27], v[222:223], v[86:87] op_sel_hi:[0,1,1]
	v_pk_fma_f32 v[88:89], s[26:27], v[224:225], v[88:89] op_sel_hi:[0,1,1]
	v_pk_fma_f32 v[90:91], s[26:27], v[226:227], v[90:91] op_sel_hi:[0,1,1]
	v_pk_fma_f32 v[92:93], s[26:27], v[228:229], v[92:93] op_sel_hi:[0,1,1]
	v_pk_fma_f32 v[94:95], s[26:27], v[230:231], v[94:95] op_sel_hi:[0,1,1]
	v_readlane_b32 s31, v180, 63
	s_lshl_b32 s31, s31, 10
	v_add_u32_e32 v235, s31, v208
	global_load_dwordx4 v[60:63], v235, s[12:13]
	s_waitcnt vmcnt(15)
	v_readlane_b32 s22, v182, 56
	v_cvt_pk_f32_fp8_e32 v[216:217], v0
	v_cvt_pk_f32_fp8_sdwa v[218:219], v0 src0_sel:WORD_1
	v_cvt_pk_f32_fp8_e32 v[220:221], v1
	v_cvt_pk_f32_fp8_sdwa v[222:223], v1 src0_sel:WORD_1
	v_cvt_pk_f32_fp8_e32 v[224:225], v2
	v_cvt_pk_f32_fp8_sdwa v[226:227], v2 src0_sel:WORD_1
	v_cvt_pk_f32_fp8_e32 v[228:229], v3
	v_cvt_pk_f32_fp8_sdwa v[230:231], v3 src0_sel:WORD_1
	v_pk_fma_f32 v[64:65], s[20:21], v[216:217], v[64:65] op_sel_hi:[0,1,1]
	v_pk_fma_f32 v[66:67], s[20:21], v[218:219], v[66:67] op_sel_hi:[0,1,1]
	v_pk_fma_f32 v[68:69], s[20:21], v[220:221], v[68:69] op_sel_hi:[0,1,1]
	v_pk_fma_f32 v[70:71], s[20:21], v[222:223], v[70:71] op_sel_hi:[0,1,1]
	v_pk_fma_f32 v[72:73], s[20:21], v[224:225], v[72:73] op_sel_hi:[0,1,1]
	v_pk_fma_f32 v[74:75], s[20:21], v[226:227], v[74:75] op_sel_hi:[0,1,1]
	v_pk_fma_f32 v[76:77], s[20:21], v[228:229], v[76:77] op_sel_hi:[0,1,1]
	v_pk_fma_f32 v[78:79], s[20:21], v[230:231], v[78:79] op_sel_hi:[0,1,1]
	v_readlane_b32 s28, v177, 0
	s_lshl_b32 s28, s28, 10
	v_add_u32_e32 v232, s28, v208
	global_load_dwordx4 v[0:3], v232, s[12:13]
	s_waitcnt vmcnt(15)
	v_readlane_b32 s24, v178, 57
	v_cvt_pk_f32_fp8_e32 v[216:217], v4
	v_cvt_pk_f32_fp8_sdwa v[218:219], v4 src0_sel:WORD_1
	v_cvt_pk_f32_fp8_e32 v[220:221], v5
	v_cvt_pk_f32_fp8_sdwa v[222:223], v5 src0_sel:WORD_1
	v_cvt_pk_f32_fp8_e32 v[224:225], v6
	v_cvt_pk_f32_fp8_sdwa v[226:227], v6 src0_sel:WORD_1
	v_cvt_pk_f32_fp8_e32 v[228:229], v7
	v_cvt_pk_f32_fp8_sdwa v[230:231], v7 src0_sel:WORD_1
	v_pk_fma_f32 v[80:81], s[22:23], v[216:217], v[80:81] op_sel_hi:[0,1,1]
	v_pk_fma_f32 v[82:83], s[22:23], v[218:219], v[82:83] op_sel_hi:[0,1,1]
	v_pk_fma_f32 v[84:85], s[22:23], v[220:221], v[84:85] op_sel_hi:[0,1,1]
	v_pk_fma_f32 v[86:87], s[22:23], v[222:223], v[86:87] op_sel_hi:[0,1,1]
	v_pk_fma_f32 v[88:89], s[22:23], v[224:225], v[88:89] op_sel_hi:[0,1,1]
	v_pk_fma_f32 v[90:91], s[22:23], v[226:227], v[90:91] op_sel_hi:[0,1,1]
	v_pk_fma_f32 v[92:93], s[22:23], v[228:229], v[92:93] op_sel_hi:[0,1,1]
	v_pk_fma_f32 v[94:95], s[22:23], v[230:231], v[94:95] op_sel_hi:[0,1,1]
	v_readlane_b32 s29, v181, 0
	s_lshl_b32 s29, s29, 10
	v_add_u32_e32 v233, s29, v208
	global_load_dwordx4 v[4:7], v233, s[12:13]
	s_waitcnt vmcnt(15)
	v_readlane_b32 s26, v182, 57
	v_cvt_pk_f32_fp8_e32 v[216:217], v8
	v_cvt_pk_f32_fp8_sdwa v[218:219], v8 src0_sel:WORD_1
	v_cvt_pk_f32_fp8_e32 v[220:221], v9
	v_cvt_pk_f32_fp8_sdwa v[222:223], v9 src0_sel:WORD_1
	v_cvt_pk_f32_fp8_e32 v[224:225], v10
	v_cvt_pk_f32_fp8_sdwa v[226:227], v10 src0_sel:WORD_1
	v_cvt_pk_f32_fp8_e32 v[228:229], v11
	v_cvt_pk_f32_fp8_sdwa v[230:231], v11 src0_sel:WORD_1
	v_pk_fma_f32 v[64:65], s[24:25], v[216:217], v[64:65] op_sel_hi:[0,1,1]
	v_pk_fma_f32 v[66:67], s[24:25], v[218:219], v[66:67] op_sel_hi:[0,1,1]
	v_pk_fma_f32 v[68:69], s[24:25], v[220:221], v[68:69] op_sel_hi:[0,1,1]
	v_pk_fma_f32 v[70:71], s[24:25], v[222:223], v[70:71] op_sel_hi:[0,1,1]
	v_pk_fma_f32 v[72:73], s[24:25], v[224:225], v[72:73] op_sel_hi:[0,1,1]
	v_pk_fma_f32 v[74:75], s[24:25], v[226:227], v[74:75] op_sel_hi:[0,1,1]
	v_pk_fma_f32 v[76:77], s[24:25], v[228:229], v[76:77] op_sel_hi:[0,1,1]
	v_pk_fma_f32 v[78:79], s[24:25], v[230:231], v[78:79] op_sel_hi:[0,1,1]
	v_readlane_b32 s30, v177, 1
	s_lshl_b32 s30, s30, 10
	v_add_u32_e32 v234, s30, v208
	global_load_dwordx4 v[8:11], v234, s[12:13]
	s_waitcnt vmcnt(15)
	v_readlane_b32 s20, v178, 58
	v_cvt_pk_f32_fp8_e32 v[216:217], v12
	v_cvt_pk_f32_fp8_sdwa v[218:219], v12 src0_sel:WORD_1
	v_cvt_pk_f32_fp8_e32 v[220:221], v13
	v_cvt_pk_f32_fp8_sdwa v[222:223], v13 src0_sel:WORD_1
	v_cvt_pk_f32_fp8_e32 v[224:225], v14
	v_cvt_pk_f32_fp8_sdwa v[226:227], v14 src0_sel:WORD_1
	v_cvt_pk_f32_fp8_e32 v[228:229], v15
	v_cvt_pk_f32_fp8_sdwa v[230:231], v15 src0_sel:WORD_1
	v_pk_fma_f32 v[80:81], s[26:27], v[216:217], v[80:81] op_sel_hi:[0,1,1]
	v_pk_fma_f32 v[82:83], s[26:27], v[218:219], v[82:83] op_sel_hi:[0,1,1]
	v_pk_fma_f32 v[84:85], s[26:27], v[220:221], v[84:85] op_sel_hi:[0,1,1]
	v_pk_fma_f32 v[86:87], s[26:27], v[222:223], v[86:87] op_sel_hi:[0,1,1]
	v_pk_fma_f32 v[88:89], s[26:27], v[224:225], v[88:89] op_sel_hi:[0,1,1]
	v_pk_fma_f32 v[90:91], s[26:27], v[226:227], v[90:91] op_sel_hi:[0,1,1]
	v_pk_fma_f32 v[92:93], s[26:27], v[228:229], v[92:93] op_sel_hi:[0,1,1]
	v_pk_fma_f32 v[94:95], s[26:27], v[230:231], v[94:95] op_sel_hi:[0,1,1]
	v_readlane_b32 s31, v181, 1
	s_lshl_b32 s31, s31, 10
	v_add_u32_e32 v235, s31, v208
	global_load_dwordx4 v[12:15], v235, s[12:13]
	s_waitcnt vmcnt(15)
	v_readlane_b32 s22, v182, 58
	v_cvt_pk_f32_fp8_e32 v[216:217], v16
	v_cvt_pk_f32_fp8_sdwa v[218:219], v16 src0_sel:WORD_1
	v_cvt_pk_f32_fp8_e32 v[220:221], v17
	v_cvt_pk_f32_fp8_sdwa v[222:223], v17 src0_sel:WORD_1
	v_cvt_pk_f32_fp8_e32 v[224:225], v18
	v_cvt_pk_f32_fp8_sdwa v[226:227], v18 src0_sel:WORD_1
	v_cvt_pk_f32_fp8_e32 v[228:229], v19
	v_cvt_pk_f32_fp8_sdwa v[230:231], v19 src0_sel:WORD_1
	v_pk_fma_f32 v[64:65], s[20:21], v[216:217], v[64:65] op_sel_hi:[0,1,1]
	v_pk_fma_f32 v[66:67], s[20:21], v[218:219], v[66:67] op_sel_hi:[0,1,1]
	v_pk_fma_f32 v[68:69], s[20:21], v[220:221], v[68:69] op_sel_hi:[0,1,1]
	v_pk_fma_f32 v[70:71], s[20:21], v[222:223], v[70:71] op_sel_hi:[0,1,1]
	v_pk_fma_f32 v[72:73], s[20:21], v[224:225], v[72:73] op_sel_hi:[0,1,1]
	v_pk_fma_f32 v[74:75], s[20:21], v[226:227], v[74:75] op_sel_hi:[0,1,1]
	v_pk_fma_f32 v[76:77], s[20:21], v[228:229], v[76:77] op_sel_hi:[0,1,1]
	v_pk_fma_f32 v[78:79], s[20:21], v[230:231], v[78:79] op_sel_hi:[0,1,1]
	v_readlane_b32 s28, v177, 2
	s_lshl_b32 s28, s28, 10
	v_add_u32_e32 v232, s28, v208
	global_load_dwordx4 v[16:19], v232, s[12:13]
	s_waitcnt vmcnt(15)
	v_readlane_b32 s24, v178, 59
	v_cvt_pk_f32_fp8_e32 v[216:217], v20
	v_cvt_pk_f32_fp8_sdwa v[218:219], v20 src0_sel:WORD_1
	v_cvt_pk_f32_fp8_e32 v[220:221], v21
	v_cvt_pk_f32_fp8_sdwa v[222:223], v21 src0_sel:WORD_1
	v_cvt_pk_f32_fp8_e32 v[224:225], v22
	v_cvt_pk_f32_fp8_sdwa v[226:227], v22 src0_sel:WORD_1
	v_cvt_pk_f32_fp8_e32 v[228:229], v23
	v_cvt_pk_f32_fp8_sdwa v[230:231], v23 src0_sel:WORD_1
	v_pk_fma_f32 v[80:81], s[22:23], v[216:217], v[80:81] op_sel_hi:[0,1,1]
	v_pk_fma_f32 v[82:83], s[22:23], v[218:219], v[82:83] op_sel_hi:[0,1,1]
	v_pk_fma_f32 v[84:85], s[22:23], v[220:221], v[84:85] op_sel_hi:[0,1,1]
	v_pk_fma_f32 v[86:87], s[22:23], v[222:223], v[86:87] op_sel_hi:[0,1,1]
	v_pk_fma_f32 v[88:89], s[22:23], v[224:225], v[88:89] op_sel_hi:[0,1,1]
	v_pk_fma_f32 v[90:91], s[22:23], v[226:227], v[90:91] op_sel_hi:[0,1,1]
	v_pk_fma_f32 v[92:93], s[22:23], v[228:229], v[92:93] op_sel_hi:[0,1,1]
	v_pk_fma_f32 v[94:95], s[22:23], v[230:231], v[94:95] op_sel_hi:[0,1,1]
	v_readlane_b32 s29, v181, 2
	s_lshl_b32 s29, s29, 10
	v_add_u32_e32 v233, s29, v208
	global_load_dwordx4 v[20:23], v233, s[12:13]
	s_waitcnt vmcnt(15)
	v_readlane_b32 s26, v182, 59
	v_cvt_pk_f32_fp8_e32 v[216:217], v24
	v_cvt_pk_f32_fp8_sdwa v[218:219], v24 src0_sel:WORD_1
	v_cvt_pk_f32_fp8_e32 v[220:221], v25
	v_cvt_pk_f32_fp8_sdwa v[222:223], v25 src0_sel:WORD_1
	v_cvt_pk_f32_fp8_e32 v[224:225], v26
	v_cvt_pk_f32_fp8_sdwa v[226:227], v26 src0_sel:WORD_1
	v_cvt_pk_f32_fp8_e32 v[228:229], v27
	v_cvt_pk_f32_fp8_sdwa v[230:231], v27 src0_sel:WORD_1
	v_pk_fma_f32 v[64:65], s[24:25], v[216:217], v[64:65] op_sel_hi:[0,1,1]
	v_pk_fma_f32 v[66:67], s[24:25], v[218:219], v[66:67] op_sel_hi:[0,1,1]
	v_pk_fma_f32 v[68:69], s[24:25], v[220:221], v[68:69] op_sel_hi:[0,1,1]
	v_pk_fma_f32 v[70:71], s[24:25], v[222:223], v[70:71] op_sel_hi:[0,1,1]
	v_pk_fma_f32 v[72:73], s[24:25], v[224:225], v[72:73] op_sel_hi:[0,1,1]
	v_pk_fma_f32 v[74:75], s[24:25], v[226:227], v[74:75] op_sel_hi:[0,1,1]
	v_pk_fma_f32 v[76:77], s[24:25], v[228:229], v[76:77] op_sel_hi:[0,1,1]
	v_pk_fma_f32 v[78:79], s[24:25], v[230:231], v[78:79] op_sel_hi:[0,1,1]
	v_readlane_b32 s30, v177, 3
	s_lshl_b32 s30, s30, 10
	v_add_u32_e32 v234, s30, v208
	global_load_dwordx4 v[24:27], v234, s[12:13]
	s_waitcnt vmcnt(15)
	v_readlane_b32 s20, v178, 60
	v_cvt_pk_f32_fp8_e32 v[216:217], v28
	v_cvt_pk_f32_fp8_sdwa v[218:219], v28 src0_sel:WORD_1
	v_cvt_pk_f32_fp8_e32 v[220:221], v29
	v_cvt_pk_f32_fp8_sdwa v[222:223], v29 src0_sel:WORD_1
	v_cvt_pk_f32_fp8_e32 v[224:225], v30
	v_cvt_pk_f32_fp8_sdwa v[226:227], v30 src0_sel:WORD_1
	v_cvt_pk_f32_fp8_e32 v[228:229], v31
	v_cvt_pk_f32_fp8_sdwa v[230:231], v31 src0_sel:WORD_1
	v_pk_fma_f32 v[80:81], s[26:27], v[216:217], v[80:81] op_sel_hi:[0,1,1]
	v_pk_fma_f32 v[82:83], s[26:27], v[218:219], v[82:83] op_sel_hi:[0,1,1]
	v_pk_fma_f32 v[84:85], s[26:27], v[220:221], v[84:85] op_sel_hi:[0,1,1]
	v_pk_fma_f32 v[86:87], s[26:27], v[222:223], v[86:87] op_sel_hi:[0,1,1]
	v_pk_fma_f32 v[88:89], s[26:27], v[224:225], v[88:89] op_sel_hi:[0,1,1]
	v_pk_fma_f32 v[90:91], s[26:27], v[226:227], v[90:91] op_sel_hi:[0,1,1]
	v_pk_fma_f32 v[92:93], s[26:27], v[228:229], v[92:93] op_sel_hi:[0,1,1]
	v_pk_fma_f32 v[94:95], s[26:27], v[230:231], v[94:95] op_sel_hi:[0,1,1]
	v_readlane_b32 s31, v181, 3
	s_lshl_b32 s31, s31, 10
	v_add_u32_e32 v235, s31, v208
	global_load_dwordx4 v[28:31], v235, s[12:13]
	s_waitcnt vmcnt(15)
	v_readlane_b32 s22, v182, 60
	v_cvt_pk_f32_fp8_e32 v[216:217], v32
	v_cvt_pk_f32_fp8_sdwa v[218:219], v32 src0_sel:WORD_1
	v_cvt_pk_f32_fp8_e32 v[220:221], v33
	v_cvt_pk_f32_fp8_sdwa v[222:223], v33 src0_sel:WORD_1
	v_cvt_pk_f32_fp8_e32 v[224:225], v34
	v_cvt_pk_f32_fp8_sdwa v[226:227], v34 src0_sel:WORD_1
	v_cvt_pk_f32_fp8_e32 v[228:229], v35
	v_cvt_pk_f32_fp8_sdwa v[230:231], v35 src0_sel:WORD_1
	v_pk_fma_f32 v[64:65], s[20:21], v[216:217], v[64:65] op_sel_hi:[0,1,1]
	v_pk_fma_f32 v[66:67], s[20:21], v[218:219], v[66:67] op_sel_hi:[0,1,1]
	v_pk_fma_f32 v[68:69], s[20:21], v[220:221], v[68:69] op_sel_hi:[0,1,1]
	v_pk_fma_f32 v[70:71], s[20:21], v[222:223], v[70:71] op_sel_hi:[0,1,1]
	v_pk_fma_f32 v[72:73], s[20:21], v[224:225], v[72:73] op_sel_hi:[0,1,1]
	v_pk_fma_f32 v[74:75], s[20:21], v[226:227], v[74:75] op_sel_hi:[0,1,1]
	v_pk_fma_f32 v[76:77], s[20:21], v[228:229], v[76:77] op_sel_hi:[0,1,1]
	v_pk_fma_f32 v[78:79], s[20:21], v[230:231], v[78:79] op_sel_hi:[0,1,1]
	v_readlane_b32 s28, v177, 4
	s_lshl_b32 s28, s28, 10
	v_add_u32_e32 v232, s28, v208
	global_load_dwordx4 v[32:35], v232, s[12:13]
	s_waitcnt vmcnt(15)
	v_readlane_b32 s24, v178, 61
	v_cvt_pk_f32_fp8_e32 v[216:217], v36
	v_cvt_pk_f32_fp8_sdwa v[218:219], v36 src0_sel:WORD_1
	v_cvt_pk_f32_fp8_e32 v[220:221], v37
	v_cvt_pk_f32_fp8_sdwa v[222:223], v37 src0_sel:WORD_1
	v_cvt_pk_f32_fp8_e32 v[224:225], v38
	v_cvt_pk_f32_fp8_sdwa v[226:227], v38 src0_sel:WORD_1
	v_cvt_pk_f32_fp8_e32 v[228:229], v39
	v_cvt_pk_f32_fp8_sdwa v[230:231], v39 src0_sel:WORD_1
	v_pk_fma_f32 v[80:81], s[22:23], v[216:217], v[80:81] op_sel_hi:[0,1,1]
	v_pk_fma_f32 v[82:83], s[22:23], v[218:219], v[82:83] op_sel_hi:[0,1,1]
	v_pk_fma_f32 v[84:85], s[22:23], v[220:221], v[84:85] op_sel_hi:[0,1,1]
	v_pk_fma_f32 v[86:87], s[22:23], v[222:223], v[86:87] op_sel_hi:[0,1,1]
	v_pk_fma_f32 v[88:89], s[22:23], v[224:225], v[88:89] op_sel_hi:[0,1,1]
	v_pk_fma_f32 v[90:91], s[22:23], v[226:227], v[90:91] op_sel_hi:[0,1,1]
	v_pk_fma_f32 v[92:93], s[22:23], v[228:229], v[92:93] op_sel_hi:[0,1,1]
	v_pk_fma_f32 v[94:95], s[22:23], v[230:231], v[94:95] op_sel_hi:[0,1,1]
	v_readlane_b32 s29, v181, 4
	s_lshl_b32 s29, s29, 10
	v_add_u32_e32 v233, s29, v208
	global_load_dwordx4 v[36:39], v233, s[12:13]
	s_waitcnt vmcnt(15)
	v_readlane_b32 s26, v182, 61
	v_cvt_pk_f32_fp8_e32 v[216:217], v40
	v_cvt_pk_f32_fp8_sdwa v[218:219], v40 src0_sel:WORD_1
	v_cvt_pk_f32_fp8_e32 v[220:221], v41
	v_cvt_pk_f32_fp8_sdwa v[222:223], v41 src0_sel:WORD_1
	v_cvt_pk_f32_fp8_e32 v[224:225], v42
	v_cvt_pk_f32_fp8_sdwa v[226:227], v42 src0_sel:WORD_1
	v_cvt_pk_f32_fp8_e32 v[228:229], v43
	v_cvt_pk_f32_fp8_sdwa v[230:231], v43 src0_sel:WORD_1
	v_pk_fma_f32 v[64:65], s[24:25], v[216:217], v[64:65] op_sel_hi:[0,1,1]
	v_pk_fma_f32 v[66:67], s[24:25], v[218:219], v[66:67] op_sel_hi:[0,1,1]
	v_pk_fma_f32 v[68:69], s[24:25], v[220:221], v[68:69] op_sel_hi:[0,1,1]
	v_pk_fma_f32 v[70:71], s[24:25], v[222:223], v[70:71] op_sel_hi:[0,1,1]
	v_pk_fma_f32 v[72:73], s[24:25], v[224:225], v[72:73] op_sel_hi:[0,1,1]
	v_pk_fma_f32 v[74:75], s[24:25], v[226:227], v[74:75] op_sel_hi:[0,1,1]
	v_pk_fma_f32 v[76:77], s[24:25], v[228:229], v[76:77] op_sel_hi:[0,1,1]
	v_pk_fma_f32 v[78:79], s[24:25], v[230:231], v[78:79] op_sel_hi:[0,1,1]
	v_readlane_b32 s30, v177, 5
	s_lshl_b32 s30, s30, 10
	v_add_u32_e32 v234, s30, v208
	global_load_dwordx4 v[40:43], v234, s[12:13]
	s_waitcnt vmcnt(15)
	v_readlane_b32 s20, v178, 62
	v_cvt_pk_f32_fp8_e32 v[216:217], v44
	v_cvt_pk_f32_fp8_sdwa v[218:219], v44 src0_sel:WORD_1
	v_cvt_pk_f32_fp8_e32 v[220:221], v45
	v_cvt_pk_f32_fp8_sdwa v[222:223], v45 src0_sel:WORD_1
	v_cvt_pk_f32_fp8_e32 v[224:225], v46
	v_cvt_pk_f32_fp8_sdwa v[226:227], v46 src0_sel:WORD_1
	v_cvt_pk_f32_fp8_e32 v[228:229], v47
	v_cvt_pk_f32_fp8_sdwa v[230:231], v47 src0_sel:WORD_1
	v_pk_fma_f32 v[80:81], s[26:27], v[216:217], v[80:81] op_sel_hi:[0,1,1]
	v_pk_fma_f32 v[82:83], s[26:27], v[218:219], v[82:83] op_sel_hi:[0,1,1]
	v_pk_fma_f32 v[84:85], s[26:27], v[220:221], v[84:85] op_sel_hi:[0,1,1]
	v_pk_fma_f32 v[86:87], s[26:27], v[222:223], v[86:87] op_sel_hi:[0,1,1]
	v_pk_fma_f32 v[88:89], s[26:27], v[224:225], v[88:89] op_sel_hi:[0,1,1]
	v_pk_fma_f32 v[90:91], s[26:27], v[226:227], v[90:91] op_sel_hi:[0,1,1]
	v_pk_fma_f32 v[92:93], s[26:27], v[228:229], v[92:93] op_sel_hi:[0,1,1]
	v_pk_fma_f32 v[94:95], s[26:27], v[230:231], v[94:95] op_sel_hi:[0,1,1]
	v_readlane_b32 s31, v181, 5
	s_lshl_b32 s31, s31, 10
	v_add_u32_e32 v235, s31, v208
	global_load_dwordx4 v[44:47], v235, s[12:13]
	s_waitcnt vmcnt(15)
	v_readlane_b32 s22, v182, 62
	v_cvt_pk_f32_fp8_e32 v[216:217], v48
	v_cvt_pk_f32_fp8_sdwa v[218:219], v48 src0_sel:WORD_1
	v_cvt_pk_f32_fp8_e32 v[220:221], v49
	v_cvt_pk_f32_fp8_sdwa v[222:223], v49 src0_sel:WORD_1
	v_cvt_pk_f32_fp8_e32 v[224:225], v50
	v_cvt_pk_f32_fp8_sdwa v[226:227], v50 src0_sel:WORD_1
	v_cvt_pk_f32_fp8_e32 v[228:229], v51
	v_cvt_pk_f32_fp8_sdwa v[230:231], v51 src0_sel:WORD_1
	v_pk_fma_f32 v[64:65], s[20:21], v[216:217], v[64:65] op_sel_hi:[0,1,1]
	v_pk_fma_f32 v[66:67], s[20:21], v[218:219], v[66:67] op_sel_hi:[0,1,1]
	v_pk_fma_f32 v[68:69], s[20:21], v[220:221], v[68:69] op_sel_hi:[0,1,1]
	v_pk_fma_f32 v[70:71], s[20:21], v[222:223], v[70:71] op_sel_hi:[0,1,1]
	v_pk_fma_f32 v[72:73], s[20:21], v[224:225], v[72:73] op_sel_hi:[0,1,1]
	v_pk_fma_f32 v[74:75], s[20:21], v[226:227], v[74:75] op_sel_hi:[0,1,1]
	v_pk_fma_f32 v[76:77], s[20:21], v[228:229], v[76:77] op_sel_hi:[0,1,1]
	v_pk_fma_f32 v[78:79], s[20:21], v[230:231], v[78:79] op_sel_hi:[0,1,1]
	v_readlane_b32 s28, v177, 6
	s_lshl_b32 s28, s28, 10
	v_add_u32_e32 v232, s28, v208
	global_load_dwordx4 v[48:51], v232, s[12:13]
	s_waitcnt vmcnt(15)
	v_readlane_b32 s24, v178, 63
	v_cvt_pk_f32_fp8_e32 v[216:217], v52
	v_cvt_pk_f32_fp8_sdwa v[218:219], v52 src0_sel:WORD_1
	v_cvt_pk_f32_fp8_e32 v[220:221], v53
	v_cvt_pk_f32_fp8_sdwa v[222:223], v53 src0_sel:WORD_1
	v_cvt_pk_f32_fp8_e32 v[224:225], v54
	v_cvt_pk_f32_fp8_sdwa v[226:227], v54 src0_sel:WORD_1
	v_cvt_pk_f32_fp8_e32 v[228:229], v55
	v_cvt_pk_f32_fp8_sdwa v[230:231], v55 src0_sel:WORD_1
	v_pk_fma_f32 v[80:81], s[22:23], v[216:217], v[80:81] op_sel_hi:[0,1,1]
	v_pk_fma_f32 v[82:83], s[22:23], v[218:219], v[82:83] op_sel_hi:[0,1,1]
	v_pk_fma_f32 v[84:85], s[22:23], v[220:221], v[84:85] op_sel_hi:[0,1,1]
	v_pk_fma_f32 v[86:87], s[22:23], v[222:223], v[86:87] op_sel_hi:[0,1,1]
	v_pk_fma_f32 v[88:89], s[22:23], v[224:225], v[88:89] op_sel_hi:[0,1,1]
	v_pk_fma_f32 v[90:91], s[22:23], v[226:227], v[90:91] op_sel_hi:[0,1,1]
	v_pk_fma_f32 v[92:93], s[22:23], v[228:229], v[92:93] op_sel_hi:[0,1,1]
	v_pk_fma_f32 v[94:95], s[22:23], v[230:231], v[94:95] op_sel_hi:[0,1,1]
	v_readlane_b32 s29, v181, 6
	s_lshl_b32 s29, s29, 10
	v_add_u32_e32 v233, s29, v208
	global_load_dwordx4 v[52:55], v233, s[12:13]
	s_waitcnt vmcnt(15)
	v_readlane_b32 s26, v182, 63
	v_cvt_pk_f32_fp8_e32 v[216:217], v56
	v_cvt_pk_f32_fp8_sdwa v[218:219], v56 src0_sel:WORD_1
	v_cvt_pk_f32_fp8_e32 v[220:221], v57
	v_cvt_pk_f32_fp8_sdwa v[222:223], v57 src0_sel:WORD_1
	v_cvt_pk_f32_fp8_e32 v[224:225], v58
	v_cvt_pk_f32_fp8_sdwa v[226:227], v58 src0_sel:WORD_1
	v_cvt_pk_f32_fp8_e32 v[228:229], v59
	v_cvt_pk_f32_fp8_sdwa v[230:231], v59 src0_sel:WORD_1
	v_pk_fma_f32 v[64:65], s[24:25], v[216:217], v[64:65] op_sel_hi:[0,1,1]
	v_pk_fma_f32 v[66:67], s[24:25], v[218:219], v[66:67] op_sel_hi:[0,1,1]
	v_pk_fma_f32 v[68:69], s[24:25], v[220:221], v[68:69] op_sel_hi:[0,1,1]
	v_pk_fma_f32 v[70:71], s[24:25], v[222:223], v[70:71] op_sel_hi:[0,1,1]
	v_pk_fma_f32 v[72:73], s[24:25], v[224:225], v[72:73] op_sel_hi:[0,1,1]
	v_pk_fma_f32 v[74:75], s[24:25], v[226:227], v[74:75] op_sel_hi:[0,1,1]
	v_pk_fma_f32 v[76:77], s[24:25], v[228:229], v[76:77] op_sel_hi:[0,1,1]
	v_pk_fma_f32 v[78:79], s[24:25], v[230:231], v[78:79] op_sel_hi:[0,1,1]
	v_readlane_b32 s30, v177, 7
	s_lshl_b32 s30, s30, 10
	v_add_u32_e32 v234, s30, v208
	global_load_dwordx4 v[56:59], v234, s[12:13]
	s_waitcnt vmcnt(15)
	v_readlane_b32 s20, v179, 0
	v_cvt_pk_f32_fp8_e32 v[216:217], v60
	v_cvt_pk_f32_fp8_sdwa v[218:219], v60 src0_sel:WORD_1
	v_cvt_pk_f32_fp8_e32 v[220:221], v61
	v_cvt_pk_f32_fp8_sdwa v[222:223], v61 src0_sel:WORD_1
	v_cvt_pk_f32_fp8_e32 v[224:225], v62
	v_cvt_pk_f32_fp8_sdwa v[226:227], v62 src0_sel:WORD_1
	v_cvt_pk_f32_fp8_e32 v[228:229], v63
	v_cvt_pk_f32_fp8_sdwa v[230:231], v63 src0_sel:WORD_1
	v_pk_fma_f32 v[80:81], s[26:27], v[216:217], v[80:81] op_sel_hi:[0,1,1]
	v_pk_fma_f32 v[82:83], s[26:27], v[218:219], v[82:83] op_sel_hi:[0,1,1]
	v_pk_fma_f32 v[84:85], s[26:27], v[220:221], v[84:85] op_sel_hi:[0,1,1]
	v_pk_fma_f32 v[86:87], s[26:27], v[222:223], v[86:87] op_sel_hi:[0,1,1]
	v_pk_fma_f32 v[88:89], s[26:27], v[224:225], v[88:89] op_sel_hi:[0,1,1]
	v_pk_fma_f32 v[90:91], s[26:27], v[226:227], v[90:91] op_sel_hi:[0,1,1]
	v_pk_fma_f32 v[92:93], s[26:27], v[228:229], v[92:93] op_sel_hi:[0,1,1]
	v_pk_fma_f32 v[94:95], s[26:27], v[230:231], v[94:95] op_sel_hi:[0,1,1]
	v_readlane_b32 s31, v181, 7
	s_lshl_b32 s31, s31, 10
	v_add_u32_e32 v235, s31, v208
	global_load_dwordx4 v[60:63], v235, s[12:13]
	s_waitcnt vmcnt(15)
	v_readlane_b32 s22, v183, 0
	v_cvt_pk_f32_fp8_e32 v[216:217], v0
	v_cvt_pk_f32_fp8_sdwa v[218:219], v0 src0_sel:WORD_1
	v_cvt_pk_f32_fp8_e32 v[220:221], v1
	v_cvt_pk_f32_fp8_sdwa v[222:223], v1 src0_sel:WORD_1
	v_cvt_pk_f32_fp8_e32 v[224:225], v2
	v_cvt_pk_f32_fp8_sdwa v[226:227], v2 src0_sel:WORD_1
	v_cvt_pk_f32_fp8_e32 v[228:229], v3
	v_cvt_pk_f32_fp8_sdwa v[230:231], v3 src0_sel:WORD_1
	v_pk_fma_f32 v[64:65], s[20:21], v[216:217], v[64:65] op_sel_hi:[0,1,1]
	v_pk_fma_f32 v[66:67], s[20:21], v[218:219], v[66:67] op_sel_hi:[0,1,1]
	v_pk_fma_f32 v[68:69], s[20:21], v[220:221], v[68:69] op_sel_hi:[0,1,1]
	v_pk_fma_f32 v[70:71], s[20:21], v[222:223], v[70:71] op_sel_hi:[0,1,1]
	v_pk_fma_f32 v[72:73], s[20:21], v[224:225], v[72:73] op_sel_hi:[0,1,1]
	v_pk_fma_f32 v[74:75], s[20:21], v[226:227], v[74:75] op_sel_hi:[0,1,1]
	v_pk_fma_f32 v[76:77], s[20:21], v[228:229], v[76:77] op_sel_hi:[0,1,1]
	v_pk_fma_f32 v[78:79], s[20:21], v[230:231], v[78:79] op_sel_hi:[0,1,1]
	v_readlane_b32 s28, v177, 8
	s_lshl_b32 s28, s28, 10
	v_add_u32_e32 v232, s28, v208
	global_load_dwordx4 v[0:3], v232, s[12:13]
	s_waitcnt vmcnt(15)
	v_readlane_b32 s24, v179, 1
	v_cvt_pk_f32_fp8_e32 v[216:217], v4
	v_cvt_pk_f32_fp8_sdwa v[218:219], v4 src0_sel:WORD_1
	v_cvt_pk_f32_fp8_e32 v[220:221], v5
	v_cvt_pk_f32_fp8_sdwa v[222:223], v5 src0_sel:WORD_1
	v_cvt_pk_f32_fp8_e32 v[224:225], v6
	v_cvt_pk_f32_fp8_sdwa v[226:227], v6 src0_sel:WORD_1
	v_cvt_pk_f32_fp8_e32 v[228:229], v7
	v_cvt_pk_f32_fp8_sdwa v[230:231], v7 src0_sel:WORD_1
	v_pk_fma_f32 v[80:81], s[22:23], v[216:217], v[80:81] op_sel_hi:[0,1,1]
	v_pk_fma_f32 v[82:83], s[22:23], v[218:219], v[82:83] op_sel_hi:[0,1,1]
	v_pk_fma_f32 v[84:85], s[22:23], v[220:221], v[84:85] op_sel_hi:[0,1,1]
	v_pk_fma_f32 v[86:87], s[22:23], v[222:223], v[86:87] op_sel_hi:[0,1,1]
	v_pk_fma_f32 v[88:89], s[22:23], v[224:225], v[88:89] op_sel_hi:[0,1,1]
	v_pk_fma_f32 v[90:91], s[22:23], v[226:227], v[90:91] op_sel_hi:[0,1,1]
	v_pk_fma_f32 v[92:93], s[22:23], v[228:229], v[92:93] op_sel_hi:[0,1,1]
	v_pk_fma_f32 v[94:95], s[22:23], v[230:231], v[94:95] op_sel_hi:[0,1,1]
	v_readlane_b32 s29, v181, 8
	s_lshl_b32 s29, s29, 10
	v_add_u32_e32 v233, s29, v208
	global_load_dwordx4 v[4:7], v233, s[12:13]
	s_waitcnt vmcnt(15)
	v_readlane_b32 s26, v183, 1
	v_cvt_pk_f32_fp8_e32 v[216:217], v8
	v_cvt_pk_f32_fp8_sdwa v[218:219], v8 src0_sel:WORD_1
	v_cvt_pk_f32_fp8_e32 v[220:221], v9
	v_cvt_pk_f32_fp8_sdwa v[222:223], v9 src0_sel:WORD_1
	v_cvt_pk_f32_fp8_e32 v[224:225], v10
	v_cvt_pk_f32_fp8_sdwa v[226:227], v10 src0_sel:WORD_1
	v_cvt_pk_f32_fp8_e32 v[228:229], v11
	v_cvt_pk_f32_fp8_sdwa v[230:231], v11 src0_sel:WORD_1
	v_pk_fma_f32 v[64:65], s[24:25], v[216:217], v[64:65] op_sel_hi:[0,1,1]
	v_pk_fma_f32 v[66:67], s[24:25], v[218:219], v[66:67] op_sel_hi:[0,1,1]
	v_pk_fma_f32 v[68:69], s[24:25], v[220:221], v[68:69] op_sel_hi:[0,1,1]
	v_pk_fma_f32 v[70:71], s[24:25], v[222:223], v[70:71] op_sel_hi:[0,1,1]
	v_pk_fma_f32 v[72:73], s[24:25], v[224:225], v[72:73] op_sel_hi:[0,1,1]
	v_pk_fma_f32 v[74:75], s[24:25], v[226:227], v[74:75] op_sel_hi:[0,1,1]
	v_pk_fma_f32 v[76:77], s[24:25], v[228:229], v[76:77] op_sel_hi:[0,1,1]
	v_pk_fma_f32 v[78:79], s[24:25], v[230:231], v[78:79] op_sel_hi:[0,1,1]
	v_readlane_b32 s30, v177, 9
	s_lshl_b32 s30, s30, 10
	v_add_u32_e32 v234, s30, v208
	global_load_dwordx4 v[8:11], v234, s[12:13]
	s_waitcnt vmcnt(15)
	v_readlane_b32 s20, v179, 2
	v_cvt_pk_f32_fp8_e32 v[216:217], v12
	v_cvt_pk_f32_fp8_sdwa v[218:219], v12 src0_sel:WORD_1
	v_cvt_pk_f32_fp8_e32 v[220:221], v13
	v_cvt_pk_f32_fp8_sdwa v[222:223], v13 src0_sel:WORD_1
	v_cvt_pk_f32_fp8_e32 v[224:225], v14
	v_cvt_pk_f32_fp8_sdwa v[226:227], v14 src0_sel:WORD_1
	v_cvt_pk_f32_fp8_e32 v[228:229], v15
	v_cvt_pk_f32_fp8_sdwa v[230:231], v15 src0_sel:WORD_1
	v_pk_fma_f32 v[80:81], s[26:27], v[216:217], v[80:81] op_sel_hi:[0,1,1]
	v_pk_fma_f32 v[82:83], s[26:27], v[218:219], v[82:83] op_sel_hi:[0,1,1]
	v_pk_fma_f32 v[84:85], s[26:27], v[220:221], v[84:85] op_sel_hi:[0,1,1]
	v_pk_fma_f32 v[86:87], s[26:27], v[222:223], v[86:87] op_sel_hi:[0,1,1]
	v_pk_fma_f32 v[88:89], s[26:27], v[224:225], v[88:89] op_sel_hi:[0,1,1]
	v_pk_fma_f32 v[90:91], s[26:27], v[226:227], v[90:91] op_sel_hi:[0,1,1]
	v_pk_fma_f32 v[92:93], s[26:27], v[228:229], v[92:93] op_sel_hi:[0,1,1]
	v_pk_fma_f32 v[94:95], s[26:27], v[230:231], v[94:95] op_sel_hi:[0,1,1]
	v_readlane_b32 s31, v181, 9
	s_lshl_b32 s31, s31, 10
	v_add_u32_e32 v235, s31, v208
	global_load_dwordx4 v[12:15], v235, s[12:13]
	s_waitcnt vmcnt(15)
	v_readlane_b32 s22, v183, 2
	v_cvt_pk_f32_fp8_e32 v[216:217], v16
	v_cvt_pk_f32_fp8_sdwa v[218:219], v16 src0_sel:WORD_1
	v_cvt_pk_f32_fp8_e32 v[220:221], v17
	v_cvt_pk_f32_fp8_sdwa v[222:223], v17 src0_sel:WORD_1
	v_cvt_pk_f32_fp8_e32 v[224:225], v18
	v_cvt_pk_f32_fp8_sdwa v[226:227], v18 src0_sel:WORD_1
	v_cvt_pk_f32_fp8_e32 v[228:229], v19
	v_cvt_pk_f32_fp8_sdwa v[230:231], v19 src0_sel:WORD_1
	v_pk_fma_f32 v[64:65], s[20:21], v[216:217], v[64:65] op_sel_hi:[0,1,1]
	v_pk_fma_f32 v[66:67], s[20:21], v[218:219], v[66:67] op_sel_hi:[0,1,1]
	v_pk_fma_f32 v[68:69], s[20:21], v[220:221], v[68:69] op_sel_hi:[0,1,1]
	v_pk_fma_f32 v[70:71], s[20:21], v[222:223], v[70:71] op_sel_hi:[0,1,1]
	v_pk_fma_f32 v[72:73], s[20:21], v[224:225], v[72:73] op_sel_hi:[0,1,1]
	v_pk_fma_f32 v[74:75], s[20:21], v[226:227], v[74:75] op_sel_hi:[0,1,1]
	v_pk_fma_f32 v[76:77], s[20:21], v[228:229], v[76:77] op_sel_hi:[0,1,1]
	v_pk_fma_f32 v[78:79], s[20:21], v[230:231], v[78:79] op_sel_hi:[0,1,1]
	v_readlane_b32 s28, v177, 10
	s_lshl_b32 s28, s28, 10
	v_add_u32_e32 v232, s28, v208
	global_load_dwordx4 v[16:19], v232, s[12:13]
	s_waitcnt vmcnt(15)
	v_readlane_b32 s24, v179, 3
	v_cvt_pk_f32_fp8_e32 v[216:217], v20
	v_cvt_pk_f32_fp8_sdwa v[218:219], v20 src0_sel:WORD_1
	v_cvt_pk_f32_fp8_e32 v[220:221], v21
	v_cvt_pk_f32_fp8_sdwa v[222:223], v21 src0_sel:WORD_1
	v_cvt_pk_f32_fp8_e32 v[224:225], v22
	v_cvt_pk_f32_fp8_sdwa v[226:227], v22 src0_sel:WORD_1
	v_cvt_pk_f32_fp8_e32 v[228:229], v23
	v_cvt_pk_f32_fp8_sdwa v[230:231], v23 src0_sel:WORD_1
	v_pk_fma_f32 v[80:81], s[22:23], v[216:217], v[80:81] op_sel_hi:[0,1,1]
	v_pk_fma_f32 v[82:83], s[22:23], v[218:219], v[82:83] op_sel_hi:[0,1,1]
	v_pk_fma_f32 v[84:85], s[22:23], v[220:221], v[84:85] op_sel_hi:[0,1,1]
	v_pk_fma_f32 v[86:87], s[22:23], v[222:223], v[86:87] op_sel_hi:[0,1,1]
	v_pk_fma_f32 v[88:89], s[22:23], v[224:225], v[88:89] op_sel_hi:[0,1,1]
	v_pk_fma_f32 v[90:91], s[22:23], v[226:227], v[90:91] op_sel_hi:[0,1,1]
	v_pk_fma_f32 v[92:93], s[22:23], v[228:229], v[92:93] op_sel_hi:[0,1,1]
	v_pk_fma_f32 v[94:95], s[22:23], v[230:231], v[94:95] op_sel_hi:[0,1,1]
	v_readlane_b32 s29, v181, 10
	s_lshl_b32 s29, s29, 10
	v_add_u32_e32 v233, s29, v208
	global_load_dwordx4 v[20:23], v233, s[12:13]
	s_waitcnt vmcnt(15)
	v_readlane_b32 s26, v183, 3
	v_cvt_pk_f32_fp8_e32 v[216:217], v24
	v_cvt_pk_f32_fp8_sdwa v[218:219], v24 src0_sel:WORD_1
	v_cvt_pk_f32_fp8_e32 v[220:221], v25
	v_cvt_pk_f32_fp8_sdwa v[222:223], v25 src0_sel:WORD_1
	v_cvt_pk_f32_fp8_e32 v[224:225], v26
	v_cvt_pk_f32_fp8_sdwa v[226:227], v26 src0_sel:WORD_1
	v_cvt_pk_f32_fp8_e32 v[228:229], v27
	v_cvt_pk_f32_fp8_sdwa v[230:231], v27 src0_sel:WORD_1
	v_pk_fma_f32 v[64:65], s[24:25], v[216:217], v[64:65] op_sel_hi:[0,1,1]
	v_pk_fma_f32 v[66:67], s[24:25], v[218:219], v[66:67] op_sel_hi:[0,1,1]
	v_pk_fma_f32 v[68:69], s[24:25], v[220:221], v[68:69] op_sel_hi:[0,1,1]
	v_pk_fma_f32 v[70:71], s[24:25], v[222:223], v[70:71] op_sel_hi:[0,1,1]
	v_pk_fma_f32 v[72:73], s[24:25], v[224:225], v[72:73] op_sel_hi:[0,1,1]
	v_pk_fma_f32 v[74:75], s[24:25], v[226:227], v[74:75] op_sel_hi:[0,1,1]
	v_pk_fma_f32 v[76:77], s[24:25], v[228:229], v[76:77] op_sel_hi:[0,1,1]
	v_pk_fma_f32 v[78:79], s[24:25], v[230:231], v[78:79] op_sel_hi:[0,1,1]
	v_readlane_b32 s30, v177, 11
	s_lshl_b32 s30, s30, 10
	v_add_u32_e32 v234, s30, v208
	global_load_dwordx4 v[24:27], v234, s[12:13]
	s_waitcnt vmcnt(15)
	v_readlane_b32 s20, v179, 4
	v_cvt_pk_f32_fp8_e32 v[216:217], v28
	v_cvt_pk_f32_fp8_sdwa v[218:219], v28 src0_sel:WORD_1
	v_cvt_pk_f32_fp8_e32 v[220:221], v29
	v_cvt_pk_f32_fp8_sdwa v[222:223], v29 src0_sel:WORD_1
	v_cvt_pk_f32_fp8_e32 v[224:225], v30
	v_cvt_pk_f32_fp8_sdwa v[226:227], v30 src0_sel:WORD_1
	v_cvt_pk_f32_fp8_e32 v[228:229], v31
	v_cvt_pk_f32_fp8_sdwa v[230:231], v31 src0_sel:WORD_1
	v_pk_fma_f32 v[80:81], s[26:27], v[216:217], v[80:81] op_sel_hi:[0,1,1]
	v_pk_fma_f32 v[82:83], s[26:27], v[218:219], v[82:83] op_sel_hi:[0,1,1]
	v_pk_fma_f32 v[84:85], s[26:27], v[220:221], v[84:85] op_sel_hi:[0,1,1]
	v_pk_fma_f32 v[86:87], s[26:27], v[222:223], v[86:87] op_sel_hi:[0,1,1]
	v_pk_fma_f32 v[88:89], s[26:27], v[224:225], v[88:89] op_sel_hi:[0,1,1]
	v_pk_fma_f32 v[90:91], s[26:27], v[226:227], v[90:91] op_sel_hi:[0,1,1]
	v_pk_fma_f32 v[92:93], s[26:27], v[228:229], v[92:93] op_sel_hi:[0,1,1]
	v_pk_fma_f32 v[94:95], s[26:27], v[230:231], v[94:95] op_sel_hi:[0,1,1]
	v_readlane_b32 s31, v181, 11
	s_lshl_b32 s31, s31, 10
	v_add_u32_e32 v235, s31, v208
	global_load_dwordx4 v[28:31], v235, s[12:13]
	s_waitcnt vmcnt(15)
	v_readlane_b32 s22, v183, 4
	v_cvt_pk_f32_fp8_e32 v[216:217], v32
	v_cvt_pk_f32_fp8_sdwa v[218:219], v32 src0_sel:WORD_1
	v_cvt_pk_f32_fp8_e32 v[220:221], v33
	v_cvt_pk_f32_fp8_sdwa v[222:223], v33 src0_sel:WORD_1
	v_cvt_pk_f32_fp8_e32 v[224:225], v34
	v_cvt_pk_f32_fp8_sdwa v[226:227], v34 src0_sel:WORD_1
	v_cvt_pk_f32_fp8_e32 v[228:229], v35
	v_cvt_pk_f32_fp8_sdwa v[230:231], v35 src0_sel:WORD_1
	v_pk_fma_f32 v[64:65], s[20:21], v[216:217], v[64:65] op_sel_hi:[0,1,1]
	v_pk_fma_f32 v[66:67], s[20:21], v[218:219], v[66:67] op_sel_hi:[0,1,1]
	v_pk_fma_f32 v[68:69], s[20:21], v[220:221], v[68:69] op_sel_hi:[0,1,1]
	v_pk_fma_f32 v[70:71], s[20:21], v[222:223], v[70:71] op_sel_hi:[0,1,1]
	v_pk_fma_f32 v[72:73], s[20:21], v[224:225], v[72:73] op_sel_hi:[0,1,1]
	v_pk_fma_f32 v[74:75], s[20:21], v[226:227], v[74:75] op_sel_hi:[0,1,1]
	v_pk_fma_f32 v[76:77], s[20:21], v[228:229], v[76:77] op_sel_hi:[0,1,1]
	v_pk_fma_f32 v[78:79], s[20:21], v[230:231], v[78:79] op_sel_hi:[0,1,1]
	v_readlane_b32 s28, v177, 12
	s_lshl_b32 s28, s28, 10
	v_add_u32_e32 v232, s28, v208
	global_load_dwordx4 v[32:35], v232, s[12:13]
	s_waitcnt vmcnt(15)
	v_readlane_b32 s24, v179, 5
	v_cvt_pk_f32_fp8_e32 v[216:217], v36
	v_cvt_pk_f32_fp8_sdwa v[218:219], v36 src0_sel:WORD_1
	v_cvt_pk_f32_fp8_e32 v[220:221], v37
	v_cvt_pk_f32_fp8_sdwa v[222:223], v37 src0_sel:WORD_1
	v_cvt_pk_f32_fp8_e32 v[224:225], v38
	v_cvt_pk_f32_fp8_sdwa v[226:227], v38 src0_sel:WORD_1
	v_cvt_pk_f32_fp8_e32 v[228:229], v39
	v_cvt_pk_f32_fp8_sdwa v[230:231], v39 src0_sel:WORD_1
	v_pk_fma_f32 v[80:81], s[22:23], v[216:217], v[80:81] op_sel_hi:[0,1,1]
	v_pk_fma_f32 v[82:83], s[22:23], v[218:219], v[82:83] op_sel_hi:[0,1,1]
	v_pk_fma_f32 v[84:85], s[22:23], v[220:221], v[84:85] op_sel_hi:[0,1,1]
	v_pk_fma_f32 v[86:87], s[22:23], v[222:223], v[86:87] op_sel_hi:[0,1,1]
	v_pk_fma_f32 v[88:89], s[22:23], v[224:225], v[88:89] op_sel_hi:[0,1,1]
	v_pk_fma_f32 v[90:91], s[22:23], v[226:227], v[90:91] op_sel_hi:[0,1,1]
	v_pk_fma_f32 v[92:93], s[22:23], v[228:229], v[92:93] op_sel_hi:[0,1,1]
	v_pk_fma_f32 v[94:95], s[22:23], v[230:231], v[94:95] op_sel_hi:[0,1,1]
	v_readlane_b32 s29, v181, 12
	s_lshl_b32 s29, s29, 10
	v_add_u32_e32 v233, s29, v208
	global_load_dwordx4 v[36:39], v233, s[12:13]
	s_waitcnt vmcnt(15)
	v_readlane_b32 s26, v183, 5
	v_cvt_pk_f32_fp8_e32 v[216:217], v40
	v_cvt_pk_f32_fp8_sdwa v[218:219], v40 src0_sel:WORD_1
	v_cvt_pk_f32_fp8_e32 v[220:221], v41
	v_cvt_pk_f32_fp8_sdwa v[222:223], v41 src0_sel:WORD_1
	v_cvt_pk_f32_fp8_e32 v[224:225], v42
	v_cvt_pk_f32_fp8_sdwa v[226:227], v42 src0_sel:WORD_1
	v_cvt_pk_f32_fp8_e32 v[228:229], v43
	v_cvt_pk_f32_fp8_sdwa v[230:231], v43 src0_sel:WORD_1
	v_pk_fma_f32 v[64:65], s[24:25], v[216:217], v[64:65] op_sel_hi:[0,1,1]
	v_pk_fma_f32 v[66:67], s[24:25], v[218:219], v[66:67] op_sel_hi:[0,1,1]
	v_pk_fma_f32 v[68:69], s[24:25], v[220:221], v[68:69] op_sel_hi:[0,1,1]
	v_pk_fma_f32 v[70:71], s[24:25], v[222:223], v[70:71] op_sel_hi:[0,1,1]
	v_pk_fma_f32 v[72:73], s[24:25], v[224:225], v[72:73] op_sel_hi:[0,1,1]
	v_pk_fma_f32 v[74:75], s[24:25], v[226:227], v[74:75] op_sel_hi:[0,1,1]
	v_pk_fma_f32 v[76:77], s[24:25], v[228:229], v[76:77] op_sel_hi:[0,1,1]
	v_pk_fma_f32 v[78:79], s[24:25], v[230:231], v[78:79] op_sel_hi:[0,1,1]
	v_readlane_b32 s30, v177, 13
	s_lshl_b32 s30, s30, 10
	v_add_u32_e32 v234, s30, v208
	global_load_dwordx4 v[40:43], v234, s[12:13]
	s_waitcnt vmcnt(15)
	v_readlane_b32 s20, v179, 6
	v_cvt_pk_f32_fp8_e32 v[216:217], v44
	v_cvt_pk_f32_fp8_sdwa v[218:219], v44 src0_sel:WORD_1
	v_cvt_pk_f32_fp8_e32 v[220:221], v45
	v_cvt_pk_f32_fp8_sdwa v[222:223], v45 src0_sel:WORD_1
	v_cvt_pk_f32_fp8_e32 v[224:225], v46
	v_cvt_pk_f32_fp8_sdwa v[226:227], v46 src0_sel:WORD_1
	v_cvt_pk_f32_fp8_e32 v[228:229], v47
	v_cvt_pk_f32_fp8_sdwa v[230:231], v47 src0_sel:WORD_1
	v_pk_fma_f32 v[80:81], s[26:27], v[216:217], v[80:81] op_sel_hi:[0,1,1]
	v_pk_fma_f32 v[82:83], s[26:27], v[218:219], v[82:83] op_sel_hi:[0,1,1]
	v_pk_fma_f32 v[84:85], s[26:27], v[220:221], v[84:85] op_sel_hi:[0,1,1]
	v_pk_fma_f32 v[86:87], s[26:27], v[222:223], v[86:87] op_sel_hi:[0,1,1]
	v_pk_fma_f32 v[88:89], s[26:27], v[224:225], v[88:89] op_sel_hi:[0,1,1]
	v_pk_fma_f32 v[90:91], s[26:27], v[226:227], v[90:91] op_sel_hi:[0,1,1]
	v_pk_fma_f32 v[92:93], s[26:27], v[228:229], v[92:93] op_sel_hi:[0,1,1]
	v_pk_fma_f32 v[94:95], s[26:27], v[230:231], v[94:95] op_sel_hi:[0,1,1]
	v_readlane_b32 s31, v181, 13
	s_lshl_b32 s31, s31, 10
	v_add_u32_e32 v235, s31, v208
	global_load_dwordx4 v[44:47], v235, s[12:13]
	s_waitcnt vmcnt(15)
	v_readlane_b32 s22, v183, 6
	v_cvt_pk_f32_fp8_e32 v[216:217], v48
	v_cvt_pk_f32_fp8_sdwa v[218:219], v48 src0_sel:WORD_1
	v_cvt_pk_f32_fp8_e32 v[220:221], v49
	v_cvt_pk_f32_fp8_sdwa v[222:223], v49 src0_sel:WORD_1
	v_cvt_pk_f32_fp8_e32 v[224:225], v50
	v_cvt_pk_f32_fp8_sdwa v[226:227], v50 src0_sel:WORD_1
	v_cvt_pk_f32_fp8_e32 v[228:229], v51
	v_cvt_pk_f32_fp8_sdwa v[230:231], v51 src0_sel:WORD_1
	v_pk_fma_f32 v[64:65], s[20:21], v[216:217], v[64:65] op_sel_hi:[0,1,1]
	v_pk_fma_f32 v[66:67], s[20:21], v[218:219], v[66:67] op_sel_hi:[0,1,1]
	v_pk_fma_f32 v[68:69], s[20:21], v[220:221], v[68:69] op_sel_hi:[0,1,1]
	v_pk_fma_f32 v[70:71], s[20:21], v[222:223], v[70:71] op_sel_hi:[0,1,1]
	v_pk_fma_f32 v[72:73], s[20:21], v[224:225], v[72:73] op_sel_hi:[0,1,1]
	v_pk_fma_f32 v[74:75], s[20:21], v[226:227], v[74:75] op_sel_hi:[0,1,1]
	v_pk_fma_f32 v[76:77], s[20:21], v[228:229], v[76:77] op_sel_hi:[0,1,1]
	v_pk_fma_f32 v[78:79], s[20:21], v[230:231], v[78:79] op_sel_hi:[0,1,1]
	v_readlane_b32 s28, v177, 14
	s_lshl_b32 s28, s28, 10
	v_add_u32_e32 v232, s28, v208
	global_load_dwordx4 v[48:51], v232, s[12:13]
	s_waitcnt vmcnt(15)
	v_readlane_b32 s24, v179, 7
	v_cvt_pk_f32_fp8_e32 v[216:217], v52
	v_cvt_pk_f32_fp8_sdwa v[218:219], v52 src0_sel:WORD_1
	v_cvt_pk_f32_fp8_e32 v[220:221], v53
	v_cvt_pk_f32_fp8_sdwa v[222:223], v53 src0_sel:WORD_1
	v_cvt_pk_f32_fp8_e32 v[224:225], v54
	v_cvt_pk_f32_fp8_sdwa v[226:227], v54 src0_sel:WORD_1
	v_cvt_pk_f32_fp8_e32 v[228:229], v55
	v_cvt_pk_f32_fp8_sdwa v[230:231], v55 src0_sel:WORD_1
	v_pk_fma_f32 v[80:81], s[22:23], v[216:217], v[80:81] op_sel_hi:[0,1,1]
	v_pk_fma_f32 v[82:83], s[22:23], v[218:219], v[82:83] op_sel_hi:[0,1,1]
	v_pk_fma_f32 v[84:85], s[22:23], v[220:221], v[84:85] op_sel_hi:[0,1,1]
	v_pk_fma_f32 v[86:87], s[22:23], v[222:223], v[86:87] op_sel_hi:[0,1,1]
	v_pk_fma_f32 v[88:89], s[22:23], v[224:225], v[88:89] op_sel_hi:[0,1,1]
	v_pk_fma_f32 v[90:91], s[22:23], v[226:227], v[90:91] op_sel_hi:[0,1,1]
	v_pk_fma_f32 v[92:93], s[22:23], v[228:229], v[92:93] op_sel_hi:[0,1,1]
	v_pk_fma_f32 v[94:95], s[22:23], v[230:231], v[94:95] op_sel_hi:[0,1,1]
	v_readlane_b32 s29, v181, 14
	s_lshl_b32 s29, s29, 10
	v_add_u32_e32 v233, s29, v208
	global_load_dwordx4 v[52:55], v233, s[12:13]
	s_waitcnt vmcnt(15)
	v_readlane_b32 s26, v183, 7
	v_cvt_pk_f32_fp8_e32 v[216:217], v56
	v_cvt_pk_f32_fp8_sdwa v[218:219], v56 src0_sel:WORD_1
	v_cvt_pk_f32_fp8_e32 v[220:221], v57
	v_cvt_pk_f32_fp8_sdwa v[222:223], v57 src0_sel:WORD_1
	v_cvt_pk_f32_fp8_e32 v[224:225], v58
	v_cvt_pk_f32_fp8_sdwa v[226:227], v58 src0_sel:WORD_1
	v_cvt_pk_f32_fp8_e32 v[228:229], v59
	v_cvt_pk_f32_fp8_sdwa v[230:231], v59 src0_sel:WORD_1
	v_pk_fma_f32 v[64:65], s[24:25], v[216:217], v[64:65] op_sel_hi:[0,1,1]
	v_pk_fma_f32 v[66:67], s[24:25], v[218:219], v[66:67] op_sel_hi:[0,1,1]
	v_pk_fma_f32 v[68:69], s[24:25], v[220:221], v[68:69] op_sel_hi:[0,1,1]
	v_pk_fma_f32 v[70:71], s[24:25], v[222:223], v[70:71] op_sel_hi:[0,1,1]
	v_pk_fma_f32 v[72:73], s[24:25], v[224:225], v[72:73] op_sel_hi:[0,1,1]
	v_pk_fma_f32 v[74:75], s[24:25], v[226:227], v[74:75] op_sel_hi:[0,1,1]
	v_pk_fma_f32 v[76:77], s[24:25], v[228:229], v[76:77] op_sel_hi:[0,1,1]
	v_pk_fma_f32 v[78:79], s[24:25], v[230:231], v[78:79] op_sel_hi:[0,1,1]
	v_readlane_b32 s30, v177, 15
	s_lshl_b32 s30, s30, 10
	v_add_u32_e32 v234, s30, v208
	global_load_dwordx4 v[56:59], v234, s[12:13]
	s_waitcnt vmcnt(15)
	v_readlane_b32 s20, v179, 8
	v_cvt_pk_f32_fp8_e32 v[216:217], v60
	v_cvt_pk_f32_fp8_sdwa v[218:219], v60 src0_sel:WORD_1
	v_cvt_pk_f32_fp8_e32 v[220:221], v61
	v_cvt_pk_f32_fp8_sdwa v[222:223], v61 src0_sel:WORD_1
	v_cvt_pk_f32_fp8_e32 v[224:225], v62
	v_cvt_pk_f32_fp8_sdwa v[226:227], v62 src0_sel:WORD_1
	v_cvt_pk_f32_fp8_e32 v[228:229], v63
	v_cvt_pk_f32_fp8_sdwa v[230:231], v63 src0_sel:WORD_1
	v_pk_fma_f32 v[80:81], s[26:27], v[216:217], v[80:81] op_sel_hi:[0,1,1]
	v_pk_fma_f32 v[82:83], s[26:27], v[218:219], v[82:83] op_sel_hi:[0,1,1]
	v_pk_fma_f32 v[84:85], s[26:27], v[220:221], v[84:85] op_sel_hi:[0,1,1]
	v_pk_fma_f32 v[86:87], s[26:27], v[222:223], v[86:87] op_sel_hi:[0,1,1]
	v_pk_fma_f32 v[88:89], s[26:27], v[224:225], v[88:89] op_sel_hi:[0,1,1]
	v_pk_fma_f32 v[90:91], s[26:27], v[226:227], v[90:91] op_sel_hi:[0,1,1]
	v_pk_fma_f32 v[92:93], s[26:27], v[228:229], v[92:93] op_sel_hi:[0,1,1]
	v_pk_fma_f32 v[94:95], s[26:27], v[230:231], v[94:95] op_sel_hi:[0,1,1]
	v_readlane_b32 s31, v181, 15
	s_lshl_b32 s31, s31, 10
	v_add_u32_e32 v235, s31, v208
	global_load_dwordx4 v[60:63], v235, s[12:13]
	s_waitcnt vmcnt(15)
	v_readlane_b32 s22, v183, 8
	v_cvt_pk_f32_fp8_e32 v[216:217], v0
	v_cvt_pk_f32_fp8_sdwa v[218:219], v0 src0_sel:WORD_1
	v_cvt_pk_f32_fp8_e32 v[220:221], v1
	v_cvt_pk_f32_fp8_sdwa v[222:223], v1 src0_sel:WORD_1
	v_cvt_pk_f32_fp8_e32 v[224:225], v2
	v_cvt_pk_f32_fp8_sdwa v[226:227], v2 src0_sel:WORD_1
	v_cvt_pk_f32_fp8_e32 v[228:229], v3
	v_cvt_pk_f32_fp8_sdwa v[230:231], v3 src0_sel:WORD_1
	v_pk_fma_f32 v[64:65], s[20:21], v[216:217], v[64:65] op_sel_hi:[0,1,1]
	v_pk_fma_f32 v[66:67], s[20:21], v[218:219], v[66:67] op_sel_hi:[0,1,1]
	v_pk_fma_f32 v[68:69], s[20:21], v[220:221], v[68:69] op_sel_hi:[0,1,1]
	v_pk_fma_f32 v[70:71], s[20:21], v[222:223], v[70:71] op_sel_hi:[0,1,1]
	v_pk_fma_f32 v[72:73], s[20:21], v[224:225], v[72:73] op_sel_hi:[0,1,1]
	v_pk_fma_f32 v[74:75], s[20:21], v[226:227], v[74:75] op_sel_hi:[0,1,1]
	v_pk_fma_f32 v[76:77], s[20:21], v[228:229], v[76:77] op_sel_hi:[0,1,1]
	v_pk_fma_f32 v[78:79], s[20:21], v[230:231], v[78:79] op_sel_hi:[0,1,1]
	v_readlane_b32 s28, v177, 16
	s_lshl_b32 s28, s28, 10
	v_add_u32_e32 v232, s28, v208
	global_load_dwordx4 v[0:3], v232, s[12:13]
	s_waitcnt vmcnt(15)
	v_readlane_b32 s24, v179, 9
	v_cvt_pk_f32_fp8_e32 v[216:217], v4
	v_cvt_pk_f32_fp8_sdwa v[218:219], v4 src0_sel:WORD_1
	v_cvt_pk_f32_fp8_e32 v[220:221], v5
	v_cvt_pk_f32_fp8_sdwa v[222:223], v5 src0_sel:WORD_1
	v_cvt_pk_f32_fp8_e32 v[224:225], v6
	v_cvt_pk_f32_fp8_sdwa v[226:227], v6 src0_sel:WORD_1
	v_cvt_pk_f32_fp8_e32 v[228:229], v7
	v_cvt_pk_f32_fp8_sdwa v[230:231], v7 src0_sel:WORD_1
	v_pk_fma_f32 v[80:81], s[22:23], v[216:217], v[80:81] op_sel_hi:[0,1,1]
	v_pk_fma_f32 v[82:83], s[22:23], v[218:219], v[82:83] op_sel_hi:[0,1,1]
	v_pk_fma_f32 v[84:85], s[22:23], v[220:221], v[84:85] op_sel_hi:[0,1,1]
	v_pk_fma_f32 v[86:87], s[22:23], v[222:223], v[86:87] op_sel_hi:[0,1,1]
	v_pk_fma_f32 v[88:89], s[22:23], v[224:225], v[88:89] op_sel_hi:[0,1,1]
	v_pk_fma_f32 v[90:91], s[22:23], v[226:227], v[90:91] op_sel_hi:[0,1,1]
	v_pk_fma_f32 v[92:93], s[22:23], v[228:229], v[92:93] op_sel_hi:[0,1,1]
	v_pk_fma_f32 v[94:95], s[22:23], v[230:231], v[94:95] op_sel_hi:[0,1,1]
	v_readlane_b32 s29, v181, 16
	s_lshl_b32 s29, s29, 10
	v_add_u32_e32 v233, s29, v208
	global_load_dwordx4 v[4:7], v233, s[12:13]
	s_waitcnt vmcnt(15)
	v_readlane_b32 s26, v183, 9
	v_cvt_pk_f32_fp8_e32 v[216:217], v8
	v_cvt_pk_f32_fp8_sdwa v[218:219], v8 src0_sel:WORD_1
	v_cvt_pk_f32_fp8_e32 v[220:221], v9
	v_cvt_pk_f32_fp8_sdwa v[222:223], v9 src0_sel:WORD_1
	v_cvt_pk_f32_fp8_e32 v[224:225], v10
	v_cvt_pk_f32_fp8_sdwa v[226:227], v10 src0_sel:WORD_1
	v_cvt_pk_f32_fp8_e32 v[228:229], v11
	v_cvt_pk_f32_fp8_sdwa v[230:231], v11 src0_sel:WORD_1
	v_pk_fma_f32 v[64:65], s[24:25], v[216:217], v[64:65] op_sel_hi:[0,1,1]
	v_pk_fma_f32 v[66:67], s[24:25], v[218:219], v[66:67] op_sel_hi:[0,1,1]
	v_pk_fma_f32 v[68:69], s[24:25], v[220:221], v[68:69] op_sel_hi:[0,1,1]
	v_pk_fma_f32 v[70:71], s[24:25], v[222:223], v[70:71] op_sel_hi:[0,1,1]
	v_pk_fma_f32 v[72:73], s[24:25], v[224:225], v[72:73] op_sel_hi:[0,1,1]
	v_pk_fma_f32 v[74:75], s[24:25], v[226:227], v[74:75] op_sel_hi:[0,1,1]
	v_pk_fma_f32 v[76:77], s[24:25], v[228:229], v[76:77] op_sel_hi:[0,1,1]
	v_pk_fma_f32 v[78:79], s[24:25], v[230:231], v[78:79] op_sel_hi:[0,1,1]
	v_readlane_b32 s30, v177, 17
	s_lshl_b32 s30, s30, 10
	v_add_u32_e32 v234, s30, v208
	global_load_dwordx4 v[8:11], v234, s[12:13]
	s_waitcnt vmcnt(15)
	v_readlane_b32 s20, v179, 10
	v_cvt_pk_f32_fp8_e32 v[216:217], v12
	v_cvt_pk_f32_fp8_sdwa v[218:219], v12 src0_sel:WORD_1
	v_cvt_pk_f32_fp8_e32 v[220:221], v13
	v_cvt_pk_f32_fp8_sdwa v[222:223], v13 src0_sel:WORD_1
	v_cvt_pk_f32_fp8_e32 v[224:225], v14
	v_cvt_pk_f32_fp8_sdwa v[226:227], v14 src0_sel:WORD_1
	v_cvt_pk_f32_fp8_e32 v[228:229], v15
	v_cvt_pk_f32_fp8_sdwa v[230:231], v15 src0_sel:WORD_1
	v_pk_fma_f32 v[80:81], s[26:27], v[216:217], v[80:81] op_sel_hi:[0,1,1]
	v_pk_fma_f32 v[82:83], s[26:27], v[218:219], v[82:83] op_sel_hi:[0,1,1]
	v_pk_fma_f32 v[84:85], s[26:27], v[220:221], v[84:85] op_sel_hi:[0,1,1]
	v_pk_fma_f32 v[86:87], s[26:27], v[222:223], v[86:87] op_sel_hi:[0,1,1]
	v_pk_fma_f32 v[88:89], s[26:27], v[224:225], v[88:89] op_sel_hi:[0,1,1]
	v_pk_fma_f32 v[90:91], s[26:27], v[226:227], v[90:91] op_sel_hi:[0,1,1]
	v_pk_fma_f32 v[92:93], s[26:27], v[228:229], v[92:93] op_sel_hi:[0,1,1]
	v_pk_fma_f32 v[94:95], s[26:27], v[230:231], v[94:95] op_sel_hi:[0,1,1]
	v_readlane_b32 s31, v181, 17
	s_lshl_b32 s31, s31, 10
	v_add_u32_e32 v235, s31, v208
	global_load_dwordx4 v[12:15], v235, s[12:13]
	s_waitcnt vmcnt(15)
	v_readlane_b32 s22, v183, 10
	v_cvt_pk_f32_fp8_e32 v[216:217], v16
	v_cvt_pk_f32_fp8_sdwa v[218:219], v16 src0_sel:WORD_1
	v_cvt_pk_f32_fp8_e32 v[220:221], v17
	v_cvt_pk_f32_fp8_sdwa v[222:223], v17 src0_sel:WORD_1
	v_cvt_pk_f32_fp8_e32 v[224:225], v18
	v_cvt_pk_f32_fp8_sdwa v[226:227], v18 src0_sel:WORD_1
	v_cvt_pk_f32_fp8_e32 v[228:229], v19
	v_cvt_pk_f32_fp8_sdwa v[230:231], v19 src0_sel:WORD_1
	v_pk_fma_f32 v[64:65], s[20:21], v[216:217], v[64:65] op_sel_hi:[0,1,1]
	v_pk_fma_f32 v[66:67], s[20:21], v[218:219], v[66:67] op_sel_hi:[0,1,1]
	v_pk_fma_f32 v[68:69], s[20:21], v[220:221], v[68:69] op_sel_hi:[0,1,1]
	v_pk_fma_f32 v[70:71], s[20:21], v[222:223], v[70:71] op_sel_hi:[0,1,1]
	v_pk_fma_f32 v[72:73], s[20:21], v[224:225], v[72:73] op_sel_hi:[0,1,1]
	v_pk_fma_f32 v[74:75], s[20:21], v[226:227], v[74:75] op_sel_hi:[0,1,1]
	v_pk_fma_f32 v[76:77], s[20:21], v[228:229], v[76:77] op_sel_hi:[0,1,1]
	v_pk_fma_f32 v[78:79], s[20:21], v[230:231], v[78:79] op_sel_hi:[0,1,1]
	v_readlane_b32 s28, v177, 18
	s_lshl_b32 s28, s28, 10
	v_add_u32_e32 v232, s28, v208
	global_load_dwordx4 v[16:19], v232, s[12:13]
	s_waitcnt vmcnt(15)
	v_readlane_b32 s24, v179, 11
	v_cvt_pk_f32_fp8_e32 v[216:217], v20
	v_cvt_pk_f32_fp8_sdwa v[218:219], v20 src0_sel:WORD_1
	v_cvt_pk_f32_fp8_e32 v[220:221], v21
	v_cvt_pk_f32_fp8_sdwa v[222:223], v21 src0_sel:WORD_1
	v_cvt_pk_f32_fp8_e32 v[224:225], v22
	v_cvt_pk_f32_fp8_sdwa v[226:227], v22 src0_sel:WORD_1
	v_cvt_pk_f32_fp8_e32 v[228:229], v23
	v_cvt_pk_f32_fp8_sdwa v[230:231], v23 src0_sel:WORD_1
	v_pk_fma_f32 v[80:81], s[22:23], v[216:217], v[80:81] op_sel_hi:[0,1,1]
	v_pk_fma_f32 v[82:83], s[22:23], v[218:219], v[82:83] op_sel_hi:[0,1,1]
	v_pk_fma_f32 v[84:85], s[22:23], v[220:221], v[84:85] op_sel_hi:[0,1,1]
	v_pk_fma_f32 v[86:87], s[22:23], v[222:223], v[86:87] op_sel_hi:[0,1,1]
	v_pk_fma_f32 v[88:89], s[22:23], v[224:225], v[88:89] op_sel_hi:[0,1,1]
	v_pk_fma_f32 v[90:91], s[22:23], v[226:227], v[90:91] op_sel_hi:[0,1,1]
	v_pk_fma_f32 v[92:93], s[22:23], v[228:229], v[92:93] op_sel_hi:[0,1,1]
	v_pk_fma_f32 v[94:95], s[22:23], v[230:231], v[94:95] op_sel_hi:[0,1,1]
	v_readlane_b32 s29, v181, 18
	s_lshl_b32 s29, s29, 10
	v_add_u32_e32 v233, s29, v208
	global_load_dwordx4 v[20:23], v233, s[12:13]
	s_waitcnt vmcnt(15)
	v_readlane_b32 s26, v183, 11
	v_cvt_pk_f32_fp8_e32 v[216:217], v24
	v_cvt_pk_f32_fp8_sdwa v[218:219], v24 src0_sel:WORD_1
	v_cvt_pk_f32_fp8_e32 v[220:221], v25
	v_cvt_pk_f32_fp8_sdwa v[222:223], v25 src0_sel:WORD_1
	v_cvt_pk_f32_fp8_e32 v[224:225], v26
	v_cvt_pk_f32_fp8_sdwa v[226:227], v26 src0_sel:WORD_1
	v_cvt_pk_f32_fp8_e32 v[228:229], v27
	v_cvt_pk_f32_fp8_sdwa v[230:231], v27 src0_sel:WORD_1
	v_pk_fma_f32 v[64:65], s[24:25], v[216:217], v[64:65] op_sel_hi:[0,1,1]
	v_pk_fma_f32 v[66:67], s[24:25], v[218:219], v[66:67] op_sel_hi:[0,1,1]
	v_pk_fma_f32 v[68:69], s[24:25], v[220:221], v[68:69] op_sel_hi:[0,1,1]
	v_pk_fma_f32 v[70:71], s[24:25], v[222:223], v[70:71] op_sel_hi:[0,1,1]
	v_pk_fma_f32 v[72:73], s[24:25], v[224:225], v[72:73] op_sel_hi:[0,1,1]
	v_pk_fma_f32 v[74:75], s[24:25], v[226:227], v[74:75] op_sel_hi:[0,1,1]
	v_pk_fma_f32 v[76:77], s[24:25], v[228:229], v[76:77] op_sel_hi:[0,1,1]
	v_pk_fma_f32 v[78:79], s[24:25], v[230:231], v[78:79] op_sel_hi:[0,1,1]
	v_readlane_b32 s30, v177, 19
	s_lshl_b32 s30, s30, 10
	v_add_u32_e32 v234, s30, v208
	global_load_dwordx4 v[24:27], v234, s[12:13]
	s_waitcnt vmcnt(15)
	v_readlane_b32 s20, v179, 12
	v_cvt_pk_f32_fp8_e32 v[216:217], v28
	v_cvt_pk_f32_fp8_sdwa v[218:219], v28 src0_sel:WORD_1
	v_cvt_pk_f32_fp8_e32 v[220:221], v29
	v_cvt_pk_f32_fp8_sdwa v[222:223], v29 src0_sel:WORD_1
	v_cvt_pk_f32_fp8_e32 v[224:225], v30
	v_cvt_pk_f32_fp8_sdwa v[226:227], v30 src0_sel:WORD_1
	v_cvt_pk_f32_fp8_e32 v[228:229], v31
	v_cvt_pk_f32_fp8_sdwa v[230:231], v31 src0_sel:WORD_1
	v_pk_fma_f32 v[80:81], s[26:27], v[216:217], v[80:81] op_sel_hi:[0,1,1]
	v_pk_fma_f32 v[82:83], s[26:27], v[218:219], v[82:83] op_sel_hi:[0,1,1]
	v_pk_fma_f32 v[84:85], s[26:27], v[220:221], v[84:85] op_sel_hi:[0,1,1]
	v_pk_fma_f32 v[86:87], s[26:27], v[222:223], v[86:87] op_sel_hi:[0,1,1]
	v_pk_fma_f32 v[88:89], s[26:27], v[224:225], v[88:89] op_sel_hi:[0,1,1]
	v_pk_fma_f32 v[90:91], s[26:27], v[226:227], v[90:91] op_sel_hi:[0,1,1]
	v_pk_fma_f32 v[92:93], s[26:27], v[228:229], v[92:93] op_sel_hi:[0,1,1]
	v_pk_fma_f32 v[94:95], s[26:27], v[230:231], v[94:95] op_sel_hi:[0,1,1]
	v_readlane_b32 s31, v181, 19
	s_lshl_b32 s31, s31, 10
	v_add_u32_e32 v235, s31, v208
	global_load_dwordx4 v[28:31], v235, s[12:13]
	s_waitcnt vmcnt(15)
	v_readlane_b32 s22, v183, 12
	v_cvt_pk_f32_fp8_e32 v[216:217], v32
	v_cvt_pk_f32_fp8_sdwa v[218:219], v32 src0_sel:WORD_1
	v_cvt_pk_f32_fp8_e32 v[220:221], v33
	v_cvt_pk_f32_fp8_sdwa v[222:223], v33 src0_sel:WORD_1
	v_cvt_pk_f32_fp8_e32 v[224:225], v34
	v_cvt_pk_f32_fp8_sdwa v[226:227], v34 src0_sel:WORD_1
	v_cvt_pk_f32_fp8_e32 v[228:229], v35
	v_cvt_pk_f32_fp8_sdwa v[230:231], v35 src0_sel:WORD_1
	v_pk_fma_f32 v[64:65], s[20:21], v[216:217], v[64:65] op_sel_hi:[0,1,1]
	v_pk_fma_f32 v[66:67], s[20:21], v[218:219], v[66:67] op_sel_hi:[0,1,1]
	v_pk_fma_f32 v[68:69], s[20:21], v[220:221], v[68:69] op_sel_hi:[0,1,1]
	v_pk_fma_f32 v[70:71], s[20:21], v[222:223], v[70:71] op_sel_hi:[0,1,1]
	v_pk_fma_f32 v[72:73], s[20:21], v[224:225], v[72:73] op_sel_hi:[0,1,1]
	v_pk_fma_f32 v[74:75], s[20:21], v[226:227], v[74:75] op_sel_hi:[0,1,1]
	v_pk_fma_f32 v[76:77], s[20:21], v[228:229], v[76:77] op_sel_hi:[0,1,1]
	v_pk_fma_f32 v[78:79], s[20:21], v[230:231], v[78:79] op_sel_hi:[0,1,1]
	v_readlane_b32 s28, v177, 20
	s_lshl_b32 s28, s28, 10
	v_add_u32_e32 v232, s28, v208
	global_load_dwordx4 v[32:35], v232, s[12:13]
	s_waitcnt vmcnt(15)
	v_readlane_b32 s24, v179, 13
	v_cvt_pk_f32_fp8_e32 v[216:217], v36
	v_cvt_pk_f32_fp8_sdwa v[218:219], v36 src0_sel:WORD_1
	v_cvt_pk_f32_fp8_e32 v[220:221], v37
	v_cvt_pk_f32_fp8_sdwa v[222:223], v37 src0_sel:WORD_1
	v_cvt_pk_f32_fp8_e32 v[224:225], v38
	v_cvt_pk_f32_fp8_sdwa v[226:227], v38 src0_sel:WORD_1
	v_cvt_pk_f32_fp8_e32 v[228:229], v39
	v_cvt_pk_f32_fp8_sdwa v[230:231], v39 src0_sel:WORD_1
	v_pk_fma_f32 v[80:81], s[22:23], v[216:217], v[80:81] op_sel_hi:[0,1,1]
	v_pk_fma_f32 v[82:83], s[22:23], v[218:219], v[82:83] op_sel_hi:[0,1,1]
	v_pk_fma_f32 v[84:85], s[22:23], v[220:221], v[84:85] op_sel_hi:[0,1,1]
	v_pk_fma_f32 v[86:87], s[22:23], v[222:223], v[86:87] op_sel_hi:[0,1,1]
	v_pk_fma_f32 v[88:89], s[22:23], v[224:225], v[88:89] op_sel_hi:[0,1,1]
	v_pk_fma_f32 v[90:91], s[22:23], v[226:227], v[90:91] op_sel_hi:[0,1,1]
	v_pk_fma_f32 v[92:93], s[22:23], v[228:229], v[92:93] op_sel_hi:[0,1,1]
	v_pk_fma_f32 v[94:95], s[22:23], v[230:231], v[94:95] op_sel_hi:[0,1,1]
	v_readlane_b32 s29, v181, 20
	s_lshl_b32 s29, s29, 10
	v_add_u32_e32 v233, s29, v208
	global_load_dwordx4 v[36:39], v233, s[12:13]
	s_waitcnt vmcnt(15)
	v_readlane_b32 s26, v183, 13
	v_cvt_pk_f32_fp8_e32 v[216:217], v40
	v_cvt_pk_f32_fp8_sdwa v[218:219], v40 src0_sel:WORD_1
	v_cvt_pk_f32_fp8_e32 v[220:221], v41
	v_cvt_pk_f32_fp8_sdwa v[222:223], v41 src0_sel:WORD_1
	v_cvt_pk_f32_fp8_e32 v[224:225], v42
	v_cvt_pk_f32_fp8_sdwa v[226:227], v42 src0_sel:WORD_1
	v_cvt_pk_f32_fp8_e32 v[228:229], v43
	v_cvt_pk_f32_fp8_sdwa v[230:231], v43 src0_sel:WORD_1
	v_pk_fma_f32 v[64:65], s[24:25], v[216:217], v[64:65] op_sel_hi:[0,1,1]
	v_pk_fma_f32 v[66:67], s[24:25], v[218:219], v[66:67] op_sel_hi:[0,1,1]
	v_pk_fma_f32 v[68:69], s[24:25], v[220:221], v[68:69] op_sel_hi:[0,1,1]
	v_pk_fma_f32 v[70:71], s[24:25], v[222:223], v[70:71] op_sel_hi:[0,1,1]
	v_pk_fma_f32 v[72:73], s[24:25], v[224:225], v[72:73] op_sel_hi:[0,1,1]
	v_pk_fma_f32 v[74:75], s[24:25], v[226:227], v[74:75] op_sel_hi:[0,1,1]
	v_pk_fma_f32 v[76:77], s[24:25], v[228:229], v[76:77] op_sel_hi:[0,1,1]
	v_pk_fma_f32 v[78:79], s[24:25], v[230:231], v[78:79] op_sel_hi:[0,1,1]
	v_readlane_b32 s30, v177, 21
	s_lshl_b32 s30, s30, 10
	v_add_u32_e32 v234, s30, v208
	global_load_dwordx4 v[40:43], v234, s[12:13]
	s_waitcnt vmcnt(15)
	v_readlane_b32 s20, v179, 14
	v_cvt_pk_f32_fp8_e32 v[216:217], v44
	v_cvt_pk_f32_fp8_sdwa v[218:219], v44 src0_sel:WORD_1
	v_cvt_pk_f32_fp8_e32 v[220:221], v45
	v_cvt_pk_f32_fp8_sdwa v[222:223], v45 src0_sel:WORD_1
	v_cvt_pk_f32_fp8_e32 v[224:225], v46
	v_cvt_pk_f32_fp8_sdwa v[226:227], v46 src0_sel:WORD_1
	v_cvt_pk_f32_fp8_e32 v[228:229], v47
	v_cvt_pk_f32_fp8_sdwa v[230:231], v47 src0_sel:WORD_1
	v_pk_fma_f32 v[80:81], s[26:27], v[216:217], v[80:81] op_sel_hi:[0,1,1]
	v_pk_fma_f32 v[82:83], s[26:27], v[218:219], v[82:83] op_sel_hi:[0,1,1]
	v_pk_fma_f32 v[84:85], s[26:27], v[220:221], v[84:85] op_sel_hi:[0,1,1]
	v_pk_fma_f32 v[86:87], s[26:27], v[222:223], v[86:87] op_sel_hi:[0,1,1]
	v_pk_fma_f32 v[88:89], s[26:27], v[224:225], v[88:89] op_sel_hi:[0,1,1]
	v_pk_fma_f32 v[90:91], s[26:27], v[226:227], v[90:91] op_sel_hi:[0,1,1]
	v_pk_fma_f32 v[92:93], s[26:27], v[228:229], v[92:93] op_sel_hi:[0,1,1]
	v_pk_fma_f32 v[94:95], s[26:27], v[230:231], v[94:95] op_sel_hi:[0,1,1]
	v_readlane_b32 s31, v181, 21
	s_lshl_b32 s31, s31, 10
	v_add_u32_e32 v235, s31, v208
	global_load_dwordx4 v[44:47], v235, s[12:13]
	s_waitcnt vmcnt(15)
	v_readlane_b32 s22, v183, 14
	v_cvt_pk_f32_fp8_e32 v[216:217], v48
	v_cvt_pk_f32_fp8_sdwa v[218:219], v48 src0_sel:WORD_1
	v_cvt_pk_f32_fp8_e32 v[220:221], v49
	v_cvt_pk_f32_fp8_sdwa v[222:223], v49 src0_sel:WORD_1
	v_cvt_pk_f32_fp8_e32 v[224:225], v50
	v_cvt_pk_f32_fp8_sdwa v[226:227], v50 src0_sel:WORD_1
	v_cvt_pk_f32_fp8_e32 v[228:229], v51
	v_cvt_pk_f32_fp8_sdwa v[230:231], v51 src0_sel:WORD_1
	v_pk_fma_f32 v[64:65], s[20:21], v[216:217], v[64:65] op_sel_hi:[0,1,1]
	v_pk_fma_f32 v[66:67], s[20:21], v[218:219], v[66:67] op_sel_hi:[0,1,1]
	v_pk_fma_f32 v[68:69], s[20:21], v[220:221], v[68:69] op_sel_hi:[0,1,1]
	v_pk_fma_f32 v[70:71], s[20:21], v[222:223], v[70:71] op_sel_hi:[0,1,1]
	v_pk_fma_f32 v[72:73], s[20:21], v[224:225], v[72:73] op_sel_hi:[0,1,1]
	v_pk_fma_f32 v[74:75], s[20:21], v[226:227], v[74:75] op_sel_hi:[0,1,1]
	v_pk_fma_f32 v[76:77], s[20:21], v[228:229], v[76:77] op_sel_hi:[0,1,1]
	v_pk_fma_f32 v[78:79], s[20:21], v[230:231], v[78:79] op_sel_hi:[0,1,1]
	v_readlane_b32 s28, v177, 22
	s_lshl_b32 s28, s28, 10
	v_add_u32_e32 v232, s28, v208
	global_load_dwordx4 v[48:51], v232, s[12:13]
	s_waitcnt vmcnt(15)
	v_readlane_b32 s24, v179, 15
	v_cvt_pk_f32_fp8_e32 v[216:217], v52
	v_cvt_pk_f32_fp8_sdwa v[218:219], v52 src0_sel:WORD_1
	v_cvt_pk_f32_fp8_e32 v[220:221], v53
	v_cvt_pk_f32_fp8_sdwa v[222:223], v53 src0_sel:WORD_1
	v_cvt_pk_f32_fp8_e32 v[224:225], v54
	v_cvt_pk_f32_fp8_sdwa v[226:227], v54 src0_sel:WORD_1
	v_cvt_pk_f32_fp8_e32 v[228:229], v55
	v_cvt_pk_f32_fp8_sdwa v[230:231], v55 src0_sel:WORD_1
	v_pk_fma_f32 v[80:81], s[22:23], v[216:217], v[80:81] op_sel_hi:[0,1,1]
	v_pk_fma_f32 v[82:83], s[22:23], v[218:219], v[82:83] op_sel_hi:[0,1,1]
	v_pk_fma_f32 v[84:85], s[22:23], v[220:221], v[84:85] op_sel_hi:[0,1,1]
	v_pk_fma_f32 v[86:87], s[22:23], v[222:223], v[86:87] op_sel_hi:[0,1,1]
	v_pk_fma_f32 v[88:89], s[22:23], v[224:225], v[88:89] op_sel_hi:[0,1,1]
	v_pk_fma_f32 v[90:91], s[22:23], v[226:227], v[90:91] op_sel_hi:[0,1,1]
	v_pk_fma_f32 v[92:93], s[22:23], v[228:229], v[92:93] op_sel_hi:[0,1,1]
	v_pk_fma_f32 v[94:95], s[22:23], v[230:231], v[94:95] op_sel_hi:[0,1,1]
	v_readlane_b32 s29, v181, 22
	s_lshl_b32 s29, s29, 10
	v_add_u32_e32 v233, s29, v208
	global_load_dwordx4 v[52:55], v233, s[12:13]
	s_waitcnt vmcnt(15)
	v_readlane_b32 s26, v183, 15
	v_cvt_pk_f32_fp8_e32 v[216:217], v56
	v_cvt_pk_f32_fp8_sdwa v[218:219], v56 src0_sel:WORD_1
	v_cvt_pk_f32_fp8_e32 v[220:221], v57
	v_cvt_pk_f32_fp8_sdwa v[222:223], v57 src0_sel:WORD_1
	v_cvt_pk_f32_fp8_e32 v[224:225], v58
	v_cvt_pk_f32_fp8_sdwa v[226:227], v58 src0_sel:WORD_1
	v_cvt_pk_f32_fp8_e32 v[228:229], v59
	v_cvt_pk_f32_fp8_sdwa v[230:231], v59 src0_sel:WORD_1
	v_pk_fma_f32 v[64:65], s[24:25], v[216:217], v[64:65] op_sel_hi:[0,1,1]
	v_pk_fma_f32 v[66:67], s[24:25], v[218:219], v[66:67] op_sel_hi:[0,1,1]
	v_pk_fma_f32 v[68:69], s[24:25], v[220:221], v[68:69] op_sel_hi:[0,1,1]
	v_pk_fma_f32 v[70:71], s[24:25], v[222:223], v[70:71] op_sel_hi:[0,1,1]
	v_pk_fma_f32 v[72:73], s[24:25], v[224:225], v[72:73] op_sel_hi:[0,1,1]
	v_pk_fma_f32 v[74:75], s[24:25], v[226:227], v[74:75] op_sel_hi:[0,1,1]
	v_pk_fma_f32 v[76:77], s[24:25], v[228:229], v[76:77] op_sel_hi:[0,1,1]
	v_pk_fma_f32 v[78:79], s[24:25], v[230:231], v[78:79] op_sel_hi:[0,1,1]
	v_readlane_b32 s30, v177, 23
	s_lshl_b32 s30, s30, 10
	v_add_u32_e32 v234, s30, v208
	global_load_dwordx4 v[56:59], v234, s[12:13]
	s_waitcnt vmcnt(15)
	v_readlane_b32 s20, v179, 16
	v_cvt_pk_f32_fp8_e32 v[216:217], v60
	v_cvt_pk_f32_fp8_sdwa v[218:219], v60 src0_sel:WORD_1
	v_cvt_pk_f32_fp8_e32 v[220:221], v61
	v_cvt_pk_f32_fp8_sdwa v[222:223], v61 src0_sel:WORD_1
	v_cvt_pk_f32_fp8_e32 v[224:225], v62
	v_cvt_pk_f32_fp8_sdwa v[226:227], v62 src0_sel:WORD_1
	v_cvt_pk_f32_fp8_e32 v[228:229], v63
	v_cvt_pk_f32_fp8_sdwa v[230:231], v63 src0_sel:WORD_1
	v_pk_fma_f32 v[80:81], s[26:27], v[216:217], v[80:81] op_sel_hi:[0,1,1]
	v_pk_fma_f32 v[82:83], s[26:27], v[218:219], v[82:83] op_sel_hi:[0,1,1]
	v_pk_fma_f32 v[84:85], s[26:27], v[220:221], v[84:85] op_sel_hi:[0,1,1]
	v_pk_fma_f32 v[86:87], s[26:27], v[222:223], v[86:87] op_sel_hi:[0,1,1]
	v_pk_fma_f32 v[88:89], s[26:27], v[224:225], v[88:89] op_sel_hi:[0,1,1]
	v_pk_fma_f32 v[90:91], s[26:27], v[226:227], v[90:91] op_sel_hi:[0,1,1]
	v_pk_fma_f32 v[92:93], s[26:27], v[228:229], v[92:93] op_sel_hi:[0,1,1]
	v_pk_fma_f32 v[94:95], s[26:27], v[230:231], v[94:95] op_sel_hi:[0,1,1]
	v_readlane_b32 s31, v181, 23
	s_lshl_b32 s31, s31, 10
	v_add_u32_e32 v235, s31, v208
	global_load_dwordx4 v[60:63], v235, s[12:13]
	s_waitcnt vmcnt(15)
	v_readlane_b32 s22, v183, 16
	v_cvt_pk_f32_fp8_e32 v[216:217], v0
	v_cvt_pk_f32_fp8_sdwa v[218:219], v0 src0_sel:WORD_1
	v_cvt_pk_f32_fp8_e32 v[220:221], v1
	v_cvt_pk_f32_fp8_sdwa v[222:223], v1 src0_sel:WORD_1
	v_cvt_pk_f32_fp8_e32 v[224:225], v2
	v_cvt_pk_f32_fp8_sdwa v[226:227], v2 src0_sel:WORD_1
	v_cvt_pk_f32_fp8_e32 v[228:229], v3
	v_cvt_pk_f32_fp8_sdwa v[230:231], v3 src0_sel:WORD_1
	v_pk_fma_f32 v[64:65], s[20:21], v[216:217], v[64:65] op_sel_hi:[0,1,1]
	v_pk_fma_f32 v[66:67], s[20:21], v[218:219], v[66:67] op_sel_hi:[0,1,1]
	v_pk_fma_f32 v[68:69], s[20:21], v[220:221], v[68:69] op_sel_hi:[0,1,1]
	v_pk_fma_f32 v[70:71], s[20:21], v[222:223], v[70:71] op_sel_hi:[0,1,1]
	v_pk_fma_f32 v[72:73], s[20:21], v[224:225], v[72:73] op_sel_hi:[0,1,1]
	v_pk_fma_f32 v[74:75], s[20:21], v[226:227], v[74:75] op_sel_hi:[0,1,1]
	v_pk_fma_f32 v[76:77], s[20:21], v[228:229], v[76:77] op_sel_hi:[0,1,1]
	v_pk_fma_f32 v[78:79], s[20:21], v[230:231], v[78:79] op_sel_hi:[0,1,1]
	v_readlane_b32 s28, v177, 24
	s_lshl_b32 s28, s28, 10
	v_add_u32_e32 v232, s28, v208
	global_load_dwordx4 v[0:3], v232, s[12:13]
	s_waitcnt vmcnt(15)
	v_readlane_b32 s24, v179, 17
	v_cvt_pk_f32_fp8_e32 v[216:217], v4
	v_cvt_pk_f32_fp8_sdwa v[218:219], v4 src0_sel:WORD_1
	v_cvt_pk_f32_fp8_e32 v[220:221], v5
	v_cvt_pk_f32_fp8_sdwa v[222:223], v5 src0_sel:WORD_1
	v_cvt_pk_f32_fp8_e32 v[224:225], v6
	v_cvt_pk_f32_fp8_sdwa v[226:227], v6 src0_sel:WORD_1
	v_cvt_pk_f32_fp8_e32 v[228:229], v7
	v_cvt_pk_f32_fp8_sdwa v[230:231], v7 src0_sel:WORD_1
	v_pk_fma_f32 v[80:81], s[22:23], v[216:217], v[80:81] op_sel_hi:[0,1,1]
	v_pk_fma_f32 v[82:83], s[22:23], v[218:219], v[82:83] op_sel_hi:[0,1,1]
	v_pk_fma_f32 v[84:85], s[22:23], v[220:221], v[84:85] op_sel_hi:[0,1,1]
	v_pk_fma_f32 v[86:87], s[22:23], v[222:223], v[86:87] op_sel_hi:[0,1,1]
	v_pk_fma_f32 v[88:89], s[22:23], v[224:225], v[88:89] op_sel_hi:[0,1,1]
	v_pk_fma_f32 v[90:91], s[22:23], v[226:227], v[90:91] op_sel_hi:[0,1,1]
	v_pk_fma_f32 v[92:93], s[22:23], v[228:229], v[92:93] op_sel_hi:[0,1,1]
	v_pk_fma_f32 v[94:95], s[22:23], v[230:231], v[94:95] op_sel_hi:[0,1,1]
	v_readlane_b32 s29, v181, 24
	s_lshl_b32 s29, s29, 10
	v_add_u32_e32 v233, s29, v208
	global_load_dwordx4 v[4:7], v233, s[12:13]
	s_waitcnt vmcnt(15)
	v_readlane_b32 s26, v183, 17
	v_cvt_pk_f32_fp8_e32 v[216:217], v8
	v_cvt_pk_f32_fp8_sdwa v[218:219], v8 src0_sel:WORD_1
	v_cvt_pk_f32_fp8_e32 v[220:221], v9
	v_cvt_pk_f32_fp8_sdwa v[222:223], v9 src0_sel:WORD_1
	v_cvt_pk_f32_fp8_e32 v[224:225], v10
	v_cvt_pk_f32_fp8_sdwa v[226:227], v10 src0_sel:WORD_1
	v_cvt_pk_f32_fp8_e32 v[228:229], v11
	v_cvt_pk_f32_fp8_sdwa v[230:231], v11 src0_sel:WORD_1
	v_pk_fma_f32 v[64:65], s[24:25], v[216:217], v[64:65] op_sel_hi:[0,1,1]
	v_pk_fma_f32 v[66:67], s[24:25], v[218:219], v[66:67] op_sel_hi:[0,1,1]
	v_pk_fma_f32 v[68:69], s[24:25], v[220:221], v[68:69] op_sel_hi:[0,1,1]
	v_pk_fma_f32 v[70:71], s[24:25], v[222:223], v[70:71] op_sel_hi:[0,1,1]
	v_pk_fma_f32 v[72:73], s[24:25], v[224:225], v[72:73] op_sel_hi:[0,1,1]
	v_pk_fma_f32 v[74:75], s[24:25], v[226:227], v[74:75] op_sel_hi:[0,1,1]
	v_pk_fma_f32 v[76:77], s[24:25], v[228:229], v[76:77] op_sel_hi:[0,1,1]
	v_pk_fma_f32 v[78:79], s[24:25], v[230:231], v[78:79] op_sel_hi:[0,1,1]
	v_readlane_b32 s30, v177, 25
	s_lshl_b32 s30, s30, 10
	v_add_u32_e32 v234, s30, v208
	global_load_dwordx4 v[8:11], v234, s[12:13]
	s_waitcnt vmcnt(15)
	v_readlane_b32 s20, v179, 18
	v_cvt_pk_f32_fp8_e32 v[216:217], v12
	v_cvt_pk_f32_fp8_sdwa v[218:219], v12 src0_sel:WORD_1
	v_cvt_pk_f32_fp8_e32 v[220:221], v13
	v_cvt_pk_f32_fp8_sdwa v[222:223], v13 src0_sel:WORD_1
	v_cvt_pk_f32_fp8_e32 v[224:225], v14
	v_cvt_pk_f32_fp8_sdwa v[226:227], v14 src0_sel:WORD_1
	v_cvt_pk_f32_fp8_e32 v[228:229], v15
	v_cvt_pk_f32_fp8_sdwa v[230:231], v15 src0_sel:WORD_1
	v_pk_fma_f32 v[80:81], s[26:27], v[216:217], v[80:81] op_sel_hi:[0,1,1]
	v_pk_fma_f32 v[82:83], s[26:27], v[218:219], v[82:83] op_sel_hi:[0,1,1]
	v_pk_fma_f32 v[84:85], s[26:27], v[220:221], v[84:85] op_sel_hi:[0,1,1]
	v_pk_fma_f32 v[86:87], s[26:27], v[222:223], v[86:87] op_sel_hi:[0,1,1]
	v_pk_fma_f32 v[88:89], s[26:27], v[224:225], v[88:89] op_sel_hi:[0,1,1]
	v_pk_fma_f32 v[90:91], s[26:27], v[226:227], v[90:91] op_sel_hi:[0,1,1]
	v_pk_fma_f32 v[92:93], s[26:27], v[228:229], v[92:93] op_sel_hi:[0,1,1]
	v_pk_fma_f32 v[94:95], s[26:27], v[230:231], v[94:95] op_sel_hi:[0,1,1]
	v_readlane_b32 s31, v181, 25
	s_lshl_b32 s31, s31, 10
	v_add_u32_e32 v235, s31, v208
	global_load_dwordx4 v[12:15], v235, s[12:13]
	s_waitcnt vmcnt(15)
	v_readlane_b32 s22, v183, 18
	v_cvt_pk_f32_fp8_e32 v[216:217], v16
	v_cvt_pk_f32_fp8_sdwa v[218:219], v16 src0_sel:WORD_1
	v_cvt_pk_f32_fp8_e32 v[220:221], v17
	v_cvt_pk_f32_fp8_sdwa v[222:223], v17 src0_sel:WORD_1
	v_cvt_pk_f32_fp8_e32 v[224:225], v18
	v_cvt_pk_f32_fp8_sdwa v[226:227], v18 src0_sel:WORD_1
	v_cvt_pk_f32_fp8_e32 v[228:229], v19
	v_cvt_pk_f32_fp8_sdwa v[230:231], v19 src0_sel:WORD_1
	v_pk_fma_f32 v[64:65], s[20:21], v[216:217], v[64:65] op_sel_hi:[0,1,1]
	v_pk_fma_f32 v[66:67], s[20:21], v[218:219], v[66:67] op_sel_hi:[0,1,1]
	v_pk_fma_f32 v[68:69], s[20:21], v[220:221], v[68:69] op_sel_hi:[0,1,1]
	v_pk_fma_f32 v[70:71], s[20:21], v[222:223], v[70:71] op_sel_hi:[0,1,1]
	v_pk_fma_f32 v[72:73], s[20:21], v[224:225], v[72:73] op_sel_hi:[0,1,1]
	v_pk_fma_f32 v[74:75], s[20:21], v[226:227], v[74:75] op_sel_hi:[0,1,1]
	v_pk_fma_f32 v[76:77], s[20:21], v[228:229], v[76:77] op_sel_hi:[0,1,1]
	v_pk_fma_f32 v[78:79], s[20:21], v[230:231], v[78:79] op_sel_hi:[0,1,1]
	v_readlane_b32 s28, v177, 26
	s_lshl_b32 s28, s28, 10
	v_add_u32_e32 v232, s28, v208
	global_load_dwordx4 v[16:19], v232, s[12:13]
	s_waitcnt vmcnt(15)
	v_readlane_b32 s24, v179, 19
	v_cvt_pk_f32_fp8_e32 v[216:217], v20
	v_cvt_pk_f32_fp8_sdwa v[218:219], v20 src0_sel:WORD_1
	v_cvt_pk_f32_fp8_e32 v[220:221], v21
	v_cvt_pk_f32_fp8_sdwa v[222:223], v21 src0_sel:WORD_1
	v_cvt_pk_f32_fp8_e32 v[224:225], v22
	v_cvt_pk_f32_fp8_sdwa v[226:227], v22 src0_sel:WORD_1
	v_cvt_pk_f32_fp8_e32 v[228:229], v23
	v_cvt_pk_f32_fp8_sdwa v[230:231], v23 src0_sel:WORD_1
	v_pk_fma_f32 v[80:81], s[22:23], v[216:217], v[80:81] op_sel_hi:[0,1,1]
	v_pk_fma_f32 v[82:83], s[22:23], v[218:219], v[82:83] op_sel_hi:[0,1,1]
	v_pk_fma_f32 v[84:85], s[22:23], v[220:221], v[84:85] op_sel_hi:[0,1,1]
	v_pk_fma_f32 v[86:87], s[22:23], v[222:223], v[86:87] op_sel_hi:[0,1,1]
	v_pk_fma_f32 v[88:89], s[22:23], v[224:225], v[88:89] op_sel_hi:[0,1,1]
	v_pk_fma_f32 v[90:91], s[22:23], v[226:227], v[90:91] op_sel_hi:[0,1,1]
	v_pk_fma_f32 v[92:93], s[22:23], v[228:229], v[92:93] op_sel_hi:[0,1,1]
	v_pk_fma_f32 v[94:95], s[22:23], v[230:231], v[94:95] op_sel_hi:[0,1,1]
	v_readlane_b32 s29, v181, 26
	s_lshl_b32 s29, s29, 10
	v_add_u32_e32 v233, s29, v208
	global_load_dwordx4 v[20:23], v233, s[12:13]
	s_waitcnt vmcnt(15)
	v_readlane_b32 s26, v183, 19
	v_cvt_pk_f32_fp8_e32 v[216:217], v24
	v_cvt_pk_f32_fp8_sdwa v[218:219], v24 src0_sel:WORD_1
	v_cvt_pk_f32_fp8_e32 v[220:221], v25
	v_cvt_pk_f32_fp8_sdwa v[222:223], v25 src0_sel:WORD_1
	v_cvt_pk_f32_fp8_e32 v[224:225], v26
	v_cvt_pk_f32_fp8_sdwa v[226:227], v26 src0_sel:WORD_1
	v_cvt_pk_f32_fp8_e32 v[228:229], v27
	v_cvt_pk_f32_fp8_sdwa v[230:231], v27 src0_sel:WORD_1
	v_pk_fma_f32 v[64:65], s[24:25], v[216:217], v[64:65] op_sel_hi:[0,1,1]
	v_pk_fma_f32 v[66:67], s[24:25], v[218:219], v[66:67] op_sel_hi:[0,1,1]
	v_pk_fma_f32 v[68:69], s[24:25], v[220:221], v[68:69] op_sel_hi:[0,1,1]
	v_pk_fma_f32 v[70:71], s[24:25], v[222:223], v[70:71] op_sel_hi:[0,1,1]
	v_pk_fma_f32 v[72:73], s[24:25], v[224:225], v[72:73] op_sel_hi:[0,1,1]
	v_pk_fma_f32 v[74:75], s[24:25], v[226:227], v[74:75] op_sel_hi:[0,1,1]
	v_pk_fma_f32 v[76:77], s[24:25], v[228:229], v[76:77] op_sel_hi:[0,1,1]
	v_pk_fma_f32 v[78:79], s[24:25], v[230:231], v[78:79] op_sel_hi:[0,1,1]
	v_readlane_b32 s30, v177, 27
	s_lshl_b32 s30, s30, 10
	v_add_u32_e32 v234, s30, v208
	global_load_dwordx4 v[24:27], v234, s[12:13]
	s_waitcnt vmcnt(15)
	v_readlane_b32 s20, v179, 20
	v_cvt_pk_f32_fp8_e32 v[216:217], v28
	v_cvt_pk_f32_fp8_sdwa v[218:219], v28 src0_sel:WORD_1
	v_cvt_pk_f32_fp8_e32 v[220:221], v29
	v_cvt_pk_f32_fp8_sdwa v[222:223], v29 src0_sel:WORD_1
	v_cvt_pk_f32_fp8_e32 v[224:225], v30
	v_cvt_pk_f32_fp8_sdwa v[226:227], v30 src0_sel:WORD_1
	v_cvt_pk_f32_fp8_e32 v[228:229], v31
	v_cvt_pk_f32_fp8_sdwa v[230:231], v31 src0_sel:WORD_1
	v_pk_fma_f32 v[80:81], s[26:27], v[216:217], v[80:81] op_sel_hi:[0,1,1]
	v_pk_fma_f32 v[82:83], s[26:27], v[218:219], v[82:83] op_sel_hi:[0,1,1]
	v_pk_fma_f32 v[84:85], s[26:27], v[220:221], v[84:85] op_sel_hi:[0,1,1]
	v_pk_fma_f32 v[86:87], s[26:27], v[222:223], v[86:87] op_sel_hi:[0,1,1]
	v_pk_fma_f32 v[88:89], s[26:27], v[224:225], v[88:89] op_sel_hi:[0,1,1]
	v_pk_fma_f32 v[90:91], s[26:27], v[226:227], v[90:91] op_sel_hi:[0,1,1]
	v_pk_fma_f32 v[92:93], s[26:27], v[228:229], v[92:93] op_sel_hi:[0,1,1]
	v_pk_fma_f32 v[94:95], s[26:27], v[230:231], v[94:95] op_sel_hi:[0,1,1]
	v_readlane_b32 s31, v181, 27
	s_lshl_b32 s31, s31, 10
	v_add_u32_e32 v235, s31, v208
	global_load_dwordx4 v[28:31], v235, s[12:13]
	s_waitcnt vmcnt(15)
	v_readlane_b32 s22, v183, 20
	v_cvt_pk_f32_fp8_e32 v[216:217], v32
	v_cvt_pk_f32_fp8_sdwa v[218:219], v32 src0_sel:WORD_1
	v_cvt_pk_f32_fp8_e32 v[220:221], v33
	v_cvt_pk_f32_fp8_sdwa v[222:223], v33 src0_sel:WORD_1
	v_cvt_pk_f32_fp8_e32 v[224:225], v34
	v_cvt_pk_f32_fp8_sdwa v[226:227], v34 src0_sel:WORD_1
	v_cvt_pk_f32_fp8_e32 v[228:229], v35
	v_cvt_pk_f32_fp8_sdwa v[230:231], v35 src0_sel:WORD_1
	v_pk_fma_f32 v[64:65], s[20:21], v[216:217], v[64:65] op_sel_hi:[0,1,1]
	v_pk_fma_f32 v[66:67], s[20:21], v[218:219], v[66:67] op_sel_hi:[0,1,1]
	v_pk_fma_f32 v[68:69], s[20:21], v[220:221], v[68:69] op_sel_hi:[0,1,1]
	v_pk_fma_f32 v[70:71], s[20:21], v[222:223], v[70:71] op_sel_hi:[0,1,1]
	v_pk_fma_f32 v[72:73], s[20:21], v[224:225], v[72:73] op_sel_hi:[0,1,1]
	v_pk_fma_f32 v[74:75], s[20:21], v[226:227], v[74:75] op_sel_hi:[0,1,1]
	v_pk_fma_f32 v[76:77], s[20:21], v[228:229], v[76:77] op_sel_hi:[0,1,1]
	v_pk_fma_f32 v[78:79], s[20:21], v[230:231], v[78:79] op_sel_hi:[0,1,1]
	v_readlane_b32 s28, v177, 28
	s_lshl_b32 s28, s28, 10
	v_add_u32_e32 v232, s28, v208
	global_load_dwordx4 v[32:35], v232, s[12:13]
	s_waitcnt vmcnt(15)
	v_readlane_b32 s24, v179, 21
	v_cvt_pk_f32_fp8_e32 v[216:217], v36
	v_cvt_pk_f32_fp8_sdwa v[218:219], v36 src0_sel:WORD_1
	v_cvt_pk_f32_fp8_e32 v[220:221], v37
	v_cvt_pk_f32_fp8_sdwa v[222:223], v37 src0_sel:WORD_1
	v_cvt_pk_f32_fp8_e32 v[224:225], v38
	v_cvt_pk_f32_fp8_sdwa v[226:227], v38 src0_sel:WORD_1
	v_cvt_pk_f32_fp8_e32 v[228:229], v39
	v_cvt_pk_f32_fp8_sdwa v[230:231], v39 src0_sel:WORD_1
	v_pk_fma_f32 v[80:81], s[22:23], v[216:217], v[80:81] op_sel_hi:[0,1,1]
	v_pk_fma_f32 v[82:83], s[22:23], v[218:219], v[82:83] op_sel_hi:[0,1,1]
	v_pk_fma_f32 v[84:85], s[22:23], v[220:221], v[84:85] op_sel_hi:[0,1,1]
	v_pk_fma_f32 v[86:87], s[22:23], v[222:223], v[86:87] op_sel_hi:[0,1,1]
	v_pk_fma_f32 v[88:89], s[22:23], v[224:225], v[88:89] op_sel_hi:[0,1,1]
	v_pk_fma_f32 v[90:91], s[22:23], v[226:227], v[90:91] op_sel_hi:[0,1,1]
	v_pk_fma_f32 v[92:93], s[22:23], v[228:229], v[92:93] op_sel_hi:[0,1,1]
	v_pk_fma_f32 v[94:95], s[22:23], v[230:231], v[94:95] op_sel_hi:[0,1,1]
	v_readlane_b32 s29, v181, 28
	s_lshl_b32 s29, s29, 10
	v_add_u32_e32 v233, s29, v208
	global_load_dwordx4 v[36:39], v233, s[12:13]
	s_waitcnt vmcnt(15)
	v_readlane_b32 s26, v183, 21
	v_cvt_pk_f32_fp8_e32 v[216:217], v40
	v_cvt_pk_f32_fp8_sdwa v[218:219], v40 src0_sel:WORD_1
	v_cvt_pk_f32_fp8_e32 v[220:221], v41
	v_cvt_pk_f32_fp8_sdwa v[222:223], v41 src0_sel:WORD_1
	v_cvt_pk_f32_fp8_e32 v[224:225], v42
	v_cvt_pk_f32_fp8_sdwa v[226:227], v42 src0_sel:WORD_1
	v_cvt_pk_f32_fp8_e32 v[228:229], v43
	v_cvt_pk_f32_fp8_sdwa v[230:231], v43 src0_sel:WORD_1
	v_pk_fma_f32 v[64:65], s[24:25], v[216:217], v[64:65] op_sel_hi:[0,1,1]
	v_pk_fma_f32 v[66:67], s[24:25], v[218:219], v[66:67] op_sel_hi:[0,1,1]
	v_pk_fma_f32 v[68:69], s[24:25], v[220:221], v[68:69] op_sel_hi:[0,1,1]
	v_pk_fma_f32 v[70:71], s[24:25], v[222:223], v[70:71] op_sel_hi:[0,1,1]
	v_pk_fma_f32 v[72:73], s[24:25], v[224:225], v[72:73] op_sel_hi:[0,1,1]
	v_pk_fma_f32 v[74:75], s[24:25], v[226:227], v[74:75] op_sel_hi:[0,1,1]
	v_pk_fma_f32 v[76:77], s[24:25], v[228:229], v[76:77] op_sel_hi:[0,1,1]
	v_pk_fma_f32 v[78:79], s[24:25], v[230:231], v[78:79] op_sel_hi:[0,1,1]
	v_readlane_b32 s30, v177, 29
	s_lshl_b32 s30, s30, 10
	v_add_u32_e32 v234, s30, v208
	global_load_dwordx4 v[40:43], v234, s[12:13]
	s_waitcnt vmcnt(15)
	v_readlane_b32 s20, v179, 22
	v_cvt_pk_f32_fp8_e32 v[216:217], v44
	v_cvt_pk_f32_fp8_sdwa v[218:219], v44 src0_sel:WORD_1
	v_cvt_pk_f32_fp8_e32 v[220:221], v45
	v_cvt_pk_f32_fp8_sdwa v[222:223], v45 src0_sel:WORD_1
	v_cvt_pk_f32_fp8_e32 v[224:225], v46
	v_cvt_pk_f32_fp8_sdwa v[226:227], v46 src0_sel:WORD_1
	v_cvt_pk_f32_fp8_e32 v[228:229], v47
	v_cvt_pk_f32_fp8_sdwa v[230:231], v47 src0_sel:WORD_1
	v_pk_fma_f32 v[80:81], s[26:27], v[216:217], v[80:81] op_sel_hi:[0,1,1]
	v_pk_fma_f32 v[82:83], s[26:27], v[218:219], v[82:83] op_sel_hi:[0,1,1]
	v_pk_fma_f32 v[84:85], s[26:27], v[220:221], v[84:85] op_sel_hi:[0,1,1]
	v_pk_fma_f32 v[86:87], s[26:27], v[222:223], v[86:87] op_sel_hi:[0,1,1]
	v_pk_fma_f32 v[88:89], s[26:27], v[224:225], v[88:89] op_sel_hi:[0,1,1]
	v_pk_fma_f32 v[90:91], s[26:27], v[226:227], v[90:91] op_sel_hi:[0,1,1]
	v_pk_fma_f32 v[92:93], s[26:27], v[228:229], v[92:93] op_sel_hi:[0,1,1]
	v_pk_fma_f32 v[94:95], s[26:27], v[230:231], v[94:95] op_sel_hi:[0,1,1]
	v_readlane_b32 s31, v181, 29
	s_lshl_b32 s31, s31, 10
	v_add_u32_e32 v235, s31, v208
	global_load_dwordx4 v[44:47], v235, s[12:13]
	s_waitcnt vmcnt(15)
	v_readlane_b32 s22, v183, 22
	v_cvt_pk_f32_fp8_e32 v[216:217], v48
	v_cvt_pk_f32_fp8_sdwa v[218:219], v48 src0_sel:WORD_1
	v_cvt_pk_f32_fp8_e32 v[220:221], v49
	v_cvt_pk_f32_fp8_sdwa v[222:223], v49 src0_sel:WORD_1
	v_cvt_pk_f32_fp8_e32 v[224:225], v50
	v_cvt_pk_f32_fp8_sdwa v[226:227], v50 src0_sel:WORD_1
	v_cvt_pk_f32_fp8_e32 v[228:229], v51
	v_cvt_pk_f32_fp8_sdwa v[230:231], v51 src0_sel:WORD_1
	v_pk_fma_f32 v[64:65], s[20:21], v[216:217], v[64:65] op_sel_hi:[0,1,1]
	v_pk_fma_f32 v[66:67], s[20:21], v[218:219], v[66:67] op_sel_hi:[0,1,1]
	v_pk_fma_f32 v[68:69], s[20:21], v[220:221], v[68:69] op_sel_hi:[0,1,1]
	v_pk_fma_f32 v[70:71], s[20:21], v[222:223], v[70:71] op_sel_hi:[0,1,1]
	v_pk_fma_f32 v[72:73], s[20:21], v[224:225], v[72:73] op_sel_hi:[0,1,1]
	v_pk_fma_f32 v[74:75], s[20:21], v[226:227], v[74:75] op_sel_hi:[0,1,1]
	v_pk_fma_f32 v[76:77], s[20:21], v[228:229], v[76:77] op_sel_hi:[0,1,1]
	v_pk_fma_f32 v[78:79], s[20:21], v[230:231], v[78:79] op_sel_hi:[0,1,1]
	v_readlane_b32 s28, v177, 30
	s_lshl_b32 s28, s28, 10
	v_add_u32_e32 v232, s28, v208
	global_load_dwordx4 v[48:51], v232, s[12:13]
	s_waitcnt vmcnt(15)
	v_readlane_b32 s24, v179, 23
	v_cvt_pk_f32_fp8_e32 v[216:217], v52
	v_cvt_pk_f32_fp8_sdwa v[218:219], v52 src0_sel:WORD_1
	v_cvt_pk_f32_fp8_e32 v[220:221], v53
	v_cvt_pk_f32_fp8_sdwa v[222:223], v53 src0_sel:WORD_1
	v_cvt_pk_f32_fp8_e32 v[224:225], v54
	v_cvt_pk_f32_fp8_sdwa v[226:227], v54 src0_sel:WORD_1
	v_cvt_pk_f32_fp8_e32 v[228:229], v55
	v_cvt_pk_f32_fp8_sdwa v[230:231], v55 src0_sel:WORD_1
	v_pk_fma_f32 v[80:81], s[22:23], v[216:217], v[80:81] op_sel_hi:[0,1,1]
	v_pk_fma_f32 v[82:83], s[22:23], v[218:219], v[82:83] op_sel_hi:[0,1,1]
	v_pk_fma_f32 v[84:85], s[22:23], v[220:221], v[84:85] op_sel_hi:[0,1,1]
	v_pk_fma_f32 v[86:87], s[22:23], v[222:223], v[86:87] op_sel_hi:[0,1,1]
	v_pk_fma_f32 v[88:89], s[22:23], v[224:225], v[88:89] op_sel_hi:[0,1,1]
	v_pk_fma_f32 v[90:91], s[22:23], v[226:227], v[90:91] op_sel_hi:[0,1,1]
	v_pk_fma_f32 v[92:93], s[22:23], v[228:229], v[92:93] op_sel_hi:[0,1,1]
	v_pk_fma_f32 v[94:95], s[22:23], v[230:231], v[94:95] op_sel_hi:[0,1,1]
	v_readlane_b32 s29, v181, 30
	s_lshl_b32 s29, s29, 10
	v_add_u32_e32 v233, s29, v208
	global_load_dwordx4 v[52:55], v233, s[12:13]
	s_waitcnt vmcnt(15)
	v_readlane_b32 s26, v183, 23
	v_cvt_pk_f32_fp8_e32 v[216:217], v56
	v_cvt_pk_f32_fp8_sdwa v[218:219], v56 src0_sel:WORD_1
	v_cvt_pk_f32_fp8_e32 v[220:221], v57
	v_cvt_pk_f32_fp8_sdwa v[222:223], v57 src0_sel:WORD_1
	v_cvt_pk_f32_fp8_e32 v[224:225], v58
	v_cvt_pk_f32_fp8_sdwa v[226:227], v58 src0_sel:WORD_1
	v_cvt_pk_f32_fp8_e32 v[228:229], v59
	v_cvt_pk_f32_fp8_sdwa v[230:231], v59 src0_sel:WORD_1
	v_pk_fma_f32 v[64:65], s[24:25], v[216:217], v[64:65] op_sel_hi:[0,1,1]
	v_pk_fma_f32 v[66:67], s[24:25], v[218:219], v[66:67] op_sel_hi:[0,1,1]
	v_pk_fma_f32 v[68:69], s[24:25], v[220:221], v[68:69] op_sel_hi:[0,1,1]
	v_pk_fma_f32 v[70:71], s[24:25], v[222:223], v[70:71] op_sel_hi:[0,1,1]
	v_pk_fma_f32 v[72:73], s[24:25], v[224:225], v[72:73] op_sel_hi:[0,1,1]
	v_pk_fma_f32 v[74:75], s[24:25], v[226:227], v[74:75] op_sel_hi:[0,1,1]
	v_pk_fma_f32 v[76:77], s[24:25], v[228:229], v[76:77] op_sel_hi:[0,1,1]
	v_pk_fma_f32 v[78:79], s[24:25], v[230:231], v[78:79] op_sel_hi:[0,1,1]
	v_readlane_b32 s30, v177, 31
	s_lshl_b32 s30, s30, 10
	v_add_u32_e32 v234, s30, v208
	global_load_dwordx4 v[56:59], v234, s[12:13]
	s_waitcnt vmcnt(15)
	v_readlane_b32 s20, v179, 24
	v_cvt_pk_f32_fp8_e32 v[216:217], v60
	v_cvt_pk_f32_fp8_sdwa v[218:219], v60 src0_sel:WORD_1
	v_cvt_pk_f32_fp8_e32 v[220:221], v61
	v_cvt_pk_f32_fp8_sdwa v[222:223], v61 src0_sel:WORD_1
	v_cvt_pk_f32_fp8_e32 v[224:225], v62
	v_cvt_pk_f32_fp8_sdwa v[226:227], v62 src0_sel:WORD_1
	v_cvt_pk_f32_fp8_e32 v[228:229], v63
	v_cvt_pk_f32_fp8_sdwa v[230:231], v63 src0_sel:WORD_1
	v_pk_fma_f32 v[80:81], s[26:27], v[216:217], v[80:81] op_sel_hi:[0,1,1]
	v_pk_fma_f32 v[82:83], s[26:27], v[218:219], v[82:83] op_sel_hi:[0,1,1]
	v_pk_fma_f32 v[84:85], s[26:27], v[220:221], v[84:85] op_sel_hi:[0,1,1]
	v_pk_fma_f32 v[86:87], s[26:27], v[222:223], v[86:87] op_sel_hi:[0,1,1]
	v_pk_fma_f32 v[88:89], s[26:27], v[224:225], v[88:89] op_sel_hi:[0,1,1]
	v_pk_fma_f32 v[90:91], s[26:27], v[226:227], v[90:91] op_sel_hi:[0,1,1]
	v_pk_fma_f32 v[92:93], s[26:27], v[228:229], v[92:93] op_sel_hi:[0,1,1]
	v_pk_fma_f32 v[94:95], s[26:27], v[230:231], v[94:95] op_sel_hi:[0,1,1]
	v_readlane_b32 s31, v181, 31
	s_lshl_b32 s31, s31, 10
	v_add_u32_e32 v235, s31, v208
	global_load_dwordx4 v[60:63], v235, s[12:13]
	s_waitcnt vmcnt(15)
	v_readlane_b32 s22, v183, 24
	v_cvt_pk_f32_fp8_e32 v[216:217], v0
	v_cvt_pk_f32_fp8_sdwa v[218:219], v0 src0_sel:WORD_1
	v_cvt_pk_f32_fp8_e32 v[220:221], v1
	v_cvt_pk_f32_fp8_sdwa v[222:223], v1 src0_sel:WORD_1
	v_cvt_pk_f32_fp8_e32 v[224:225], v2
	v_cvt_pk_f32_fp8_sdwa v[226:227], v2 src0_sel:WORD_1
	v_cvt_pk_f32_fp8_e32 v[228:229], v3
	v_cvt_pk_f32_fp8_sdwa v[230:231], v3 src0_sel:WORD_1
	v_pk_fma_f32 v[64:65], s[20:21], v[216:217], v[64:65] op_sel_hi:[0,1,1]
	v_pk_fma_f32 v[66:67], s[20:21], v[218:219], v[66:67] op_sel_hi:[0,1,1]
	v_pk_fma_f32 v[68:69], s[20:21], v[220:221], v[68:69] op_sel_hi:[0,1,1]
	v_pk_fma_f32 v[70:71], s[20:21], v[222:223], v[70:71] op_sel_hi:[0,1,1]
	v_pk_fma_f32 v[72:73], s[20:21], v[224:225], v[72:73] op_sel_hi:[0,1,1]
	v_pk_fma_f32 v[74:75], s[20:21], v[226:227], v[74:75] op_sel_hi:[0,1,1]
	v_pk_fma_f32 v[76:77], s[20:21], v[228:229], v[76:77] op_sel_hi:[0,1,1]
	v_pk_fma_f32 v[78:79], s[20:21], v[230:231], v[78:79] op_sel_hi:[0,1,1]
	v_readlane_b32 s28, v177, 32
	s_lshl_b32 s28, s28, 10
	v_add_u32_e32 v232, s28, v208
	global_load_dwordx4 v[0:3], v232, s[12:13]
	s_waitcnt vmcnt(15)
	v_readlane_b32 s24, v179, 25
	v_cvt_pk_f32_fp8_e32 v[216:217], v4
	v_cvt_pk_f32_fp8_sdwa v[218:219], v4 src0_sel:WORD_1
	v_cvt_pk_f32_fp8_e32 v[220:221], v5
	v_cvt_pk_f32_fp8_sdwa v[222:223], v5 src0_sel:WORD_1
	v_cvt_pk_f32_fp8_e32 v[224:225], v6
	v_cvt_pk_f32_fp8_sdwa v[226:227], v6 src0_sel:WORD_1
	v_cvt_pk_f32_fp8_e32 v[228:229], v7
	v_cvt_pk_f32_fp8_sdwa v[230:231], v7 src0_sel:WORD_1
	v_pk_fma_f32 v[80:81], s[22:23], v[216:217], v[80:81] op_sel_hi:[0,1,1]
	v_pk_fma_f32 v[82:83], s[22:23], v[218:219], v[82:83] op_sel_hi:[0,1,1]
	v_pk_fma_f32 v[84:85], s[22:23], v[220:221], v[84:85] op_sel_hi:[0,1,1]
	v_pk_fma_f32 v[86:87], s[22:23], v[222:223], v[86:87] op_sel_hi:[0,1,1]
	v_pk_fma_f32 v[88:89], s[22:23], v[224:225], v[88:89] op_sel_hi:[0,1,1]
	v_pk_fma_f32 v[90:91], s[22:23], v[226:227], v[90:91] op_sel_hi:[0,1,1]
	v_pk_fma_f32 v[92:93], s[22:23], v[228:229], v[92:93] op_sel_hi:[0,1,1]
	v_pk_fma_f32 v[94:95], s[22:23], v[230:231], v[94:95] op_sel_hi:[0,1,1]
	v_readlane_b32 s29, v181, 32
	s_lshl_b32 s29, s29, 10
	v_add_u32_e32 v233, s29, v208
	global_load_dwordx4 v[4:7], v233, s[12:13]
	s_waitcnt vmcnt(15)
	v_readlane_b32 s26, v183, 25
	v_cvt_pk_f32_fp8_e32 v[216:217], v8
	v_cvt_pk_f32_fp8_sdwa v[218:219], v8 src0_sel:WORD_1
	v_cvt_pk_f32_fp8_e32 v[220:221], v9
	v_cvt_pk_f32_fp8_sdwa v[222:223], v9 src0_sel:WORD_1
	v_cvt_pk_f32_fp8_e32 v[224:225], v10
	v_cvt_pk_f32_fp8_sdwa v[226:227], v10 src0_sel:WORD_1
	v_cvt_pk_f32_fp8_e32 v[228:229], v11
	v_cvt_pk_f32_fp8_sdwa v[230:231], v11 src0_sel:WORD_1
	v_pk_fma_f32 v[64:65], s[24:25], v[216:217], v[64:65] op_sel_hi:[0,1,1]
	v_pk_fma_f32 v[66:67], s[24:25], v[218:219], v[66:67] op_sel_hi:[0,1,1]
	v_pk_fma_f32 v[68:69], s[24:25], v[220:221], v[68:69] op_sel_hi:[0,1,1]
	v_pk_fma_f32 v[70:71], s[24:25], v[222:223], v[70:71] op_sel_hi:[0,1,1]
	v_pk_fma_f32 v[72:73], s[24:25], v[224:225], v[72:73] op_sel_hi:[0,1,1]
	v_pk_fma_f32 v[74:75], s[24:25], v[226:227], v[74:75] op_sel_hi:[0,1,1]
	v_pk_fma_f32 v[76:77], s[24:25], v[228:229], v[76:77] op_sel_hi:[0,1,1]
	v_pk_fma_f32 v[78:79], s[24:25], v[230:231], v[78:79] op_sel_hi:[0,1,1]
	v_readlane_b32 s30, v177, 33
	s_lshl_b32 s30, s30, 10
	v_add_u32_e32 v234, s30, v208
	global_load_dwordx4 v[8:11], v234, s[12:13]
	s_waitcnt vmcnt(15)
	v_readlane_b32 s20, v179, 26
	v_cvt_pk_f32_fp8_e32 v[216:217], v12
	v_cvt_pk_f32_fp8_sdwa v[218:219], v12 src0_sel:WORD_1
	v_cvt_pk_f32_fp8_e32 v[220:221], v13
	v_cvt_pk_f32_fp8_sdwa v[222:223], v13 src0_sel:WORD_1
	v_cvt_pk_f32_fp8_e32 v[224:225], v14
	v_cvt_pk_f32_fp8_sdwa v[226:227], v14 src0_sel:WORD_1
	v_cvt_pk_f32_fp8_e32 v[228:229], v15
	v_cvt_pk_f32_fp8_sdwa v[230:231], v15 src0_sel:WORD_1
	v_pk_fma_f32 v[80:81], s[26:27], v[216:217], v[80:81] op_sel_hi:[0,1,1]
	v_pk_fma_f32 v[82:83], s[26:27], v[218:219], v[82:83] op_sel_hi:[0,1,1]
	v_pk_fma_f32 v[84:85], s[26:27], v[220:221], v[84:85] op_sel_hi:[0,1,1]
	v_pk_fma_f32 v[86:87], s[26:27], v[222:223], v[86:87] op_sel_hi:[0,1,1]
	v_pk_fma_f32 v[88:89], s[26:27], v[224:225], v[88:89] op_sel_hi:[0,1,1]
	v_pk_fma_f32 v[90:91], s[26:27], v[226:227], v[90:91] op_sel_hi:[0,1,1]
	v_pk_fma_f32 v[92:93], s[26:27], v[228:229], v[92:93] op_sel_hi:[0,1,1]
	v_pk_fma_f32 v[94:95], s[26:27], v[230:231], v[94:95] op_sel_hi:[0,1,1]
	v_readlane_b32 s31, v181, 33
	s_lshl_b32 s31, s31, 10
	v_add_u32_e32 v235, s31, v208
	global_load_dwordx4 v[12:15], v235, s[12:13]
	s_waitcnt vmcnt(15)
	v_readlane_b32 s22, v183, 26
	v_cvt_pk_f32_fp8_e32 v[216:217], v16
	v_cvt_pk_f32_fp8_sdwa v[218:219], v16 src0_sel:WORD_1
	v_cvt_pk_f32_fp8_e32 v[220:221], v17
	v_cvt_pk_f32_fp8_sdwa v[222:223], v17 src0_sel:WORD_1
	v_cvt_pk_f32_fp8_e32 v[224:225], v18
	v_cvt_pk_f32_fp8_sdwa v[226:227], v18 src0_sel:WORD_1
	v_cvt_pk_f32_fp8_e32 v[228:229], v19
	v_cvt_pk_f32_fp8_sdwa v[230:231], v19 src0_sel:WORD_1
	v_pk_fma_f32 v[64:65], s[20:21], v[216:217], v[64:65] op_sel_hi:[0,1,1]
	v_pk_fma_f32 v[66:67], s[20:21], v[218:219], v[66:67] op_sel_hi:[0,1,1]
	v_pk_fma_f32 v[68:69], s[20:21], v[220:221], v[68:69] op_sel_hi:[0,1,1]
	v_pk_fma_f32 v[70:71], s[20:21], v[222:223], v[70:71] op_sel_hi:[0,1,1]
	v_pk_fma_f32 v[72:73], s[20:21], v[224:225], v[72:73] op_sel_hi:[0,1,1]
	v_pk_fma_f32 v[74:75], s[20:21], v[226:227], v[74:75] op_sel_hi:[0,1,1]
	v_pk_fma_f32 v[76:77], s[20:21], v[228:229], v[76:77] op_sel_hi:[0,1,1]
	v_pk_fma_f32 v[78:79], s[20:21], v[230:231], v[78:79] op_sel_hi:[0,1,1]
	v_readlane_b32 s28, v177, 34
	s_lshl_b32 s28, s28, 10
	v_add_u32_e32 v232, s28, v208
	global_load_dwordx4 v[16:19], v232, s[12:13]
	s_waitcnt vmcnt(15)
	v_readlane_b32 s24, v179, 27
	v_cvt_pk_f32_fp8_e32 v[216:217], v20
	v_cvt_pk_f32_fp8_sdwa v[218:219], v20 src0_sel:WORD_1
	v_cvt_pk_f32_fp8_e32 v[220:221], v21
	v_cvt_pk_f32_fp8_sdwa v[222:223], v21 src0_sel:WORD_1
	v_cvt_pk_f32_fp8_e32 v[224:225], v22
	v_cvt_pk_f32_fp8_sdwa v[226:227], v22 src0_sel:WORD_1
	v_cvt_pk_f32_fp8_e32 v[228:229], v23
	v_cvt_pk_f32_fp8_sdwa v[230:231], v23 src0_sel:WORD_1
	v_pk_fma_f32 v[80:81], s[22:23], v[216:217], v[80:81] op_sel_hi:[0,1,1]
	v_pk_fma_f32 v[82:83], s[22:23], v[218:219], v[82:83] op_sel_hi:[0,1,1]
	v_pk_fma_f32 v[84:85], s[22:23], v[220:221], v[84:85] op_sel_hi:[0,1,1]
	v_pk_fma_f32 v[86:87], s[22:23], v[222:223], v[86:87] op_sel_hi:[0,1,1]
	v_pk_fma_f32 v[88:89], s[22:23], v[224:225], v[88:89] op_sel_hi:[0,1,1]
	v_pk_fma_f32 v[90:91], s[22:23], v[226:227], v[90:91] op_sel_hi:[0,1,1]
	v_pk_fma_f32 v[92:93], s[22:23], v[228:229], v[92:93] op_sel_hi:[0,1,1]
	v_pk_fma_f32 v[94:95], s[22:23], v[230:231], v[94:95] op_sel_hi:[0,1,1]
	v_readlane_b32 s29, v181, 34
	s_lshl_b32 s29, s29, 10
	v_add_u32_e32 v233, s29, v208
	global_load_dwordx4 v[20:23], v233, s[12:13]
	s_waitcnt vmcnt(15)
	v_readlane_b32 s26, v183, 27
	v_cvt_pk_f32_fp8_e32 v[216:217], v24
	v_cvt_pk_f32_fp8_sdwa v[218:219], v24 src0_sel:WORD_1
	v_cvt_pk_f32_fp8_e32 v[220:221], v25
	v_cvt_pk_f32_fp8_sdwa v[222:223], v25 src0_sel:WORD_1
	v_cvt_pk_f32_fp8_e32 v[224:225], v26
	v_cvt_pk_f32_fp8_sdwa v[226:227], v26 src0_sel:WORD_1
	v_cvt_pk_f32_fp8_e32 v[228:229], v27
	v_cvt_pk_f32_fp8_sdwa v[230:231], v27 src0_sel:WORD_1
	v_pk_fma_f32 v[64:65], s[24:25], v[216:217], v[64:65] op_sel_hi:[0,1,1]
	v_pk_fma_f32 v[66:67], s[24:25], v[218:219], v[66:67] op_sel_hi:[0,1,1]
	v_pk_fma_f32 v[68:69], s[24:25], v[220:221], v[68:69] op_sel_hi:[0,1,1]
	v_pk_fma_f32 v[70:71], s[24:25], v[222:223], v[70:71] op_sel_hi:[0,1,1]
	v_pk_fma_f32 v[72:73], s[24:25], v[224:225], v[72:73] op_sel_hi:[0,1,1]
	v_pk_fma_f32 v[74:75], s[24:25], v[226:227], v[74:75] op_sel_hi:[0,1,1]
	v_pk_fma_f32 v[76:77], s[24:25], v[228:229], v[76:77] op_sel_hi:[0,1,1]
	v_pk_fma_f32 v[78:79], s[24:25], v[230:231], v[78:79] op_sel_hi:[0,1,1]
	v_readlane_b32 s30, v177, 35
	s_lshl_b32 s30, s30, 10
	v_add_u32_e32 v234, s30, v208
	global_load_dwordx4 v[24:27], v234, s[12:13]
	s_waitcnt vmcnt(15)
	v_readlane_b32 s20, v179, 28
	v_cvt_pk_f32_fp8_e32 v[216:217], v28
	v_cvt_pk_f32_fp8_sdwa v[218:219], v28 src0_sel:WORD_1
	v_cvt_pk_f32_fp8_e32 v[220:221], v29
	v_cvt_pk_f32_fp8_sdwa v[222:223], v29 src0_sel:WORD_1
	v_cvt_pk_f32_fp8_e32 v[224:225], v30
	v_cvt_pk_f32_fp8_sdwa v[226:227], v30 src0_sel:WORD_1
	v_cvt_pk_f32_fp8_e32 v[228:229], v31
	v_cvt_pk_f32_fp8_sdwa v[230:231], v31 src0_sel:WORD_1
	v_pk_fma_f32 v[80:81], s[26:27], v[216:217], v[80:81] op_sel_hi:[0,1,1]
	v_pk_fma_f32 v[82:83], s[26:27], v[218:219], v[82:83] op_sel_hi:[0,1,1]
	v_pk_fma_f32 v[84:85], s[26:27], v[220:221], v[84:85] op_sel_hi:[0,1,1]
	v_pk_fma_f32 v[86:87], s[26:27], v[222:223], v[86:87] op_sel_hi:[0,1,1]
	v_pk_fma_f32 v[88:89], s[26:27], v[224:225], v[88:89] op_sel_hi:[0,1,1]
	v_pk_fma_f32 v[90:91], s[26:27], v[226:227], v[90:91] op_sel_hi:[0,1,1]
	v_pk_fma_f32 v[92:93], s[26:27], v[228:229], v[92:93] op_sel_hi:[0,1,1]
	v_pk_fma_f32 v[94:95], s[26:27], v[230:231], v[94:95] op_sel_hi:[0,1,1]
	v_readlane_b32 s31, v181, 35
	s_lshl_b32 s31, s31, 10
	v_add_u32_e32 v235, s31, v208
	global_load_dwordx4 v[28:31], v235, s[12:13]
	s_waitcnt vmcnt(15)
	v_readlane_b32 s22, v183, 28
	v_cvt_pk_f32_fp8_e32 v[216:217], v32
	v_cvt_pk_f32_fp8_sdwa v[218:219], v32 src0_sel:WORD_1
	v_cvt_pk_f32_fp8_e32 v[220:221], v33
	v_cvt_pk_f32_fp8_sdwa v[222:223], v33 src0_sel:WORD_1
	v_cvt_pk_f32_fp8_e32 v[224:225], v34
	v_cvt_pk_f32_fp8_sdwa v[226:227], v34 src0_sel:WORD_1
	v_cvt_pk_f32_fp8_e32 v[228:229], v35
	v_cvt_pk_f32_fp8_sdwa v[230:231], v35 src0_sel:WORD_1
	v_pk_fma_f32 v[64:65], s[20:21], v[216:217], v[64:65] op_sel_hi:[0,1,1]
	v_pk_fma_f32 v[66:67], s[20:21], v[218:219], v[66:67] op_sel_hi:[0,1,1]
	v_pk_fma_f32 v[68:69], s[20:21], v[220:221], v[68:69] op_sel_hi:[0,1,1]
	v_pk_fma_f32 v[70:71], s[20:21], v[222:223], v[70:71] op_sel_hi:[0,1,1]
	v_pk_fma_f32 v[72:73], s[20:21], v[224:225], v[72:73] op_sel_hi:[0,1,1]
	v_pk_fma_f32 v[74:75], s[20:21], v[226:227], v[74:75] op_sel_hi:[0,1,1]
	v_pk_fma_f32 v[76:77], s[20:21], v[228:229], v[76:77] op_sel_hi:[0,1,1]
	v_pk_fma_f32 v[78:79], s[20:21], v[230:231], v[78:79] op_sel_hi:[0,1,1]
	v_readlane_b32 s28, v177, 36
	s_lshl_b32 s28, s28, 10
	v_add_u32_e32 v232, s28, v208
	global_load_dwordx4 v[32:35], v232, s[12:13]
	s_waitcnt vmcnt(15)
	v_readlane_b32 s24, v179, 29
	v_cvt_pk_f32_fp8_e32 v[216:217], v36
	v_cvt_pk_f32_fp8_sdwa v[218:219], v36 src0_sel:WORD_1
	v_cvt_pk_f32_fp8_e32 v[220:221], v37
	v_cvt_pk_f32_fp8_sdwa v[222:223], v37 src0_sel:WORD_1
	v_cvt_pk_f32_fp8_e32 v[224:225], v38
	v_cvt_pk_f32_fp8_sdwa v[226:227], v38 src0_sel:WORD_1
	v_cvt_pk_f32_fp8_e32 v[228:229], v39
	v_cvt_pk_f32_fp8_sdwa v[230:231], v39 src0_sel:WORD_1
	v_pk_fma_f32 v[80:81], s[22:23], v[216:217], v[80:81] op_sel_hi:[0,1,1]
	v_pk_fma_f32 v[82:83], s[22:23], v[218:219], v[82:83] op_sel_hi:[0,1,1]
	v_pk_fma_f32 v[84:85], s[22:23], v[220:221], v[84:85] op_sel_hi:[0,1,1]
	v_pk_fma_f32 v[86:87], s[22:23], v[222:223], v[86:87] op_sel_hi:[0,1,1]
	v_pk_fma_f32 v[88:89], s[22:23], v[224:225], v[88:89] op_sel_hi:[0,1,1]
	v_pk_fma_f32 v[90:91], s[22:23], v[226:227], v[90:91] op_sel_hi:[0,1,1]
	v_pk_fma_f32 v[92:93], s[22:23], v[228:229], v[92:93] op_sel_hi:[0,1,1]
	v_pk_fma_f32 v[94:95], s[22:23], v[230:231], v[94:95] op_sel_hi:[0,1,1]
	v_readlane_b32 s29, v181, 36
	s_lshl_b32 s29, s29, 10
	v_add_u32_e32 v233, s29, v208
	global_load_dwordx4 v[36:39], v233, s[12:13]
	s_waitcnt vmcnt(15)
	v_readlane_b32 s26, v183, 29
	v_cvt_pk_f32_fp8_e32 v[216:217], v40
	v_cvt_pk_f32_fp8_sdwa v[218:219], v40 src0_sel:WORD_1
	v_cvt_pk_f32_fp8_e32 v[220:221], v41
	v_cvt_pk_f32_fp8_sdwa v[222:223], v41 src0_sel:WORD_1
	v_cvt_pk_f32_fp8_e32 v[224:225], v42
	v_cvt_pk_f32_fp8_sdwa v[226:227], v42 src0_sel:WORD_1
	v_cvt_pk_f32_fp8_e32 v[228:229], v43
	v_cvt_pk_f32_fp8_sdwa v[230:231], v43 src0_sel:WORD_1
	v_pk_fma_f32 v[64:65], s[24:25], v[216:217], v[64:65] op_sel_hi:[0,1,1]
	v_pk_fma_f32 v[66:67], s[24:25], v[218:219], v[66:67] op_sel_hi:[0,1,1]
	v_pk_fma_f32 v[68:69], s[24:25], v[220:221], v[68:69] op_sel_hi:[0,1,1]
	v_pk_fma_f32 v[70:71], s[24:25], v[222:223], v[70:71] op_sel_hi:[0,1,1]
	v_pk_fma_f32 v[72:73], s[24:25], v[224:225], v[72:73] op_sel_hi:[0,1,1]
	v_pk_fma_f32 v[74:75], s[24:25], v[226:227], v[74:75] op_sel_hi:[0,1,1]
	v_pk_fma_f32 v[76:77], s[24:25], v[228:229], v[76:77] op_sel_hi:[0,1,1]
	v_pk_fma_f32 v[78:79], s[24:25], v[230:231], v[78:79] op_sel_hi:[0,1,1]
	v_readlane_b32 s30, v177, 37
	s_lshl_b32 s30, s30, 10
	v_add_u32_e32 v234, s30, v208
	global_load_dwordx4 v[40:43], v234, s[12:13]
	s_waitcnt vmcnt(15)
	v_readlane_b32 s20, v179, 30
	v_cvt_pk_f32_fp8_e32 v[216:217], v44
	v_cvt_pk_f32_fp8_sdwa v[218:219], v44 src0_sel:WORD_1
	v_cvt_pk_f32_fp8_e32 v[220:221], v45
	v_cvt_pk_f32_fp8_sdwa v[222:223], v45 src0_sel:WORD_1
	v_cvt_pk_f32_fp8_e32 v[224:225], v46
	v_cvt_pk_f32_fp8_sdwa v[226:227], v46 src0_sel:WORD_1
	v_cvt_pk_f32_fp8_e32 v[228:229], v47
	v_cvt_pk_f32_fp8_sdwa v[230:231], v47 src0_sel:WORD_1
	v_pk_fma_f32 v[80:81], s[26:27], v[216:217], v[80:81] op_sel_hi:[0,1,1]
	v_pk_fma_f32 v[82:83], s[26:27], v[218:219], v[82:83] op_sel_hi:[0,1,1]
	v_pk_fma_f32 v[84:85], s[26:27], v[220:221], v[84:85] op_sel_hi:[0,1,1]
	v_pk_fma_f32 v[86:87], s[26:27], v[222:223], v[86:87] op_sel_hi:[0,1,1]
	v_pk_fma_f32 v[88:89], s[26:27], v[224:225], v[88:89] op_sel_hi:[0,1,1]
	v_pk_fma_f32 v[90:91], s[26:27], v[226:227], v[90:91] op_sel_hi:[0,1,1]
	v_pk_fma_f32 v[92:93], s[26:27], v[228:229], v[92:93] op_sel_hi:[0,1,1]
	v_pk_fma_f32 v[94:95], s[26:27], v[230:231], v[94:95] op_sel_hi:[0,1,1]
	v_readlane_b32 s31, v181, 37
	s_lshl_b32 s31, s31, 10
	v_add_u32_e32 v235, s31, v208
	global_load_dwordx4 v[44:47], v235, s[12:13]
	s_waitcnt vmcnt(15)
	v_readlane_b32 s22, v183, 30
	v_cvt_pk_f32_fp8_e32 v[216:217], v48
	v_cvt_pk_f32_fp8_sdwa v[218:219], v48 src0_sel:WORD_1
	v_cvt_pk_f32_fp8_e32 v[220:221], v49
	v_cvt_pk_f32_fp8_sdwa v[222:223], v49 src0_sel:WORD_1
	v_cvt_pk_f32_fp8_e32 v[224:225], v50
	v_cvt_pk_f32_fp8_sdwa v[226:227], v50 src0_sel:WORD_1
	v_cvt_pk_f32_fp8_e32 v[228:229], v51
	v_cvt_pk_f32_fp8_sdwa v[230:231], v51 src0_sel:WORD_1
	v_pk_fma_f32 v[64:65], s[20:21], v[216:217], v[64:65] op_sel_hi:[0,1,1]
	v_pk_fma_f32 v[66:67], s[20:21], v[218:219], v[66:67] op_sel_hi:[0,1,1]
	v_pk_fma_f32 v[68:69], s[20:21], v[220:221], v[68:69] op_sel_hi:[0,1,1]
	v_pk_fma_f32 v[70:71], s[20:21], v[222:223], v[70:71] op_sel_hi:[0,1,1]
	v_pk_fma_f32 v[72:73], s[20:21], v[224:225], v[72:73] op_sel_hi:[0,1,1]
	v_pk_fma_f32 v[74:75], s[20:21], v[226:227], v[74:75] op_sel_hi:[0,1,1]
	v_pk_fma_f32 v[76:77], s[20:21], v[228:229], v[76:77] op_sel_hi:[0,1,1]
	v_pk_fma_f32 v[78:79], s[20:21], v[230:231], v[78:79] op_sel_hi:[0,1,1]
	v_readlane_b32 s28, v177, 38
	s_lshl_b32 s28, s28, 10
	v_add_u32_e32 v232, s28, v208
	global_load_dwordx4 v[48:51], v232, s[12:13]
	s_waitcnt vmcnt(15)
	v_readlane_b32 s24, v179, 31
	v_cvt_pk_f32_fp8_e32 v[216:217], v52
	v_cvt_pk_f32_fp8_sdwa v[218:219], v52 src0_sel:WORD_1
	v_cvt_pk_f32_fp8_e32 v[220:221], v53
	v_cvt_pk_f32_fp8_sdwa v[222:223], v53 src0_sel:WORD_1
	v_cvt_pk_f32_fp8_e32 v[224:225], v54
	v_cvt_pk_f32_fp8_sdwa v[226:227], v54 src0_sel:WORD_1
	v_cvt_pk_f32_fp8_e32 v[228:229], v55
	v_cvt_pk_f32_fp8_sdwa v[230:231], v55 src0_sel:WORD_1
	v_pk_fma_f32 v[80:81], s[22:23], v[216:217], v[80:81] op_sel_hi:[0,1,1]
	v_pk_fma_f32 v[82:83], s[22:23], v[218:219], v[82:83] op_sel_hi:[0,1,1]
	v_pk_fma_f32 v[84:85], s[22:23], v[220:221], v[84:85] op_sel_hi:[0,1,1]
	v_pk_fma_f32 v[86:87], s[22:23], v[222:223], v[86:87] op_sel_hi:[0,1,1]
	v_pk_fma_f32 v[88:89], s[22:23], v[224:225], v[88:89] op_sel_hi:[0,1,1]
	v_pk_fma_f32 v[90:91], s[22:23], v[226:227], v[90:91] op_sel_hi:[0,1,1]
	v_pk_fma_f32 v[92:93], s[22:23], v[228:229], v[92:93] op_sel_hi:[0,1,1]
	v_pk_fma_f32 v[94:95], s[22:23], v[230:231], v[94:95] op_sel_hi:[0,1,1]
	v_readlane_b32 s29, v181, 38
	s_lshl_b32 s29, s29, 10
	v_add_u32_e32 v233, s29, v208
	global_load_dwordx4 v[52:55], v233, s[12:13]
	s_waitcnt vmcnt(15)
	v_readlane_b32 s26, v183, 31
	v_cvt_pk_f32_fp8_e32 v[216:217], v56
	v_cvt_pk_f32_fp8_sdwa v[218:219], v56 src0_sel:WORD_1
	v_cvt_pk_f32_fp8_e32 v[220:221], v57
	v_cvt_pk_f32_fp8_sdwa v[222:223], v57 src0_sel:WORD_1
	v_cvt_pk_f32_fp8_e32 v[224:225], v58
	v_cvt_pk_f32_fp8_sdwa v[226:227], v58 src0_sel:WORD_1
	v_cvt_pk_f32_fp8_e32 v[228:229], v59
	v_cvt_pk_f32_fp8_sdwa v[230:231], v59 src0_sel:WORD_1
	v_pk_fma_f32 v[64:65], s[24:25], v[216:217], v[64:65] op_sel_hi:[0,1,1]
	v_pk_fma_f32 v[66:67], s[24:25], v[218:219], v[66:67] op_sel_hi:[0,1,1]
	v_pk_fma_f32 v[68:69], s[24:25], v[220:221], v[68:69] op_sel_hi:[0,1,1]
	v_pk_fma_f32 v[70:71], s[24:25], v[222:223], v[70:71] op_sel_hi:[0,1,1]
	v_pk_fma_f32 v[72:73], s[24:25], v[224:225], v[72:73] op_sel_hi:[0,1,1]
	v_pk_fma_f32 v[74:75], s[24:25], v[226:227], v[74:75] op_sel_hi:[0,1,1]
	v_pk_fma_f32 v[76:77], s[24:25], v[228:229], v[76:77] op_sel_hi:[0,1,1]
	v_pk_fma_f32 v[78:79], s[24:25], v[230:231], v[78:79] op_sel_hi:[0,1,1]
	v_readlane_b32 s30, v177, 39
	s_lshl_b32 s30, s30, 10
	v_add_u32_e32 v234, s30, v208
	global_load_dwordx4 v[56:59], v234, s[12:13]
	s_waitcnt vmcnt(15)
	v_readlane_b32 s20, v179, 32
	v_cvt_pk_f32_fp8_e32 v[216:217], v60
	v_cvt_pk_f32_fp8_sdwa v[218:219], v60 src0_sel:WORD_1
	v_cvt_pk_f32_fp8_e32 v[220:221], v61
	v_cvt_pk_f32_fp8_sdwa v[222:223], v61 src0_sel:WORD_1
	v_cvt_pk_f32_fp8_e32 v[224:225], v62
	v_cvt_pk_f32_fp8_sdwa v[226:227], v62 src0_sel:WORD_1
	v_cvt_pk_f32_fp8_e32 v[228:229], v63
	v_cvt_pk_f32_fp8_sdwa v[230:231], v63 src0_sel:WORD_1
	v_pk_fma_f32 v[80:81], s[26:27], v[216:217], v[80:81] op_sel_hi:[0,1,1]
	v_pk_fma_f32 v[82:83], s[26:27], v[218:219], v[82:83] op_sel_hi:[0,1,1]
	v_pk_fma_f32 v[84:85], s[26:27], v[220:221], v[84:85] op_sel_hi:[0,1,1]
	v_pk_fma_f32 v[86:87], s[26:27], v[222:223], v[86:87] op_sel_hi:[0,1,1]
	v_pk_fma_f32 v[88:89], s[26:27], v[224:225], v[88:89] op_sel_hi:[0,1,1]
	v_pk_fma_f32 v[90:91], s[26:27], v[226:227], v[90:91] op_sel_hi:[0,1,1]
	v_pk_fma_f32 v[92:93], s[26:27], v[228:229], v[92:93] op_sel_hi:[0,1,1]
	v_pk_fma_f32 v[94:95], s[26:27], v[230:231], v[94:95] op_sel_hi:[0,1,1]
	v_readlane_b32 s31, v181, 39
	s_lshl_b32 s31, s31, 10
	v_add_u32_e32 v235, s31, v208
	global_load_dwordx4 v[60:63], v235, s[12:13]
	s_waitcnt vmcnt(15)
	v_readlane_b32 s22, v183, 32
	v_cvt_pk_f32_fp8_e32 v[216:217], v0
	v_cvt_pk_f32_fp8_sdwa v[218:219], v0 src0_sel:WORD_1
	v_cvt_pk_f32_fp8_e32 v[220:221], v1
	v_cvt_pk_f32_fp8_sdwa v[222:223], v1 src0_sel:WORD_1
	v_cvt_pk_f32_fp8_e32 v[224:225], v2
	v_cvt_pk_f32_fp8_sdwa v[226:227], v2 src0_sel:WORD_1
	v_cvt_pk_f32_fp8_e32 v[228:229], v3
	v_cvt_pk_f32_fp8_sdwa v[230:231], v3 src0_sel:WORD_1
	v_pk_fma_f32 v[64:65], s[20:21], v[216:217], v[64:65] op_sel_hi:[0,1,1]
	v_pk_fma_f32 v[66:67], s[20:21], v[218:219], v[66:67] op_sel_hi:[0,1,1]
	v_pk_fma_f32 v[68:69], s[20:21], v[220:221], v[68:69] op_sel_hi:[0,1,1]
	v_pk_fma_f32 v[70:71], s[20:21], v[222:223], v[70:71] op_sel_hi:[0,1,1]
	v_pk_fma_f32 v[72:73], s[20:21], v[224:225], v[72:73] op_sel_hi:[0,1,1]
	v_pk_fma_f32 v[74:75], s[20:21], v[226:227], v[74:75] op_sel_hi:[0,1,1]
	v_pk_fma_f32 v[76:77], s[20:21], v[228:229], v[76:77] op_sel_hi:[0,1,1]
	v_pk_fma_f32 v[78:79], s[20:21], v[230:231], v[78:79] op_sel_hi:[0,1,1]
	v_readlane_b32 s28, v177, 40
	s_lshl_b32 s28, s28, 10
	v_add_u32_e32 v232, s28, v208
	global_load_dwordx4 v[0:3], v232, s[12:13]
	s_waitcnt vmcnt(15)
	v_readlane_b32 s24, v179, 33
	v_cvt_pk_f32_fp8_e32 v[216:217], v4
	v_cvt_pk_f32_fp8_sdwa v[218:219], v4 src0_sel:WORD_1
	v_cvt_pk_f32_fp8_e32 v[220:221], v5
	v_cvt_pk_f32_fp8_sdwa v[222:223], v5 src0_sel:WORD_1
	v_cvt_pk_f32_fp8_e32 v[224:225], v6
	v_cvt_pk_f32_fp8_sdwa v[226:227], v6 src0_sel:WORD_1
	v_cvt_pk_f32_fp8_e32 v[228:229], v7
	v_cvt_pk_f32_fp8_sdwa v[230:231], v7 src0_sel:WORD_1
	v_pk_fma_f32 v[80:81], s[22:23], v[216:217], v[80:81] op_sel_hi:[0,1,1]
	v_pk_fma_f32 v[82:83], s[22:23], v[218:219], v[82:83] op_sel_hi:[0,1,1]
	v_pk_fma_f32 v[84:85], s[22:23], v[220:221], v[84:85] op_sel_hi:[0,1,1]
	v_pk_fma_f32 v[86:87], s[22:23], v[222:223], v[86:87] op_sel_hi:[0,1,1]
	v_pk_fma_f32 v[88:89], s[22:23], v[224:225], v[88:89] op_sel_hi:[0,1,1]
	v_pk_fma_f32 v[90:91], s[22:23], v[226:227], v[90:91] op_sel_hi:[0,1,1]
	v_pk_fma_f32 v[92:93], s[22:23], v[228:229], v[92:93] op_sel_hi:[0,1,1]
	v_pk_fma_f32 v[94:95], s[22:23], v[230:231], v[94:95] op_sel_hi:[0,1,1]
	v_readlane_b32 s29, v181, 40
	s_lshl_b32 s29, s29, 10
	v_add_u32_e32 v233, s29, v208
	global_load_dwordx4 v[4:7], v233, s[12:13]
	s_waitcnt vmcnt(15)
	v_readlane_b32 s26, v183, 33
	v_cvt_pk_f32_fp8_e32 v[216:217], v8
	v_cvt_pk_f32_fp8_sdwa v[218:219], v8 src0_sel:WORD_1
	v_cvt_pk_f32_fp8_e32 v[220:221], v9
	v_cvt_pk_f32_fp8_sdwa v[222:223], v9 src0_sel:WORD_1
	v_cvt_pk_f32_fp8_e32 v[224:225], v10
	v_cvt_pk_f32_fp8_sdwa v[226:227], v10 src0_sel:WORD_1
	v_cvt_pk_f32_fp8_e32 v[228:229], v11
	v_cvt_pk_f32_fp8_sdwa v[230:231], v11 src0_sel:WORD_1
	v_pk_fma_f32 v[64:65], s[24:25], v[216:217], v[64:65] op_sel_hi:[0,1,1]
	v_pk_fma_f32 v[66:67], s[24:25], v[218:219], v[66:67] op_sel_hi:[0,1,1]
	v_pk_fma_f32 v[68:69], s[24:25], v[220:221], v[68:69] op_sel_hi:[0,1,1]
	v_pk_fma_f32 v[70:71], s[24:25], v[222:223], v[70:71] op_sel_hi:[0,1,1]
	v_pk_fma_f32 v[72:73], s[24:25], v[224:225], v[72:73] op_sel_hi:[0,1,1]
	v_pk_fma_f32 v[74:75], s[24:25], v[226:227], v[74:75] op_sel_hi:[0,1,1]
	v_pk_fma_f32 v[76:77], s[24:25], v[228:229], v[76:77] op_sel_hi:[0,1,1]
	v_pk_fma_f32 v[78:79], s[24:25], v[230:231], v[78:79] op_sel_hi:[0,1,1]
	v_readlane_b32 s30, v177, 41
	s_lshl_b32 s30, s30, 10
	v_add_u32_e32 v234, s30, v208
	global_load_dwordx4 v[8:11], v234, s[12:13]
	s_waitcnt vmcnt(15)
	v_readlane_b32 s20, v179, 34
	v_cvt_pk_f32_fp8_e32 v[216:217], v12
	v_cvt_pk_f32_fp8_sdwa v[218:219], v12 src0_sel:WORD_1
	v_cvt_pk_f32_fp8_e32 v[220:221], v13
	v_cvt_pk_f32_fp8_sdwa v[222:223], v13 src0_sel:WORD_1
	v_cvt_pk_f32_fp8_e32 v[224:225], v14
	v_cvt_pk_f32_fp8_sdwa v[226:227], v14 src0_sel:WORD_1
	v_cvt_pk_f32_fp8_e32 v[228:229], v15
	v_cvt_pk_f32_fp8_sdwa v[230:231], v15 src0_sel:WORD_1
	v_pk_fma_f32 v[80:81], s[26:27], v[216:217], v[80:81] op_sel_hi:[0,1,1]
	v_pk_fma_f32 v[82:83], s[26:27], v[218:219], v[82:83] op_sel_hi:[0,1,1]
	v_pk_fma_f32 v[84:85], s[26:27], v[220:221], v[84:85] op_sel_hi:[0,1,1]
	v_pk_fma_f32 v[86:87], s[26:27], v[222:223], v[86:87] op_sel_hi:[0,1,1]
	v_pk_fma_f32 v[88:89], s[26:27], v[224:225], v[88:89] op_sel_hi:[0,1,1]
	v_pk_fma_f32 v[90:91], s[26:27], v[226:227], v[90:91] op_sel_hi:[0,1,1]
	v_pk_fma_f32 v[92:93], s[26:27], v[228:229], v[92:93] op_sel_hi:[0,1,1]
	v_pk_fma_f32 v[94:95], s[26:27], v[230:231], v[94:95] op_sel_hi:[0,1,1]
	v_readlane_b32 s31, v181, 41
	s_lshl_b32 s31, s31, 10
	v_add_u32_e32 v235, s31, v208
	global_load_dwordx4 v[12:15], v235, s[12:13]
	s_waitcnt vmcnt(15)
	v_readlane_b32 s22, v183, 34
	v_cvt_pk_f32_fp8_e32 v[216:217], v16
	v_cvt_pk_f32_fp8_sdwa v[218:219], v16 src0_sel:WORD_1
	v_cvt_pk_f32_fp8_e32 v[220:221], v17
	v_cvt_pk_f32_fp8_sdwa v[222:223], v17 src0_sel:WORD_1
	v_cvt_pk_f32_fp8_e32 v[224:225], v18
	v_cvt_pk_f32_fp8_sdwa v[226:227], v18 src0_sel:WORD_1
	v_cvt_pk_f32_fp8_e32 v[228:229], v19
	v_cvt_pk_f32_fp8_sdwa v[230:231], v19 src0_sel:WORD_1
	v_pk_fma_f32 v[64:65], s[20:21], v[216:217], v[64:65] op_sel_hi:[0,1,1]
	v_pk_fma_f32 v[66:67], s[20:21], v[218:219], v[66:67] op_sel_hi:[0,1,1]
	v_pk_fma_f32 v[68:69], s[20:21], v[220:221], v[68:69] op_sel_hi:[0,1,1]
	v_pk_fma_f32 v[70:71], s[20:21], v[222:223], v[70:71] op_sel_hi:[0,1,1]
	v_pk_fma_f32 v[72:73], s[20:21], v[224:225], v[72:73] op_sel_hi:[0,1,1]
	v_pk_fma_f32 v[74:75], s[20:21], v[226:227], v[74:75] op_sel_hi:[0,1,1]
	v_pk_fma_f32 v[76:77], s[20:21], v[228:229], v[76:77] op_sel_hi:[0,1,1]
	v_pk_fma_f32 v[78:79], s[20:21], v[230:231], v[78:79] op_sel_hi:[0,1,1]
	v_readlane_b32 s28, v177, 42
	s_lshl_b32 s28, s28, 10
	v_add_u32_e32 v232, s28, v208
	global_load_dwordx4 v[16:19], v232, s[12:13]
	s_waitcnt vmcnt(15)
	v_readlane_b32 s24, v179, 35
	v_cvt_pk_f32_fp8_e32 v[216:217], v20
	v_cvt_pk_f32_fp8_sdwa v[218:219], v20 src0_sel:WORD_1
	v_cvt_pk_f32_fp8_e32 v[220:221], v21
	v_cvt_pk_f32_fp8_sdwa v[222:223], v21 src0_sel:WORD_1
	v_cvt_pk_f32_fp8_e32 v[224:225], v22
	v_cvt_pk_f32_fp8_sdwa v[226:227], v22 src0_sel:WORD_1
	v_cvt_pk_f32_fp8_e32 v[228:229], v23
	v_cvt_pk_f32_fp8_sdwa v[230:231], v23 src0_sel:WORD_1
	v_pk_fma_f32 v[80:81], s[22:23], v[216:217], v[80:81] op_sel_hi:[0,1,1]
	v_pk_fma_f32 v[82:83], s[22:23], v[218:219], v[82:83] op_sel_hi:[0,1,1]
	v_pk_fma_f32 v[84:85], s[22:23], v[220:221], v[84:85] op_sel_hi:[0,1,1]
	v_pk_fma_f32 v[86:87], s[22:23], v[222:223], v[86:87] op_sel_hi:[0,1,1]
	v_pk_fma_f32 v[88:89], s[22:23], v[224:225], v[88:89] op_sel_hi:[0,1,1]
	v_pk_fma_f32 v[90:91], s[22:23], v[226:227], v[90:91] op_sel_hi:[0,1,1]
	v_pk_fma_f32 v[92:93], s[22:23], v[228:229], v[92:93] op_sel_hi:[0,1,1]
	v_pk_fma_f32 v[94:95], s[22:23], v[230:231], v[94:95] op_sel_hi:[0,1,1]
	v_readlane_b32 s29, v181, 42
	s_lshl_b32 s29, s29, 10
	v_add_u32_e32 v233, s29, v208
	global_load_dwordx4 v[20:23], v233, s[12:13]
	s_waitcnt vmcnt(15)
	v_readlane_b32 s26, v183, 35
	v_cvt_pk_f32_fp8_e32 v[216:217], v24
	v_cvt_pk_f32_fp8_sdwa v[218:219], v24 src0_sel:WORD_1
	v_cvt_pk_f32_fp8_e32 v[220:221], v25
	v_cvt_pk_f32_fp8_sdwa v[222:223], v25 src0_sel:WORD_1
	v_cvt_pk_f32_fp8_e32 v[224:225], v26
	v_cvt_pk_f32_fp8_sdwa v[226:227], v26 src0_sel:WORD_1
	v_cvt_pk_f32_fp8_e32 v[228:229], v27
	v_cvt_pk_f32_fp8_sdwa v[230:231], v27 src0_sel:WORD_1
	v_pk_fma_f32 v[64:65], s[24:25], v[216:217], v[64:65] op_sel_hi:[0,1,1]
	v_pk_fma_f32 v[66:67], s[24:25], v[218:219], v[66:67] op_sel_hi:[0,1,1]
	v_pk_fma_f32 v[68:69], s[24:25], v[220:221], v[68:69] op_sel_hi:[0,1,1]
	v_pk_fma_f32 v[70:71], s[24:25], v[222:223], v[70:71] op_sel_hi:[0,1,1]
	v_pk_fma_f32 v[72:73], s[24:25], v[224:225], v[72:73] op_sel_hi:[0,1,1]
	v_pk_fma_f32 v[74:75], s[24:25], v[226:227], v[74:75] op_sel_hi:[0,1,1]
	v_pk_fma_f32 v[76:77], s[24:25], v[228:229], v[76:77] op_sel_hi:[0,1,1]
	v_pk_fma_f32 v[78:79], s[24:25], v[230:231], v[78:79] op_sel_hi:[0,1,1]
	v_readlane_b32 s30, v177, 43
	s_lshl_b32 s30, s30, 10
	v_add_u32_e32 v234, s30, v208
	global_load_dwordx4 v[24:27], v234, s[12:13]
	s_waitcnt vmcnt(15)
	v_readlane_b32 s20, v179, 36
	v_cvt_pk_f32_fp8_e32 v[216:217], v28
	v_cvt_pk_f32_fp8_sdwa v[218:219], v28 src0_sel:WORD_1
	v_cvt_pk_f32_fp8_e32 v[220:221], v29
	v_cvt_pk_f32_fp8_sdwa v[222:223], v29 src0_sel:WORD_1
	v_cvt_pk_f32_fp8_e32 v[224:225], v30
	v_cvt_pk_f32_fp8_sdwa v[226:227], v30 src0_sel:WORD_1
	v_cvt_pk_f32_fp8_e32 v[228:229], v31
	v_cvt_pk_f32_fp8_sdwa v[230:231], v31 src0_sel:WORD_1
	v_pk_fma_f32 v[80:81], s[26:27], v[216:217], v[80:81] op_sel_hi:[0,1,1]
	v_pk_fma_f32 v[82:83], s[26:27], v[218:219], v[82:83] op_sel_hi:[0,1,1]
	v_pk_fma_f32 v[84:85], s[26:27], v[220:221], v[84:85] op_sel_hi:[0,1,1]
	v_pk_fma_f32 v[86:87], s[26:27], v[222:223], v[86:87] op_sel_hi:[0,1,1]
	v_pk_fma_f32 v[88:89], s[26:27], v[224:225], v[88:89] op_sel_hi:[0,1,1]
	v_pk_fma_f32 v[90:91], s[26:27], v[226:227], v[90:91] op_sel_hi:[0,1,1]
	v_pk_fma_f32 v[92:93], s[26:27], v[228:229], v[92:93] op_sel_hi:[0,1,1]
	v_pk_fma_f32 v[94:95], s[26:27], v[230:231], v[94:95] op_sel_hi:[0,1,1]
	v_readlane_b32 s31, v181, 43
	s_lshl_b32 s31, s31, 10
	v_add_u32_e32 v235, s31, v208
	global_load_dwordx4 v[28:31], v235, s[12:13]
	s_waitcnt vmcnt(15)
	v_readlane_b32 s22, v183, 36
	v_cvt_pk_f32_fp8_e32 v[216:217], v32
	v_cvt_pk_f32_fp8_sdwa v[218:219], v32 src0_sel:WORD_1
	v_cvt_pk_f32_fp8_e32 v[220:221], v33
	v_cvt_pk_f32_fp8_sdwa v[222:223], v33 src0_sel:WORD_1
	v_cvt_pk_f32_fp8_e32 v[224:225], v34
	v_cvt_pk_f32_fp8_sdwa v[226:227], v34 src0_sel:WORD_1
	v_cvt_pk_f32_fp8_e32 v[228:229], v35
	v_cvt_pk_f32_fp8_sdwa v[230:231], v35 src0_sel:WORD_1
	v_pk_fma_f32 v[64:65], s[20:21], v[216:217], v[64:65] op_sel_hi:[0,1,1]
	v_pk_fma_f32 v[66:67], s[20:21], v[218:219], v[66:67] op_sel_hi:[0,1,1]
	v_pk_fma_f32 v[68:69], s[20:21], v[220:221], v[68:69] op_sel_hi:[0,1,1]
	v_pk_fma_f32 v[70:71], s[20:21], v[222:223], v[70:71] op_sel_hi:[0,1,1]
	v_pk_fma_f32 v[72:73], s[20:21], v[224:225], v[72:73] op_sel_hi:[0,1,1]
	v_pk_fma_f32 v[74:75], s[20:21], v[226:227], v[74:75] op_sel_hi:[0,1,1]
	v_pk_fma_f32 v[76:77], s[20:21], v[228:229], v[76:77] op_sel_hi:[0,1,1]
	v_pk_fma_f32 v[78:79], s[20:21], v[230:231], v[78:79] op_sel_hi:[0,1,1]
	v_readlane_b32 s28, v177, 44
	s_lshl_b32 s28, s28, 10
	v_add_u32_e32 v232, s28, v208
	global_load_dwordx4 v[32:35], v232, s[12:13]
	s_waitcnt vmcnt(15)
	v_readlane_b32 s24, v179, 37
	v_cvt_pk_f32_fp8_e32 v[216:217], v36
	v_cvt_pk_f32_fp8_sdwa v[218:219], v36 src0_sel:WORD_1
	v_cvt_pk_f32_fp8_e32 v[220:221], v37
	v_cvt_pk_f32_fp8_sdwa v[222:223], v37 src0_sel:WORD_1
	v_cvt_pk_f32_fp8_e32 v[224:225], v38
	v_cvt_pk_f32_fp8_sdwa v[226:227], v38 src0_sel:WORD_1
	v_cvt_pk_f32_fp8_e32 v[228:229], v39
	v_cvt_pk_f32_fp8_sdwa v[230:231], v39 src0_sel:WORD_1
	v_pk_fma_f32 v[80:81], s[22:23], v[216:217], v[80:81] op_sel_hi:[0,1,1]
	v_pk_fma_f32 v[82:83], s[22:23], v[218:219], v[82:83] op_sel_hi:[0,1,1]
	v_pk_fma_f32 v[84:85], s[22:23], v[220:221], v[84:85] op_sel_hi:[0,1,1]
	v_pk_fma_f32 v[86:87], s[22:23], v[222:223], v[86:87] op_sel_hi:[0,1,1]
	v_pk_fma_f32 v[88:89], s[22:23], v[224:225], v[88:89] op_sel_hi:[0,1,1]
	v_pk_fma_f32 v[90:91], s[22:23], v[226:227], v[90:91] op_sel_hi:[0,1,1]
	v_pk_fma_f32 v[92:93], s[22:23], v[228:229], v[92:93] op_sel_hi:[0,1,1]
	v_pk_fma_f32 v[94:95], s[22:23], v[230:231], v[94:95] op_sel_hi:[0,1,1]
	v_readlane_b32 s29, v181, 44
	s_lshl_b32 s29, s29, 10
	v_add_u32_e32 v233, s29, v208
	global_load_dwordx4 v[36:39], v233, s[12:13]
	s_waitcnt vmcnt(15)
	v_readlane_b32 s26, v183, 37
	v_cvt_pk_f32_fp8_e32 v[216:217], v40
	v_cvt_pk_f32_fp8_sdwa v[218:219], v40 src0_sel:WORD_1
	v_cvt_pk_f32_fp8_e32 v[220:221], v41
	v_cvt_pk_f32_fp8_sdwa v[222:223], v41 src0_sel:WORD_1
	v_cvt_pk_f32_fp8_e32 v[224:225], v42
	v_cvt_pk_f32_fp8_sdwa v[226:227], v42 src0_sel:WORD_1
	v_cvt_pk_f32_fp8_e32 v[228:229], v43
	v_cvt_pk_f32_fp8_sdwa v[230:231], v43 src0_sel:WORD_1
	v_pk_fma_f32 v[64:65], s[24:25], v[216:217], v[64:65] op_sel_hi:[0,1,1]
	v_pk_fma_f32 v[66:67], s[24:25], v[218:219], v[66:67] op_sel_hi:[0,1,1]
	v_pk_fma_f32 v[68:69], s[24:25], v[220:221], v[68:69] op_sel_hi:[0,1,1]
	v_pk_fma_f32 v[70:71], s[24:25], v[222:223], v[70:71] op_sel_hi:[0,1,1]
	v_pk_fma_f32 v[72:73], s[24:25], v[224:225], v[72:73] op_sel_hi:[0,1,1]
	v_pk_fma_f32 v[74:75], s[24:25], v[226:227], v[74:75] op_sel_hi:[0,1,1]
	v_pk_fma_f32 v[76:77], s[24:25], v[228:229], v[76:77] op_sel_hi:[0,1,1]
	v_pk_fma_f32 v[78:79], s[24:25], v[230:231], v[78:79] op_sel_hi:[0,1,1]
	v_readlane_b32 s30, v177, 45
	s_lshl_b32 s30, s30, 10
	v_add_u32_e32 v234, s30, v208
	global_load_dwordx4 v[40:43], v234, s[12:13]
	s_waitcnt vmcnt(15)
	v_readlane_b32 s20, v179, 38
	v_cvt_pk_f32_fp8_e32 v[216:217], v44
	v_cvt_pk_f32_fp8_sdwa v[218:219], v44 src0_sel:WORD_1
	v_cvt_pk_f32_fp8_e32 v[220:221], v45
	v_cvt_pk_f32_fp8_sdwa v[222:223], v45 src0_sel:WORD_1
	v_cvt_pk_f32_fp8_e32 v[224:225], v46
	v_cvt_pk_f32_fp8_sdwa v[226:227], v46 src0_sel:WORD_1
	v_cvt_pk_f32_fp8_e32 v[228:229], v47
	v_cvt_pk_f32_fp8_sdwa v[230:231], v47 src0_sel:WORD_1
	v_pk_fma_f32 v[80:81], s[26:27], v[216:217], v[80:81] op_sel_hi:[0,1,1]
	v_pk_fma_f32 v[82:83], s[26:27], v[218:219], v[82:83] op_sel_hi:[0,1,1]
	v_pk_fma_f32 v[84:85], s[26:27], v[220:221], v[84:85] op_sel_hi:[0,1,1]
	v_pk_fma_f32 v[86:87], s[26:27], v[222:223], v[86:87] op_sel_hi:[0,1,1]
	v_pk_fma_f32 v[88:89], s[26:27], v[224:225], v[88:89] op_sel_hi:[0,1,1]
	v_pk_fma_f32 v[90:91], s[26:27], v[226:227], v[90:91] op_sel_hi:[0,1,1]
	v_pk_fma_f32 v[92:93], s[26:27], v[228:229], v[92:93] op_sel_hi:[0,1,1]
	v_pk_fma_f32 v[94:95], s[26:27], v[230:231], v[94:95] op_sel_hi:[0,1,1]
	v_readlane_b32 s31, v181, 45
	s_lshl_b32 s31, s31, 10
	v_add_u32_e32 v235, s31, v208
	global_load_dwordx4 v[44:47], v235, s[12:13]
	s_waitcnt vmcnt(15)
	v_readlane_b32 s22, v183, 38
	v_cvt_pk_f32_fp8_e32 v[216:217], v48
	v_cvt_pk_f32_fp8_sdwa v[218:219], v48 src0_sel:WORD_1
	v_cvt_pk_f32_fp8_e32 v[220:221], v49
	v_cvt_pk_f32_fp8_sdwa v[222:223], v49 src0_sel:WORD_1
	v_cvt_pk_f32_fp8_e32 v[224:225], v50
	v_cvt_pk_f32_fp8_sdwa v[226:227], v50 src0_sel:WORD_1
	v_cvt_pk_f32_fp8_e32 v[228:229], v51
	v_cvt_pk_f32_fp8_sdwa v[230:231], v51 src0_sel:WORD_1
	v_pk_fma_f32 v[64:65], s[20:21], v[216:217], v[64:65] op_sel_hi:[0,1,1]
	v_pk_fma_f32 v[66:67], s[20:21], v[218:219], v[66:67] op_sel_hi:[0,1,1]
	v_pk_fma_f32 v[68:69], s[20:21], v[220:221], v[68:69] op_sel_hi:[0,1,1]
	v_pk_fma_f32 v[70:71], s[20:21], v[222:223], v[70:71] op_sel_hi:[0,1,1]
	v_pk_fma_f32 v[72:73], s[20:21], v[224:225], v[72:73] op_sel_hi:[0,1,1]
	v_pk_fma_f32 v[74:75], s[20:21], v[226:227], v[74:75] op_sel_hi:[0,1,1]
	v_pk_fma_f32 v[76:77], s[20:21], v[228:229], v[76:77] op_sel_hi:[0,1,1]
	v_pk_fma_f32 v[78:79], s[20:21], v[230:231], v[78:79] op_sel_hi:[0,1,1]
	v_readlane_b32 s28, v177, 46
	s_lshl_b32 s28, s28, 10
	v_add_u32_e32 v232, s28, v208
	global_load_dwordx4 v[48:51], v232, s[12:13]
	s_waitcnt vmcnt(15)
	v_readlane_b32 s24, v179, 39
	v_cvt_pk_f32_fp8_e32 v[216:217], v52
	v_cvt_pk_f32_fp8_sdwa v[218:219], v52 src0_sel:WORD_1
	v_cvt_pk_f32_fp8_e32 v[220:221], v53
	v_cvt_pk_f32_fp8_sdwa v[222:223], v53 src0_sel:WORD_1
	v_cvt_pk_f32_fp8_e32 v[224:225], v54
	v_cvt_pk_f32_fp8_sdwa v[226:227], v54 src0_sel:WORD_1
	v_cvt_pk_f32_fp8_e32 v[228:229], v55
	v_cvt_pk_f32_fp8_sdwa v[230:231], v55 src0_sel:WORD_1
	v_pk_fma_f32 v[80:81], s[22:23], v[216:217], v[80:81] op_sel_hi:[0,1,1]
	v_pk_fma_f32 v[82:83], s[22:23], v[218:219], v[82:83] op_sel_hi:[0,1,1]
	v_pk_fma_f32 v[84:85], s[22:23], v[220:221], v[84:85] op_sel_hi:[0,1,1]
	v_pk_fma_f32 v[86:87], s[22:23], v[222:223], v[86:87] op_sel_hi:[0,1,1]
	v_pk_fma_f32 v[88:89], s[22:23], v[224:225], v[88:89] op_sel_hi:[0,1,1]
	v_pk_fma_f32 v[90:91], s[22:23], v[226:227], v[90:91] op_sel_hi:[0,1,1]
	v_pk_fma_f32 v[92:93], s[22:23], v[228:229], v[92:93] op_sel_hi:[0,1,1]
	v_pk_fma_f32 v[94:95], s[22:23], v[230:231], v[94:95] op_sel_hi:[0,1,1]
	v_readlane_b32 s29, v181, 46
	s_lshl_b32 s29, s29, 10
	v_add_u32_e32 v233, s29, v208
	global_load_dwordx4 v[52:55], v233, s[12:13]
	s_waitcnt vmcnt(15)
	v_readlane_b32 s26, v183, 39
	v_cvt_pk_f32_fp8_e32 v[216:217], v56
	v_cvt_pk_f32_fp8_sdwa v[218:219], v56 src0_sel:WORD_1
	v_cvt_pk_f32_fp8_e32 v[220:221], v57
	v_cvt_pk_f32_fp8_sdwa v[222:223], v57 src0_sel:WORD_1
	v_cvt_pk_f32_fp8_e32 v[224:225], v58
	v_cvt_pk_f32_fp8_sdwa v[226:227], v58 src0_sel:WORD_1
	v_cvt_pk_f32_fp8_e32 v[228:229], v59
	v_cvt_pk_f32_fp8_sdwa v[230:231], v59 src0_sel:WORD_1
	v_pk_fma_f32 v[64:65], s[24:25], v[216:217], v[64:65] op_sel_hi:[0,1,1]
	v_pk_fma_f32 v[66:67], s[24:25], v[218:219], v[66:67] op_sel_hi:[0,1,1]
	v_pk_fma_f32 v[68:69], s[24:25], v[220:221], v[68:69] op_sel_hi:[0,1,1]
	v_pk_fma_f32 v[70:71], s[24:25], v[222:223], v[70:71] op_sel_hi:[0,1,1]
	v_pk_fma_f32 v[72:73], s[24:25], v[224:225], v[72:73] op_sel_hi:[0,1,1]
	v_pk_fma_f32 v[74:75], s[24:25], v[226:227], v[74:75] op_sel_hi:[0,1,1]
	v_pk_fma_f32 v[76:77], s[24:25], v[228:229], v[76:77] op_sel_hi:[0,1,1]
	v_pk_fma_f32 v[78:79], s[24:25], v[230:231], v[78:79] op_sel_hi:[0,1,1]
	v_readlane_b32 s30, v177, 47
	s_lshl_b32 s30, s30, 10
	v_add_u32_e32 v234, s30, v208
	global_load_dwordx4 v[56:59], v234, s[12:13]
	s_waitcnt vmcnt(15)
	v_readlane_b32 s20, v179, 40
	v_cvt_pk_f32_fp8_e32 v[216:217], v60
	v_cvt_pk_f32_fp8_sdwa v[218:219], v60 src0_sel:WORD_1
	v_cvt_pk_f32_fp8_e32 v[220:221], v61
	v_cvt_pk_f32_fp8_sdwa v[222:223], v61 src0_sel:WORD_1
	v_cvt_pk_f32_fp8_e32 v[224:225], v62
	v_cvt_pk_f32_fp8_sdwa v[226:227], v62 src0_sel:WORD_1
	v_cvt_pk_f32_fp8_e32 v[228:229], v63
	v_cvt_pk_f32_fp8_sdwa v[230:231], v63 src0_sel:WORD_1
	v_pk_fma_f32 v[80:81], s[26:27], v[216:217], v[80:81] op_sel_hi:[0,1,1]
	v_pk_fma_f32 v[82:83], s[26:27], v[218:219], v[82:83] op_sel_hi:[0,1,1]
	v_pk_fma_f32 v[84:85], s[26:27], v[220:221], v[84:85] op_sel_hi:[0,1,1]
	v_pk_fma_f32 v[86:87], s[26:27], v[222:223], v[86:87] op_sel_hi:[0,1,1]
	v_pk_fma_f32 v[88:89], s[26:27], v[224:225], v[88:89] op_sel_hi:[0,1,1]
	v_pk_fma_f32 v[90:91], s[26:27], v[226:227], v[90:91] op_sel_hi:[0,1,1]
	v_pk_fma_f32 v[92:93], s[26:27], v[228:229], v[92:93] op_sel_hi:[0,1,1]
	v_pk_fma_f32 v[94:95], s[26:27], v[230:231], v[94:95] op_sel_hi:[0,1,1]
	v_readlane_b32 s31, v181, 47
	s_lshl_b32 s31, s31, 10
	v_add_u32_e32 v235, s31, v208
	global_load_dwordx4 v[60:63], v235, s[12:13]
	s_waitcnt vmcnt(15)
	v_readlane_b32 s22, v183, 40
	v_cvt_pk_f32_fp8_e32 v[216:217], v0
	v_cvt_pk_f32_fp8_sdwa v[218:219], v0 src0_sel:WORD_1
	v_cvt_pk_f32_fp8_e32 v[220:221], v1
	v_cvt_pk_f32_fp8_sdwa v[222:223], v1 src0_sel:WORD_1
	v_cvt_pk_f32_fp8_e32 v[224:225], v2
	v_cvt_pk_f32_fp8_sdwa v[226:227], v2 src0_sel:WORD_1
	v_cvt_pk_f32_fp8_e32 v[228:229], v3
	v_cvt_pk_f32_fp8_sdwa v[230:231], v3 src0_sel:WORD_1
	v_pk_fma_f32 v[64:65], s[20:21], v[216:217], v[64:65] op_sel_hi:[0,1,1]
	v_pk_fma_f32 v[66:67], s[20:21], v[218:219], v[66:67] op_sel_hi:[0,1,1]
	v_pk_fma_f32 v[68:69], s[20:21], v[220:221], v[68:69] op_sel_hi:[0,1,1]
	v_pk_fma_f32 v[70:71], s[20:21], v[222:223], v[70:71] op_sel_hi:[0,1,1]
	v_pk_fma_f32 v[72:73], s[20:21], v[224:225], v[72:73] op_sel_hi:[0,1,1]
	v_pk_fma_f32 v[74:75], s[20:21], v[226:227], v[74:75] op_sel_hi:[0,1,1]
	v_pk_fma_f32 v[76:77], s[20:21], v[228:229], v[76:77] op_sel_hi:[0,1,1]
	v_pk_fma_f32 v[78:79], s[20:21], v[230:231], v[78:79] op_sel_hi:[0,1,1]
	v_readlane_b32 s28, v177, 48
	s_lshl_b32 s28, s28, 10
	v_add_u32_e32 v232, s28, v208
	global_load_dwordx4 v[0:3], v232, s[12:13]
	s_waitcnt vmcnt(15)
	v_readlane_b32 s24, v179, 41
	v_cvt_pk_f32_fp8_e32 v[216:217], v4
	v_cvt_pk_f32_fp8_sdwa v[218:219], v4 src0_sel:WORD_1
	v_cvt_pk_f32_fp8_e32 v[220:221], v5
	v_cvt_pk_f32_fp8_sdwa v[222:223], v5 src0_sel:WORD_1
	v_cvt_pk_f32_fp8_e32 v[224:225], v6
	v_cvt_pk_f32_fp8_sdwa v[226:227], v6 src0_sel:WORD_1
	v_cvt_pk_f32_fp8_e32 v[228:229], v7
	v_cvt_pk_f32_fp8_sdwa v[230:231], v7 src0_sel:WORD_1
	v_pk_fma_f32 v[80:81], s[22:23], v[216:217], v[80:81] op_sel_hi:[0,1,1]
	v_pk_fma_f32 v[82:83], s[22:23], v[218:219], v[82:83] op_sel_hi:[0,1,1]
	v_pk_fma_f32 v[84:85], s[22:23], v[220:221], v[84:85] op_sel_hi:[0,1,1]
	v_pk_fma_f32 v[86:87], s[22:23], v[222:223], v[86:87] op_sel_hi:[0,1,1]
	v_pk_fma_f32 v[88:89], s[22:23], v[224:225], v[88:89] op_sel_hi:[0,1,1]
	v_pk_fma_f32 v[90:91], s[22:23], v[226:227], v[90:91] op_sel_hi:[0,1,1]
	v_pk_fma_f32 v[92:93], s[22:23], v[228:229], v[92:93] op_sel_hi:[0,1,1]
	v_pk_fma_f32 v[94:95], s[22:23], v[230:231], v[94:95] op_sel_hi:[0,1,1]
	v_readlane_b32 s29, v181, 48
	s_lshl_b32 s29, s29, 10
	v_add_u32_e32 v233, s29, v208
	global_load_dwordx4 v[4:7], v233, s[12:13]
	s_waitcnt vmcnt(15)
	v_readlane_b32 s26, v183, 41
	v_cvt_pk_f32_fp8_e32 v[216:217], v8
	v_cvt_pk_f32_fp8_sdwa v[218:219], v8 src0_sel:WORD_1
	v_cvt_pk_f32_fp8_e32 v[220:221], v9
	v_cvt_pk_f32_fp8_sdwa v[222:223], v9 src0_sel:WORD_1
	v_cvt_pk_f32_fp8_e32 v[224:225], v10
	v_cvt_pk_f32_fp8_sdwa v[226:227], v10 src0_sel:WORD_1
	v_cvt_pk_f32_fp8_e32 v[228:229], v11
	v_cvt_pk_f32_fp8_sdwa v[230:231], v11 src0_sel:WORD_1
	v_pk_fma_f32 v[64:65], s[24:25], v[216:217], v[64:65] op_sel_hi:[0,1,1]
	v_pk_fma_f32 v[66:67], s[24:25], v[218:219], v[66:67] op_sel_hi:[0,1,1]
	v_pk_fma_f32 v[68:69], s[24:25], v[220:221], v[68:69] op_sel_hi:[0,1,1]
	v_pk_fma_f32 v[70:71], s[24:25], v[222:223], v[70:71] op_sel_hi:[0,1,1]
	v_pk_fma_f32 v[72:73], s[24:25], v[224:225], v[72:73] op_sel_hi:[0,1,1]
	v_pk_fma_f32 v[74:75], s[24:25], v[226:227], v[74:75] op_sel_hi:[0,1,1]
	v_pk_fma_f32 v[76:77], s[24:25], v[228:229], v[76:77] op_sel_hi:[0,1,1]
	v_pk_fma_f32 v[78:79], s[24:25], v[230:231], v[78:79] op_sel_hi:[0,1,1]
	v_readlane_b32 s30, v177, 49
	s_lshl_b32 s30, s30, 10
	v_add_u32_e32 v234, s30, v208
	global_load_dwordx4 v[8:11], v234, s[12:13]
	s_waitcnt vmcnt(15)
	v_readlane_b32 s20, v179, 42
	v_cvt_pk_f32_fp8_e32 v[216:217], v12
	v_cvt_pk_f32_fp8_sdwa v[218:219], v12 src0_sel:WORD_1
	v_cvt_pk_f32_fp8_e32 v[220:221], v13
	v_cvt_pk_f32_fp8_sdwa v[222:223], v13 src0_sel:WORD_1
	v_cvt_pk_f32_fp8_e32 v[224:225], v14
	v_cvt_pk_f32_fp8_sdwa v[226:227], v14 src0_sel:WORD_1
	v_cvt_pk_f32_fp8_e32 v[228:229], v15
	v_cvt_pk_f32_fp8_sdwa v[230:231], v15 src0_sel:WORD_1
	v_pk_fma_f32 v[80:81], s[26:27], v[216:217], v[80:81] op_sel_hi:[0,1,1]
	v_pk_fma_f32 v[82:83], s[26:27], v[218:219], v[82:83] op_sel_hi:[0,1,1]
	v_pk_fma_f32 v[84:85], s[26:27], v[220:221], v[84:85] op_sel_hi:[0,1,1]
	v_pk_fma_f32 v[86:87], s[26:27], v[222:223], v[86:87] op_sel_hi:[0,1,1]
	v_pk_fma_f32 v[88:89], s[26:27], v[224:225], v[88:89] op_sel_hi:[0,1,1]
	v_pk_fma_f32 v[90:91], s[26:27], v[226:227], v[90:91] op_sel_hi:[0,1,1]
	v_pk_fma_f32 v[92:93], s[26:27], v[228:229], v[92:93] op_sel_hi:[0,1,1]
	v_pk_fma_f32 v[94:95], s[26:27], v[230:231], v[94:95] op_sel_hi:[0,1,1]
	v_readlane_b32 s31, v181, 49
	s_lshl_b32 s31, s31, 10
	v_add_u32_e32 v235, s31, v208
	global_load_dwordx4 v[12:15], v235, s[12:13]
	s_waitcnt vmcnt(15)
	v_readlane_b32 s22, v183, 42
	v_cvt_pk_f32_fp8_e32 v[216:217], v16
	v_cvt_pk_f32_fp8_sdwa v[218:219], v16 src0_sel:WORD_1
	v_cvt_pk_f32_fp8_e32 v[220:221], v17
	v_cvt_pk_f32_fp8_sdwa v[222:223], v17 src0_sel:WORD_1
	v_cvt_pk_f32_fp8_e32 v[224:225], v18
	v_cvt_pk_f32_fp8_sdwa v[226:227], v18 src0_sel:WORD_1
	v_cvt_pk_f32_fp8_e32 v[228:229], v19
	v_cvt_pk_f32_fp8_sdwa v[230:231], v19 src0_sel:WORD_1
	v_pk_fma_f32 v[64:65], s[20:21], v[216:217], v[64:65] op_sel_hi:[0,1,1]
	v_pk_fma_f32 v[66:67], s[20:21], v[218:219], v[66:67] op_sel_hi:[0,1,1]
	v_pk_fma_f32 v[68:69], s[20:21], v[220:221], v[68:69] op_sel_hi:[0,1,1]
	v_pk_fma_f32 v[70:71], s[20:21], v[222:223], v[70:71] op_sel_hi:[0,1,1]
	v_pk_fma_f32 v[72:73], s[20:21], v[224:225], v[72:73] op_sel_hi:[0,1,1]
	v_pk_fma_f32 v[74:75], s[20:21], v[226:227], v[74:75] op_sel_hi:[0,1,1]
	v_pk_fma_f32 v[76:77], s[20:21], v[228:229], v[76:77] op_sel_hi:[0,1,1]
	v_pk_fma_f32 v[78:79], s[20:21], v[230:231], v[78:79] op_sel_hi:[0,1,1]
	v_readlane_b32 s28, v177, 50
	s_lshl_b32 s28, s28, 10
	v_add_u32_e32 v232, s28, v208
	global_load_dwordx4 v[16:19], v232, s[12:13]
	s_waitcnt vmcnt(15)
	v_readlane_b32 s24, v179, 43
	v_cvt_pk_f32_fp8_e32 v[216:217], v20
	v_cvt_pk_f32_fp8_sdwa v[218:219], v20 src0_sel:WORD_1
	v_cvt_pk_f32_fp8_e32 v[220:221], v21
	v_cvt_pk_f32_fp8_sdwa v[222:223], v21 src0_sel:WORD_1
	v_cvt_pk_f32_fp8_e32 v[224:225], v22
	v_cvt_pk_f32_fp8_sdwa v[226:227], v22 src0_sel:WORD_1
	v_cvt_pk_f32_fp8_e32 v[228:229], v23
	v_cvt_pk_f32_fp8_sdwa v[230:231], v23 src0_sel:WORD_1
	v_pk_fma_f32 v[80:81], s[22:23], v[216:217], v[80:81] op_sel_hi:[0,1,1]
	v_pk_fma_f32 v[82:83], s[22:23], v[218:219], v[82:83] op_sel_hi:[0,1,1]
	v_pk_fma_f32 v[84:85], s[22:23], v[220:221], v[84:85] op_sel_hi:[0,1,1]
	v_pk_fma_f32 v[86:87], s[22:23], v[222:223], v[86:87] op_sel_hi:[0,1,1]
	v_pk_fma_f32 v[88:89], s[22:23], v[224:225], v[88:89] op_sel_hi:[0,1,1]
	v_pk_fma_f32 v[90:91], s[22:23], v[226:227], v[90:91] op_sel_hi:[0,1,1]
	v_pk_fma_f32 v[92:93], s[22:23], v[228:229], v[92:93] op_sel_hi:[0,1,1]
	v_pk_fma_f32 v[94:95], s[22:23], v[230:231], v[94:95] op_sel_hi:[0,1,1]
	v_readlane_b32 s29, v181, 50
	s_lshl_b32 s29, s29, 10
	v_add_u32_e32 v233, s29, v208
	global_load_dwordx4 v[20:23], v233, s[12:13]
	s_waitcnt vmcnt(15)
	v_readlane_b32 s26, v183, 43
	v_cvt_pk_f32_fp8_e32 v[216:217], v24
	v_cvt_pk_f32_fp8_sdwa v[218:219], v24 src0_sel:WORD_1
	v_cvt_pk_f32_fp8_e32 v[220:221], v25
	v_cvt_pk_f32_fp8_sdwa v[222:223], v25 src0_sel:WORD_1
	v_cvt_pk_f32_fp8_e32 v[224:225], v26
	v_cvt_pk_f32_fp8_sdwa v[226:227], v26 src0_sel:WORD_1
	v_cvt_pk_f32_fp8_e32 v[228:229], v27
	v_cvt_pk_f32_fp8_sdwa v[230:231], v27 src0_sel:WORD_1
	v_pk_fma_f32 v[64:65], s[24:25], v[216:217], v[64:65] op_sel_hi:[0,1,1]
	v_pk_fma_f32 v[66:67], s[24:25], v[218:219], v[66:67] op_sel_hi:[0,1,1]
	v_pk_fma_f32 v[68:69], s[24:25], v[220:221], v[68:69] op_sel_hi:[0,1,1]
	v_pk_fma_f32 v[70:71], s[24:25], v[222:223], v[70:71] op_sel_hi:[0,1,1]
	v_pk_fma_f32 v[72:73], s[24:25], v[224:225], v[72:73] op_sel_hi:[0,1,1]
	v_pk_fma_f32 v[74:75], s[24:25], v[226:227], v[74:75] op_sel_hi:[0,1,1]
	v_pk_fma_f32 v[76:77], s[24:25], v[228:229], v[76:77] op_sel_hi:[0,1,1]
	v_pk_fma_f32 v[78:79], s[24:25], v[230:231], v[78:79] op_sel_hi:[0,1,1]
	v_readlane_b32 s30, v177, 51
	s_lshl_b32 s30, s30, 10
	v_add_u32_e32 v234, s30, v208
	global_load_dwordx4 v[24:27], v234, s[12:13]
	s_waitcnt vmcnt(15)
	v_readlane_b32 s20, v179, 44
	v_cvt_pk_f32_fp8_e32 v[216:217], v28
	v_cvt_pk_f32_fp8_sdwa v[218:219], v28 src0_sel:WORD_1
	v_cvt_pk_f32_fp8_e32 v[220:221], v29
	v_cvt_pk_f32_fp8_sdwa v[222:223], v29 src0_sel:WORD_1
	v_cvt_pk_f32_fp8_e32 v[224:225], v30
	v_cvt_pk_f32_fp8_sdwa v[226:227], v30 src0_sel:WORD_1
	v_cvt_pk_f32_fp8_e32 v[228:229], v31
	v_cvt_pk_f32_fp8_sdwa v[230:231], v31 src0_sel:WORD_1
	v_pk_fma_f32 v[80:81], s[26:27], v[216:217], v[80:81] op_sel_hi:[0,1,1]
	v_pk_fma_f32 v[82:83], s[26:27], v[218:219], v[82:83] op_sel_hi:[0,1,1]
	v_pk_fma_f32 v[84:85], s[26:27], v[220:221], v[84:85] op_sel_hi:[0,1,1]
	v_pk_fma_f32 v[86:87], s[26:27], v[222:223], v[86:87] op_sel_hi:[0,1,1]
	v_pk_fma_f32 v[88:89], s[26:27], v[224:225], v[88:89] op_sel_hi:[0,1,1]
	v_pk_fma_f32 v[90:91], s[26:27], v[226:227], v[90:91] op_sel_hi:[0,1,1]
	v_pk_fma_f32 v[92:93], s[26:27], v[228:229], v[92:93] op_sel_hi:[0,1,1]
	v_pk_fma_f32 v[94:95], s[26:27], v[230:231], v[94:95] op_sel_hi:[0,1,1]
	v_readlane_b32 s31, v181, 51
	s_lshl_b32 s31, s31, 10
	v_add_u32_e32 v235, s31, v208
	global_load_dwordx4 v[28:31], v235, s[12:13]
	s_waitcnt vmcnt(15)
	v_readlane_b32 s22, v183, 44
	v_cvt_pk_f32_fp8_e32 v[216:217], v32
	v_cvt_pk_f32_fp8_sdwa v[218:219], v32 src0_sel:WORD_1
	v_cvt_pk_f32_fp8_e32 v[220:221], v33
	v_cvt_pk_f32_fp8_sdwa v[222:223], v33 src0_sel:WORD_1
	v_cvt_pk_f32_fp8_e32 v[224:225], v34
	v_cvt_pk_f32_fp8_sdwa v[226:227], v34 src0_sel:WORD_1
	v_cvt_pk_f32_fp8_e32 v[228:229], v35
	v_cvt_pk_f32_fp8_sdwa v[230:231], v35 src0_sel:WORD_1
	v_pk_fma_f32 v[64:65], s[20:21], v[216:217], v[64:65] op_sel_hi:[0,1,1]
	v_pk_fma_f32 v[66:67], s[20:21], v[218:219], v[66:67] op_sel_hi:[0,1,1]
	v_pk_fma_f32 v[68:69], s[20:21], v[220:221], v[68:69] op_sel_hi:[0,1,1]
	v_pk_fma_f32 v[70:71], s[20:21], v[222:223], v[70:71] op_sel_hi:[0,1,1]
	v_pk_fma_f32 v[72:73], s[20:21], v[224:225], v[72:73] op_sel_hi:[0,1,1]
	v_pk_fma_f32 v[74:75], s[20:21], v[226:227], v[74:75] op_sel_hi:[0,1,1]
	v_pk_fma_f32 v[76:77], s[20:21], v[228:229], v[76:77] op_sel_hi:[0,1,1]
	v_pk_fma_f32 v[78:79], s[20:21], v[230:231], v[78:79] op_sel_hi:[0,1,1]
	v_readlane_b32 s28, v177, 52
	s_lshl_b32 s28, s28, 10
	v_add_u32_e32 v232, s28, v208
	global_load_dwordx4 v[32:35], v232, s[12:13]
	s_waitcnt vmcnt(15)
	v_readlane_b32 s24, v179, 45
	v_cvt_pk_f32_fp8_e32 v[216:217], v36
	v_cvt_pk_f32_fp8_sdwa v[218:219], v36 src0_sel:WORD_1
	v_cvt_pk_f32_fp8_e32 v[220:221], v37
	v_cvt_pk_f32_fp8_sdwa v[222:223], v37 src0_sel:WORD_1
	v_cvt_pk_f32_fp8_e32 v[224:225], v38
	v_cvt_pk_f32_fp8_sdwa v[226:227], v38 src0_sel:WORD_1
	v_cvt_pk_f32_fp8_e32 v[228:229], v39
	v_cvt_pk_f32_fp8_sdwa v[230:231], v39 src0_sel:WORD_1
	v_pk_fma_f32 v[80:81], s[22:23], v[216:217], v[80:81] op_sel_hi:[0,1,1]
	v_pk_fma_f32 v[82:83], s[22:23], v[218:219], v[82:83] op_sel_hi:[0,1,1]
	v_pk_fma_f32 v[84:85], s[22:23], v[220:221], v[84:85] op_sel_hi:[0,1,1]
	v_pk_fma_f32 v[86:87], s[22:23], v[222:223], v[86:87] op_sel_hi:[0,1,1]
	v_pk_fma_f32 v[88:89], s[22:23], v[224:225], v[88:89] op_sel_hi:[0,1,1]
	v_pk_fma_f32 v[90:91], s[22:23], v[226:227], v[90:91] op_sel_hi:[0,1,1]
	v_pk_fma_f32 v[92:93], s[22:23], v[228:229], v[92:93] op_sel_hi:[0,1,1]
	v_pk_fma_f32 v[94:95], s[22:23], v[230:231], v[94:95] op_sel_hi:[0,1,1]
	v_readlane_b32 s29, v181, 52
	s_lshl_b32 s29, s29, 10
	v_add_u32_e32 v233, s29, v208
	global_load_dwordx4 v[36:39], v233, s[12:13]
	s_waitcnt vmcnt(15)
	v_readlane_b32 s26, v183, 45
	v_cvt_pk_f32_fp8_e32 v[216:217], v40
	v_cvt_pk_f32_fp8_sdwa v[218:219], v40 src0_sel:WORD_1
	v_cvt_pk_f32_fp8_e32 v[220:221], v41
	v_cvt_pk_f32_fp8_sdwa v[222:223], v41 src0_sel:WORD_1
	v_cvt_pk_f32_fp8_e32 v[224:225], v42
	v_cvt_pk_f32_fp8_sdwa v[226:227], v42 src0_sel:WORD_1
	v_cvt_pk_f32_fp8_e32 v[228:229], v43
	v_cvt_pk_f32_fp8_sdwa v[230:231], v43 src0_sel:WORD_1
	v_pk_fma_f32 v[64:65], s[24:25], v[216:217], v[64:65] op_sel_hi:[0,1,1]
	v_pk_fma_f32 v[66:67], s[24:25], v[218:219], v[66:67] op_sel_hi:[0,1,1]
	v_pk_fma_f32 v[68:69], s[24:25], v[220:221], v[68:69] op_sel_hi:[0,1,1]
	v_pk_fma_f32 v[70:71], s[24:25], v[222:223], v[70:71] op_sel_hi:[0,1,1]
	v_pk_fma_f32 v[72:73], s[24:25], v[224:225], v[72:73] op_sel_hi:[0,1,1]
	v_pk_fma_f32 v[74:75], s[24:25], v[226:227], v[74:75] op_sel_hi:[0,1,1]
	v_pk_fma_f32 v[76:77], s[24:25], v[228:229], v[76:77] op_sel_hi:[0,1,1]
	v_pk_fma_f32 v[78:79], s[24:25], v[230:231], v[78:79] op_sel_hi:[0,1,1]
	v_readlane_b32 s30, v177, 53
	s_lshl_b32 s30, s30, 10
	v_add_u32_e32 v234, s30, v208
	global_load_dwordx4 v[40:43], v234, s[12:13]
	s_waitcnt vmcnt(15)
	v_readlane_b32 s20, v179, 46
	v_cvt_pk_f32_fp8_e32 v[216:217], v44
	v_cvt_pk_f32_fp8_sdwa v[218:219], v44 src0_sel:WORD_1
	v_cvt_pk_f32_fp8_e32 v[220:221], v45
	v_cvt_pk_f32_fp8_sdwa v[222:223], v45 src0_sel:WORD_1
	v_cvt_pk_f32_fp8_e32 v[224:225], v46
	v_cvt_pk_f32_fp8_sdwa v[226:227], v46 src0_sel:WORD_1
	v_cvt_pk_f32_fp8_e32 v[228:229], v47
	v_cvt_pk_f32_fp8_sdwa v[230:231], v47 src0_sel:WORD_1
	v_pk_fma_f32 v[80:81], s[26:27], v[216:217], v[80:81] op_sel_hi:[0,1,1]
	v_pk_fma_f32 v[82:83], s[26:27], v[218:219], v[82:83] op_sel_hi:[0,1,1]
	v_pk_fma_f32 v[84:85], s[26:27], v[220:221], v[84:85] op_sel_hi:[0,1,1]
	v_pk_fma_f32 v[86:87], s[26:27], v[222:223], v[86:87] op_sel_hi:[0,1,1]
	v_pk_fma_f32 v[88:89], s[26:27], v[224:225], v[88:89] op_sel_hi:[0,1,1]
	v_pk_fma_f32 v[90:91], s[26:27], v[226:227], v[90:91] op_sel_hi:[0,1,1]
	v_pk_fma_f32 v[92:93], s[26:27], v[228:229], v[92:93] op_sel_hi:[0,1,1]
	v_pk_fma_f32 v[94:95], s[26:27], v[230:231], v[94:95] op_sel_hi:[0,1,1]
	v_readlane_b32 s31, v181, 53
	s_lshl_b32 s31, s31, 10
	v_add_u32_e32 v235, s31, v208
	global_load_dwordx4 v[44:47], v235, s[12:13]
	s_waitcnt vmcnt(15)
	v_readlane_b32 s22, v183, 46
	v_cvt_pk_f32_fp8_e32 v[216:217], v48
	v_cvt_pk_f32_fp8_sdwa v[218:219], v48 src0_sel:WORD_1
	v_cvt_pk_f32_fp8_e32 v[220:221], v49
	v_cvt_pk_f32_fp8_sdwa v[222:223], v49 src0_sel:WORD_1
	v_cvt_pk_f32_fp8_e32 v[224:225], v50
	v_cvt_pk_f32_fp8_sdwa v[226:227], v50 src0_sel:WORD_1
	v_cvt_pk_f32_fp8_e32 v[228:229], v51
	v_cvt_pk_f32_fp8_sdwa v[230:231], v51 src0_sel:WORD_1
	v_pk_fma_f32 v[64:65], s[20:21], v[216:217], v[64:65] op_sel_hi:[0,1,1]
	v_pk_fma_f32 v[66:67], s[20:21], v[218:219], v[66:67] op_sel_hi:[0,1,1]
	v_pk_fma_f32 v[68:69], s[20:21], v[220:221], v[68:69] op_sel_hi:[0,1,1]
	v_pk_fma_f32 v[70:71], s[20:21], v[222:223], v[70:71] op_sel_hi:[0,1,1]
	v_pk_fma_f32 v[72:73], s[20:21], v[224:225], v[72:73] op_sel_hi:[0,1,1]
	v_pk_fma_f32 v[74:75], s[20:21], v[226:227], v[74:75] op_sel_hi:[0,1,1]
	v_pk_fma_f32 v[76:77], s[20:21], v[228:229], v[76:77] op_sel_hi:[0,1,1]
	v_pk_fma_f32 v[78:79], s[20:21], v[230:231], v[78:79] op_sel_hi:[0,1,1]
	v_readlane_b32 s28, v177, 54
	s_lshl_b32 s28, s28, 10
	v_add_u32_e32 v232, s28, v208
	global_load_dwordx4 v[48:51], v232, s[12:13]
	s_waitcnt vmcnt(15)
	v_readlane_b32 s24, v179, 47
	v_cvt_pk_f32_fp8_e32 v[216:217], v52
	v_cvt_pk_f32_fp8_sdwa v[218:219], v52 src0_sel:WORD_1
	v_cvt_pk_f32_fp8_e32 v[220:221], v53
	v_cvt_pk_f32_fp8_sdwa v[222:223], v53 src0_sel:WORD_1
	v_cvt_pk_f32_fp8_e32 v[224:225], v54
	v_cvt_pk_f32_fp8_sdwa v[226:227], v54 src0_sel:WORD_1
	v_cvt_pk_f32_fp8_e32 v[228:229], v55
	v_cvt_pk_f32_fp8_sdwa v[230:231], v55 src0_sel:WORD_1
	v_pk_fma_f32 v[80:81], s[22:23], v[216:217], v[80:81] op_sel_hi:[0,1,1]
	v_pk_fma_f32 v[82:83], s[22:23], v[218:219], v[82:83] op_sel_hi:[0,1,1]
	v_pk_fma_f32 v[84:85], s[22:23], v[220:221], v[84:85] op_sel_hi:[0,1,1]
	v_pk_fma_f32 v[86:87], s[22:23], v[222:223], v[86:87] op_sel_hi:[0,1,1]
	v_pk_fma_f32 v[88:89], s[22:23], v[224:225], v[88:89] op_sel_hi:[0,1,1]
	v_pk_fma_f32 v[90:91], s[22:23], v[226:227], v[90:91] op_sel_hi:[0,1,1]
	v_pk_fma_f32 v[92:93], s[22:23], v[228:229], v[92:93] op_sel_hi:[0,1,1]
	v_pk_fma_f32 v[94:95], s[22:23], v[230:231], v[94:95] op_sel_hi:[0,1,1]
	v_readlane_b32 s29, v181, 54
	s_lshl_b32 s29, s29, 10
	v_add_u32_e32 v233, s29, v208
	global_load_dwordx4 v[52:55], v233, s[12:13]
	s_waitcnt vmcnt(15)
	v_readlane_b32 s26, v183, 47
	v_cvt_pk_f32_fp8_e32 v[216:217], v56
	v_cvt_pk_f32_fp8_sdwa v[218:219], v56 src0_sel:WORD_1
	v_cvt_pk_f32_fp8_e32 v[220:221], v57
	v_cvt_pk_f32_fp8_sdwa v[222:223], v57 src0_sel:WORD_1
	v_cvt_pk_f32_fp8_e32 v[224:225], v58
	v_cvt_pk_f32_fp8_sdwa v[226:227], v58 src0_sel:WORD_1
	v_cvt_pk_f32_fp8_e32 v[228:229], v59
	v_cvt_pk_f32_fp8_sdwa v[230:231], v59 src0_sel:WORD_1
	v_pk_fma_f32 v[64:65], s[24:25], v[216:217], v[64:65] op_sel_hi:[0,1,1]
	v_pk_fma_f32 v[66:67], s[24:25], v[218:219], v[66:67] op_sel_hi:[0,1,1]
	v_pk_fma_f32 v[68:69], s[24:25], v[220:221], v[68:69] op_sel_hi:[0,1,1]
	v_pk_fma_f32 v[70:71], s[24:25], v[222:223], v[70:71] op_sel_hi:[0,1,1]
	v_pk_fma_f32 v[72:73], s[24:25], v[224:225], v[72:73] op_sel_hi:[0,1,1]
	v_pk_fma_f32 v[74:75], s[24:25], v[226:227], v[74:75] op_sel_hi:[0,1,1]
	v_pk_fma_f32 v[76:77], s[24:25], v[228:229], v[76:77] op_sel_hi:[0,1,1]
	v_pk_fma_f32 v[78:79], s[24:25], v[230:231], v[78:79] op_sel_hi:[0,1,1]
	v_readlane_b32 s30, v177, 55
	s_lshl_b32 s30, s30, 10
	v_add_u32_e32 v234, s30, v208
	global_load_dwordx4 v[56:59], v234, s[12:13]
	s_waitcnt vmcnt(15)
	v_readlane_b32 s20, v179, 48
	v_cvt_pk_f32_fp8_e32 v[216:217], v60
	v_cvt_pk_f32_fp8_sdwa v[218:219], v60 src0_sel:WORD_1
	v_cvt_pk_f32_fp8_e32 v[220:221], v61
	v_cvt_pk_f32_fp8_sdwa v[222:223], v61 src0_sel:WORD_1
	v_cvt_pk_f32_fp8_e32 v[224:225], v62
	v_cvt_pk_f32_fp8_sdwa v[226:227], v62 src0_sel:WORD_1
	v_cvt_pk_f32_fp8_e32 v[228:229], v63
	v_cvt_pk_f32_fp8_sdwa v[230:231], v63 src0_sel:WORD_1
	v_pk_fma_f32 v[80:81], s[26:27], v[216:217], v[80:81] op_sel_hi:[0,1,1]
	v_pk_fma_f32 v[82:83], s[26:27], v[218:219], v[82:83] op_sel_hi:[0,1,1]
	v_pk_fma_f32 v[84:85], s[26:27], v[220:221], v[84:85] op_sel_hi:[0,1,1]
	v_pk_fma_f32 v[86:87], s[26:27], v[222:223], v[86:87] op_sel_hi:[0,1,1]
	v_pk_fma_f32 v[88:89], s[26:27], v[224:225], v[88:89] op_sel_hi:[0,1,1]
	v_pk_fma_f32 v[90:91], s[26:27], v[226:227], v[90:91] op_sel_hi:[0,1,1]
	v_pk_fma_f32 v[92:93], s[26:27], v[228:229], v[92:93] op_sel_hi:[0,1,1]
	v_pk_fma_f32 v[94:95], s[26:27], v[230:231], v[94:95] op_sel_hi:[0,1,1]
	v_readlane_b32 s31, v181, 55
	s_lshl_b32 s31, s31, 10
	v_add_u32_e32 v235, s31, v208
	global_load_dwordx4 v[60:63], v235, s[12:13]
	s_waitcnt vmcnt(15)
	v_readlane_b32 s22, v183, 48
	v_cvt_pk_f32_fp8_e32 v[216:217], v0
	v_cvt_pk_f32_fp8_sdwa v[218:219], v0 src0_sel:WORD_1
	v_cvt_pk_f32_fp8_e32 v[220:221], v1
	v_cvt_pk_f32_fp8_sdwa v[222:223], v1 src0_sel:WORD_1
	v_cvt_pk_f32_fp8_e32 v[224:225], v2
	v_cvt_pk_f32_fp8_sdwa v[226:227], v2 src0_sel:WORD_1
	v_cvt_pk_f32_fp8_e32 v[228:229], v3
	v_cvt_pk_f32_fp8_sdwa v[230:231], v3 src0_sel:WORD_1
	v_pk_fma_f32 v[64:65], s[20:21], v[216:217], v[64:65] op_sel_hi:[0,1,1]
	v_pk_fma_f32 v[66:67], s[20:21], v[218:219], v[66:67] op_sel_hi:[0,1,1]
	v_pk_fma_f32 v[68:69], s[20:21], v[220:221], v[68:69] op_sel_hi:[0,1,1]
	v_pk_fma_f32 v[70:71], s[20:21], v[222:223], v[70:71] op_sel_hi:[0,1,1]
	v_pk_fma_f32 v[72:73], s[20:21], v[224:225], v[72:73] op_sel_hi:[0,1,1]
	v_pk_fma_f32 v[74:75], s[20:21], v[226:227], v[74:75] op_sel_hi:[0,1,1]
	v_pk_fma_f32 v[76:77], s[20:21], v[228:229], v[76:77] op_sel_hi:[0,1,1]
	v_pk_fma_f32 v[78:79], s[20:21], v[230:231], v[78:79] op_sel_hi:[0,1,1]
	v_readlane_b32 s28, v177, 56
	s_lshl_b32 s28, s28, 10
	v_add_u32_e32 v232, s28, v208
	global_load_dwordx4 v[0:3], v232, s[12:13]
	s_waitcnt vmcnt(15)
	v_readlane_b32 s24, v179, 49
	v_cvt_pk_f32_fp8_e32 v[216:217], v4
	v_cvt_pk_f32_fp8_sdwa v[218:219], v4 src0_sel:WORD_1
	v_cvt_pk_f32_fp8_e32 v[220:221], v5
	v_cvt_pk_f32_fp8_sdwa v[222:223], v5 src0_sel:WORD_1
	v_cvt_pk_f32_fp8_e32 v[224:225], v6
	v_cvt_pk_f32_fp8_sdwa v[226:227], v6 src0_sel:WORD_1
	v_cvt_pk_f32_fp8_e32 v[228:229], v7
	v_cvt_pk_f32_fp8_sdwa v[230:231], v7 src0_sel:WORD_1
	v_pk_fma_f32 v[80:81], s[22:23], v[216:217], v[80:81] op_sel_hi:[0,1,1]
	v_pk_fma_f32 v[82:83], s[22:23], v[218:219], v[82:83] op_sel_hi:[0,1,1]
	v_pk_fma_f32 v[84:85], s[22:23], v[220:221], v[84:85] op_sel_hi:[0,1,1]
	v_pk_fma_f32 v[86:87], s[22:23], v[222:223], v[86:87] op_sel_hi:[0,1,1]
	v_pk_fma_f32 v[88:89], s[22:23], v[224:225], v[88:89] op_sel_hi:[0,1,1]
	v_pk_fma_f32 v[90:91], s[22:23], v[226:227], v[90:91] op_sel_hi:[0,1,1]
	v_pk_fma_f32 v[92:93], s[22:23], v[228:229], v[92:93] op_sel_hi:[0,1,1]
	v_pk_fma_f32 v[94:95], s[22:23], v[230:231], v[94:95] op_sel_hi:[0,1,1]
	v_readlane_b32 s29, v181, 56
	s_lshl_b32 s29, s29, 10
	v_add_u32_e32 v233, s29, v208
	global_load_dwordx4 v[4:7], v233, s[12:13]
	s_waitcnt vmcnt(15)
	v_readlane_b32 s26, v183, 49
	v_cvt_pk_f32_fp8_e32 v[216:217], v8
	v_cvt_pk_f32_fp8_sdwa v[218:219], v8 src0_sel:WORD_1
	v_cvt_pk_f32_fp8_e32 v[220:221], v9
	v_cvt_pk_f32_fp8_sdwa v[222:223], v9 src0_sel:WORD_1
	v_cvt_pk_f32_fp8_e32 v[224:225], v10
	v_cvt_pk_f32_fp8_sdwa v[226:227], v10 src0_sel:WORD_1
	v_cvt_pk_f32_fp8_e32 v[228:229], v11
	v_cvt_pk_f32_fp8_sdwa v[230:231], v11 src0_sel:WORD_1
	v_pk_fma_f32 v[64:65], s[24:25], v[216:217], v[64:65] op_sel_hi:[0,1,1]
	v_pk_fma_f32 v[66:67], s[24:25], v[218:219], v[66:67] op_sel_hi:[0,1,1]
	v_pk_fma_f32 v[68:69], s[24:25], v[220:221], v[68:69] op_sel_hi:[0,1,1]
	v_pk_fma_f32 v[70:71], s[24:25], v[222:223], v[70:71] op_sel_hi:[0,1,1]
	v_pk_fma_f32 v[72:73], s[24:25], v[224:225], v[72:73] op_sel_hi:[0,1,1]
	v_pk_fma_f32 v[74:75], s[24:25], v[226:227], v[74:75] op_sel_hi:[0,1,1]
	v_pk_fma_f32 v[76:77], s[24:25], v[228:229], v[76:77] op_sel_hi:[0,1,1]
	v_pk_fma_f32 v[78:79], s[24:25], v[230:231], v[78:79] op_sel_hi:[0,1,1]
	v_readlane_b32 s30, v177, 57
	s_lshl_b32 s30, s30, 10
	v_add_u32_e32 v234, s30, v208
	global_load_dwordx4 v[8:11], v234, s[12:13]
	s_waitcnt vmcnt(15)
	v_readlane_b32 s20, v179, 50
	v_cvt_pk_f32_fp8_e32 v[216:217], v12
	v_cvt_pk_f32_fp8_sdwa v[218:219], v12 src0_sel:WORD_1
	v_cvt_pk_f32_fp8_e32 v[220:221], v13
	v_cvt_pk_f32_fp8_sdwa v[222:223], v13 src0_sel:WORD_1
	v_cvt_pk_f32_fp8_e32 v[224:225], v14
	v_cvt_pk_f32_fp8_sdwa v[226:227], v14 src0_sel:WORD_1
	v_cvt_pk_f32_fp8_e32 v[228:229], v15
	v_cvt_pk_f32_fp8_sdwa v[230:231], v15 src0_sel:WORD_1
	v_pk_fma_f32 v[80:81], s[26:27], v[216:217], v[80:81] op_sel_hi:[0,1,1]
	v_pk_fma_f32 v[82:83], s[26:27], v[218:219], v[82:83] op_sel_hi:[0,1,1]
	v_pk_fma_f32 v[84:85], s[26:27], v[220:221], v[84:85] op_sel_hi:[0,1,1]
	v_pk_fma_f32 v[86:87], s[26:27], v[222:223], v[86:87] op_sel_hi:[0,1,1]
	v_pk_fma_f32 v[88:89], s[26:27], v[224:225], v[88:89] op_sel_hi:[0,1,1]
	v_pk_fma_f32 v[90:91], s[26:27], v[226:227], v[90:91] op_sel_hi:[0,1,1]
	v_pk_fma_f32 v[92:93], s[26:27], v[228:229], v[92:93] op_sel_hi:[0,1,1]
	v_pk_fma_f32 v[94:95], s[26:27], v[230:231], v[94:95] op_sel_hi:[0,1,1]
	v_readlane_b32 s31, v181, 57
	s_lshl_b32 s31, s31, 10
	v_add_u32_e32 v235, s31, v208
	global_load_dwordx4 v[12:15], v235, s[12:13]
	s_waitcnt vmcnt(15)
	v_readlane_b32 s22, v183, 50
	v_cvt_pk_f32_fp8_e32 v[216:217], v16
	v_cvt_pk_f32_fp8_sdwa v[218:219], v16 src0_sel:WORD_1
	v_cvt_pk_f32_fp8_e32 v[220:221], v17
	v_cvt_pk_f32_fp8_sdwa v[222:223], v17 src0_sel:WORD_1
	v_cvt_pk_f32_fp8_e32 v[224:225], v18
	v_cvt_pk_f32_fp8_sdwa v[226:227], v18 src0_sel:WORD_1
	v_cvt_pk_f32_fp8_e32 v[228:229], v19
	v_cvt_pk_f32_fp8_sdwa v[230:231], v19 src0_sel:WORD_1
	v_pk_fma_f32 v[64:65], s[20:21], v[216:217], v[64:65] op_sel_hi:[0,1,1]
	v_pk_fma_f32 v[66:67], s[20:21], v[218:219], v[66:67] op_sel_hi:[0,1,1]
	v_pk_fma_f32 v[68:69], s[20:21], v[220:221], v[68:69] op_sel_hi:[0,1,1]
	v_pk_fma_f32 v[70:71], s[20:21], v[222:223], v[70:71] op_sel_hi:[0,1,1]
	v_pk_fma_f32 v[72:73], s[20:21], v[224:225], v[72:73] op_sel_hi:[0,1,1]
	v_pk_fma_f32 v[74:75], s[20:21], v[226:227], v[74:75] op_sel_hi:[0,1,1]
	v_pk_fma_f32 v[76:77], s[20:21], v[228:229], v[76:77] op_sel_hi:[0,1,1]
	v_pk_fma_f32 v[78:79], s[20:21], v[230:231], v[78:79] op_sel_hi:[0,1,1]
	v_readlane_b32 s28, v177, 58
	s_lshl_b32 s28, s28, 10
	v_add_u32_e32 v232, s28, v208
	global_load_dwordx4 v[16:19], v232, s[12:13]
	s_waitcnt vmcnt(15)
	v_readlane_b32 s24, v179, 51
	v_cvt_pk_f32_fp8_e32 v[216:217], v20
	v_cvt_pk_f32_fp8_sdwa v[218:219], v20 src0_sel:WORD_1
	v_cvt_pk_f32_fp8_e32 v[220:221], v21
	v_cvt_pk_f32_fp8_sdwa v[222:223], v21 src0_sel:WORD_1
	v_cvt_pk_f32_fp8_e32 v[224:225], v22
	v_cvt_pk_f32_fp8_sdwa v[226:227], v22 src0_sel:WORD_1
	v_cvt_pk_f32_fp8_e32 v[228:229], v23
	v_cvt_pk_f32_fp8_sdwa v[230:231], v23 src0_sel:WORD_1
	v_pk_fma_f32 v[80:81], s[22:23], v[216:217], v[80:81] op_sel_hi:[0,1,1]
	v_pk_fma_f32 v[82:83], s[22:23], v[218:219], v[82:83] op_sel_hi:[0,1,1]
	v_pk_fma_f32 v[84:85], s[22:23], v[220:221], v[84:85] op_sel_hi:[0,1,1]
	v_pk_fma_f32 v[86:87], s[22:23], v[222:223], v[86:87] op_sel_hi:[0,1,1]
	v_pk_fma_f32 v[88:89], s[22:23], v[224:225], v[88:89] op_sel_hi:[0,1,1]
	v_pk_fma_f32 v[90:91], s[22:23], v[226:227], v[90:91] op_sel_hi:[0,1,1]
	v_pk_fma_f32 v[92:93], s[22:23], v[228:229], v[92:93] op_sel_hi:[0,1,1]
	v_pk_fma_f32 v[94:95], s[22:23], v[230:231], v[94:95] op_sel_hi:[0,1,1]
	v_readlane_b32 s29, v181, 58
	s_lshl_b32 s29, s29, 10
	v_add_u32_e32 v233, s29, v208
	global_load_dwordx4 v[20:23], v233, s[12:13]
	s_waitcnt vmcnt(15)
	v_readlane_b32 s26, v183, 51
	v_cvt_pk_f32_fp8_e32 v[216:217], v24
	v_cvt_pk_f32_fp8_sdwa v[218:219], v24 src0_sel:WORD_1
	v_cvt_pk_f32_fp8_e32 v[220:221], v25
	v_cvt_pk_f32_fp8_sdwa v[222:223], v25 src0_sel:WORD_1
	v_cvt_pk_f32_fp8_e32 v[224:225], v26
	v_cvt_pk_f32_fp8_sdwa v[226:227], v26 src0_sel:WORD_1
	v_cvt_pk_f32_fp8_e32 v[228:229], v27
	v_cvt_pk_f32_fp8_sdwa v[230:231], v27 src0_sel:WORD_1
	v_pk_fma_f32 v[64:65], s[24:25], v[216:217], v[64:65] op_sel_hi:[0,1,1]
	v_pk_fma_f32 v[66:67], s[24:25], v[218:219], v[66:67] op_sel_hi:[0,1,1]
	v_pk_fma_f32 v[68:69], s[24:25], v[220:221], v[68:69] op_sel_hi:[0,1,1]
	v_pk_fma_f32 v[70:71], s[24:25], v[222:223], v[70:71] op_sel_hi:[0,1,1]
	v_pk_fma_f32 v[72:73], s[24:25], v[224:225], v[72:73] op_sel_hi:[0,1,1]
	v_pk_fma_f32 v[74:75], s[24:25], v[226:227], v[74:75] op_sel_hi:[0,1,1]
	v_pk_fma_f32 v[76:77], s[24:25], v[228:229], v[76:77] op_sel_hi:[0,1,1]
	v_pk_fma_f32 v[78:79], s[24:25], v[230:231], v[78:79] op_sel_hi:[0,1,1]
	v_readlane_b32 s30, v177, 59
	s_lshl_b32 s30, s30, 10
	v_add_u32_e32 v234, s30, v208
	global_load_dwordx4 v[24:27], v234, s[12:13]
	s_waitcnt vmcnt(15)
	v_readlane_b32 s20, v179, 52
	v_cvt_pk_f32_fp8_e32 v[216:217], v28
	v_cvt_pk_f32_fp8_sdwa v[218:219], v28 src0_sel:WORD_1
	v_cvt_pk_f32_fp8_e32 v[220:221], v29
	v_cvt_pk_f32_fp8_sdwa v[222:223], v29 src0_sel:WORD_1
	v_cvt_pk_f32_fp8_e32 v[224:225], v30
	v_cvt_pk_f32_fp8_sdwa v[226:227], v30 src0_sel:WORD_1
	v_cvt_pk_f32_fp8_e32 v[228:229], v31
	v_cvt_pk_f32_fp8_sdwa v[230:231], v31 src0_sel:WORD_1
	v_pk_fma_f32 v[80:81], s[26:27], v[216:217], v[80:81] op_sel_hi:[0,1,1]
	v_pk_fma_f32 v[82:83], s[26:27], v[218:219], v[82:83] op_sel_hi:[0,1,1]
	v_pk_fma_f32 v[84:85], s[26:27], v[220:221], v[84:85] op_sel_hi:[0,1,1]
	v_pk_fma_f32 v[86:87], s[26:27], v[222:223], v[86:87] op_sel_hi:[0,1,1]
	v_pk_fma_f32 v[88:89], s[26:27], v[224:225], v[88:89] op_sel_hi:[0,1,1]
	v_pk_fma_f32 v[90:91], s[26:27], v[226:227], v[90:91] op_sel_hi:[0,1,1]
	v_pk_fma_f32 v[92:93], s[26:27], v[228:229], v[92:93] op_sel_hi:[0,1,1]
	v_pk_fma_f32 v[94:95], s[26:27], v[230:231], v[94:95] op_sel_hi:[0,1,1]
	v_readlane_b32 s31, v181, 59
	s_lshl_b32 s31, s31, 10
	v_add_u32_e32 v235, s31, v208
	global_load_dwordx4 v[28:31], v235, s[12:13]
	s_waitcnt vmcnt(15)
	v_readlane_b32 s22, v183, 52
	v_cvt_pk_f32_fp8_e32 v[216:217], v32
	v_cvt_pk_f32_fp8_sdwa v[218:219], v32 src0_sel:WORD_1
	v_cvt_pk_f32_fp8_e32 v[220:221], v33
	v_cvt_pk_f32_fp8_sdwa v[222:223], v33 src0_sel:WORD_1
	v_cvt_pk_f32_fp8_e32 v[224:225], v34
	v_cvt_pk_f32_fp8_sdwa v[226:227], v34 src0_sel:WORD_1
	v_cvt_pk_f32_fp8_e32 v[228:229], v35
	v_cvt_pk_f32_fp8_sdwa v[230:231], v35 src0_sel:WORD_1
	v_pk_fma_f32 v[64:65], s[20:21], v[216:217], v[64:65] op_sel_hi:[0,1,1]
	v_pk_fma_f32 v[66:67], s[20:21], v[218:219], v[66:67] op_sel_hi:[0,1,1]
	v_pk_fma_f32 v[68:69], s[20:21], v[220:221], v[68:69] op_sel_hi:[0,1,1]
	v_pk_fma_f32 v[70:71], s[20:21], v[222:223], v[70:71] op_sel_hi:[0,1,1]
	v_pk_fma_f32 v[72:73], s[20:21], v[224:225], v[72:73] op_sel_hi:[0,1,1]
	v_pk_fma_f32 v[74:75], s[20:21], v[226:227], v[74:75] op_sel_hi:[0,1,1]
	v_pk_fma_f32 v[76:77], s[20:21], v[228:229], v[76:77] op_sel_hi:[0,1,1]
	v_pk_fma_f32 v[78:79], s[20:21], v[230:231], v[78:79] op_sel_hi:[0,1,1]
	v_readlane_b32 s28, v177, 60
	s_lshl_b32 s28, s28, 10
	v_add_u32_e32 v232, s28, v208
	global_load_dwordx4 v[32:35], v232, s[12:13]
	s_waitcnt vmcnt(15)
	v_readlane_b32 s24, v179, 53
	v_cvt_pk_f32_fp8_e32 v[216:217], v36
	v_cvt_pk_f32_fp8_sdwa v[218:219], v36 src0_sel:WORD_1
	v_cvt_pk_f32_fp8_e32 v[220:221], v37
	v_cvt_pk_f32_fp8_sdwa v[222:223], v37 src0_sel:WORD_1
	v_cvt_pk_f32_fp8_e32 v[224:225], v38
	v_cvt_pk_f32_fp8_sdwa v[226:227], v38 src0_sel:WORD_1
	v_cvt_pk_f32_fp8_e32 v[228:229], v39
	v_cvt_pk_f32_fp8_sdwa v[230:231], v39 src0_sel:WORD_1
	v_pk_fma_f32 v[80:81], s[22:23], v[216:217], v[80:81] op_sel_hi:[0,1,1]
	v_pk_fma_f32 v[82:83], s[22:23], v[218:219], v[82:83] op_sel_hi:[0,1,1]
	v_pk_fma_f32 v[84:85], s[22:23], v[220:221], v[84:85] op_sel_hi:[0,1,1]
	v_pk_fma_f32 v[86:87], s[22:23], v[222:223], v[86:87] op_sel_hi:[0,1,1]
	v_pk_fma_f32 v[88:89], s[22:23], v[224:225], v[88:89] op_sel_hi:[0,1,1]
	v_pk_fma_f32 v[90:91], s[22:23], v[226:227], v[90:91] op_sel_hi:[0,1,1]
	v_pk_fma_f32 v[92:93], s[22:23], v[228:229], v[92:93] op_sel_hi:[0,1,1]
	v_pk_fma_f32 v[94:95], s[22:23], v[230:231], v[94:95] op_sel_hi:[0,1,1]
	v_readlane_b32 s29, v181, 60
	s_lshl_b32 s29, s29, 10
	v_add_u32_e32 v233, s29, v208
	global_load_dwordx4 v[36:39], v233, s[12:13]
	s_waitcnt vmcnt(15)
	v_readlane_b32 s26, v183, 53
	v_cvt_pk_f32_fp8_e32 v[216:217], v40
	v_cvt_pk_f32_fp8_sdwa v[218:219], v40 src0_sel:WORD_1
	v_cvt_pk_f32_fp8_e32 v[220:221], v41
	v_cvt_pk_f32_fp8_sdwa v[222:223], v41 src0_sel:WORD_1
	v_cvt_pk_f32_fp8_e32 v[224:225], v42
	v_cvt_pk_f32_fp8_sdwa v[226:227], v42 src0_sel:WORD_1
	v_cvt_pk_f32_fp8_e32 v[228:229], v43
	v_cvt_pk_f32_fp8_sdwa v[230:231], v43 src0_sel:WORD_1
	v_pk_fma_f32 v[64:65], s[24:25], v[216:217], v[64:65] op_sel_hi:[0,1,1]
	v_pk_fma_f32 v[66:67], s[24:25], v[218:219], v[66:67] op_sel_hi:[0,1,1]
	v_pk_fma_f32 v[68:69], s[24:25], v[220:221], v[68:69] op_sel_hi:[0,1,1]
	v_pk_fma_f32 v[70:71], s[24:25], v[222:223], v[70:71] op_sel_hi:[0,1,1]
	v_pk_fma_f32 v[72:73], s[24:25], v[224:225], v[72:73] op_sel_hi:[0,1,1]
	v_pk_fma_f32 v[74:75], s[24:25], v[226:227], v[74:75] op_sel_hi:[0,1,1]
	v_pk_fma_f32 v[76:77], s[24:25], v[228:229], v[76:77] op_sel_hi:[0,1,1]
	v_pk_fma_f32 v[78:79], s[24:25], v[230:231], v[78:79] op_sel_hi:[0,1,1]
	v_readlane_b32 s30, v177, 61
	s_lshl_b32 s30, s30, 10
	v_add_u32_e32 v234, s30, v208
	global_load_dwordx4 v[40:43], v234, s[12:13]
	s_waitcnt vmcnt(15)
	v_readlane_b32 s20, v179, 54
	v_cvt_pk_f32_fp8_e32 v[216:217], v44
	v_cvt_pk_f32_fp8_sdwa v[218:219], v44 src0_sel:WORD_1
	v_cvt_pk_f32_fp8_e32 v[220:221], v45
	v_cvt_pk_f32_fp8_sdwa v[222:223], v45 src0_sel:WORD_1
	v_cvt_pk_f32_fp8_e32 v[224:225], v46
	v_cvt_pk_f32_fp8_sdwa v[226:227], v46 src0_sel:WORD_1
	v_cvt_pk_f32_fp8_e32 v[228:229], v47
	v_cvt_pk_f32_fp8_sdwa v[230:231], v47 src0_sel:WORD_1
	v_pk_fma_f32 v[80:81], s[26:27], v[216:217], v[80:81] op_sel_hi:[0,1,1]
	v_pk_fma_f32 v[82:83], s[26:27], v[218:219], v[82:83] op_sel_hi:[0,1,1]
	v_pk_fma_f32 v[84:85], s[26:27], v[220:221], v[84:85] op_sel_hi:[0,1,1]
	v_pk_fma_f32 v[86:87], s[26:27], v[222:223], v[86:87] op_sel_hi:[0,1,1]
	v_pk_fma_f32 v[88:89], s[26:27], v[224:225], v[88:89] op_sel_hi:[0,1,1]
	v_pk_fma_f32 v[90:91], s[26:27], v[226:227], v[90:91] op_sel_hi:[0,1,1]
	v_pk_fma_f32 v[92:93], s[26:27], v[228:229], v[92:93] op_sel_hi:[0,1,1]
	v_pk_fma_f32 v[94:95], s[26:27], v[230:231], v[94:95] op_sel_hi:[0,1,1]
	v_readlane_b32 s31, v181, 61
	s_lshl_b32 s31, s31, 10
	v_add_u32_e32 v235, s31, v208
	global_load_dwordx4 v[44:47], v235, s[12:13]
	s_waitcnt vmcnt(15)
	v_readlane_b32 s22, v183, 54
	v_cvt_pk_f32_fp8_e32 v[216:217], v48
	v_cvt_pk_f32_fp8_sdwa v[218:219], v48 src0_sel:WORD_1
	v_cvt_pk_f32_fp8_e32 v[220:221], v49
	v_cvt_pk_f32_fp8_sdwa v[222:223], v49 src0_sel:WORD_1
	v_cvt_pk_f32_fp8_e32 v[224:225], v50
	v_cvt_pk_f32_fp8_sdwa v[226:227], v50 src0_sel:WORD_1
	v_cvt_pk_f32_fp8_e32 v[228:229], v51
	v_cvt_pk_f32_fp8_sdwa v[230:231], v51 src0_sel:WORD_1
	v_pk_fma_f32 v[64:65], s[20:21], v[216:217], v[64:65] op_sel_hi:[0,1,1]
	v_pk_fma_f32 v[66:67], s[20:21], v[218:219], v[66:67] op_sel_hi:[0,1,1]
	v_pk_fma_f32 v[68:69], s[20:21], v[220:221], v[68:69] op_sel_hi:[0,1,1]
	v_pk_fma_f32 v[70:71], s[20:21], v[222:223], v[70:71] op_sel_hi:[0,1,1]
	v_pk_fma_f32 v[72:73], s[20:21], v[224:225], v[72:73] op_sel_hi:[0,1,1]
	v_pk_fma_f32 v[74:75], s[20:21], v[226:227], v[74:75] op_sel_hi:[0,1,1]
	v_pk_fma_f32 v[76:77], s[20:21], v[228:229], v[76:77] op_sel_hi:[0,1,1]
	v_pk_fma_f32 v[78:79], s[20:21], v[230:231], v[78:79] op_sel_hi:[0,1,1]
	v_readlane_b32 s28, v177, 62
	s_lshl_b32 s28, s28, 10
	v_add_u32_e32 v232, s28, v208
	global_load_dwordx4 v[48:51], v232, s[12:13]
	s_waitcnt vmcnt(15)
	v_readlane_b32 s24, v179, 55
	v_cvt_pk_f32_fp8_e32 v[216:217], v52
	v_cvt_pk_f32_fp8_sdwa v[218:219], v52 src0_sel:WORD_1
	v_cvt_pk_f32_fp8_e32 v[220:221], v53
	v_cvt_pk_f32_fp8_sdwa v[222:223], v53 src0_sel:WORD_1
	v_cvt_pk_f32_fp8_e32 v[224:225], v54
	v_cvt_pk_f32_fp8_sdwa v[226:227], v54 src0_sel:WORD_1
	v_cvt_pk_f32_fp8_e32 v[228:229], v55
	v_cvt_pk_f32_fp8_sdwa v[230:231], v55 src0_sel:WORD_1
	v_pk_fma_f32 v[80:81], s[22:23], v[216:217], v[80:81] op_sel_hi:[0,1,1]
	v_pk_fma_f32 v[82:83], s[22:23], v[218:219], v[82:83] op_sel_hi:[0,1,1]
	v_pk_fma_f32 v[84:85], s[22:23], v[220:221], v[84:85] op_sel_hi:[0,1,1]
	v_pk_fma_f32 v[86:87], s[22:23], v[222:223], v[86:87] op_sel_hi:[0,1,1]
	v_pk_fma_f32 v[88:89], s[22:23], v[224:225], v[88:89] op_sel_hi:[0,1,1]
	v_pk_fma_f32 v[90:91], s[22:23], v[226:227], v[90:91] op_sel_hi:[0,1,1]
	v_pk_fma_f32 v[92:93], s[22:23], v[228:229], v[92:93] op_sel_hi:[0,1,1]
	v_pk_fma_f32 v[94:95], s[22:23], v[230:231], v[94:95] op_sel_hi:[0,1,1]
	v_readlane_b32 s29, v181, 62
	s_lshl_b32 s29, s29, 10
	v_add_u32_e32 v233, s29, v208
	global_load_dwordx4 v[52:55], v233, s[12:13]
	s_waitcnt vmcnt(15)
	v_readlane_b32 s26, v183, 55
	v_cvt_pk_f32_fp8_e32 v[216:217], v56
	v_cvt_pk_f32_fp8_sdwa v[218:219], v56 src0_sel:WORD_1
	v_cvt_pk_f32_fp8_e32 v[220:221], v57
	v_cvt_pk_f32_fp8_sdwa v[222:223], v57 src0_sel:WORD_1
	v_cvt_pk_f32_fp8_e32 v[224:225], v58
	v_cvt_pk_f32_fp8_sdwa v[226:227], v58 src0_sel:WORD_1
	v_cvt_pk_f32_fp8_e32 v[228:229], v59
	v_cvt_pk_f32_fp8_sdwa v[230:231], v59 src0_sel:WORD_1
	v_pk_fma_f32 v[64:65], s[24:25], v[216:217], v[64:65] op_sel_hi:[0,1,1]
	v_pk_fma_f32 v[66:67], s[24:25], v[218:219], v[66:67] op_sel_hi:[0,1,1]
	v_pk_fma_f32 v[68:69], s[24:25], v[220:221], v[68:69] op_sel_hi:[0,1,1]
	v_pk_fma_f32 v[70:71], s[24:25], v[222:223], v[70:71] op_sel_hi:[0,1,1]
	v_pk_fma_f32 v[72:73], s[24:25], v[224:225], v[72:73] op_sel_hi:[0,1,1]
	v_pk_fma_f32 v[74:75], s[24:25], v[226:227], v[74:75] op_sel_hi:[0,1,1]
	v_pk_fma_f32 v[76:77], s[24:25], v[228:229], v[76:77] op_sel_hi:[0,1,1]
	v_pk_fma_f32 v[78:79], s[24:25], v[230:231], v[78:79] op_sel_hi:[0,1,1]
	v_readlane_b32 s30, v177, 63
	s_lshl_b32 s30, s30, 10
	v_add_u32_e32 v234, s30, v208
	global_load_dwordx4 v[56:59], v234, s[12:13]
	s_waitcnt vmcnt(15)
	v_readlane_b32 s20, v179, 56
	v_cvt_pk_f32_fp8_e32 v[216:217], v60
	v_cvt_pk_f32_fp8_sdwa v[218:219], v60 src0_sel:WORD_1
	v_cvt_pk_f32_fp8_e32 v[220:221], v61
	v_cvt_pk_f32_fp8_sdwa v[222:223], v61 src0_sel:WORD_1
	v_cvt_pk_f32_fp8_e32 v[224:225], v62
	v_cvt_pk_f32_fp8_sdwa v[226:227], v62 src0_sel:WORD_1
	v_cvt_pk_f32_fp8_e32 v[228:229], v63
	v_cvt_pk_f32_fp8_sdwa v[230:231], v63 src0_sel:WORD_1
	v_pk_fma_f32 v[80:81], s[26:27], v[216:217], v[80:81] op_sel_hi:[0,1,1]
	v_pk_fma_f32 v[82:83], s[26:27], v[218:219], v[82:83] op_sel_hi:[0,1,1]
	v_pk_fma_f32 v[84:85], s[26:27], v[220:221], v[84:85] op_sel_hi:[0,1,1]
	v_pk_fma_f32 v[86:87], s[26:27], v[222:223], v[86:87] op_sel_hi:[0,1,1]
	v_pk_fma_f32 v[88:89], s[26:27], v[224:225], v[88:89] op_sel_hi:[0,1,1]
	v_pk_fma_f32 v[90:91], s[26:27], v[226:227], v[90:91] op_sel_hi:[0,1,1]
	v_pk_fma_f32 v[92:93], s[26:27], v[228:229], v[92:93] op_sel_hi:[0,1,1]
	v_pk_fma_f32 v[94:95], s[26:27], v[230:231], v[94:95] op_sel_hi:[0,1,1]
	v_readlane_b32 s31, v181, 63
	s_lshl_b32 s31, s31, 10
	v_add_u32_e32 v235, s31, v208
	global_load_dwordx4 v[60:63], v235, s[12:13]
	s_waitcnt vmcnt(15)
	v_readlane_b32 s22, v183, 56
	v_cvt_pk_f32_fp8_e32 v[216:217], v0
	v_cvt_pk_f32_fp8_sdwa v[218:219], v0 src0_sel:WORD_1
	v_cvt_pk_f32_fp8_e32 v[220:221], v1
	v_cvt_pk_f32_fp8_sdwa v[222:223], v1 src0_sel:WORD_1
	v_cvt_pk_f32_fp8_e32 v[224:225], v2
	v_cvt_pk_f32_fp8_sdwa v[226:227], v2 src0_sel:WORD_1
	v_cvt_pk_f32_fp8_e32 v[228:229], v3
	v_cvt_pk_f32_fp8_sdwa v[230:231], v3 src0_sel:WORD_1
	v_pk_fma_f32 v[64:65], s[20:21], v[216:217], v[64:65] op_sel_hi:[0,1,1]
	v_pk_fma_f32 v[66:67], s[20:21], v[218:219], v[66:67] op_sel_hi:[0,1,1]
	v_pk_fma_f32 v[68:69], s[20:21], v[220:221], v[68:69] op_sel_hi:[0,1,1]
	v_pk_fma_f32 v[70:71], s[20:21], v[222:223], v[70:71] op_sel_hi:[0,1,1]
	v_pk_fma_f32 v[72:73], s[20:21], v[224:225], v[72:73] op_sel_hi:[0,1,1]
	v_pk_fma_f32 v[74:75], s[20:21], v[226:227], v[74:75] op_sel_hi:[0,1,1]
	v_pk_fma_f32 v[76:77], s[20:21], v[228:229], v[76:77] op_sel_hi:[0,1,1]
	v_pk_fma_f32 v[78:79], s[20:21], v[230:231], v[78:79] op_sel_hi:[0,1,1]
	v_readlane_b32 s28, v192, 0
	s_lshl_b32 s28, s28, 10
	v_add_u32_e32 v232, s28, v208
	global_load_dwordx4 v[0:3], v232, s[12:13]
	s_waitcnt vmcnt(15)
	v_readlane_b32 s24, v179, 57
	v_cvt_pk_f32_fp8_e32 v[216:217], v4
	v_cvt_pk_f32_fp8_sdwa v[218:219], v4 src0_sel:WORD_1
	v_cvt_pk_f32_fp8_e32 v[220:221], v5
	v_cvt_pk_f32_fp8_sdwa v[222:223], v5 src0_sel:WORD_1
	v_cvt_pk_f32_fp8_e32 v[224:225], v6
	v_cvt_pk_f32_fp8_sdwa v[226:227], v6 src0_sel:WORD_1
	v_cvt_pk_f32_fp8_e32 v[228:229], v7
	v_cvt_pk_f32_fp8_sdwa v[230:231], v7 src0_sel:WORD_1
	v_pk_fma_f32 v[80:81], s[22:23], v[216:217], v[80:81] op_sel_hi:[0,1,1]
	v_pk_fma_f32 v[82:83], s[22:23], v[218:219], v[82:83] op_sel_hi:[0,1,1]
	v_pk_fma_f32 v[84:85], s[22:23], v[220:221], v[84:85] op_sel_hi:[0,1,1]
	v_pk_fma_f32 v[86:87], s[22:23], v[222:223], v[86:87] op_sel_hi:[0,1,1]
	v_pk_fma_f32 v[88:89], s[22:23], v[224:225], v[88:89] op_sel_hi:[0,1,1]
	v_pk_fma_f32 v[90:91], s[22:23], v[226:227], v[90:91] op_sel_hi:[0,1,1]
	v_pk_fma_f32 v[92:93], s[22:23], v[228:229], v[92:93] op_sel_hi:[0,1,1]
	v_pk_fma_f32 v[94:95], s[22:23], v[230:231], v[94:95] op_sel_hi:[0,1,1]
	v_readlane_b32 s29, v196, 0
	s_lshl_b32 s29, s29, 10
	v_add_u32_e32 v233, s29, v208
	global_load_dwordx4 v[4:7], v233, s[12:13]
	s_waitcnt vmcnt(15)
	v_readlane_b32 s26, v183, 57
	v_cvt_pk_f32_fp8_e32 v[216:217], v8
	v_cvt_pk_f32_fp8_sdwa v[218:219], v8 src0_sel:WORD_1
	v_cvt_pk_f32_fp8_e32 v[220:221], v9
	v_cvt_pk_f32_fp8_sdwa v[222:223], v9 src0_sel:WORD_1
	v_cvt_pk_f32_fp8_e32 v[224:225], v10
	v_cvt_pk_f32_fp8_sdwa v[226:227], v10 src0_sel:WORD_1
	v_cvt_pk_f32_fp8_e32 v[228:229], v11
	v_cvt_pk_f32_fp8_sdwa v[230:231], v11 src0_sel:WORD_1
	v_pk_fma_f32 v[64:65], s[24:25], v[216:217], v[64:65] op_sel_hi:[0,1,1]
	v_pk_fma_f32 v[66:67], s[24:25], v[218:219], v[66:67] op_sel_hi:[0,1,1]
	v_pk_fma_f32 v[68:69], s[24:25], v[220:221], v[68:69] op_sel_hi:[0,1,1]
	v_pk_fma_f32 v[70:71], s[24:25], v[222:223], v[70:71] op_sel_hi:[0,1,1]
	v_pk_fma_f32 v[72:73], s[24:25], v[224:225], v[72:73] op_sel_hi:[0,1,1]
	v_pk_fma_f32 v[74:75], s[24:25], v[226:227], v[74:75] op_sel_hi:[0,1,1]
	v_pk_fma_f32 v[76:77], s[24:25], v[228:229], v[76:77] op_sel_hi:[0,1,1]
	v_pk_fma_f32 v[78:79], s[24:25], v[230:231], v[78:79] op_sel_hi:[0,1,1]
	v_readlane_b32 s30, v192, 1
	s_lshl_b32 s30, s30, 10
	v_add_u32_e32 v234, s30, v208
	global_load_dwordx4 v[8:11], v234, s[12:13]
	s_waitcnt vmcnt(15)
	v_readlane_b32 s20, v179, 58
	v_cvt_pk_f32_fp8_e32 v[216:217], v12
	v_cvt_pk_f32_fp8_sdwa v[218:219], v12 src0_sel:WORD_1
	v_cvt_pk_f32_fp8_e32 v[220:221], v13
	v_cvt_pk_f32_fp8_sdwa v[222:223], v13 src0_sel:WORD_1
	v_cvt_pk_f32_fp8_e32 v[224:225], v14
	v_cvt_pk_f32_fp8_sdwa v[226:227], v14 src0_sel:WORD_1
	v_cvt_pk_f32_fp8_e32 v[228:229], v15
	v_cvt_pk_f32_fp8_sdwa v[230:231], v15 src0_sel:WORD_1
	v_pk_fma_f32 v[80:81], s[26:27], v[216:217], v[80:81] op_sel_hi:[0,1,1]
	v_pk_fma_f32 v[82:83], s[26:27], v[218:219], v[82:83] op_sel_hi:[0,1,1]
	v_pk_fma_f32 v[84:85], s[26:27], v[220:221], v[84:85] op_sel_hi:[0,1,1]
	v_pk_fma_f32 v[86:87], s[26:27], v[222:223], v[86:87] op_sel_hi:[0,1,1]
	v_pk_fma_f32 v[88:89], s[26:27], v[224:225], v[88:89] op_sel_hi:[0,1,1]
	v_pk_fma_f32 v[90:91], s[26:27], v[226:227], v[90:91] op_sel_hi:[0,1,1]
	v_pk_fma_f32 v[92:93], s[26:27], v[228:229], v[92:93] op_sel_hi:[0,1,1]
	v_pk_fma_f32 v[94:95], s[26:27], v[230:231], v[94:95] op_sel_hi:[0,1,1]
	v_readlane_b32 s31, v196, 1
	s_lshl_b32 s31, s31, 10
	v_add_u32_e32 v235, s31, v208
	global_load_dwordx4 v[12:15], v235, s[12:13]
	s_waitcnt vmcnt(15)
	v_readlane_b32 s22, v183, 58
	v_cvt_pk_f32_fp8_e32 v[216:217], v16
	v_cvt_pk_f32_fp8_sdwa v[218:219], v16 src0_sel:WORD_1
	v_cvt_pk_f32_fp8_e32 v[220:221], v17
	v_cvt_pk_f32_fp8_sdwa v[222:223], v17 src0_sel:WORD_1
	v_cvt_pk_f32_fp8_e32 v[224:225], v18
	v_cvt_pk_f32_fp8_sdwa v[226:227], v18 src0_sel:WORD_1
	v_cvt_pk_f32_fp8_e32 v[228:229], v19
	v_cvt_pk_f32_fp8_sdwa v[230:231], v19 src0_sel:WORD_1
	v_pk_fma_f32 v[64:65], s[20:21], v[216:217], v[64:65] op_sel_hi:[0,1,1]
	v_pk_fma_f32 v[66:67], s[20:21], v[218:219], v[66:67] op_sel_hi:[0,1,1]
	v_pk_fma_f32 v[68:69], s[20:21], v[220:221], v[68:69] op_sel_hi:[0,1,1]
	v_pk_fma_f32 v[70:71], s[20:21], v[222:223], v[70:71] op_sel_hi:[0,1,1]
	v_pk_fma_f32 v[72:73], s[20:21], v[224:225], v[72:73] op_sel_hi:[0,1,1]
	v_pk_fma_f32 v[74:75], s[20:21], v[226:227], v[74:75] op_sel_hi:[0,1,1]
	v_pk_fma_f32 v[76:77], s[20:21], v[228:229], v[76:77] op_sel_hi:[0,1,1]
	v_pk_fma_f32 v[78:79], s[20:21], v[230:231], v[78:79] op_sel_hi:[0,1,1]
	v_readlane_b32 s28, v192, 2
	s_lshl_b32 s28, s28, 10
	v_add_u32_e32 v232, s28, v208
	global_load_dwordx4 v[16:19], v232, s[12:13]
	s_waitcnt vmcnt(15)
	v_readlane_b32 s24, v179, 59
	v_cvt_pk_f32_fp8_e32 v[216:217], v20
	v_cvt_pk_f32_fp8_sdwa v[218:219], v20 src0_sel:WORD_1
	v_cvt_pk_f32_fp8_e32 v[220:221], v21
	v_cvt_pk_f32_fp8_sdwa v[222:223], v21 src0_sel:WORD_1
	v_cvt_pk_f32_fp8_e32 v[224:225], v22
	v_cvt_pk_f32_fp8_sdwa v[226:227], v22 src0_sel:WORD_1
	v_cvt_pk_f32_fp8_e32 v[228:229], v23
	v_cvt_pk_f32_fp8_sdwa v[230:231], v23 src0_sel:WORD_1
	v_pk_fma_f32 v[80:81], s[22:23], v[216:217], v[80:81] op_sel_hi:[0,1,1]
	v_pk_fma_f32 v[82:83], s[22:23], v[218:219], v[82:83] op_sel_hi:[0,1,1]
	v_pk_fma_f32 v[84:85], s[22:23], v[220:221], v[84:85] op_sel_hi:[0,1,1]
	v_pk_fma_f32 v[86:87], s[22:23], v[222:223], v[86:87] op_sel_hi:[0,1,1]
	v_pk_fma_f32 v[88:89], s[22:23], v[224:225], v[88:89] op_sel_hi:[0,1,1]
	v_pk_fma_f32 v[90:91], s[22:23], v[226:227], v[90:91] op_sel_hi:[0,1,1]
	v_pk_fma_f32 v[92:93], s[22:23], v[228:229], v[92:93] op_sel_hi:[0,1,1]
	v_pk_fma_f32 v[94:95], s[22:23], v[230:231], v[94:95] op_sel_hi:[0,1,1]
	v_readlane_b32 s29, v196, 2
	s_lshl_b32 s29, s29, 10
	v_add_u32_e32 v233, s29, v208
	global_load_dwordx4 v[20:23], v233, s[12:13]
	s_waitcnt vmcnt(15)
	v_readlane_b32 s26, v183, 59
	v_cvt_pk_f32_fp8_e32 v[216:217], v24
	v_cvt_pk_f32_fp8_sdwa v[218:219], v24 src0_sel:WORD_1
	v_cvt_pk_f32_fp8_e32 v[220:221], v25
	v_cvt_pk_f32_fp8_sdwa v[222:223], v25 src0_sel:WORD_1
	v_cvt_pk_f32_fp8_e32 v[224:225], v26
	v_cvt_pk_f32_fp8_sdwa v[226:227], v26 src0_sel:WORD_1
	v_cvt_pk_f32_fp8_e32 v[228:229], v27
	v_cvt_pk_f32_fp8_sdwa v[230:231], v27 src0_sel:WORD_1
	v_pk_fma_f32 v[64:65], s[24:25], v[216:217], v[64:65] op_sel_hi:[0,1,1]
	v_pk_fma_f32 v[66:67], s[24:25], v[218:219], v[66:67] op_sel_hi:[0,1,1]
	v_pk_fma_f32 v[68:69], s[24:25], v[220:221], v[68:69] op_sel_hi:[0,1,1]
	v_pk_fma_f32 v[70:71], s[24:25], v[222:223], v[70:71] op_sel_hi:[0,1,1]
	v_pk_fma_f32 v[72:73], s[24:25], v[224:225], v[72:73] op_sel_hi:[0,1,1]
	v_pk_fma_f32 v[74:75], s[24:25], v[226:227], v[74:75] op_sel_hi:[0,1,1]
	v_pk_fma_f32 v[76:77], s[24:25], v[228:229], v[76:77] op_sel_hi:[0,1,1]
	v_pk_fma_f32 v[78:79], s[24:25], v[230:231], v[78:79] op_sel_hi:[0,1,1]
	v_readlane_b32 s30, v192, 3
	s_lshl_b32 s30, s30, 10
	v_add_u32_e32 v234, s30, v208
	global_load_dwordx4 v[24:27], v234, s[12:13]
	s_waitcnt vmcnt(15)
	v_readlane_b32 s20, v179, 60
	v_cvt_pk_f32_fp8_e32 v[216:217], v28
	v_cvt_pk_f32_fp8_sdwa v[218:219], v28 src0_sel:WORD_1
	v_cvt_pk_f32_fp8_e32 v[220:221], v29
	v_cvt_pk_f32_fp8_sdwa v[222:223], v29 src0_sel:WORD_1
	v_cvt_pk_f32_fp8_e32 v[224:225], v30
	v_cvt_pk_f32_fp8_sdwa v[226:227], v30 src0_sel:WORD_1
	v_cvt_pk_f32_fp8_e32 v[228:229], v31
	v_cvt_pk_f32_fp8_sdwa v[230:231], v31 src0_sel:WORD_1
	v_pk_fma_f32 v[80:81], s[26:27], v[216:217], v[80:81] op_sel_hi:[0,1,1]
	v_pk_fma_f32 v[82:83], s[26:27], v[218:219], v[82:83] op_sel_hi:[0,1,1]
	v_pk_fma_f32 v[84:85], s[26:27], v[220:221], v[84:85] op_sel_hi:[0,1,1]
	v_pk_fma_f32 v[86:87], s[26:27], v[222:223], v[86:87] op_sel_hi:[0,1,1]
	v_pk_fma_f32 v[88:89], s[26:27], v[224:225], v[88:89] op_sel_hi:[0,1,1]
	v_pk_fma_f32 v[90:91], s[26:27], v[226:227], v[90:91] op_sel_hi:[0,1,1]
	v_pk_fma_f32 v[92:93], s[26:27], v[228:229], v[92:93] op_sel_hi:[0,1,1]
	v_pk_fma_f32 v[94:95], s[26:27], v[230:231], v[94:95] op_sel_hi:[0,1,1]
	v_readlane_b32 s31, v196, 3
	s_lshl_b32 s31, s31, 10
	v_add_u32_e32 v235, s31, v208
	global_load_dwordx4 v[28:31], v235, s[12:13]
	s_waitcnt vmcnt(15)
	v_readlane_b32 s22, v183, 60
	v_cvt_pk_f32_fp8_e32 v[216:217], v32
	v_cvt_pk_f32_fp8_sdwa v[218:219], v32 src0_sel:WORD_1
	v_cvt_pk_f32_fp8_e32 v[220:221], v33
	v_cvt_pk_f32_fp8_sdwa v[222:223], v33 src0_sel:WORD_1
	v_cvt_pk_f32_fp8_e32 v[224:225], v34
	v_cvt_pk_f32_fp8_sdwa v[226:227], v34 src0_sel:WORD_1
	v_cvt_pk_f32_fp8_e32 v[228:229], v35
	v_cvt_pk_f32_fp8_sdwa v[230:231], v35 src0_sel:WORD_1
	v_pk_fma_f32 v[64:65], s[20:21], v[216:217], v[64:65] op_sel_hi:[0,1,1]
	v_pk_fma_f32 v[66:67], s[20:21], v[218:219], v[66:67] op_sel_hi:[0,1,1]
	v_pk_fma_f32 v[68:69], s[20:21], v[220:221], v[68:69] op_sel_hi:[0,1,1]
	v_pk_fma_f32 v[70:71], s[20:21], v[222:223], v[70:71] op_sel_hi:[0,1,1]
	v_pk_fma_f32 v[72:73], s[20:21], v[224:225], v[72:73] op_sel_hi:[0,1,1]
	v_pk_fma_f32 v[74:75], s[20:21], v[226:227], v[74:75] op_sel_hi:[0,1,1]
	v_pk_fma_f32 v[76:77], s[20:21], v[228:229], v[76:77] op_sel_hi:[0,1,1]
	v_pk_fma_f32 v[78:79], s[20:21], v[230:231], v[78:79] op_sel_hi:[0,1,1]
	v_readlane_b32 s28, v192, 4
	s_lshl_b32 s28, s28, 10
	v_add_u32_e32 v232, s28, v208
	global_load_dwordx4 v[32:35], v232, s[12:13]
	s_waitcnt vmcnt(15)
	v_readlane_b32 s24, v179, 61
	v_cvt_pk_f32_fp8_e32 v[216:217], v36
	v_cvt_pk_f32_fp8_sdwa v[218:219], v36 src0_sel:WORD_1
	v_cvt_pk_f32_fp8_e32 v[220:221], v37
	v_cvt_pk_f32_fp8_sdwa v[222:223], v37 src0_sel:WORD_1
	v_cvt_pk_f32_fp8_e32 v[224:225], v38
	v_cvt_pk_f32_fp8_sdwa v[226:227], v38 src0_sel:WORD_1
	v_cvt_pk_f32_fp8_e32 v[228:229], v39
	v_cvt_pk_f32_fp8_sdwa v[230:231], v39 src0_sel:WORD_1
	v_pk_fma_f32 v[80:81], s[22:23], v[216:217], v[80:81] op_sel_hi:[0,1,1]
	v_pk_fma_f32 v[82:83], s[22:23], v[218:219], v[82:83] op_sel_hi:[0,1,1]
	v_pk_fma_f32 v[84:85], s[22:23], v[220:221], v[84:85] op_sel_hi:[0,1,1]
	v_pk_fma_f32 v[86:87], s[22:23], v[222:223], v[86:87] op_sel_hi:[0,1,1]
	v_pk_fma_f32 v[88:89], s[22:23], v[224:225], v[88:89] op_sel_hi:[0,1,1]
	v_pk_fma_f32 v[90:91], s[22:23], v[226:227], v[90:91] op_sel_hi:[0,1,1]
	v_pk_fma_f32 v[92:93], s[22:23], v[228:229], v[92:93] op_sel_hi:[0,1,1]
	v_pk_fma_f32 v[94:95], s[22:23], v[230:231], v[94:95] op_sel_hi:[0,1,1]
	v_readlane_b32 s29, v196, 4
	s_lshl_b32 s29, s29, 10
	v_add_u32_e32 v233, s29, v208
	global_load_dwordx4 v[36:39], v233, s[12:13]
	s_waitcnt vmcnt(15)
	v_readlane_b32 s26, v183, 61
	v_cvt_pk_f32_fp8_e32 v[216:217], v40
	v_cvt_pk_f32_fp8_sdwa v[218:219], v40 src0_sel:WORD_1
	v_cvt_pk_f32_fp8_e32 v[220:221], v41
	v_cvt_pk_f32_fp8_sdwa v[222:223], v41 src0_sel:WORD_1
	v_cvt_pk_f32_fp8_e32 v[224:225], v42
	v_cvt_pk_f32_fp8_sdwa v[226:227], v42 src0_sel:WORD_1
	v_cvt_pk_f32_fp8_e32 v[228:229], v43
	v_cvt_pk_f32_fp8_sdwa v[230:231], v43 src0_sel:WORD_1
	v_pk_fma_f32 v[64:65], s[24:25], v[216:217], v[64:65] op_sel_hi:[0,1,1]
	v_pk_fma_f32 v[66:67], s[24:25], v[218:219], v[66:67] op_sel_hi:[0,1,1]
	v_pk_fma_f32 v[68:69], s[24:25], v[220:221], v[68:69] op_sel_hi:[0,1,1]
	v_pk_fma_f32 v[70:71], s[24:25], v[222:223], v[70:71] op_sel_hi:[0,1,1]
	v_pk_fma_f32 v[72:73], s[24:25], v[224:225], v[72:73] op_sel_hi:[0,1,1]
	v_pk_fma_f32 v[74:75], s[24:25], v[226:227], v[74:75] op_sel_hi:[0,1,1]
	v_pk_fma_f32 v[76:77], s[24:25], v[228:229], v[76:77] op_sel_hi:[0,1,1]
	v_pk_fma_f32 v[78:79], s[24:25], v[230:231], v[78:79] op_sel_hi:[0,1,1]
	v_readlane_b32 s30, v192, 5
	s_lshl_b32 s30, s30, 10
	v_add_u32_e32 v234, s30, v208
	global_load_dwordx4 v[40:43], v234, s[12:13]
	s_waitcnt vmcnt(15)
	v_readlane_b32 s20, v179, 62
	v_cvt_pk_f32_fp8_e32 v[216:217], v44
	v_cvt_pk_f32_fp8_sdwa v[218:219], v44 src0_sel:WORD_1
	v_cvt_pk_f32_fp8_e32 v[220:221], v45
	v_cvt_pk_f32_fp8_sdwa v[222:223], v45 src0_sel:WORD_1
	v_cvt_pk_f32_fp8_e32 v[224:225], v46
	v_cvt_pk_f32_fp8_sdwa v[226:227], v46 src0_sel:WORD_1
	v_cvt_pk_f32_fp8_e32 v[228:229], v47
	v_cvt_pk_f32_fp8_sdwa v[230:231], v47 src0_sel:WORD_1
	v_pk_fma_f32 v[80:81], s[26:27], v[216:217], v[80:81] op_sel_hi:[0,1,1]
	v_pk_fma_f32 v[82:83], s[26:27], v[218:219], v[82:83] op_sel_hi:[0,1,1]
	v_pk_fma_f32 v[84:85], s[26:27], v[220:221], v[84:85] op_sel_hi:[0,1,1]
	v_pk_fma_f32 v[86:87], s[26:27], v[222:223], v[86:87] op_sel_hi:[0,1,1]
	v_pk_fma_f32 v[88:89], s[26:27], v[224:225], v[88:89] op_sel_hi:[0,1,1]
	v_pk_fma_f32 v[90:91], s[26:27], v[226:227], v[90:91] op_sel_hi:[0,1,1]
	v_pk_fma_f32 v[92:93], s[26:27], v[228:229], v[92:93] op_sel_hi:[0,1,1]
	v_pk_fma_f32 v[94:95], s[26:27], v[230:231], v[94:95] op_sel_hi:[0,1,1]
	v_readlane_b32 s31, v196, 5
	s_lshl_b32 s31, s31, 10
	v_add_u32_e32 v235, s31, v208
	global_load_dwordx4 v[44:47], v235, s[12:13]
	s_waitcnt vmcnt(15)
	v_readlane_b32 s22, v183, 62
	v_cvt_pk_f32_fp8_e32 v[216:217], v48
	v_cvt_pk_f32_fp8_sdwa v[218:219], v48 src0_sel:WORD_1
	v_cvt_pk_f32_fp8_e32 v[220:221], v49
	v_cvt_pk_f32_fp8_sdwa v[222:223], v49 src0_sel:WORD_1
	v_cvt_pk_f32_fp8_e32 v[224:225], v50
	v_cvt_pk_f32_fp8_sdwa v[226:227], v50 src0_sel:WORD_1
	v_cvt_pk_f32_fp8_e32 v[228:229], v51
	v_cvt_pk_f32_fp8_sdwa v[230:231], v51 src0_sel:WORD_1
	v_pk_fma_f32 v[64:65], s[20:21], v[216:217], v[64:65] op_sel_hi:[0,1,1]
	v_pk_fma_f32 v[66:67], s[20:21], v[218:219], v[66:67] op_sel_hi:[0,1,1]
	v_pk_fma_f32 v[68:69], s[20:21], v[220:221], v[68:69] op_sel_hi:[0,1,1]
	v_pk_fma_f32 v[70:71], s[20:21], v[222:223], v[70:71] op_sel_hi:[0,1,1]
	v_pk_fma_f32 v[72:73], s[20:21], v[224:225], v[72:73] op_sel_hi:[0,1,1]
	v_pk_fma_f32 v[74:75], s[20:21], v[226:227], v[74:75] op_sel_hi:[0,1,1]
	v_pk_fma_f32 v[76:77], s[20:21], v[228:229], v[76:77] op_sel_hi:[0,1,1]
	v_pk_fma_f32 v[78:79], s[20:21], v[230:231], v[78:79] op_sel_hi:[0,1,1]
	v_readlane_b32 s28, v192, 6
	s_lshl_b32 s28, s28, 10
	v_add_u32_e32 v232, s28, v208
	global_load_dwordx4 v[48:51], v232, s[12:13]
	s_waitcnt vmcnt(15)
	v_readlane_b32 s24, v179, 63
	v_cvt_pk_f32_fp8_e32 v[216:217], v52
	v_cvt_pk_f32_fp8_sdwa v[218:219], v52 src0_sel:WORD_1
	v_cvt_pk_f32_fp8_e32 v[220:221], v53
	v_cvt_pk_f32_fp8_sdwa v[222:223], v53 src0_sel:WORD_1
	v_cvt_pk_f32_fp8_e32 v[224:225], v54
	v_cvt_pk_f32_fp8_sdwa v[226:227], v54 src0_sel:WORD_1
	v_cvt_pk_f32_fp8_e32 v[228:229], v55
	v_cvt_pk_f32_fp8_sdwa v[230:231], v55 src0_sel:WORD_1
	v_pk_fma_f32 v[80:81], s[22:23], v[216:217], v[80:81] op_sel_hi:[0,1,1]
	v_pk_fma_f32 v[82:83], s[22:23], v[218:219], v[82:83] op_sel_hi:[0,1,1]
	v_pk_fma_f32 v[84:85], s[22:23], v[220:221], v[84:85] op_sel_hi:[0,1,1]
	v_pk_fma_f32 v[86:87], s[22:23], v[222:223], v[86:87] op_sel_hi:[0,1,1]
	v_pk_fma_f32 v[88:89], s[22:23], v[224:225], v[88:89] op_sel_hi:[0,1,1]
	v_pk_fma_f32 v[90:91], s[22:23], v[226:227], v[90:91] op_sel_hi:[0,1,1]
	v_pk_fma_f32 v[92:93], s[22:23], v[228:229], v[92:93] op_sel_hi:[0,1,1]
	v_pk_fma_f32 v[94:95], s[22:23], v[230:231], v[94:95] op_sel_hi:[0,1,1]
	v_readlane_b32 s29, v196, 6
	s_lshl_b32 s29, s29, 10
	v_add_u32_e32 v233, s29, v208
	global_load_dwordx4 v[52:55], v233, s[12:13]
	s_waitcnt vmcnt(15)
; template <int PART>
; DEVI void phase_peer_gather(const Params& p, unsigned char* smem) {
;     ...
; #pragma unroll
;     for (int i = 0; i < 8; ++i) { y[2 * i] = y2[i][0]; y[2 * i + 1] = y2[i][1]; }
;     float s2 = 0.f;
;     {
;       const uint4 a0 = hp4[0], a1 = hp4[1];
;       const unsigned hu[8] = {a0.x, a0.y, a0.z, a0.w, a1.x, a1.y, a1.z, a1.w};
; #pragma unroll
;       for (int i = 0; i < 8; ++i) {
;         y[2 * i] += __uint_as_float(hu[i] << 16);
;         y[2 * i + 1] += __uint_as_float(hu[i] & 0xffff0000u);
;         s2 += y[2 * i] * y[2 * i] + y[2 * i + 1] * y[2 * i + 1];
;       }
;     }
;     s2 = wave_sum(s2);
;     const float rs2 = rsqrtf(s2 * (1.f / D) + 1e-6f);
;     {
;       const float4* g4 = (const float4*)p.final_g + lane * 4;
;       const float4 a0 = g4[0], a1 = g4[1], a2 = g4[2], a3 = g4[3];
;       float4* o4 = (float4*)(p.out + (size_t)tok * D) + lane * 4;
;       o4[0] = make_float4(y[0] * rs2 * a0.x, y[1] * rs2 * a0.y, y[2] * rs2 * a0.z, y[3] * rs2 * a0.w);
;       o4[1] = make_float4(y[4] * rs2 * a1.x, y[5] * rs2 * a1.y, y[6] * rs2 * a1.z, y[7] * rs2 * a1.w);
;       o4[2] = make_float4(y[8] * rs2 * a2.x, y[9] * rs2 * a2.y, y[10] * rs2 * a2.z, y[11] * rs2 * a2.w);
;       o4[3] = make_float4(y[12] * rs2 * a3.x, y[13] * rs2 * a3.y, y[14] * rs2 * a3.z, y[15] * rs2 * a3.w);
;     }
	v_readlane_b32 s26, v183, 63
	v_cvt_pk_f32_fp8_e32 v[216:217], v56
	v_cvt_pk_f32_fp8_sdwa v[218:219], v56 src0_sel:WORD_1
	v_cvt_pk_f32_fp8_e32 v[220:221], v57
	v_cvt_pk_f32_fp8_sdwa v[222:223], v57 src0_sel:WORD_1
	v_cvt_pk_f32_fp8_e32 v[224:225], v58
	v_cvt_pk_f32_fp8_sdwa v[226:227], v58 src0_sel:WORD_1
	v_cvt_pk_f32_fp8_e32 v[228:229], v59
	v_cvt_pk_f32_fp8_sdwa v[230:231], v59 src0_sel:WORD_1
	v_pk_fma_f32 v[64:65], s[24:25], v[216:217], v[64:65] op_sel_hi:[0,1,1]
	v_pk_fma_f32 v[66:67], s[24:25], v[218:219], v[66:67] op_sel_hi:[0,1,1]
	v_pk_fma_f32 v[68:69], s[24:25], v[220:221], v[68:69] op_sel_hi:[0,1,1]
	v_pk_fma_f32 v[70:71], s[24:25], v[222:223], v[70:71] op_sel_hi:[0,1,1]
	v_pk_fma_f32 v[72:73], s[24:25], v[224:225], v[72:73] op_sel_hi:[0,1,1]
	v_pk_fma_f32 v[74:75], s[24:25], v[226:227], v[74:75] op_sel_hi:[0,1,1]
	v_pk_fma_f32 v[76:77], s[24:25], v[228:229], v[76:77] op_sel_hi:[0,1,1]
	v_pk_fma_f32 v[78:79], s[24:25], v[230:231], v[78:79] op_sel_hi:[0,1,1]
	v_readlane_b32 s30, v192, 7
	s_lshl_b32 s30, s30, 10
	v_add_u32_e32 v234, s30, v208
	global_load_dwordx4 v[56:59], v234, s[12:13]
	s_waitcnt vmcnt(15)
	v_cvt_pk_f32_fp8_e32 v[216:217], v60
	v_cvt_pk_f32_fp8_sdwa v[218:219], v60 src0_sel:WORD_1
	v_cvt_pk_f32_fp8_e32 v[220:221], v61
	v_cvt_pk_f32_fp8_sdwa v[222:223], v61 src0_sel:WORD_1
	v_cvt_pk_f32_fp8_e32 v[224:225], v62
	v_cvt_pk_f32_fp8_sdwa v[226:227], v62 src0_sel:WORD_1
	v_cvt_pk_f32_fp8_e32 v[228:229], v63
	v_cvt_pk_f32_fp8_sdwa v[230:231], v63 src0_sel:WORD_1
	v_pk_fma_f32 v[80:81], s[26:27], v[216:217], v[80:81] op_sel_hi:[0,1,1]
	v_pk_fma_f32 v[82:83], s[26:27], v[218:219], v[82:83] op_sel_hi:[0,1,1]
	v_pk_fma_f32 v[84:85], s[26:27], v[220:221], v[84:85] op_sel_hi:[0,1,1]
	v_pk_fma_f32 v[86:87], s[26:27], v[222:223], v[86:87] op_sel_hi:[0,1,1]
	v_pk_fma_f32 v[88:89], s[26:27], v[224:225], v[88:89] op_sel_hi:[0,1,1]
	v_pk_fma_f32 v[90:91], s[26:27], v[226:227], v[90:91] op_sel_hi:[0,1,1]
	v_pk_fma_f32 v[92:93], s[26:27], v[228:229], v[92:93] op_sel_hi:[0,1,1]
	v_pk_fma_f32 v[94:95], s[26:27], v[230:231], v[94:95] op_sel_hi:[0,1,1]
	v_readlane_b32 s31, v196, 7
	s_lshl_b32 s31, s31, 10
	v_add_u32_e32 v235, s31, v208
	global_load_dwordx4 v[60:63], v235, s[12:13]
	v_lshlrev_b32_e32 v240, 16, v144
	v_add_f32_e32 v64, v240, v64
	v_and_b32_e32 v240, 0xffff0000, v144
	v_add_f32_e32 v65, v240, v65
	v_lshlrev_b32_e32 v240, 16, v145
	v_add_f32_e32 v66, v240, v66
	v_and_b32_e32 v240, 0xffff0000, v145
	v_add_f32_e32 v67, v240, v67
	v_lshlrev_b32_e32 v240, 16, v146
	v_add_f32_e32 v68, v240, v68
	v_and_b32_e32 v240, 0xffff0000, v146
	v_add_f32_e32 v69, v240, v69
	v_lshlrev_b32_e32 v240, 16, v147
	v_add_f32_e32 v70, v240, v70
	v_and_b32_e32 v240, 0xffff0000, v147
	v_add_f32_e32 v71, v240, v71
	v_lshlrev_b32_e32 v240, 16, v148
	v_add_f32_e32 v72, v240, v72
	v_and_b32_e32 v240, 0xffff0000, v148
	v_add_f32_e32 v73, v240, v73
	v_lshlrev_b32_e32 v240, 16, v149
	v_add_f32_e32 v74, v240, v74
	v_and_b32_e32 v240, 0xffff0000, v149
	v_add_f32_e32 v75, v240, v75
	v_lshlrev_b32_e32 v240, 16, v150
	v_add_f32_e32 v76, v240, v76
	v_and_b32_e32 v240, 0xffff0000, v150
	v_add_f32_e32 v77, v240, v77
	v_lshlrev_b32_e32 v240, 16, v151
	v_add_f32_e32 v78, v240, v78
	v_and_b32_e32 v240, 0xffff0000, v151
	v_add_f32_e32 v79, v240, v79
	v_mul_f32_e32 v241, v64, v64
	v_fmac_f32_e32 v241, v65, v65
	v_fmac_f32_e32 v241, v66, v66
	v_fmac_f32_e32 v241, v67, v67
	v_fmac_f32_e32 v241, v68, v68
	v_fmac_f32_e32 v241, v69, v69
	v_fmac_f32_e32 v241, v70, v70
	v_fmac_f32_e32 v241, v71, v71
	v_fmac_f32_e32 v241, v72, v72
	v_fmac_f32_e32 v241, v73, v73
	v_fmac_f32_e32 v241, v74, v74
	v_fmac_f32_e32 v241, v75, v75
	v_fmac_f32_e32 v241, v76, v76
	v_fmac_f32_e32 v241, v77, v77
	v_fmac_f32_e32 v241, v78, v78
	v_fmac_f32_e32 v241, v79, v79
	s_nop 1
	v_add_f32_dpp v238, v241, v241 quad_perm:[1,0,3,2] row_mask:0xf bank_mask:0xf
	v_mov_b32_e32 v241, v238
	s_nop 1
	v_add_f32_dpp v238, v241, v241 quad_perm:[2,3,0,1] row_mask:0xf bank_mask:0xf
	v_mov_b32_e32 v241, v238
	s_nop 1
	v_add_f32_dpp v238, v241, v241 row_half_mirror row_mask:0xf bank_mask:0xf
	v_mov_b32_e32 v241, v238
	s_nop 1
	v_add_f32_dpp v238, v241, v241 row_mirror row_mask:0xf bank_mask:0xf
	v_mov_b32_e32 v241, v238
	s_nop 0
	v_readlane_b32 s36, v241, 0
	v_readlane_b32 s37, v241, 16
	v_readlane_b32 s38, v241, 32
	v_readlane_b32 s39, v241, 48
	s_nop 1
	v_mov_b32_e32 v241, s36
	v_add_f32_e32 v241, s37, v241
	v_add_f32_e32 v241, s38, v241
	v_add_f32_e32 v241, s39, v241
	v_mov_b32_e32 v239, 0x358637bd
	v_fmamk_f32 v241, v241, 0x3a800000, v239
	v_rsq_f32_e32 v241, v241
	s_nop 0
	s_mov_b32 s33, s3
	s_cmp_lt_u32 s33, 0x8000
	s_lshl_b32 s18, s33, 12
	v_add_u32_e32 v236, s18, v212
	v_mul_f32_e32 v216, v241, v64
	v_mul_f32_e32 v216, v128, v216
	v_mul_f32_e32 v217, v241, v65
	v_mul_f32_e32 v217, v129, v217
	v_mul_f32_e32 v218, v241, v66
	v_mul_f32_e32 v218, v130, v218
	v_mul_f32_e32 v219, v241, v67
	v_mul_f32_e32 v219, v131, v219
	v_mul_f32_e32 v220, v241, v68
	v_mul_f32_e32 v220, v132, v220
	v_mul_f32_e32 v221, v241, v69
	v_mul_f32_e32 v221, v133, v221
	v_mul_f32_e32 v222, v241, v70
	v_mul_f32_e32 v222, v134, v222
	v_mul_f32_e32 v223, v241, v71
	v_mul_f32_e32 v223, v135, v223
	v_mul_f32_e32 v224, v241, v72
	v_mul_f32_e32 v224, v136, v224
	v_mul_f32_e32 v225, v241, v73
	v_mul_f32_e32 v225, v137, v225
	v_mul_f32_e32 v226, v241, v74
	v_mul_f32_e32 v226, v138, v226
	v_mul_f32_e32 v227, v241, v75
	v_mul_f32_e32 v227, v139, v227
	v_mul_f32_e32 v228, v241, v76
	v_mul_f32_e32 v228, v140, v228
	v_mul_f32_e32 v229, v241, v77
	v_mul_f32_e32 v229, v141, v229
	v_mul_f32_e32 v230, v241, v78
	v_mul_f32_e32 v230, v142, v230
	v_mul_f32_e32 v231, v241, v79
	v_mul_f32_e32 v231, v143, v231
	s_cmp_lt_u32 s33, 0x8000
	s_cbranch_scc0 .Lp12_skip0
	global_store_dwordx4 v236, v[216:219], s[14:15]
	global_store_dwordx4 v236, v[220:223], s[14:15] offset:16
	global_store_dwordx4 v236, v[224:227], s[14:15] offset:32
	global_store_dwordx4 v236, v[228:231], s[14:15] offset:48
; DEVI int launder(int x) { asm volatile("" : "+v"(x)); return x; }
; template <int PART>
; DEVI void phase_peer_gather(const Params& p, unsigned char* smem) {
;     ...
;   for (int tok = blockIdx.x * 4 + w0_; tok < NTOK; tok += gridDim.x * 4) {
;     if (NTOK % (gridDim.x * 4) == 0) __syncthreads();
;     const int tid = launder(threadIdx.x), lane = tid & 63;
;     ...
; #pragma unroll
;     for (int i = 0; i < 8; ++i) { y[2 * i] = y2[i][0]; y[2 * i + 1] = y2[i][1]; }
;     float s2 = 0.f;
;     {
;       const uint4 a0 = hp4[0], a1 = hp4[1];
;       const unsigned hu[8] = {a0.x, a0.y, a0.z, a0.w, a1.x, a1.y, a1.z, a1.w};
; #pragma unroll
;       for (int i = 0; i < 8; ++i) {
;         y[2 * i] += __uint_as_float(hu[i] << 16);
;         y[2 * i + 1] += __uint_as_float(hu[i] & 0xffff0000u);
;         s2 += y[2 * i] * y[2 * i] + y[2 * i + 1] * y[2 * i + 1];
;       }
;     }
;     s2 = wave_sum(s2);
;     const float rs2 = rsqrtf(s2 * (1.f / D) + 1e-6f);
;     {
;       const float4* g4 = (const float4*)p.final_g + lane * 4;
;       const float4 a0 = g4[0], a1 = g4[1], a2 = g4[2], a3 = g4[3];
;       float4* o4 = (float4*)(p.out + (size_t)tok * D) + lane * 4;
;       o4[0] = make_float4(y[0] * rs2 * a0.x, y[1] * rs2 * a0.y, y[2] * rs2 * a0.z, y[3] * rs2 * a0.w);
;       o4[1] = make_float4(y[4] * rs2 * a1.x, y[5] * rs2 * a1.y, y[6] * rs2 * a1.z, y[7] * rs2 * a1.w);
;       o4[2] = make_float4(y[8] * rs2 * a2.x, y[9] * rs2 * a2.y, y[10] * rs2 * a2.z, y[11] * rs2 * a2.w);
;       o4[3] = make_float4(y[12] * rs2 * a3.x, y[13] * rs2 * a3.y, y[14] * rs2 * a3.z, y[15] * rs2 * a3.w);
;     }
.Lp12_skip0:
	s_nop 1
	v_lshlrev_b32_e32 v240, 16, v152
	v_add_f32_e32 v80, v240, v80
	v_and_b32_e32 v240, 0xffff0000, v152
	v_add_f32_e32 v81, v240, v81
	v_lshlrev_b32_e32 v240, 16, v153
	v_add_f32_e32 v82, v240, v82
	v_and_b32_e32 v240, 0xffff0000, v153
	v_add_f32_e32 v83, v240, v83
	v_lshlrev_b32_e32 v240, 16, v154
	v_add_f32_e32 v84, v240, v84
	v_and_b32_e32 v240, 0xffff0000, v154
	v_add_f32_e32 v85, v240, v85
	v_lshlrev_b32_e32 v240, 16, v155
	v_add_f32_e32 v86, v240, v86
	v_and_b32_e32 v240, 0xffff0000, v155
	v_add_f32_e32 v87, v240, v87
	v_lshlrev_b32_e32 v240, 16, v156
	v_add_f32_e32 v88, v240, v88
	v_and_b32_e32 v240, 0xffff0000, v156
	v_add_f32_e32 v89, v240, v89
	v_lshlrev_b32_e32 v240, 16, v157
	v_add_f32_e32 v90, v240, v90
	v_and_b32_e32 v240, 0xffff0000, v157
	v_add_f32_e32 v91, v240, v91
	v_lshlrev_b32_e32 v240, 16, v158
	v_add_f32_e32 v92, v240, v92
	v_and_b32_e32 v240, 0xffff0000, v158
	v_add_f32_e32 v93, v240, v93
	v_lshlrev_b32_e32 v240, 16, v159
	v_add_f32_e32 v94, v240, v94
	v_and_b32_e32 v240, 0xffff0000, v159
	v_add_f32_e32 v95, v240, v95
	v_mul_f32_e32 v241, v80, v80
	v_fmac_f32_e32 v241, v81, v81
	v_fmac_f32_e32 v241, v82, v82
	v_fmac_f32_e32 v241, v83, v83
	v_fmac_f32_e32 v241, v84, v84
	v_fmac_f32_e32 v241, v85, v85
	v_fmac_f32_e32 v241, v86, v86
	v_fmac_f32_e32 v241, v87, v87
	v_fmac_f32_e32 v241, v88, v88
	v_fmac_f32_e32 v241, v89, v89
	v_fmac_f32_e32 v241, v90, v90
	v_fmac_f32_e32 v241, v91, v91
	v_fmac_f32_e32 v241, v92, v92
	v_fmac_f32_e32 v241, v93, v93
	v_fmac_f32_e32 v241, v94, v94
	v_fmac_f32_e32 v241, v95, v95
	s_nop 1
	v_add_f32_dpp v238, v241, v241 quad_perm:[1,0,3,2] row_mask:0xf bank_mask:0xf
	v_mov_b32_e32 v241, v238
	s_nop 1
	v_add_f32_dpp v238, v241, v241 quad_perm:[2,3,0,1] row_mask:0xf bank_mask:0xf
	v_mov_b32_e32 v241, v238
	s_nop 1
	v_add_f32_dpp v238, v241, v241 row_half_mirror row_mask:0xf bank_mask:0xf
	v_mov_b32_e32 v241, v238
	s_nop 1
	v_add_f32_dpp v238, v241, v241 row_mirror row_mask:0xf bank_mask:0xf
	v_mov_b32_e32 v241, v238
	s_nop 0
	v_readlane_b32 s36, v241, 0
	v_readlane_b32 s37, v241, 16
	v_readlane_b32 s38, v241, 32
	v_readlane_b32 s39, v241, 48
	s_nop 1
	v_mov_b32_e32 v241, s36
	v_add_f32_e32 v241, s37, v241
	v_add_f32_e32 v241, s38, v241
	v_add_f32_e32 v241, s39, v241
	v_mov_b32_e32 v239, 0x358637bd
	v_fmamk_f32 v241, v241, 0x3a800000, v239
	v_rsq_f32_e32 v241, v241
	s_nop 0
	s_mov_b32 s33, s3
	s_add_u32 s33, s33, s2
	s_add_u32 s33, s33, s2
	s_cmp_lt_u32 s33, 0x8000
	s_lshl_b32 s18, s33, 12
	v_add_u32_e32 v236, s18, v212
	v_mul_f32_e32 v216, v241, v80
	v_mul_f32_e32 v216, v128, v216
	v_mul_f32_e32 v217, v241, v81
	v_mul_f32_e32 v217, v129, v217
	v_mul_f32_e32 v218, v241, v82
	v_mul_f32_e32 v218, v130, v218
	v_mul_f32_e32 v219, v241, v83
	v_mul_f32_e32 v219, v131, v219
	v_mul_f32_e32 v220, v241, v84
	v_mul_f32_e32 v220, v132, v220
	v_mul_f32_e32 v221, v241, v85
	v_mul_f32_e32 v221, v133, v221
	v_mul_f32_e32 v222, v241, v86
	v_mul_f32_e32 v222, v134, v222
	v_mul_f32_e32 v223, v241, v87
	v_mul_f32_e32 v223, v135, v223
	v_mul_f32_e32 v224, v241, v88
	v_mul_f32_e32 v224, v136, v224
	v_mul_f32_e32 v225, v241, v89
	v_mul_f32_e32 v225, v137, v225
	v_mul_f32_e32 v226, v241, v90
	v_mul_f32_e32 v226, v138, v226
	v_mul_f32_e32 v227, v241, v91
	v_mul_f32_e32 v227, v139, v227
	v_mul_f32_e32 v228, v241, v92
	v_mul_f32_e32 v228, v140, v228
	v_mul_f32_e32 v229, v241, v93
	v_mul_f32_e32 v229, v141, v229
	v_mul_f32_e32 v230, v241, v94
	v_mul_f32_e32 v230, v142, v230
	v_mul_f32_e32 v231, v241, v95
	v_mul_f32_e32 v231, v143, v231
	s_cmp_lt_u32 s33, 0x8000
	s_cbranch_scc0 .Lp12_skip1
	global_store_dwordx4 v236, v[216:219], s[14:15]
	global_store_dwordx4 v236, v[220:223], s[14:15] offset:16
	global_store_dwordx4 v236, v[224:227], s[14:15] offset:32
	global_store_dwordx4 v236, v[228:231], s[14:15] offset:48
.Lp12_skip1:
	s_nop 1
	v_mov_b32_e32 v176, v192
	v_mov_b32_e32 v177, v193
	v_mov_b32_e32 v178, v194
	v_mov_b32_e32 v179, v195
	v_mov_b32_e32 v180, v196
	v_mov_b32_e32 v181, v197
	v_mov_b32_e32 v182, v198
	v_mov_b32_e32 v183, v199
	v_mov_b32_e32 v64, 0
	v_mov_b32_e32 v65, 0
	v_mov_b32_e32 v66, 0
	v_mov_b32_e32 v67, 0
	v_mov_b32_e32 v68, 0
	v_mov_b32_e32 v69, 0
	v_mov_b32_e32 v70, 0
	v_mov_b32_e32 v71, 0
	v_mov_b32_e32 v72, 0
	v_mov_b32_e32 v73, 0
	v_mov_b32_e32 v74, 0
	v_mov_b32_e32 v75, 0
	v_mov_b32_e32 v76, 0
	v_mov_b32_e32 v77, 0
	v_mov_b32_e32 v78, 0
	v_mov_b32_e32 v79, 0
	v_mov_b32_e32 v80, 0
	v_mov_b32_e32 v81, 0
	v_mov_b32_e32 v82, 0
	v_mov_b32_e32 v83, 0
	v_mov_b32_e32 v84, 0
	v_mov_b32_e32 v85, 0
	v_mov_b32_e32 v86, 0
	v_mov_b32_e32 v87, 0
	v_mov_b32_e32 v88, 0
	v_mov_b32_e32 v89, 0
	v_mov_b32_e32 v90, 0
	v_mov_b32_e32 v91, 0
	v_mov_b32_e32 v92, 0
	v_mov_b32_e32 v93, 0
	v_mov_b32_e32 v94, 0
	v_mov_b32_e32 v95, 0
	s_add_u32 s3, s3, s35
	s_add_u32 s34, s34, 1
	s_cmp_lt_u32 s3, 0x8000
	s_cbranch_scc1 .Lp12_group
	s_waitcnt vmcnt(0)
.Lp12_done:
.LBB0_1457:
	s_or_b64 exec, exec, s[0:1]
	s_cmp_lt_i32 s89, 13
	s_cbranch_scc1 .LBB0_1511
	s_waitcnt vmcnt(0)
	s_waitcnt lgkmcnt(0)
	s_barrier
	s_mov_b64 s[0:1], exec
	v_readlane_b32 s2, v248, 24
	v_readlane_b32 s3, v248, 25
	s_and_b64 s[2:3], s[0:1], s[2:3]
	s_mov_b64 exec, s[2:3]
	s_cbranch_execz .LBB0_1510
	v_mov_b32_e32 v0, 0x12000
	s_waitcnt vmcnt(0) expcnt(0) lgkmcnt(0)
	ds_read_b32 v2, v0
	v_mov_b32_e32 v0, 0x12004
	ds_read_b32 v0, v0
	s_waitcnt lgkmcnt(1)
	v_cmp_ne_u32_e32 vcc, 0, v2
	s_cbranch_vccnz .LBB0_1474
	s_load_dwordx2 s[6:7], s[68:69], 0x200
	s_load_dword s5, s[68:69], 0x208
	s_add_u32 s2, s64, 0x1000
	s_addc_u32 s3, s65, 0
	s_add_u32 s4, s64, 0x1100
	s_waitcnt lgkmcnt(0)
	s_mul_i32 s16, s7, s6
	s_mul_i32 s16, s16, s5
	s_addc_u32 s5, s65, 0
	s_add_u32 s6, s64, 0x1200
	s_addc_u32 s7, s65, 0
	s_add_u32 s8, s64, 0x1300
	s_addc_u32 s9, s65, 0
	s_mov_b32 s17, 1
	v_mov_b32_e32 v16, 0
	s_branch .LBB0_1462
